# baseline (speedup 1.0000x reference)
; #define WAIT_V(n) asm volatile("s_waitcnt vmcnt(" #n ")" ::: "memory")
; #define WAIT_L(n) asm volatile("s_waitcnt lgkmcnt(" #n ")" ::: "memory")
; #define BAR __builtin_amdgcn_s_barrier()
; #define SCHED __builtin_amdgcn_sched_barrier(0)
; #define STAGE(P, BASE, br, kt) do { const char* _g = (const char*)((BASE) + (size_t)(br) * GK + (kt) * BK); \
;     __builtin_amdgcn_global_load_lds((const unsigned*)(_g + voff0), (unsigned*)((char*)(P) + tx * 16), 16, 0, 0); \
;     __builtin_amdgcn_global_load_lds((const unsigned*)(_g + voff1), (unsigned*)((char*)(P) + tx * 16 + 8192), 16, 0, 0); } while (0)
; #define LDA(dst, b, h) _Pragma("unroll") for (int m = 0; m < 4; ++m) _Pragma("unroll") for (int k = 0; k < 2; ++k) \
;     dst[m][k] = *reinterpret_cast<const bf16x8*>((char*)shm + abase + (((b) * 2 + (h)) * 16384 + (m * 2 + k) * 1024))
; #define LDB(dst, b, h) _Pragma("unroll") for (int n = 0; n < 2; ++n) _Pragma("unroll") for (int k = 0; k < 2; ++k) \
;     dst[n][k] = *reinterpret_cast<const bf16x8*>((char*)shm + bbase + (((b) * 2 + (h)) * 16384 + (n * 2 + k) * 1024))
; template <bool SWAP>
; __device__ __forceinline__ void gemm_main(const u16* __restrict__ A, const u16* __restrict__ Bt, int brow, int bcol,
;                                           u16* shm, f32x4 (&acc)[2][2][4][2]) {
;     ...
;   for (int t = 0; t < nt - 2; t += 2) {
;     LDB(B0, 0, 0); SCHED; LDA(At, 0, 0); STAGE(SA(1, 1), A, brow + HALF, t + 1);
;     WAIT_L(8); BAR; WAIT_L(0); MMA(0, 0, At, B0); BAR; SCHED;
;     LDB(B1, 0, 1); STAGE(SB(0, 0), Bt, bcol, t + 2);
;     BAR; WAIT_L(0); MMA(0, 1, At, B1); BAR;
;     LDA(At, 0, 1); STAGE(SA(0, 0), A, brow, t + 2);
;     BAR; WAIT_L(0); MMA(1, 0, At, B0); BAR; SCHED;
;     STAGE(SB(0, 1), Bt, bcol + HALF, t + 2);
;     WAIT_V(6); BAR; MMA(1, 1, At, B1); BAR;
.LBB0_84:
	ds_read_b128 v[176:179], v128 offset:1024
	ds_read_b128 v[184:187], v128 offset:3072
	ds_read_b128 v[192:195], v128 offset:5120
	ds_read_b128 v[200:203], v128 offset:7168
	v_add_u32_e32 v211, 0, v146
	v_add_u32_e32 v153, 0xc000, v211
	s_add_u32 m0, s29, 0xc000
	s_nop 0
	s_add_u32 vcc_lo, s26, s6
	s_addc_u32 vcc_hi, s27, s7
	global_load_lds_dwordx4 v134, vcc
	v_add_u32_e32 v154, 0xe000, v211
	v_lshl_add_u64 v[224:225], s[26:27], 0, v[136:137]
	s_add_u32 m0, s29, 0xe000
	s_nop 0
	global_load_lds_dwordx4 v136, vcc
	s_waitcnt lgkmcnt(8)
	s_barrier
	s_waitcnt lgkmcnt(0)
	v_mfma_f32_16x16x32_bf16 v[124:127], v[172:175], v[156:159], v[124:127]
	v_mfma_f32_16x16x32_bf16 v[120:123], v[172:175], v[164:167], v[120:123]
	v_mfma_f32_16x16x32_bf16 v[116:119], v[180:183], v[156:159], v[116:119]
	v_mfma_f32_16x16x32_bf16 v[112:115], v[180:183], v[164:167], v[112:115]
	v_mfma_f32_16x16x32_bf16 v[108:111], v[188:191], v[156:159], v[108:111]
	v_mfma_f32_16x16x32_bf16 v[104:107], v[188:191], v[164:167], v[104:107]
	v_mfma_f32_16x16x32_bf16 v[100:103], v[196:199], v[156:159], v[100:103]
	v_mfma_f32_16x16x32_bf16 v[96:99], v[196:199], v[164:167], v[96:99]
	v_mfma_f32_16x16x32_bf16 v[124:127], v[176:179], v[160:163], v[124:127]
	v_mfma_f32_16x16x32_bf16 v[120:123], v[176:179], v[168:171], v[120:123]
	v_mfma_f32_16x16x32_bf16 v[116:119], v[184:187], v[160:163], v[116:119]
	v_mfma_f32_16x16x32_bf16 v[112:115], v[184:187], v[168:171], v[112:115]
	v_mfma_f32_16x16x32_bf16 v[108:111], v[192:195], v[160:163], v[108:111]
	v_mfma_f32_16x16x32_bf16 v[104:107], v[192:195], v[168:171], v[104:107]
	v_mfma_f32_16x16x32_bf16 v[100:103], v[200:203], v[160:163], v[100:103]
	v_mfma_f32_16x16x32_bf16 v[96:99], v[200:203], v[168:171], v[96:99]
	s_barrier
	ds_read_b128 v[204:207], v145 offset:16384
	ds_read_b128 v[212:215], v145 offset:17408
	ds_read_b128 v[216:219], v145 offset:18432
	ds_read_b128 v[220:223], v145 offset:19456
	v_lshl_add_u64 v[226:227], s[26:27], 0, v[130:131]
	s_add_u32 m0, s29, s44
	s_nop 0
	s_add_u32 vcc_lo, s26, s8
	s_addc_u32 vcc_hi, s27, s9
	global_load_lds_dwordx4 v130, vcc
	v_lshl_add_u64 v[228:229], s[26:27], 0, v[132:133]
	s_add_u32 m0, s29, s44
	s_add_u32 m0, m0, 0x2000
	s_nop 0
	global_load_lds_dwordx4 v132, vcc
	s_barrier
	s_waitcnt lgkmcnt(0)
	v_mfma_f32_16x16x32_bf16 v[92:95], v[172:175], v[204:207], v[92:95]
	v_mfma_f32_16x16x32_bf16 v[88:91], v[172:175], v[216:219], v[88:91]
	v_mfma_f32_16x16x32_bf16 v[84:87], v[180:183], v[204:207], v[84:87]
	v_mfma_f32_16x16x32_bf16 v[80:83], v[180:183], v[216:219], v[80:83]
	v_mfma_f32_16x16x32_bf16 v[76:79], v[188:191], v[204:207], v[76:79]
	v_mfma_f32_16x16x32_bf16 v[72:75], v[188:191], v[216:219], v[72:75]
	v_mfma_f32_16x16x32_bf16 v[68:71], v[196:199], v[204:207], v[68:71]
	v_mfma_f32_16x16x32_bf16 v[64:67], v[196:199], v[216:219], v[64:67]
	v_mfma_f32_16x16x32_bf16 v[92:95], v[176:179], v[212:215], v[92:95]
	ds_read_b128 v[172:175], v128 offset:16384
	v_mfma_f32_16x16x32_bf16 v[88:91], v[176:179], v[220:223], v[88:91]
	v_mfma_f32_16x16x32_bf16 v[84:87], v[184:187], v[212:215], v[84:87]
	ds_read_b128 v[180:183], v128 offset:18432
	v_mfma_f32_16x16x32_bf16 v[80:83], v[184:187], v[220:223], v[80:83]
	v_mfma_f32_16x16x32_bf16 v[76:79], v[192:195], v[212:215], v[76:79]
	ds_read_b128 v[188:191], v128 offset:20480
	v_mfma_f32_16x16x32_bf16 v[72:75], v[192:195], v[220:223], v[72:75]
	v_mfma_f32_16x16x32_bf16 v[68:71], v[200:203], v[212:215], v[68:71]
	ds_read_b128 v[196:199], v128 offset:22528
	v_mfma_f32_16x16x32_bf16 v[64:67], v[200:203], v[220:223], v[64:67]
	s_barrier
	ds_read_b128 v[176:179], v128 offset:17408
	ds_read_b128 v[184:187], v128 offset:19456
	ds_read_b128 v[192:195], v128 offset:21504
	ds_read_b128 v[200:203], v128 offset:23552
	s_add_u32 m0, s29, 0x0
	s_nop 0
	s_add_u32 vcc_lo, s26, s10
	s_addc_u32 vcc_hi, s27, s11
	global_load_lds_dwordx4 v134, vcc
	s_add_u32 m0, s29, 0x2000
	s_nop 0
	global_load_lds_dwordx4 v136, vcc
	s_waitcnt vmcnt(8)
	s_barrier
	s_waitcnt lgkmcnt(0)
	v_mfma_f32_16x16x32_bf16 v[60:63], v[172:175], v[156:159], v[60:63]
	v_mfma_f32_16x16x32_bf16 v[56:59], v[172:175], v[164:167], v[56:59]
	v_mfma_f32_16x16x32_bf16 v[52:55], v[180:183], v[156:159], v[52:55]
	v_mfma_f32_16x16x32_bf16 v[48:51], v[180:183], v[164:167], v[48:51]
	v_mfma_f32_16x16x32_bf16 v[44:47], v[188:191], v[156:159], v[44:47]
	v_mfma_f32_16x16x32_bf16 v[40:43], v[188:191], v[164:167], v[40:43]
	v_mfma_f32_16x16x32_bf16 v[36:39], v[196:199], v[156:159], v[36:39]
	v_mfma_f32_16x16x32_bf16 v[32:35], v[196:199], v[164:167], v[32:35]
	v_mfma_f32_16x16x32_bf16 v[60:63], v[176:179], v[160:163], v[60:63]
	v_mfma_f32_16x16x32_bf16 v[56:59], v[176:179], v[168:171], v[56:59]
	v_mfma_f32_16x16x32_bf16 v[52:55], v[184:187], v[160:163], v[52:55]
	v_mfma_f32_16x16x32_bf16 v[48:51], v[184:187], v[168:171], v[48:51]
	v_mfma_f32_16x16x32_bf16 v[44:47], v[192:195], v[160:163], v[44:47]
	v_mfma_f32_16x16x32_bf16 v[40:43], v[192:195], v[168:171], v[40:43]
	v_mfma_f32_16x16x32_bf16 v[36:39], v[200:203], v[160:163], v[36:39]
	v_mfma_f32_16x16x32_bf16 v[32:35], v[200:203], v[168:171], v[32:35]
	s_barrier
	ds_read_b128 v[156:159], v145 offset:32768
	ds_read_b128 v[160:163], v145 offset:33792
	ds_read_b128 v[164:167], v145 offset:34816
	ds_read_b128 v[168:171], v145 offset:35840
	s_add_u32 m0, s29, s45
	s_nop 0
	s_add_u32 vcc_lo, s26, s12
	s_addc_u32 vcc_hi, s27, s13
	global_load_lds_dwordx4 v130, vcc
	s_add_u32 m0, s29, s45
	s_add_u32 m0, m0, 0x2000
	s_nop 0
	global_load_lds_dwordx4 v132, vcc
	s_waitcnt vmcnt(6)
	s_barrier
; #define WAIT_V(n) asm volatile("s_waitcnt vmcnt(" #n ")" ::: "memory")
; #define WAIT_L(n) asm volatile("s_waitcnt lgkmcnt(" #n ")" ::: "memory")
; #define BAR __builtin_amdgcn_s_barrier()
; #define SCHED __builtin_amdgcn_sched_barrier(0)
; #define STAGE(P, BASE, br, kt) do { const char* _g = (const char*)((BASE) + (size_t)(br) * GK + (kt) * BK); \
;     __builtin_amdgcn_global_load_lds((const unsigned*)(_g + voff0), (unsigned*)((char*)(P) + tx * 16), 16, 0, 0); \
;     __builtin_amdgcn_global_load_lds((const unsigned*)(_g + voff1), (unsigned*)((char*)(P) + tx * 16 + 8192), 16, 0, 0); } while (0)
; #define LDA(dst, b, h) _Pragma("unroll") for (int m = 0; m < 4; ++m) _Pragma("unroll") for (int k = 0; k < 2; ++k) \
;     dst[m][k] = *reinterpret_cast<const bf16x8*>((char*)shm + abase + (((b) * 2 + (h)) * 16384 + (m * 2 + k) * 1024))
; #define LDB(dst, b, h) _Pragma("unroll") for (int n = 0; n < 2; ++n) _Pragma("unroll") for (int k = 0; k < 2; ++k) \
;     dst[n][k] = *reinterpret_cast<const bf16x8*>((char*)shm + bbase + (((b) * 2 + (h)) * 16384 + (n * 2 + k) * 1024))
; template <bool SWAP>
; __device__ __forceinline__ void gemm_main(const u16* __restrict__ A, const u16* __restrict__ Bt, int brow, int bcol,
;                                           u16* shm, f32x4 (&acc)[2][2][4][2]) {
;     ...
;     WAIT_V(6); BAR; MMA(1, 1, At, B1); BAR;
;     LDB(B0, 1, 0); SCHED; LDA(At, 1, 0); STAGE(SA(0, 1), A, brow + HALF, t + 2);
;     WAIT_L(8); BAR; WAIT_L(0); MMA(0, 0, At, B0); BAR; SCHED;
;     LDB(B1, 1, 1); STAGE(SB(1, 0), Bt, bcol, t + 3);
;     BAR; WAIT_L(0); MMA(0, 1, At, B1); BAR;
;     LDA(At, 1, 1); STAGE(SA(1, 0), A, brow, t + 3);
;     BAR; WAIT_L(0); MMA(1, 0, At, B0); BAR; SCHED;
	v_mfma_f32_16x16x32_bf16 v[28:31], v[172:175], v[204:207], v[28:31]
	v_mfma_f32_16x16x32_bf16 v[24:27], v[172:175], v[216:219], v[24:27]
	v_mfma_f32_16x16x32_bf16 v[20:23], v[180:183], v[204:207], v[20:23]
	v_mfma_f32_16x16x32_bf16 v[16:19], v[180:183], v[216:219], v[16:19]
	v_mfma_f32_16x16x32_bf16 v[12:15], v[188:191], v[204:207], v[12:15]
	v_mfma_f32_16x16x32_bf16 v[8:11], v[188:191], v[216:219], v[8:11]
	v_mfma_f32_16x16x32_bf16 v[4:7], v[196:199], v[204:207], v[4:7]
	v_mfma_f32_16x16x32_bf16 v[0:3], v[196:199], v[216:219], v[0:3]
	v_mfma_f32_16x16x32_bf16 v[28:31], v[176:179], v[212:215], v[28:31]
	ds_read_b128 v[172:175], v128 offset:32768
	v_mfma_f32_16x16x32_bf16 v[24:27], v[176:179], v[220:223], v[24:27]
	v_mfma_f32_16x16x32_bf16 v[20:23], v[184:187], v[212:215], v[20:23]
	ds_read_b128 v[180:183], v128 offset:34816
	v_mfma_f32_16x16x32_bf16 v[16:19], v[184:187], v[220:223], v[16:19]
	v_mfma_f32_16x16x32_bf16 v[12:15], v[192:195], v[212:215], v[12:15]
	ds_read_b128 v[188:191], v128 offset:36864
	v_mfma_f32_16x16x32_bf16 v[8:11], v[192:195], v[220:223], v[8:11]
	v_mfma_f32_16x16x32_bf16 v[4:7], v[200:203], v[212:215], v[4:7]
	ds_read_b128 v[196:199], v128 offset:38912
	v_mfma_f32_16x16x32_bf16 v[0:3], v[200:203], v[220:223], v[0:3]
	s_barrier
	ds_read_b128 v[176:179], v128 offset:33792
	ds_read_b128 v[184:187], v128 offset:35840
	ds_read_b128 v[192:195], v128 offset:37888
	ds_read_b128 v[200:203], v128 offset:39936
	s_add_u32 m0, s29, 0x4000
	s_nop 0
	s_add_u32 vcc_lo, s26, s14
	s_addc_u32 vcc_hi, s27, s15
	global_load_lds_dwordx4 v134, vcc
	s_add_u32 m0, s29, 0x6000
	s_nop 0
	global_load_lds_dwordx4 v136, vcc
	s_waitcnt lgkmcnt(8)
	s_barrier
	s_waitcnt lgkmcnt(0)
	v_mfma_f32_16x16x32_bf16 v[124:127], v[172:175], v[156:159], v[124:127]
	v_mfma_f32_16x16x32_bf16 v[120:123], v[172:175], v[164:167], v[120:123]
	v_mfma_f32_16x16x32_bf16 v[116:119], v[180:183], v[156:159], v[116:119]
	v_mfma_f32_16x16x32_bf16 v[112:115], v[180:183], v[164:167], v[112:115]
	v_mfma_f32_16x16x32_bf16 v[108:111], v[188:191], v[156:159], v[108:111]
	v_mfma_f32_16x16x32_bf16 v[104:107], v[188:191], v[164:167], v[104:107]
	v_mfma_f32_16x16x32_bf16 v[100:103], v[196:199], v[156:159], v[100:103]
	v_mfma_f32_16x16x32_bf16 v[96:99], v[196:199], v[164:167], v[96:99]
	v_mfma_f32_16x16x32_bf16 v[124:127], v[176:179], v[160:163], v[124:127]
	v_mfma_f32_16x16x32_bf16 v[120:123], v[176:179], v[168:171], v[120:123]
	v_mfma_f32_16x16x32_bf16 v[116:119], v[184:187], v[160:163], v[116:119]
	v_mfma_f32_16x16x32_bf16 v[112:115], v[184:187], v[168:171], v[112:115]
	v_mfma_f32_16x16x32_bf16 v[108:111], v[192:195], v[160:163], v[108:111]
	v_mfma_f32_16x16x32_bf16 v[104:107], v[192:195], v[168:171], v[104:107]
	v_mfma_f32_16x16x32_bf16 v[100:103], v[200:203], v[160:163], v[100:103]
	v_mfma_f32_16x16x32_bf16 v[96:99], v[200:203], v[168:171], v[96:99]
	s_barrier
	ds_read_b128 v[204:207], v145 offset:49152
	ds_read_b128 v[212:215], v145 offset:50176
	ds_read_b128 v[216:219], v145 offset:51200
	ds_read_b128 v[220:223], v145 offset:52224
	s_add_u32 m0, s29, s52
	s_nop 0
	s_add_u32 vcc_lo, s26, s16
	s_addc_u32 vcc_hi, s27, s17
	global_load_lds_dwordx4 v130, vcc
	v_lshl_add_u64 v[230:231], v[228:229], 0, s[16:17]
	s_add_u32 m0, s29, s52
	s_add_u32 m0, m0, 0x2000
	s_nop 0
	global_load_lds_dwordx4 v132, vcc
	s_barrier
	s_waitcnt lgkmcnt(0)
	v_mfma_f32_16x16x32_bf16 v[92:95], v[172:175], v[204:207], v[92:95]
	v_mfma_f32_16x16x32_bf16 v[88:91], v[172:175], v[216:219], v[88:91]
	v_mfma_f32_16x16x32_bf16 v[84:87], v[180:183], v[204:207], v[84:87]
	v_mfma_f32_16x16x32_bf16 v[80:83], v[180:183], v[216:219], v[80:83]
	v_mfma_f32_16x16x32_bf16 v[76:79], v[188:191], v[204:207], v[76:79]
	v_mfma_f32_16x16x32_bf16 v[72:75], v[188:191], v[216:219], v[72:75]
	v_mfma_f32_16x16x32_bf16 v[68:71], v[196:199], v[204:207], v[68:71]
	v_mfma_f32_16x16x32_bf16 v[64:67], v[196:199], v[216:219], v[64:67]
	v_mfma_f32_16x16x32_bf16 v[92:95], v[176:179], v[212:215], v[92:95]
	ds_read_b128 v[172:175], v128 offset:49152
	v_mfma_f32_16x16x32_bf16 v[88:91], v[176:179], v[220:223], v[88:91]
	v_mfma_f32_16x16x32_bf16 v[84:87], v[184:187], v[212:215], v[84:87]
	ds_read_b128 v[180:183], v128 offset:51200
	v_mfma_f32_16x16x32_bf16 v[80:83], v[184:187], v[220:223], v[80:83]
	v_mfma_f32_16x16x32_bf16 v[76:79], v[192:195], v[212:215], v[76:79]
	ds_read_b128 v[188:191], v128 offset:53248
	v_mfma_f32_16x16x32_bf16 v[72:75], v[192:195], v[220:223], v[72:75]
	v_mfma_f32_16x16x32_bf16 v[68:71], v[200:203], v[212:215], v[68:71]
	ds_read_b128 v[196:199], v128 offset:55296
	v_mfma_f32_16x16x32_bf16 v[64:67], v[200:203], v[220:223], v[64:67]
	s_barrier
	ds_read_b128 v[176:179], v128 offset:50176
	ds_read_b128 v[184:187], v128 offset:52224
	ds_read_b128 v[192:195], v128 offset:54272
	ds_read_b128 v[200:203], v128 offset:56320
	s_add_u32 m0, s29, 0x8000
	s_nop 0
	s_add_u32 vcc_lo, s26, s18
	s_addc_u32 vcc_hi, s27, s19
	global_load_lds_dwordx4 v134, vcc
	v_lshl_add_u64 v[208:209], v[224:225], 0, s[18:19]
	s_add_u32 m0, s29, 0xa000
	s_nop 0
	global_load_lds_dwordx4 v136, vcc
	s_waitcnt vmcnt(8)
	s_barrier
; #define WAIT_V(n) asm volatile("s_waitcnt vmcnt(" #n ")" ::: "memory")
; #define WAIT_L(n) asm volatile("s_waitcnt lgkmcnt(" #n ")" ::: "memory")
; #define BAR __builtin_amdgcn_s_barrier()
; #define SCHED __builtin_amdgcn_sched_barrier(0)
; #define STAGE(P, BASE, br, kt) do { const char* _g = (const char*)((BASE) + (size_t)(br) * GK + (kt) * BK); \
;     __builtin_amdgcn_global_load_lds((const unsigned*)(_g + voff0), (unsigned*)((char*)(P) + tx * 16), 16, 0, 0); \
;     __builtin_amdgcn_global_load_lds((const unsigned*)(_g + voff1), (unsigned*)((char*)(P) + tx * 16 + 8192), 16, 0, 0); } while (0)
; #define LDA(dst, b, h) _Pragma("unroll") for (int m = 0; m < 4; ++m) _Pragma("unroll") for (int k = 0; k < 2; ++k) \
;     dst[m][k] = *reinterpret_cast<const bf16x8*>((char*)shm + abase + (((b) * 2 + (h)) * 16384 + (m * 2 + k) * 1024))
; #define LDB(dst, b, h) _Pragma("unroll") for (int n = 0; n < 2; ++n) _Pragma("unroll") for (int k = 0; k < 2; ++k) \
;     dst[n][k] = *reinterpret_cast<const bf16x8*>((char*)shm + bbase + (((b) * 2 + (h)) * 16384 + (n * 2 + k) * 1024))
; template <bool SWAP>
; __device__ __forceinline__ void gemm_main(const u16* __restrict__ A, const u16* __restrict__ Bt, int brow, int bcol,
;                                           u16* shm, f32x4 (&acc)[2][2][4][2]) {
;     ...
;     BAR; WAIT_L(0); MMA(1, 0, At, B0); BAR; SCHED;
;     STAGE(SB(1, 1), Bt, bcol + HALF, t + 3);
;     WAIT_V(6); BAR; MMA(1, 1, At, B1); BAR;
;   }
;   { LDB(B0, 0, 0); LDA(At, 0, 0); STAGE(SA(1, 1), A, brow + HALF, nt - 1);
;     BAR; WAIT_L(0); MMA(0, 0, At, B0); BAR;
	s_waitcnt lgkmcnt(0)
	v_mfma_f32_16x16x32_bf16 v[60:63], v[172:175], v[156:159], v[60:63]
	v_mfma_f32_16x16x32_bf16 v[56:59], v[172:175], v[164:167], v[56:59]
	v_mfma_f32_16x16x32_bf16 v[52:55], v[180:183], v[156:159], v[52:55]
	v_mfma_f32_16x16x32_bf16 v[48:51], v[180:183], v[164:167], v[48:51]
	v_mfma_f32_16x16x32_bf16 v[44:47], v[188:191], v[156:159], v[44:47]
	v_mfma_f32_16x16x32_bf16 v[40:43], v[188:191], v[164:167], v[40:43]
	v_mfma_f32_16x16x32_bf16 v[36:39], v[196:199], v[156:159], v[36:39]
	v_mfma_f32_16x16x32_bf16 v[32:35], v[196:199], v[164:167], v[32:35]
	v_mfma_f32_16x16x32_bf16 v[60:63], v[176:179], v[160:163], v[60:63]
	v_mfma_f32_16x16x32_bf16 v[56:59], v[176:179], v[168:171], v[56:59]
	v_mfma_f32_16x16x32_bf16 v[52:55], v[184:187], v[160:163], v[52:55]
	v_mfma_f32_16x16x32_bf16 v[48:51], v[184:187], v[168:171], v[48:51]
	v_mfma_f32_16x16x32_bf16 v[44:47], v[192:195], v[160:163], v[44:47]
	v_mfma_f32_16x16x32_bf16 v[40:43], v[192:195], v[168:171], v[40:43]
	v_mfma_f32_16x16x32_bf16 v[36:39], v[200:203], v[160:163], v[36:39]
	v_mfma_f32_16x16x32_bf16 v[32:35], v[200:203], v[168:171], v[32:35]
	s_barrier
	ds_read_b128 v[156:159], v145
	ds_read_b128 v[160:163], v145 offset:1024
	ds_read_b128 v[164:167], v145 offset:2048
	ds_read_b128 v[168:171], v145 offset:3072
	s_add_u32 m0, s29, s53
	s_nop 0
	s_add_u32 vcc_lo, s26, s20
	s_addc_u32 vcc_hi, s27, s21
	global_load_lds_dwordx4 v130, vcc
	v_lshl_add_u64 v[254:255], v[228:229], 0, s[20:21]
	s_add_u32 m0, s29, s53
	s_add_u32 m0, m0, 0x2000
	s_nop 0
	global_load_lds_dwordx4 v132, vcc
	s_waitcnt vmcnt(6)
	s_barrier
	v_mfma_f32_16x16x32_bf16 v[28:31], v[172:175], v[204:207], v[28:31]
	v_mfma_f32_16x16x32_bf16 v[24:27], v[172:175], v[216:219], v[24:27]
	v_mfma_f32_16x16x32_bf16 v[20:23], v[180:183], v[204:207], v[20:23]
	v_mfma_f32_16x16x32_bf16 v[16:19], v[180:183], v[216:219], v[16:19]
	v_mfma_f32_16x16x32_bf16 v[12:15], v[188:191], v[204:207], v[12:15]
	v_mfma_f32_16x16x32_bf16 v[8:11], v[188:191], v[216:219], v[8:11]
	v_mfma_f32_16x16x32_bf16 v[4:7], v[196:199], v[204:207], v[4:7]
	v_mfma_f32_16x16x32_bf16 v[0:3], v[196:199], v[216:219], v[0:3]
	v_mfma_f32_16x16x32_bf16 v[28:31], v[176:179], v[212:215], v[28:31]
	ds_read_b128 v[172:175], v128
	v_mfma_f32_16x16x32_bf16 v[24:27], v[176:179], v[220:223], v[24:27]
	v_mfma_f32_16x16x32_bf16 v[20:23], v[184:187], v[212:215], v[20:23]
	ds_read_b128 v[180:183], v128 offset:2048
	v_mfma_f32_16x16x32_bf16 v[16:19], v[184:187], v[220:223], v[16:19]
	s_add_i32 s28, s28, 2
	s_add_u32 s26, s26, 0x100
	s_addc_u32 s27, s27, 0
	s_cmp_lt_u32 s28, 28
	v_mfma_f32_16x16x32_bf16 v[12:15], v[192:195], v[212:215], v[12:15]
	ds_read_b128 v[188:191], v128 offset:4096
	v_mfma_f32_16x16x32_bf16 v[8:11], v[192:195], v[220:223], v[8:11]
	v_mfma_f32_16x16x32_bf16 v[4:7], v[200:203], v[212:215], v[4:7]
	ds_read_b128 v[196:199], v128 offset:6144
	v_mfma_f32_16x16x32_bf16 v[0:3], v[200:203], v[220:223], v[0:3]
	s_barrier
	s_cbranch_scc1 .LBB0_84
	v_lshlrev_b32_e32 v130, 3, v147
	v_lshlrev_b32_e32 v131, 5, v147
	v_and_b32_e32 v130, 0xffff0, v130
	v_and_b32_e32 v131, 32, v131
	v_add_u32_e32 v131, v131, v149
	v_add_lshl_u32 v130, v148, v130, 12
	s_add_u32 s4, s37, s4
	v_lshl_add_u32 v155, v131, 1, v130
	v_lshlrev_b32_e32 v130, 3, v150
	v_lshlrev_b32_e32 v131, 5, v150
	s_addc_u32 s27, s38, 0
	v_and_b32_e32 v130, 0xffff0, v130
	v_and_b32_e32 v131, 32, v131
	s_add_u32 s26, s4, 0x80f80
	v_readfirstlane_b32 s4, v153
	v_add_u32_e32 v131, v131, v152
	v_add_lshl_u32 v130, v151, v130, 12
	s_addc_u32 s27, s27, 0
	s_mov_b32 m0, s4
	v_readfirstlane_b32 s4, v154
	v_lshl_add_u32 v150, v131, 1, v130
	ds_read_b128 v[130:133], v145
	ds_read_b128 v[134:137], v145 offset:1024
	ds_read_b128 v[146:149], v145 offset:2048
	ds_read_b128 v[156:159], v145 offset:3072
	ds_read_b128 v[160:163], v128
	ds_read_b128 v[164:167], v128 offset:1024
	ds_read_b128 v[168:171], v128 offset:2048
	ds_read_b128 v[172:175], v128 offset:3072
	ds_read_b128 v[176:179], v128 offset:4096
	ds_read_b128 v[180:183], v128 offset:5120
	ds_read_b128 v[184:187], v128 offset:6144
	ds_read_b128 v[188:191], v128 offset:7168
	global_load_lds_dwordx4 v155, s[26:27]
	s_mov_b32 m0, s4
	s_nop 0
	global_load_lds_dwordx4 v150, s[26:27]
	s_barrier
	s_waitcnt lgkmcnt(0)
	s_setprio 1
	s_waitcnt lgkmcnt(0)
	v_mfma_f32_16x16x32_bf16 v[124:127], v[160:163], v[130:133], v[124:127]
	v_mfma_f32_16x16x32_bf16 v[116:119], v[168:171], v[130:133], v[116:119]
	v_mfma_f32_16x16x32_bf16 v[108:111], v[176:179], v[130:133], v[108:111]
	v_mfma_f32_16x16x32_bf16 v[100:103], v[184:187], v[130:133], v[100:103]
	v_mfma_f32_16x16x32_bf16 v[96:99], v[184:187], v[146:149], v[96:99]
	v_mfma_f32_16x16x32_bf16 v[124:127], v[164:167], v[134:137], v[124:127]
	v_mfma_f32_16x16x32_bf16 v[120:123], v[160:163], v[146:149], v[120:123]
	v_mfma_f32_16x16x32_bf16 v[116:119], v[172:175], v[134:137], v[116:119]
	v_mfma_f32_16x16x32_bf16 v[112:115], v[168:171], v[146:149], v[112:115]
	v_mfma_f32_16x16x32_bf16 v[108:111], v[180:183], v[134:137], v[108:111]
	v_mfma_f32_16x16x32_bf16 v[104:107], v[176:179], v[146:149], v[104:107]
	v_mfma_f32_16x16x32_bf16 v[100:103], v[188:191], v[134:137], v[100:103]
	v_mfma_f32_16x16x32_bf16 v[96:99], v[188:191], v[156:159], v[96:99]
	v_mfma_f32_16x16x32_bf16 v[150:153], v[164:167], v[156:159], v[120:123]
	v_mfma_f32_16x16x32_bf16 v[192:195], v[172:175], v[156:159], v[112:115]
	v_mfma_f32_16x16x32_bf16 v[196:199], v[180:183], v[156:159], v[104:107]
	s_setprio 0
	s_barrier
	s_nop 0
	ds_read_b128 v[104:107], v145 offset:16384
	ds_read_b128 v[112:115], v145 offset:17408
	ds_read_b128 v[120:123], v145 offset:18432
	ds_read_b128 v[200:203], v145 offset:19456
	s_barrier
; #define WAIT_V(n) asm volatile("s_waitcnt vmcnt(" #n ")" ::: "memory")
; #define WAIT_L(n) asm volatile("s_waitcnt lgkmcnt(" #n ")" ::: "memory")
; #define BAR __builtin_amdgcn_s_barrier()
; #define LDA(dst, b, h) _Pragma("unroll") for (int m = 0; m < 4; ++m) _Pragma("unroll") for (int k = 0; k < 2; ++k) \
;     dst[m][k] = *reinterpret_cast<const bf16x8*>((char*)shm + abase + (((b) * 2 + (h)) * 16384 + (m * 2 + k) * 1024))
; #define LDB(dst, b, h) _Pragma("unroll") for (int n = 0; n < 2; ++n) _Pragma("unroll") for (int k = 0; k < 2; ++k) \
;     dst[n][k] = *reinterpret_cast<const bf16x8*>((char*)shm + bbase + (((b) * 2 + (h)) * 16384 + (n * 2 + k) * 1024))
; template <bool SWAP>
; __device__ __forceinline__ void gemm_main(const u16* __restrict__ A, const u16* __restrict__ Bt, int brow, int bcol,
;                                           u16* shm, f32x4 (&acc)[2][2][4][2]) {
;     ...
;     LDB(B1, 0, 1); BAR; WAIT_L(0); MMA(0, 1, At, B1); BAR;
;     LDA(At, 0, 1); WAIT_V(4); BAR; WAIT_L(0); MMA(1, 0, At, B0); MMA(1, 1, At, B1); BAR; }
;   { LDB(B0, 1, 0); LDA(At, 1, 0); WAIT_V(2); BAR; WAIT_L(0); MMA(0, 0, At, B0); BAR;
	s_waitcnt lgkmcnt(0)
	s_setprio 1
	s_waitcnt lgkmcnt(0)
	v_mfma_f32_16x16x32_bf16 v[84:87], v[168:171], v[104:107], v[84:87]
	v_mfma_f32_16x16x32_bf16 v[76:79], v[176:179], v[104:107], v[76:79]
	v_mfma_f32_16x16x32_bf16 v[68:71], v[184:187], v[104:107], v[68:71]
	v_mfma_f32_16x16x32_bf16 v[92:95], v[160:163], v[104:107], v[92:95]
	v_mfma_f32_16x16x32_bf16 v[88:91], v[160:163], v[120:123], v[88:91]
	v_mfma_f32_16x16x32_bf16 v[84:87], v[172:175], v[112:115], v[84:87]
	v_mfma_f32_16x16x32_bf16 v[80:83], v[168:171], v[120:123], v[80:83]
	v_mfma_f32_16x16x32_bf16 v[76:79], v[180:183], v[112:115], v[76:79]
	v_mfma_f32_16x16x32_bf16 v[72:75], v[176:179], v[120:123], v[72:75]
	v_mfma_f32_16x16x32_bf16 v[68:71], v[188:191], v[112:115], v[68:71]
	v_mfma_f32_16x16x32_bf16 v[64:67], v[184:187], v[120:123], v[64:67]
	v_mfma_f32_16x16x32_bf16 v[204:207], v[164:167], v[112:115], v[92:95]
	v_mfma_f32_16x16x32_bf16 v[160:163], v[164:167], v[200:203], v[88:91]
	v_mfma_f32_16x16x32_bf16 v[164:167], v[172:175], v[200:203], v[80:83]
	v_mfma_f32_16x16x32_bf16 v[168:171], v[180:183], v[200:203], v[72:75]
	v_mfma_f32_16x16x32_bf16 v[172:175], v[188:191], v[200:203], v[64:67]
	s_setprio 0
	s_barrier
	s_nop 0
	ds_read_b128 v[64:67], v128 offset:16384
	ds_read_b128 v[72:75], v128 offset:17408
	ds_read_b128 v[80:83], v128 offset:18432
	ds_read_b128 v[88:91], v128 offset:19456
	ds_read_b128 v[92:95], v128 offset:20480
	ds_read_b128 v[176:179], v128 offset:21504
	ds_read_b128 v[180:183], v128 offset:22528
	ds_read_b128 v[184:187], v128 offset:23552
	s_waitcnt vmcnt(4)
	s_barrier
	s_waitcnt lgkmcnt(0)
	s_setprio 1
	s_waitcnt lgkmcnt(0)
	v_mfma_f32_16x16x32_bf16 v[60:63], v[64:67], v[130:133], v[60:63]
	v_mfma_f32_16x16x32_bf16 v[52:55], v[80:83], v[130:133], v[52:55]
	v_mfma_f32_16x16x32_bf16 v[44:47], v[92:95], v[130:133], v[44:47]
	v_mfma_f32_16x16x32_bf16 v[36:39], v[180:183], v[130:133], v[36:39]
	v_mfma_f32_16x16x32_bf16 v[60:63], v[72:75], v[134:137], v[60:63]
	v_mfma_f32_16x16x32_bf16 v[56:59], v[64:67], v[146:149], v[56:59]
	v_mfma_f32_16x16x32_bf16 v[52:55], v[88:91], v[134:137], v[52:55]
	v_mfma_f32_16x16x32_bf16 v[48:51], v[80:83], v[146:149], v[48:51]
	v_mfma_f32_16x16x32_bf16 v[44:47], v[176:179], v[134:137], v[44:47]
	v_mfma_f32_16x16x32_bf16 v[40:43], v[92:95], v[146:149], v[40:43]
	v_mfma_f32_16x16x32_bf16 v[36:39], v[184:187], v[134:137], v[36:39]
	v_mfma_f32_16x16x32_bf16 v[32:35], v[180:183], v[146:149], v[32:35]
	v_mfma_f32_16x16x32_bf16 v[188:191], v[72:75], v[156:159], v[56:59]
	v_mfma_f32_16x16x32_bf16 v[212:215], v[88:91], v[156:159], v[48:51]
	v_mfma_f32_16x16x32_bf16 v[216:219], v[176:179], v[156:159], v[40:43]
	v_mfma_f32_16x16x32_bf16 v[130:133], v[184:187], v[156:159], v[32:35]
	s_setprio 0
	s_setprio 1
	v_mfma_f32_16x16x32_bf16 v[28:31], v[64:67], v[104:107], v[28:31]
	v_mfma_f32_16x16x32_bf16 v[20:23], v[80:83], v[104:107], v[20:23]
	v_mfma_f32_16x16x32_bf16 v[12:15], v[92:95], v[104:107], v[12:15]
	v_mfma_f32_16x16x32_bf16 v[4:7], v[180:183], v[104:107], v[4:7]
	v_mfma_f32_16x16x32_bf16 v[28:31], v[72:75], v[112:115], v[28:31]
	v_mfma_f32_16x16x32_bf16 v[24:27], v[64:67], v[120:123], v[24:27]
	v_mfma_f32_16x16x32_bf16 v[20:23], v[88:91], v[112:115], v[20:23]
	v_mfma_f32_16x16x32_bf16 v[16:19], v[80:83], v[120:123], v[16:19]
	v_mfma_f32_16x16x32_bf16 v[12:15], v[176:179], v[112:115], v[12:15]
	v_mfma_f32_16x16x32_bf16 v[8:11], v[92:95], v[120:123], v[8:11]
	v_mfma_f32_16x16x32_bf16 v[4:7], v[184:187], v[112:115], v[4:7]
	v_mfma_f32_16x16x32_bf16 v[0:3], v[180:183], v[120:123], v[0:3]
	v_mfma_f32_16x16x32_bf16 v[134:137], v[72:75], v[200:203], v[24:27]
	v_mfma_f32_16x16x32_bf16 v[146:149], v[88:91], v[200:203], v[16:19]
	v_mfma_f32_16x16x32_bf16 v[154:157], v[176:179], v[200:203], v[8:11]
	v_mfma_f32_16x16x32_bf16 v[176:179], v[184:187], v[200:203], v[0:3]
	s_setprio 0
	s_barrier
	s_nop 1
	ds_read_b128 v[0:3], v145 offset:32768
	ds_read_b128 v[8:11], v145 offset:33792
	ds_read_b128 v[16:19], v145 offset:34816
	ds_read_b128 v[24:27], v145 offset:35840
	ds_read_b128 v[32:35], v128 offset:32768
	ds_read_b128 v[40:43], v128 offset:33792
	ds_read_b128 v[48:51], v128 offset:34816
	ds_read_b128 v[56:59], v128 offset:35840
	ds_read_b128 v[64:67], v128 offset:36864
	ds_read_b128 v[180:183], v128 offset:37888
	ds_read_b128 v[184:187], v128 offset:38912
	ds_read_b128 v[200:203], v128 offset:39936
	s_waitcnt vmcnt(2)
	s_barrier
; #define WAIT_V(n) asm volatile("s_waitcnt vmcnt(" #n ")" ::: "memory")
; #define WAIT_L(n) asm volatile("s_waitcnt lgkmcnt(" #n ")" ::: "memory")
; #define BAR __builtin_amdgcn_s_barrier()
; #define LDA(dst, b, h) _Pragma("unroll") for (int m = 0; m < 4; ++m) _Pragma("unroll") for (int k = 0; k < 2; ++k) \
;     dst[m][k] = *reinterpret_cast<const bf16x8*>((char*)shm + abase + (((b) * 2 + (h)) * 16384 + (m * 2 + k) * 1024))
; #define LDB(dst, b, h) _Pragma("unroll") for (int n = 0; n < 2; ++n) _Pragma("unroll") for (int k = 0; k < 2; ++k) \
;     dst[n][k] = *reinterpret_cast<const bf16x8*>((char*)shm + bbase + (((b) * 2 + (h)) * 16384 + (n * 2 + k) * 1024))
; template <bool SWAP>
; __device__ __forceinline__ void gemm_main(const u16* __restrict__ A, const u16* __restrict__ Bt, int brow, int bcol,
;                                           u16* shm, f32x4 (&acc)[2][2][4][2]) {
;     ...
;   { LDB(B0, 1, 0); LDA(At, 1, 0); WAIT_V(2); BAR; WAIT_L(0); MMA(0, 0, At, B0); BAR;
;     LDB(B1, 1, 1); WAIT_V(0); BAR; WAIT_L(0); MMA(0, 1, At, B1); BAR;
;     LDA(At, 1, 1); BAR; WAIT_L(0); MMA(1, 0, At, B0); MMA(1, 1, At, B1); BAR; }
;   if (wr == 0) BAR;
	s_waitcnt lgkmcnt(0)
	s_setprio 1
	s_waitcnt lgkmcnt(0)
	v_mfma_f32_16x16x32_bf16 v[72:75], v[32:35], v[0:3], v[124:127]
	v_mfma_f32_16x16x32_bf16 v[120:123], v[40:43], v[8:11], v[72:75]
	v_mfma_f32_16x16x32_bf16 v[72:75], v[32:35], v[16:19], v[150:153]
	v_mfma_f32_16x16x32_bf16 v[112:115], v[40:43], v[24:27], v[72:75]
	v_mfma_f32_16x16x32_bf16 v[72:75], v[48:51], v[0:3], v[116:119]
	v_mfma_f32_16x16x32_bf16 v[124:127], v[56:59], v[8:11], v[72:75]
	v_mfma_f32_16x16x32_bf16 v[72:75], v[48:51], v[16:19], v[192:195]
	v_mfma_f32_16x16x32_bf16 v[116:119], v[56:59], v[24:27], v[72:75]
	v_mfma_f32_16x16x32_bf16 v[72:75], v[64:67], v[0:3], v[108:111]
	v_mfma_f32_16x16x32_bf16 v[104:107], v[180:183], v[8:11], v[72:75]
	v_mfma_f32_16x16x32_bf16 v[72:75], v[64:67], v[16:19], v[196:199]
	v_mfma_f32_16x16x32_bf16 v[92:95], v[180:183], v[24:27], v[72:75]
	v_mfma_f32_16x16x32_bf16 v[72:75], v[184:187], v[0:3], v[100:103]
	v_mfma_f32_16x16x32_bf16 v[108:111], v[200:203], v[8:11], v[72:75]
	v_mfma_f32_16x16x32_bf16 v[72:75], v[184:187], v[16:19], v[96:99]
	v_mfma_f32_16x16x32_bf16 v[100:103], v[200:203], v[24:27], v[72:75]
	s_setprio 0
	s_barrier
	ds_read_b128 v[150:153], v145 offset:49152
	ds_read_b128 v[192:195], v145 offset:50176
	ds_read_b128 v[196:199], v145 offset:51200
	ds_read_b128 v[220:223], v145 offset:52224
	s_waitcnt vmcnt(0)
	s_barrier
	s_waitcnt lgkmcnt(0)
	s_setprio 1
	s_waitcnt lgkmcnt(0)
	v_mfma_f32_16x16x32_bf16 v[72:75], v[32:35], v[150:153], v[204:207]
	v_mfma_f32_16x16x32_bf16 v[32:35], v[32:35], v[196:199], v[160:163]
	v_mfma_f32_16x16x32_bf16 v[80:83], v[40:43], v[220:223], v[32:35]
	v_mfma_f32_16x16x32_bf16 v[32:35], v[48:51], v[150:153], v[84:87]
	v_mfma_f32_16x16x32_bf16 v[96:99], v[56:59], v[192:195], v[32:35]
	v_mfma_f32_16x16x32_bf16 v[32:35], v[48:51], v[196:199], v[164:167]
	v_mfma_f32_16x16x32_bf16 v[84:87], v[56:59], v[220:223], v[32:35]
	v_mfma_f32_16x16x32_bf16 v[32:35], v[64:67], v[150:153], v[76:79]
	v_mfma_f32_16x16x32_bf16 v[88:91], v[40:43], v[192:195], v[72:75]
	v_mfma_f32_16x16x32_bf16 v[72:75], v[180:183], v[192:195], v[32:35]
	v_mfma_f32_16x16x32_bf16 v[32:35], v[64:67], v[196:199], v[168:171]
	v_mfma_f32_16x16x32_bf16 v[64:67], v[180:183], v[220:223], v[32:35]
	v_mfma_f32_16x16x32_bf16 v[32:35], v[184:187], v[150:153], v[68:71]
	v_mfma_f32_16x16x32_bf16 v[76:79], v[200:203], v[192:195], v[32:35]
	v_mfma_f32_16x16x32_bf16 v[32:35], v[184:187], v[196:199], v[172:175]
	v_mfma_f32_16x16x32_bf16 v[68:71], v[200:203], v[220:223], v[32:35]
	s_setprio 0
	s_barrier
	ds_read_b128 v[158:161], v128 offset:49152
	ds_read_b128 v[162:165], v128 offset:50176
	ds_read_b128 v[166:169], v128 offset:51200
	ds_read_b128 v[170:173], v128 offset:52224
	ds_read_b128 v[180:183], v128 offset:53248
	ds_read_b128 v[184:187], v128 offset:54272
	ds_read_b128 v[200:203], v128 offset:55296
	ds_read_b128 v[204:207], v128 offset:56320
	s_barrier
	s_waitcnt lgkmcnt(0)
	s_setprio 1
	s_waitcnt lgkmcnt(0)
	v_mfma_f32_16x16x32_bf16 v[32:35], v[158:161], v[0:3], v[60:63]
	v_mfma_f32_16x16x32_bf16 v[56:59], v[162:165], v[8:11], v[32:35]
	v_mfma_f32_16x16x32_bf16 v[32:35], v[158:161], v[16:19], v[188:191]
	v_mfma_f32_16x16x32_bf16 v[48:51], v[162:165], v[24:27], v[32:35]
	v_mfma_f32_16x16x32_bf16 v[32:35], v[166:169], v[0:3], v[52:55]
	v_mfma_f32_16x16x32_bf16 v[60:63], v[170:173], v[8:11], v[32:35]
	v_mfma_f32_16x16x32_bf16 v[32:35], v[166:169], v[16:19], v[212:215]
	v_mfma_f32_16x16x32_bf16 v[52:55], v[170:173], v[24:27], v[32:35]
	v_mfma_f32_16x16x32_bf16 v[32:35], v[180:183], v[0:3], v[44:47]
	v_mfma_f32_16x16x32_bf16 v[0:3], v[200:203], v[0:3], v[36:39]
	v_mfma_f32_16x16x32_bf16 v[40:43], v[184:187], v[8:11], v[32:35]
	v_mfma_f32_16x16x32_bf16 v[32:35], v[180:183], v[16:19], v[216:219]
	v_mfma_f32_16x16x32_bf16 v[44:47], v[204:207], v[8:11], v[0:3]
	v_mfma_f32_16x16x32_bf16 v[0:3], v[200:203], v[16:19], v[130:133]
	v_mfma_f32_16x16x32_bf16 v[32:35], v[184:187], v[24:27], v[32:35]
	v_mfma_f32_16x16x32_bf16 v[36:39], v[204:207], v[24:27], v[0:3]
	s_setprio 0
	s_setprio 1
	v_mfma_f32_16x16x32_bf16 v[0:3], v[158:161], v[150:153], v[28:31]
	v_mfma_f32_16x16x32_bf16 v[24:27], v[162:165], v[192:195], v[0:3]
	v_mfma_f32_16x16x32_bf16 v[0:3], v[158:161], v[196:199], v[134:137]
	v_mfma_f32_16x16x32_bf16 v[16:19], v[162:165], v[220:223], v[0:3]
	v_mfma_f32_16x16x32_bf16 v[0:3], v[166:169], v[150:153], v[20:23]
	v_mfma_f32_16x16x32_bf16 v[28:31], v[170:173], v[192:195], v[0:3]
	v_mfma_f32_16x16x32_bf16 v[0:3], v[166:169], v[196:199], v[146:149]
	v_mfma_f32_16x16x32_bf16 v[20:23], v[170:173], v[220:223], v[0:3]
	v_mfma_f32_16x16x32_bf16 v[0:3], v[180:183], v[150:153], v[12:15]
	v_mfma_f32_16x16x32_bf16 v[4:7], v[200:203], v[150:153], v[4:7]
	v_mfma_f32_16x16x32_bf16 v[8:11], v[184:187], v[192:195], v[0:3]
	v_mfma_f32_16x16x32_bf16 v[0:3], v[180:183], v[196:199], v[154:157]
	v_mfma_f32_16x16x32_bf16 v[12:15], v[204:207], v[192:195], v[4:7]
	v_mfma_f32_16x16x32_bf16 v[4:7], v[200:203], v[196:199], v[176:179]
	v_mfma_f32_16x16x32_bf16 v[0:3], v[184:187], v[220:223], v[0:3]
	v_mfma_f32_16x16x32_bf16 v[4:7], v[204:207], v[220:223], v[4:7]
	s_setprio 0
	v_cmp_gt_u32_e32 vcc, s55, v144
	s_barrier
	s_and_saveexec_b64 s[26:27], vcc
	s_cbranch_execz .LBB0_87
	s_barrier

; #define WAIT_V(n) asm volatile("s_waitcnt vmcnt(" #n ")" ::: "memory")
; #define WAIT_L(n) asm volatile("s_waitcnt lgkmcnt(" #n ")" ::: "memory")
; #define BAR __builtin_amdgcn_s_barrier()
; #define SCHED __builtin_amdgcn_sched_barrier(0)
; #define STAGE(P, BASE, br, kt) do { const char* _g = (const char*)((BASE) + (size_t)(br) * GK + (kt) * BK); \
;     __builtin_amdgcn_global_load_lds((const unsigned*)(_g + voff0), (unsigned*)((char*)(P) + tx * 16), 16, 0, 0); \
;     __builtin_amdgcn_global_load_lds((const unsigned*)(_g + voff1), (unsigned*)((char*)(P) + tx * 16 + 8192), 16, 0, 0); } while (0)
; #define LDA(dst, b, h) _Pragma("unroll") for (int m = 0; m < 4; ++m) _Pragma("unroll") for (int k = 0; k < 2; ++k) \
;     dst[m][k] = *reinterpret_cast<const bf16x8*>((char*)shm + abase + (((b) * 2 + (h)) * 16384 + (m * 2 + k) * 1024))
; #define LDB(dst, b, h) _Pragma("unroll") for (int n = 0; n < 2; ++n) _Pragma("unroll") for (int k = 0; k < 2; ++k) \
;     dst[n][k] = *reinterpret_cast<const bf16x8*>((char*)shm + bbase + (((b) * 2 + (h)) * 16384 + (n * 2 + k) * 1024))
; template <bool SWAP>
; __device__ __forceinline__ void gemm_main(const u16* __restrict__ A, const u16* __restrict__ Bt, int brow, int bcol,
;                                           u16* shm, f32x4 (&acc)[2][2][4][2]) {
;     ...
;   for (int t = 0; t < nt - 2; t += 2) {
;     LDB(B0, 0, 0); SCHED; LDA(At, 0, 0); STAGE(SA(1, 1), A, brow + HALF, t + 1);
;     WAIT_L(8); BAR; WAIT_L(0); MMA(0, 0, At, B0); BAR; SCHED;
;     LDB(B1, 0, 1); STAGE(SB(0, 0), Bt, bcol, t + 2);
;     BAR; WAIT_L(0); MMA(0, 1, At, B1); BAR;
;     LDA(At, 0, 1); STAGE(SA(0, 0), A, brow, t + 2);
;     BAR; WAIT_L(0); MMA(1, 0, At, B0); BAR; SCHED;
;     STAGE(SB(0, 1), Bt, bcol + HALF, t + 2);
;     WAIT_V(6); BAR; MMA(1, 1, At, B1); BAR;
.LBB0_94:
	ds_read_b128 v[176:179], v145 offset:1024
	ds_read_b128 v[184:187], v145 offset:3072
	ds_read_b128 v[192:195], v145 offset:5120
	ds_read_b128 v[200:203], v145 offset:7168
	v_add_u32_e32 v128, 0, v147
	v_add_u32_e32 v154, 0xc000, v128
	v_add_u32_e32 v155, 0xe000, v128
	s_add_u32 m0, s25, 0xc000
	v_lshl_add_u64 v[224:225], s[28:29], 0, v[132:133]
	s_add_u32 vcc_lo, s28, s6
	s_addc_u32 vcc_hi, s29, s7
	global_load_lds_dwordx4 v136, vcc
	s_add_u32 m0, s25, 0xe000
	s_nop 0
	global_load_lds_dwordx4 v132, vcc
	s_waitcnt lgkmcnt(8)
	s_barrier
	s_waitcnt lgkmcnt(0)
	v_mfma_f32_16x16x32_bf16 v[124:127], v[156:159], v[172:175], v[124:127]
	v_mfma_f32_16x16x32_bf16 v[120:123], v[164:167], v[172:175], v[120:123]
	v_mfma_f32_16x16x32_bf16 v[116:119], v[156:159], v[180:183], v[116:119]
	v_mfma_f32_16x16x32_bf16 v[112:115], v[164:167], v[180:183], v[112:115]
	v_mfma_f32_16x16x32_bf16 v[108:111], v[156:159], v[188:191], v[108:111]
	v_mfma_f32_16x16x32_bf16 v[104:107], v[164:167], v[188:191], v[104:107]
	v_mfma_f32_16x16x32_bf16 v[100:103], v[156:159], v[196:199], v[100:103]
	v_mfma_f32_16x16x32_bf16 v[96:99], v[164:167], v[196:199], v[96:99]
	v_mfma_f32_16x16x32_bf16 v[124:127], v[160:163], v[176:179], v[124:127]
	v_mfma_f32_16x16x32_bf16 v[120:123], v[168:171], v[176:179], v[120:123]
	v_mfma_f32_16x16x32_bf16 v[116:119], v[160:163], v[184:187], v[116:119]
	v_mfma_f32_16x16x32_bf16 v[112:115], v[168:171], v[184:187], v[112:115]
	v_mfma_f32_16x16x32_bf16 v[108:111], v[160:163], v[192:195], v[108:111]
	v_mfma_f32_16x16x32_bf16 v[104:107], v[168:171], v[192:195], v[104:107]
	v_mfma_f32_16x16x32_bf16 v[100:103], v[160:163], v[200:203], v[100:103]
	v_mfma_f32_16x16x32_bf16 v[96:99], v[168:171], v[200:203], v[96:99]
	s_barrier
	ds_read_b128 v[204:207], v146 offset:16384
	ds_read_b128 v[212:215], v146 offset:17408
	ds_read_b128 v[216:219], v146 offset:18432
	ds_read_b128 v[220:223], v146 offset:19456
	v_lshl_add_u64 v[226:227], s[28:29], 0, v[134:135]
	s_add_u32 m0, s25, s44
	s_nop 0
	s_add_u32 vcc_lo, s28, s8
	s_addc_u32 vcc_hi, s29, s9
	global_load_lds_dwordx4 v134, vcc
	v_lshl_add_u64 v[228:229], s[28:29], 0, v[130:131]
	s_add_u32 m0, s25, s44
	s_add_u32 m0, m0, 0x2000
	s_nop 0
	global_load_lds_dwordx4 v130, vcc
	s_barrier
	s_waitcnt lgkmcnt(0)
	v_mfma_f32_16x16x32_bf16 v[92:95], v[204:207], v[172:175], v[92:95]
	v_mfma_f32_16x16x32_bf16 v[88:91], v[216:219], v[172:175], v[88:91]
	v_mfma_f32_16x16x32_bf16 v[84:87], v[204:207], v[180:183], v[84:87]
	v_mfma_f32_16x16x32_bf16 v[80:83], v[216:219], v[180:183], v[80:83]
	v_mfma_f32_16x16x32_bf16 v[76:79], v[204:207], v[188:191], v[76:79]
	v_mfma_f32_16x16x32_bf16 v[72:75], v[216:219], v[188:191], v[72:75]
	v_mfma_f32_16x16x32_bf16 v[68:71], v[204:207], v[196:199], v[68:71]
	v_mfma_f32_16x16x32_bf16 v[64:67], v[216:219], v[196:199], v[64:67]
	v_mfma_f32_16x16x32_bf16 v[92:95], v[212:215], v[176:179], v[92:95]
	ds_read_b128 v[172:175], v145 offset:16384
	v_mfma_f32_16x16x32_bf16 v[88:91], v[220:223], v[176:179], v[88:91]
	v_mfma_f32_16x16x32_bf16 v[84:87], v[212:215], v[184:187], v[84:87]
	ds_read_b128 v[180:183], v145 offset:18432
	v_mfma_f32_16x16x32_bf16 v[80:83], v[220:223], v[184:187], v[80:83]
	v_mfma_f32_16x16x32_bf16 v[76:79], v[212:215], v[192:195], v[76:79]
	ds_read_b128 v[188:191], v145 offset:20480
	v_mfma_f32_16x16x32_bf16 v[72:75], v[220:223], v[192:195], v[72:75]
	v_mfma_f32_16x16x32_bf16 v[68:71], v[212:215], v[200:203], v[68:71]
	ds_read_b128 v[196:199], v145 offset:22528
	v_mfma_f32_16x16x32_bf16 v[64:67], v[220:223], v[200:203], v[64:67]
	s_barrier
	ds_read_b128 v[176:179], v145 offset:17408
	ds_read_b128 v[184:187], v145 offset:19456
	ds_read_b128 v[192:195], v145 offset:21504
	ds_read_b128 v[200:203], v145 offset:23552
	s_add_u32 m0, s25, 0x0
	s_nop 0
	s_add_u32 vcc_lo, s28, s10
	s_addc_u32 vcc_hi, s29, s11
	global_load_lds_dwordx4 v136, vcc
	s_add_u32 m0, s25, 0x2000
	s_nop 0
	global_load_lds_dwordx4 v132, vcc
	s_waitcnt vmcnt(8)
	s_barrier
	s_waitcnt lgkmcnt(0)
	v_mfma_f32_16x16x32_bf16 v[60:63], v[156:159], v[172:175], v[60:63]
	v_mfma_f32_16x16x32_bf16 v[56:59], v[164:167], v[172:175], v[56:59]
	v_mfma_f32_16x16x32_bf16 v[52:55], v[156:159], v[180:183], v[52:55]
	v_mfma_f32_16x16x32_bf16 v[48:51], v[164:167], v[180:183], v[48:51]
	v_mfma_f32_16x16x32_bf16 v[44:47], v[156:159], v[188:191], v[44:47]
	v_mfma_f32_16x16x32_bf16 v[40:43], v[164:167], v[188:191], v[40:43]
	v_mfma_f32_16x16x32_bf16 v[36:39], v[156:159], v[196:199], v[36:39]
	v_mfma_f32_16x16x32_bf16 v[32:35], v[164:167], v[196:199], v[32:35]
	v_mfma_f32_16x16x32_bf16 v[60:63], v[160:163], v[176:179], v[60:63]
	v_mfma_f32_16x16x32_bf16 v[56:59], v[168:171], v[176:179], v[56:59]
	v_mfma_f32_16x16x32_bf16 v[52:55], v[160:163], v[184:187], v[52:55]
	v_mfma_f32_16x16x32_bf16 v[48:51], v[168:171], v[184:187], v[48:51]
	v_mfma_f32_16x16x32_bf16 v[44:47], v[160:163], v[192:195], v[44:47]
	v_mfma_f32_16x16x32_bf16 v[40:43], v[168:171], v[192:195], v[40:43]
	v_mfma_f32_16x16x32_bf16 v[36:39], v[160:163], v[200:203], v[36:39]
	v_mfma_f32_16x16x32_bf16 v[32:35], v[168:171], v[200:203], v[32:35]
	s_barrier
	ds_read_b128 v[156:159], v146 offset:32768
	ds_read_b128 v[160:163], v146 offset:33792
	ds_read_b128 v[164:167], v146 offset:34816
	ds_read_b128 v[168:171], v146 offset:35840
	s_add_u32 m0, s25, s45
	s_nop 0
	s_add_u32 vcc_lo, s28, s12
	s_addc_u32 vcc_hi, s29, s13
	global_load_lds_dwordx4 v134, vcc
	s_add_u32 m0, s25, s45
	s_add_u32 m0, m0, 0x2000
	s_nop 0
	global_load_lds_dwordx4 v130, vcc
	s_waitcnt vmcnt(6)
	s_barrier
; #define WAIT_V(n) asm volatile("s_waitcnt vmcnt(" #n ")" ::: "memory")
; #define WAIT_L(n) asm volatile("s_waitcnt lgkmcnt(" #n ")" ::: "memory")
; #define BAR __builtin_amdgcn_s_barrier()
; #define SCHED __builtin_amdgcn_sched_barrier(0)
; #define STAGE(P, BASE, br, kt) do { const char* _g = (const char*)((BASE) + (size_t)(br) * GK + (kt) * BK); \
;     __builtin_amdgcn_global_load_lds((const unsigned*)(_g + voff0), (unsigned*)((char*)(P) + tx * 16), 16, 0, 0); \
;     __builtin_amdgcn_global_load_lds((const unsigned*)(_g + voff1), (unsigned*)((char*)(P) + tx * 16 + 8192), 16, 0, 0); } while (0)
; #define LDA(dst, b, h) _Pragma("unroll") for (int m = 0; m < 4; ++m) _Pragma("unroll") for (int k = 0; k < 2; ++k) \
;     dst[m][k] = *reinterpret_cast<const bf16x8*>((char*)shm + abase + (((b) * 2 + (h)) * 16384 + (m * 2 + k) * 1024))
; #define LDB(dst, b, h) _Pragma("unroll") for (int n = 0; n < 2; ++n) _Pragma("unroll") for (int k = 0; k < 2; ++k) \
;     dst[n][k] = *reinterpret_cast<const bf16x8*>((char*)shm + bbase + (((b) * 2 + (h)) * 16384 + (n * 2 + k) * 1024))
; template <bool SWAP>
; __device__ __forceinline__ void gemm_main(const u16* __restrict__ A, const u16* __restrict__ Bt, int brow, int bcol,
;                                           u16* shm, f32x4 (&acc)[2][2][4][2]) {
;     ...
;     WAIT_V(6); BAR; MMA(1, 1, At, B1); BAR;
;     LDB(B0, 1, 0); SCHED; LDA(At, 1, 0); STAGE(SA(0, 1), A, brow + HALF, t + 2);
;     WAIT_L(8); BAR; WAIT_L(0); MMA(0, 0, At, B0); BAR; SCHED;
;     LDB(B1, 1, 1); STAGE(SB(1, 0), Bt, bcol, t + 3);
;     BAR; WAIT_L(0); MMA(0, 1, At, B1); BAR;
;     LDA(At, 1, 1); STAGE(SA(1, 0), A, brow, t + 3);
;     BAR; WAIT_L(0); MMA(1, 0, At, B0); BAR; SCHED;
	v_mfma_f32_16x16x32_bf16 v[28:31], v[204:207], v[172:175], v[28:31]
	v_mfma_f32_16x16x32_bf16 v[24:27], v[216:219], v[172:175], v[24:27]
	v_mfma_f32_16x16x32_bf16 v[20:23], v[204:207], v[180:183], v[20:23]
	v_mfma_f32_16x16x32_bf16 v[16:19], v[216:219], v[180:183], v[16:19]
	v_mfma_f32_16x16x32_bf16 v[12:15], v[204:207], v[188:191], v[12:15]
	v_mfma_f32_16x16x32_bf16 v[8:11], v[216:219], v[188:191], v[8:11]
	v_mfma_f32_16x16x32_bf16 v[4:7], v[204:207], v[196:199], v[4:7]
	v_mfma_f32_16x16x32_bf16 v[0:3], v[216:219], v[196:199], v[0:3]
	v_mfma_f32_16x16x32_bf16 v[28:31], v[212:215], v[176:179], v[28:31]
	ds_read_b128 v[172:175], v145 offset:32768
	v_mfma_f32_16x16x32_bf16 v[24:27], v[220:223], v[176:179], v[24:27]
	v_mfma_f32_16x16x32_bf16 v[20:23], v[212:215], v[184:187], v[20:23]
	ds_read_b128 v[180:183], v145 offset:34816
	v_mfma_f32_16x16x32_bf16 v[16:19], v[220:223], v[184:187], v[16:19]
	v_mfma_f32_16x16x32_bf16 v[12:15], v[212:215], v[192:195], v[12:15]
	ds_read_b128 v[188:191], v145 offset:36864
	v_mfma_f32_16x16x32_bf16 v[8:11], v[220:223], v[192:195], v[8:11]
	v_mfma_f32_16x16x32_bf16 v[4:7], v[212:215], v[200:203], v[4:7]
	ds_read_b128 v[196:199], v145 offset:38912
	v_mfma_f32_16x16x32_bf16 v[0:3], v[220:223], v[200:203], v[0:3]
	s_barrier
	ds_read_b128 v[176:179], v145 offset:33792
	ds_read_b128 v[184:187], v145 offset:35840
	ds_read_b128 v[192:195], v145 offset:37888
	ds_read_b128 v[200:203], v145 offset:39936
	s_add_u32 m0, s25, 0x4000
	s_nop 0
	s_add_u32 vcc_lo, s28, s14
	s_addc_u32 vcc_hi, s29, s15
	global_load_lds_dwordx4 v136, vcc
	s_add_u32 m0, s25, 0x6000
	s_nop 0
	global_load_lds_dwordx4 v132, vcc
	s_waitcnt lgkmcnt(8)
	s_barrier
	s_waitcnt lgkmcnt(0)
	v_mfma_f32_16x16x32_bf16 v[124:127], v[156:159], v[172:175], v[124:127]
	v_mfma_f32_16x16x32_bf16 v[120:123], v[164:167], v[172:175], v[120:123]
	v_mfma_f32_16x16x32_bf16 v[116:119], v[156:159], v[180:183], v[116:119]
	v_mfma_f32_16x16x32_bf16 v[112:115], v[164:167], v[180:183], v[112:115]
	v_mfma_f32_16x16x32_bf16 v[108:111], v[156:159], v[188:191], v[108:111]
	v_mfma_f32_16x16x32_bf16 v[104:107], v[164:167], v[188:191], v[104:107]
	v_mfma_f32_16x16x32_bf16 v[100:103], v[156:159], v[196:199], v[100:103]
	v_mfma_f32_16x16x32_bf16 v[96:99], v[164:167], v[196:199], v[96:99]
	v_mfma_f32_16x16x32_bf16 v[124:127], v[160:163], v[176:179], v[124:127]
	v_mfma_f32_16x16x32_bf16 v[120:123], v[168:171], v[176:179], v[120:123]
	v_mfma_f32_16x16x32_bf16 v[116:119], v[160:163], v[184:187], v[116:119]
	v_mfma_f32_16x16x32_bf16 v[112:115], v[168:171], v[184:187], v[112:115]
	v_mfma_f32_16x16x32_bf16 v[108:111], v[160:163], v[192:195], v[108:111]
	v_mfma_f32_16x16x32_bf16 v[104:107], v[168:171], v[192:195], v[104:107]
	v_mfma_f32_16x16x32_bf16 v[100:103], v[160:163], v[200:203], v[100:103]
	v_mfma_f32_16x16x32_bf16 v[96:99], v[168:171], v[200:203], v[96:99]
	s_barrier
	ds_read_b128 v[204:207], v146 offset:49152
	ds_read_b128 v[212:215], v146 offset:50176
	ds_read_b128 v[216:219], v146 offset:51200
	ds_read_b128 v[220:223], v146 offset:52224
	s_add_u32 m0, s25, s52
	s_nop 0
	s_add_u32 vcc_lo, s28, s16
	s_addc_u32 vcc_hi, s29, s17
	global_load_lds_dwordx4 v134, vcc
	v_lshl_add_u64 v[230:231], v[228:229], 0, s[16:17]
	s_add_u32 m0, s25, s52
	s_add_u32 m0, m0, 0x2000
	s_nop 0
	global_load_lds_dwordx4 v130, vcc
	s_barrier
	s_waitcnt lgkmcnt(0)
	v_mfma_f32_16x16x32_bf16 v[92:95], v[204:207], v[172:175], v[92:95]
	v_mfma_f32_16x16x32_bf16 v[88:91], v[216:219], v[172:175], v[88:91]
	v_mfma_f32_16x16x32_bf16 v[84:87], v[204:207], v[180:183], v[84:87]
	v_mfma_f32_16x16x32_bf16 v[80:83], v[216:219], v[180:183], v[80:83]
	v_mfma_f32_16x16x32_bf16 v[76:79], v[204:207], v[188:191], v[76:79]
	v_mfma_f32_16x16x32_bf16 v[72:75], v[216:219], v[188:191], v[72:75]
	v_mfma_f32_16x16x32_bf16 v[68:71], v[204:207], v[196:199], v[68:71]
	v_mfma_f32_16x16x32_bf16 v[64:67], v[216:219], v[196:199], v[64:67]
	v_mfma_f32_16x16x32_bf16 v[92:95], v[212:215], v[176:179], v[92:95]
	ds_read_b128 v[172:175], v145 offset:49152
	v_mfma_f32_16x16x32_bf16 v[88:91], v[220:223], v[176:179], v[88:91]
	v_mfma_f32_16x16x32_bf16 v[84:87], v[212:215], v[184:187], v[84:87]
	ds_read_b128 v[180:183], v145 offset:51200
	v_mfma_f32_16x16x32_bf16 v[80:83], v[220:223], v[184:187], v[80:83]
	v_mfma_f32_16x16x32_bf16 v[76:79], v[212:215], v[192:195], v[76:79]
	ds_read_b128 v[188:191], v145 offset:53248
	v_mfma_f32_16x16x32_bf16 v[72:75], v[220:223], v[192:195], v[72:75]
	v_mfma_f32_16x16x32_bf16 v[68:71], v[212:215], v[200:203], v[68:71]
	ds_read_b128 v[196:199], v145 offset:55296
	v_mfma_f32_16x16x32_bf16 v[64:67], v[220:223], v[200:203], v[64:67]
	s_barrier
	ds_read_b128 v[176:179], v145 offset:50176
	ds_read_b128 v[184:187], v145 offset:52224
	ds_read_b128 v[192:195], v145 offset:54272
	ds_read_b128 v[200:203], v145 offset:56320
	s_add_u32 m0, s25, 0x8000
	s_nop 0
	s_add_u32 vcc_lo, s28, s18
	s_addc_u32 vcc_hi, s29, s19
	global_load_lds_dwordx4 v136, vcc
	v_lshl_add_u64 v[208:209], v[224:225], 0, s[18:19]
	s_add_u32 m0, s25, 0xa000
	s_nop 0
	global_load_lds_dwordx4 v132, vcc
	s_waitcnt vmcnt(8)
	s_barrier
; #define WAIT_V(n) asm volatile("s_waitcnt vmcnt(" #n ")" ::: "memory")
; #define WAIT_L(n) asm volatile("s_waitcnt lgkmcnt(" #n ")" ::: "memory")
; #define BAR __builtin_amdgcn_s_barrier()
; #define SCHED __builtin_amdgcn_sched_barrier(0)
; #define STAGE(P, BASE, br, kt) do { const char* _g = (const char*)((BASE) + (size_t)(br) * GK + (kt) * BK); \
;     __builtin_amdgcn_global_load_lds((const unsigned*)(_g + voff0), (unsigned*)((char*)(P) + tx * 16), 16, 0, 0); \
;     __builtin_amdgcn_global_load_lds((const unsigned*)(_g + voff1), (unsigned*)((char*)(P) + tx * 16 + 8192), 16, 0, 0); } while (0)
; #define LDA(dst, b, h) _Pragma("unroll") for (int m = 0; m < 4; ++m) _Pragma("unroll") for (int k = 0; k < 2; ++k) \
;     dst[m][k] = *reinterpret_cast<const bf16x8*>((char*)shm + abase + (((b) * 2 + (h)) * 16384 + (m * 2 + k) * 1024))
; #define LDB(dst, b, h) _Pragma("unroll") for (int n = 0; n < 2; ++n) _Pragma("unroll") for (int k = 0; k < 2; ++k) \
;     dst[n][k] = *reinterpret_cast<const bf16x8*>((char*)shm + bbase + (((b) * 2 + (h)) * 16384 + (n * 2 + k) * 1024))
; template <bool SWAP>
; __device__ __forceinline__ void gemm_main(const u16* __restrict__ A, const u16* __restrict__ Bt, int brow, int bcol,
;                                           u16* shm, f32x4 (&acc)[2][2][4][2]) {
;     ...
;     BAR; WAIT_L(0); MMA(1, 0, At, B0); BAR; SCHED;
;     STAGE(SB(1, 1), Bt, bcol + HALF, t + 3);
;     WAIT_V(6); BAR; MMA(1, 1, At, B1); BAR;
;   }
;   { LDB(B0, 0, 0); LDA(At, 0, 0); STAGE(SA(1, 1), A, brow + HALF, nt - 1);
;     BAR; WAIT_L(0); MMA(0, 0, At, B0); BAR;
	s_waitcnt lgkmcnt(0)
	v_mfma_f32_16x16x32_bf16 v[60:63], v[156:159], v[172:175], v[60:63]
	v_mfma_f32_16x16x32_bf16 v[56:59], v[164:167], v[172:175], v[56:59]
	v_mfma_f32_16x16x32_bf16 v[52:55], v[156:159], v[180:183], v[52:55]
	v_mfma_f32_16x16x32_bf16 v[48:51], v[164:167], v[180:183], v[48:51]
	v_mfma_f32_16x16x32_bf16 v[44:47], v[156:159], v[188:191], v[44:47]
	v_mfma_f32_16x16x32_bf16 v[40:43], v[164:167], v[188:191], v[40:43]
	v_mfma_f32_16x16x32_bf16 v[36:39], v[156:159], v[196:199], v[36:39]
	v_mfma_f32_16x16x32_bf16 v[32:35], v[164:167], v[196:199], v[32:35]
	v_mfma_f32_16x16x32_bf16 v[60:63], v[160:163], v[176:179], v[60:63]
	v_mfma_f32_16x16x32_bf16 v[56:59], v[168:171], v[176:179], v[56:59]
	v_mfma_f32_16x16x32_bf16 v[52:55], v[160:163], v[184:187], v[52:55]
	v_mfma_f32_16x16x32_bf16 v[48:51], v[168:171], v[184:187], v[48:51]
	v_mfma_f32_16x16x32_bf16 v[44:47], v[160:163], v[192:195], v[44:47]
	v_mfma_f32_16x16x32_bf16 v[40:43], v[168:171], v[192:195], v[40:43]
	v_mfma_f32_16x16x32_bf16 v[36:39], v[160:163], v[200:203], v[36:39]
	v_mfma_f32_16x16x32_bf16 v[32:35], v[168:171], v[200:203], v[32:35]
	s_barrier
	ds_read_b128 v[156:159], v146
	ds_read_b128 v[160:163], v146 offset:1024
	ds_read_b128 v[164:167], v146 offset:2048
	ds_read_b128 v[168:171], v146 offset:3072
	s_add_u32 m0, s25, s53
	s_nop 0
	s_add_u32 vcc_lo, s28, s20
	s_addc_u32 vcc_hi, s29, s21
	global_load_lds_dwordx4 v134, vcc
	v_lshl_add_u64 v[254:255], v[228:229], 0, s[20:21]
	s_add_u32 m0, s25, s53
	s_add_u32 m0, m0, 0x2000
	s_nop 0
	global_load_lds_dwordx4 v130, vcc
	s_waitcnt vmcnt(6)
	s_barrier
	v_mfma_f32_16x16x32_bf16 v[28:31], v[204:207], v[172:175], v[28:31]
	v_mfma_f32_16x16x32_bf16 v[24:27], v[216:219], v[172:175], v[24:27]
	v_mfma_f32_16x16x32_bf16 v[20:23], v[204:207], v[180:183], v[20:23]
	v_mfma_f32_16x16x32_bf16 v[16:19], v[216:219], v[180:183], v[16:19]
	v_mfma_f32_16x16x32_bf16 v[12:15], v[204:207], v[188:191], v[12:15]
	v_mfma_f32_16x16x32_bf16 v[8:11], v[216:219], v[188:191], v[8:11]
	v_mfma_f32_16x16x32_bf16 v[4:7], v[204:207], v[196:199], v[4:7]
	v_mfma_f32_16x16x32_bf16 v[0:3], v[216:219], v[196:199], v[0:3]
	v_mfma_f32_16x16x32_bf16 v[28:31], v[212:215], v[176:179], v[28:31]
	ds_read_b128 v[172:175], v145
	v_mfma_f32_16x16x32_bf16 v[24:27], v[220:223], v[176:179], v[24:27]
	v_mfma_f32_16x16x32_bf16 v[20:23], v[212:215], v[184:187], v[20:23]
	ds_read_b128 v[180:183], v145 offset:2048
	v_mfma_f32_16x16x32_bf16 v[16:19], v[220:223], v[184:187], v[16:19]
	s_add_i32 s4, s4, 2
	s_add_u32 s28, s28, 0x100
	s_addc_u32 s29, s29, 0
	s_cmp_lt_u32 s4, 28
	v_mfma_f32_16x16x32_bf16 v[12:15], v[212:215], v[192:195], v[12:15]
	ds_read_b128 v[188:191], v145 offset:4096
	v_mfma_f32_16x16x32_bf16 v[8:11], v[220:223], v[192:195], v[8:11]
	v_mfma_f32_16x16x32_bf16 v[4:7], v[212:215], v[200:203], v[4:7]
	ds_read_b128 v[196:199], v145 offset:6144
	v_mfma_f32_16x16x32_bf16 v[0:3], v[220:223], v[200:203], v[0:3]
	s_barrier
	s_cbranch_scc1 .LBB0_94
	v_lshlrev_b32_e32 v128, 3, v148
	v_lshlrev_b32_e32 v130, 5, v148
	v_and_b32_e32 v128, 0xffff0, v128
	v_and_b32_e32 v130, 32, v130
	s_or_b32 s28, s26, 0x80
	v_add_u32_e32 v130, v130, v150
	v_add_lshl_u32 v128, v149, v128, 12
	s_ashr_i32 s29, s28, 31
	v_lshl_add_u32 v128, v130, 1, v128
	v_lshlrev_b32_e32 v130, 3, v151
	v_lshlrev_b32_e32 v131, 5, v151
	s_lshl_b64 s[28:29], s[28:29], 12
	v_and_b32_e32 v130, 0xffff0, v130
	v_and_b32_e32 v131, 32, v131
	s_add_u32 s28, s37, s28
	v_add_u32_e32 v131, v131, v153
	v_add_lshl_u32 v130, v152, v130, 12
	s_addc_u32 s29, s38, s29
	v_lshl_add_u32 v152, v131, 1, v130
	v_mov_b32_e32 v153, v129
	v_lshl_add_u64 v[192:193], s[28:29], 0, v[128:129]
	v_readfirstlane_b32 s4, v154
	v_lshl_add_u64 v[192:193], v[192:193], 0, s[22:23]
	s_mov_b32 m0, s4
	v_lshl_add_u64 v[152:153], s[28:29], 0, v[152:153]
	v_readfirstlane_b32 s4, v155
	ds_read_b128 v[130:133], v146
	ds_read_b128 v[134:137], v146 offset:1024
	ds_read_b128 v[148:151], v146 offset:2048
	ds_read_b128 v[156:159], v146 offset:3072
	ds_read_b128 v[160:163], v145
	ds_read_b128 v[164:167], v145 offset:1024
	ds_read_b128 v[168:171], v145 offset:2048
	ds_read_b128 v[172:175], v145 offset:3072
	ds_read_b128 v[176:179], v145 offset:4096
	ds_read_b128 v[180:183], v145 offset:5120
	ds_read_b128 v[184:187], v145 offset:6144
	ds_read_b128 v[188:191], v145 offset:7168
	global_load_lds_dwordx4 v[192:193], off
	v_lshl_add_u64 v[152:153], v[152:153], 0, s[22:23]
	s_mov_b32 m0, s4
	s_nop 0
	global_load_lds_dwordx4 v[152:153], off
	s_barrier
	s_waitcnt lgkmcnt(0)
	s_setprio 1
	s_waitcnt lgkmcnt(0)
	v_mfma_f32_16x16x32_bf16 v[124:127], v[130:133], v[160:163], v[124:127]
	v_mfma_f32_16x16x32_bf16 v[116:119], v[130:133], v[168:171], v[116:119]
	v_mfma_f32_16x16x32_bf16 v[108:111], v[130:133], v[176:179], v[108:111]
	v_mfma_f32_16x16x32_bf16 v[100:103], v[130:133], v[184:187], v[100:103]
	v_mfma_f32_16x16x32_bf16 v[124:127], v[134:137], v[164:167], v[124:127]
	v_mfma_f32_16x16x32_bf16 v[120:123], v[148:151], v[160:163], v[120:123]
	v_mfma_f32_16x16x32_bf16 v[116:119], v[134:137], v[172:175], v[116:119]
	v_mfma_f32_16x16x32_bf16 v[112:115], v[148:151], v[168:171], v[112:115]
	v_mfma_f32_16x16x32_bf16 v[108:111], v[134:137], v[180:183], v[108:111]
	v_mfma_f32_16x16x32_bf16 v[104:107], v[148:151], v[176:179], v[104:107]
	v_mfma_f32_16x16x32_bf16 v[100:103], v[134:137], v[188:191], v[100:103]
	v_mfma_f32_16x16x32_bf16 v[96:99], v[148:151], v[184:187], v[96:99]
	v_mfma_f32_16x16x32_bf16 v[152:155], v[156:159], v[164:167], v[120:123]
	v_mfma_f32_16x16x32_bf16 v[192:195], v[156:159], v[172:175], v[112:115]
	v_mfma_f32_16x16x32_bf16 v[196:199], v[156:159], v[180:183], v[104:107]
	v_mfma_f32_16x16x32_bf16 v[200:203], v[156:159], v[188:191], v[96:99]
	s_setprio 0
	s_barrier
; #define WAIT_V(n) asm volatile("s_waitcnt vmcnt(" #n ")" ::: "memory")
; #define WAIT_L(n) asm volatile("s_waitcnt lgkmcnt(" #n ")" ::: "memory")
; #define BAR __builtin_amdgcn_s_barrier()
; #define LDA(dst, b, h) _Pragma("unroll") for (int m = 0; m < 4; ++m) _Pragma("unroll") for (int k = 0; k < 2; ++k) \
;     dst[m][k] = *reinterpret_cast<const bf16x8*>((char*)shm + abase + (((b) * 2 + (h)) * 16384 + (m * 2 + k) * 1024))
; #define LDB(dst, b, h) _Pragma("unroll") for (int n = 0; n < 2; ++n) _Pragma("unroll") for (int k = 0; k < 2; ++k) \
;     dst[n][k] = *reinterpret_cast<const bf16x8*>((char*)shm + bbase + (((b) * 2 + (h)) * 16384 + (n * 2 + k) * 1024))
; template <bool SWAP>
; __device__ __forceinline__ void gemm_main(const u16* __restrict__ A, const u16* __restrict__ Bt, int brow, int bcol,
;                                           u16* shm, f32x4 (&acc)[2][2][4][2]) {
;     ...
;     LDB(B1, 0, 1); BAR; WAIT_L(0); MMA(0, 1, At, B1); BAR;
;     LDA(At, 0, 1); WAIT_V(4); BAR; WAIT_L(0); MMA(1, 0, At, B0); MMA(1, 1, At, B1); BAR; }
;   { LDB(B0, 1, 0); LDA(At, 1, 0); WAIT_V(2); BAR; WAIT_L(0); MMA(0, 0, At, B0); BAR;
	s_nop 1
	ds_read_b128 v[96:99], v146 offset:16384
	ds_read_b128 v[104:107], v146 offset:17408
	ds_read_b128 v[112:115], v146 offset:18432
	ds_read_b128 v[120:123], v146 offset:19456
	s_barrier
	s_waitcnt lgkmcnt(0)
	s_setprio 1
	s_waitcnt lgkmcnt(0)
	v_mfma_f32_16x16x32_bf16 v[92:95], v[96:99], v[160:163], v[92:95]
	v_mfma_f32_16x16x32_bf16 v[84:87], v[96:99], v[168:171], v[84:87]
	v_mfma_f32_16x16x32_bf16 v[76:79], v[96:99], v[176:179], v[76:79]
	v_mfma_f32_16x16x32_bf16 v[68:71], v[96:99], v[184:187], v[68:71]
	v_mfma_f32_16x16x32_bf16 v[92:95], v[104:107], v[164:167], v[92:95]
	v_mfma_f32_16x16x32_bf16 v[88:91], v[112:115], v[160:163], v[88:91]
	v_mfma_f32_16x16x32_bf16 v[84:87], v[104:107], v[172:175], v[84:87]
	v_mfma_f32_16x16x32_bf16 v[80:83], v[112:115], v[168:171], v[80:83]
	v_mfma_f32_16x16x32_bf16 v[76:79], v[104:107], v[180:183], v[76:79]
	v_mfma_f32_16x16x32_bf16 v[72:75], v[112:115], v[176:179], v[72:75]
	v_mfma_f32_16x16x32_bf16 v[68:71], v[104:107], v[188:191], v[68:71]
	v_mfma_f32_16x16x32_bf16 v[64:67], v[112:115], v[184:187], v[64:67]
	v_mfma_f32_16x16x32_bf16 v[160:163], v[120:123], v[164:167], v[88:91]
	v_mfma_f32_16x16x32_bf16 v[164:167], v[120:123], v[172:175], v[80:83]
	v_mfma_f32_16x16x32_bf16 v[168:171], v[120:123], v[180:183], v[72:75]
	v_mfma_f32_16x16x32_bf16 v[172:175], v[120:123], v[188:191], v[64:67]
	s_setprio 0
	s_barrier
	s_nop 1
	ds_read_b128 v[64:67], v145 offset:16384
	ds_read_b128 v[72:75], v145 offset:17408
	ds_read_b128 v[80:83], v145 offset:18432
	ds_read_b128 v[88:91], v145 offset:19456
	ds_read_b128 v[176:179], v145 offset:20480
	ds_read_b128 v[180:183], v145 offset:21504
	ds_read_b128 v[184:187], v145 offset:22528
	ds_read_b128 v[188:191], v145 offset:23552
	s_waitcnt vmcnt(4)
	s_barrier
	s_waitcnt lgkmcnt(0)
	s_setprio 1
	s_waitcnt lgkmcnt(0)
	v_mfma_f32_16x16x32_bf16 v[60:63], v[130:133], v[64:67], v[60:63]
	v_mfma_f32_16x16x32_bf16 v[52:55], v[130:133], v[80:83], v[52:55]
	v_mfma_f32_16x16x32_bf16 v[44:47], v[130:133], v[176:179], v[44:47]
	v_mfma_f32_16x16x32_bf16 v[36:39], v[130:133], v[184:187], v[36:39]
	v_mfma_f32_16x16x32_bf16 v[60:63], v[134:137], v[72:75], v[60:63]
	v_mfma_f32_16x16x32_bf16 v[56:59], v[148:151], v[64:67], v[56:59]
	v_mfma_f32_16x16x32_bf16 v[52:55], v[134:137], v[88:91], v[52:55]
	v_mfma_f32_16x16x32_bf16 v[48:51], v[148:151], v[80:83], v[48:51]
	v_mfma_f32_16x16x32_bf16 v[44:47], v[134:137], v[180:183], v[44:47]
	v_mfma_f32_16x16x32_bf16 v[40:43], v[148:151], v[176:179], v[40:43]
	v_mfma_f32_16x16x32_bf16 v[36:39], v[134:137], v[188:191], v[36:39]
	v_mfma_f32_16x16x32_bf16 v[32:35], v[148:151], v[184:187], v[32:35]
	v_mfma_f32_16x16x32_bf16 v[204:207], v[156:159], v[72:75], v[56:59]
	v_mfma_f32_16x16x32_bf16 v[212:215], v[156:159], v[88:91], v[48:51]
	v_mfma_f32_16x16x32_bf16 v[216:219], v[156:159], v[180:183], v[40:43]
	v_mfma_f32_16x16x32_bf16 v[130:133], v[156:159], v[188:191], v[32:35]
	s_setprio 0
	s_setprio 1
	v_mfma_f32_16x16x32_bf16 v[28:31], v[96:99], v[64:67], v[28:31]
	v_mfma_f32_16x16x32_bf16 v[20:23], v[96:99], v[80:83], v[20:23]
	v_mfma_f32_16x16x32_bf16 v[12:15], v[96:99], v[176:179], v[12:15]
	v_mfma_f32_16x16x32_bf16 v[4:7], v[96:99], v[184:187], v[4:7]
	v_mfma_f32_16x16x32_bf16 v[28:31], v[104:107], v[72:75], v[28:31]
	v_mfma_f32_16x16x32_bf16 v[24:27], v[112:115], v[64:67], v[24:27]
	v_mfma_f32_16x16x32_bf16 v[20:23], v[104:107], v[88:91], v[20:23]
	v_mfma_f32_16x16x32_bf16 v[16:19], v[112:115], v[80:83], v[16:19]
	v_mfma_f32_16x16x32_bf16 v[12:15], v[104:107], v[180:183], v[12:15]
	v_mfma_f32_16x16x32_bf16 v[8:11], v[112:115], v[176:179], v[8:11]
	v_mfma_f32_16x16x32_bf16 v[4:7], v[104:107], v[188:191], v[4:7]
	v_mfma_f32_16x16x32_bf16 v[0:3], v[112:115], v[184:187], v[0:3]
	v_mfma_f32_16x16x32_bf16 v[134:137], v[120:123], v[72:75], v[24:27]
	v_mfma_f32_16x16x32_bf16 v[148:151], v[120:123], v[88:91], v[16:19]
	v_mfma_f32_16x16x32_bf16 v[156:159], v[120:123], v[180:183], v[8:11]
	v_mfma_f32_16x16x32_bf16 v[176:179], v[120:123], v[188:191], v[0:3]
	s_setprio 0
	s_barrier
	s_nop 1
	ds_read_b128 v[0:3], v146 offset:32768
	ds_read_b128 v[8:11], v146 offset:33792
	ds_read_b128 v[16:19], v146 offset:34816
	ds_read_b128 v[24:27], v146 offset:35840
	ds_read_b128 v[32:35], v145 offset:32768
	ds_read_b128 v[40:43], v145 offset:33792
	ds_read_b128 v[48:51], v145 offset:34816
	ds_read_b128 v[56:59], v145 offset:35840
	ds_read_b128 v[64:67], v145 offset:36864
	ds_read_b128 v[180:183], v145 offset:37888
	ds_read_b128 v[184:187], v145 offset:38912
	ds_read_b128 v[188:191], v145 offset:39936
	s_waitcnt vmcnt(2)
	s_barrier
; #define WAIT_V(n) asm volatile("s_waitcnt vmcnt(" #n ")" ::: "memory")
; #define WAIT_L(n) asm volatile("s_waitcnt lgkmcnt(" #n ")" ::: "memory")
; #define BAR __builtin_amdgcn_s_barrier()
; #define LDA(dst, b, h) _Pragma("unroll") for (int m = 0; m < 4; ++m) _Pragma("unroll") for (int k = 0; k < 2; ++k) \
;     dst[m][k] = *reinterpret_cast<const bf16x8*>((char*)shm + abase + (((b) * 2 + (h)) * 16384 + (m * 2 + k) * 1024))
; #define LDB(dst, b, h) _Pragma("unroll") for (int n = 0; n < 2; ++n) _Pragma("unroll") for (int k = 0; k < 2; ++k) \
;     dst[n][k] = *reinterpret_cast<const bf16x8*>((char*)shm + bbase + (((b) * 2 + (h)) * 16384 + (n * 2 + k) * 1024))
; template <bool SWAP>
; __device__ __forceinline__ void gemm_main(const u16* __restrict__ A, const u16* __restrict__ Bt, int brow, int bcol,
;                                           u16* shm, f32x4 (&acc)[2][2][4][2]) {
;     ...
;   { LDB(B0, 1, 0); LDA(At, 1, 0); WAIT_V(2); BAR; WAIT_L(0); MMA(0, 0, At, B0); BAR;
;     LDB(B1, 1, 1); WAIT_V(0); BAR; WAIT_L(0); MMA(0, 1, At, B1); BAR;
;     LDA(At, 1, 1); BAR; WAIT_L(0); MMA(1, 0, At, B0); MMA(1, 1, At, B1); BAR; }
;   if (wr == 0) BAR;
	s_waitcnt lgkmcnt(0)
	s_setprio 1
	s_waitcnt lgkmcnt(0)
	v_mfma_f32_16x16x32_bf16 v[72:75], v[0:3], v[32:35], v[124:127]
	v_mfma_f32_16x16x32_bf16 v[120:123], v[8:11], v[40:43], v[72:75]
	v_mfma_f32_16x16x32_bf16 v[72:75], v[16:19], v[32:35], v[152:155]
	v_mfma_f32_16x16x32_bf16 v[124:127], v[24:27], v[40:43], v[72:75]
	v_mfma_f32_16x16x32_bf16 v[72:75], v[0:3], v[48:51], v[116:119]
	v_mfma_f32_16x16x32_bf16 v[112:115], v[8:11], v[56:59], v[72:75]
	v_mfma_f32_16x16x32_bf16 v[72:75], v[16:19], v[48:51], v[192:195]
	v_mfma_f32_16x16x32_bf16 v[116:119], v[24:27], v[56:59], v[72:75]
	v_mfma_f32_16x16x32_bf16 v[72:75], v[0:3], v[64:67], v[108:111]
	v_mfma_f32_16x16x32_bf16 v[104:107], v[8:11], v[180:183], v[72:75]
	v_mfma_f32_16x16x32_bf16 v[72:75], v[16:19], v[64:67], v[196:199]
	v_mfma_f32_16x16x32_bf16 v[108:111], v[24:27], v[180:183], v[72:75]
	v_mfma_f32_16x16x32_bf16 v[72:75], v[0:3], v[184:187], v[100:103]
	v_mfma_f32_16x16x32_bf16 v[96:99], v[8:11], v[188:191], v[72:75]
	v_mfma_f32_16x16x32_bf16 v[72:75], v[16:19], v[184:187], v[200:203]
	v_mfma_f32_16x16x32_bf16 v[100:103], v[24:27], v[188:191], v[72:75]
	s_setprio 0
	s_barrier
	ds_read_b128 v[152:155], v146 offset:49152
	ds_read_b128 v[192:195], v146 offset:50176
	ds_read_b128 v[196:199], v146 offset:51200
	ds_read_b128 v[200:203], v146 offset:52224
	s_waitcnt vmcnt(0)
	s_barrier
	s_waitcnt lgkmcnt(0)
	s_setprio 1
	s_waitcnt lgkmcnt(0)
	v_mfma_f32_16x16x32_bf16 v[72:75], v[152:155], v[32:35], v[92:95]
	v_mfma_f32_16x16x32_bf16 v[32:35], v[196:199], v[32:35], v[160:163]
	v_mfma_f32_16x16x32_bf16 v[92:95], v[200:203], v[40:43], v[32:35]
	v_mfma_f32_16x16x32_bf16 v[32:35], v[152:155], v[48:51], v[84:87]
	v_mfma_f32_16x16x32_bf16 v[80:83], v[192:195], v[56:59], v[32:35]
	v_mfma_f32_16x16x32_bf16 v[32:35], v[196:199], v[48:51], v[164:167]
	v_mfma_f32_16x16x32_bf16 v[84:87], v[200:203], v[56:59], v[32:35]
	v_mfma_f32_16x16x32_bf16 v[32:35], v[152:155], v[64:67], v[76:79]
	v_mfma_f32_16x16x32_bf16 v[88:91], v[192:195], v[40:43], v[72:75]
	v_mfma_f32_16x16x32_bf16 v[72:75], v[192:195], v[180:183], v[32:35]
	v_mfma_f32_16x16x32_bf16 v[32:35], v[196:199], v[64:67], v[168:171]
	v_mfma_f32_16x16x32_bf16 v[76:79], v[200:203], v[180:183], v[32:35]
	v_mfma_f32_16x16x32_bf16 v[32:35], v[152:155], v[184:187], v[68:71]
	v_mfma_f32_16x16x32_bf16 v[64:67], v[192:195], v[188:191], v[32:35]
	v_mfma_f32_16x16x32_bf16 v[32:35], v[196:199], v[184:187], v[172:175]
	v_mfma_f32_16x16x32_bf16 v[68:71], v[200:203], v[188:191], v[32:35]
	s_setprio 0
	s_barrier
	ds_read_b128 v[160:163], v145 offset:49152
	ds_read_b128 v[164:167], v145 offset:50176
	ds_read_b128 v[168:171], v145 offset:51200
	ds_read_b128 v[172:175], v145 offset:52224
	ds_read_b128 v[180:183], v145 offset:53248
	ds_read_b128 v[184:187], v145 offset:54272
	ds_read_b128 v[188:191], v145 offset:55296
	ds_read_b128 v[220:223], v145 offset:56320
	s_barrier
	s_waitcnt lgkmcnt(0)
	s_setprio 1
	s_waitcnt lgkmcnt(0)
	v_mfma_f32_16x16x32_bf16 v[32:35], v[0:3], v[160:163], v[60:63]
	v_mfma_f32_16x16x32_bf16 v[56:59], v[8:11], v[164:167], v[32:35]
	v_mfma_f32_16x16x32_bf16 v[32:35], v[16:19], v[160:163], v[204:207]
	v_mfma_f32_16x16x32_bf16 v[60:63], v[24:27], v[164:167], v[32:35]
	v_mfma_f32_16x16x32_bf16 v[32:35], v[0:3], v[168:171], v[52:55]
	v_mfma_f32_16x16x32_bf16 v[48:51], v[8:11], v[172:175], v[32:35]
	v_mfma_f32_16x16x32_bf16 v[32:35], v[16:19], v[168:171], v[212:215]
	v_mfma_f32_16x16x32_bf16 v[52:55], v[24:27], v[172:175], v[32:35]
	v_mfma_f32_16x16x32_bf16 v[32:35], v[0:3], v[180:183], v[44:47]
	v_mfma_f32_16x16x32_bf16 v[40:43], v[8:11], v[184:187], v[32:35]
	v_mfma_f32_16x16x32_bf16 v[32:35], v[16:19], v[180:183], v[216:219]
	v_mfma_f32_16x16x32_bf16 v[0:3], v[0:3], v[188:191], v[36:39]
	v_mfma_f32_16x16x32_bf16 v[44:47], v[24:27], v[184:187], v[32:35]
	v_mfma_f32_16x16x32_bf16 v[32:35], v[8:11], v[220:223], v[0:3]
	v_mfma_f32_16x16x32_bf16 v[0:3], v[16:19], v[188:191], v[130:133]
	v_mfma_f32_16x16x32_bf16 v[36:39], v[24:27], v[220:223], v[0:3]
	s_setprio 0
	s_setprio 1
	v_mfma_f32_16x16x32_bf16 v[0:3], v[152:155], v[160:163], v[28:31]
	v_mfma_f32_16x16x32_bf16 v[24:27], v[192:195], v[164:167], v[0:3]
	v_mfma_f32_16x16x32_bf16 v[0:3], v[196:199], v[160:163], v[134:137]
	v_mfma_f32_16x16x32_bf16 v[28:31], v[200:203], v[164:167], v[0:3]
	v_mfma_f32_16x16x32_bf16 v[0:3], v[152:155], v[168:171], v[20:23]
	v_mfma_f32_16x16x32_bf16 v[16:19], v[192:195], v[172:175], v[0:3]
	v_mfma_f32_16x16x32_bf16 v[0:3], v[196:199], v[168:171], v[148:151]
	v_mfma_f32_16x16x32_bf16 v[20:23], v[200:203], v[172:175], v[0:3]
	v_mfma_f32_16x16x32_bf16 v[0:3], v[152:155], v[180:183], v[12:15]
	v_mfma_f32_16x16x32_bf16 v[8:11], v[192:195], v[184:187], v[0:3]
	v_mfma_f32_16x16x32_bf16 v[0:3], v[196:199], v[180:183], v[156:159]
	v_mfma_f32_16x16x32_bf16 v[12:15], v[200:203], v[184:187], v[0:3]
	v_mfma_f32_16x16x32_bf16 v[0:3], v[152:155], v[188:191], v[4:7]
	v_mfma_f32_16x16x32_bf16 v[4:7], v[196:199], v[188:191], v[176:179]
	v_mfma_f32_16x16x32_bf16 v[0:3], v[192:195], v[220:223], v[0:3]
	v_mfma_f32_16x16x32_bf16 v[4:7], v[200:203], v[220:223], v[4:7]
	s_setprio 0
	v_cmp_gt_u32_e32 vcc, s55, v144
	s_barrier
	s_and_saveexec_b64 s[28:29], vcc
	s_cbranch_execz .LBB0_97
	s_barrier

; #define WAIT_V(n) asm volatile("s_waitcnt vmcnt(" #n ")" ::: "memory")
; #define WAIT_L(n) asm volatile("s_waitcnt lgkmcnt(" #n ")" ::: "memory")
; #define BAR __builtin_amdgcn_s_barrier()
; #define SCHED __builtin_amdgcn_sched_barrier(0)
; #define STAGE(P, BASE, br, kt) do { const char* _g = (const char*)((BASE) + (size_t)(br) * GK + (kt) * BK); \
;     __builtin_amdgcn_global_load_lds((const unsigned*)(_g + voff0), (unsigned*)((char*)(P) + tx * 16), 16, 0, 0); \
;     __builtin_amdgcn_global_load_lds((const unsigned*)(_g + voff1), (unsigned*)((char*)(P) + tx * 16 + 8192), 16, 0, 0); } while (0)
; #define LDA(dst, b, h) _Pragma("unroll") for (int m = 0; m < 4; ++m) _Pragma("unroll") for (int k = 0; k < 2; ++k) \
;     dst[m][k] = *reinterpret_cast<const bf16x8*>((char*)shm + abase + (((b) * 2 + (h)) * 16384 + (m * 2 + k) * 1024))
; #define LDB(dst, b, h) _Pragma("unroll") for (int n = 0; n < 2; ++n) _Pragma("unroll") for (int k = 0; k < 2; ++k) \
;     dst[n][k] = *reinterpret_cast<const bf16x8*>((char*)shm + bbase + (((b) * 2 + (h)) * 16384 + (n * 2 + k) * 1024))
; template <bool SWAP>
; __device__ __forceinline__ void gemm_main(const u16* __restrict__ A, const u16* __restrict__ Bt, int brow, int bcol,
;                                           u16* shm, f32x4 (&acc)[2][2][4][2]) {
;     ...
;   for (int t = 0; t < nt - 2; t += 2) {
;     LDB(B0, 0, 0); SCHED; LDA(At, 0, 0); STAGE(SA(1, 1), A, brow + HALF, t + 1);
;     WAIT_L(8); BAR; WAIT_L(0); MMA(0, 0, At, B0); BAR; SCHED;
;     LDB(B1, 0, 1); STAGE(SB(0, 0), Bt, bcol, t + 2);
;     BAR; WAIT_L(0); MMA(0, 1, At, B1); BAR;
;     LDA(At, 0, 1); STAGE(SA(0, 0), A, brow, t + 2);
;     BAR; WAIT_L(0); MMA(1, 0, At, B0); BAR; SCHED;
;     STAGE(SB(0, 1), Bt, bcol + HALF, t + 2);
;     WAIT_V(6); BAR; MMA(1, 1, At, B1); BAR;
.LBB0_114:
	ds_read_b128 v[182:185], v137 offset:1024
	ds_read_b128 v[194:197], v137 offset:3072
	ds_read_b128 v[202:205], v137 offset:5120
	ds_read_b128 v[222:225], v137 offset:7168
	v_add_u32_e32 v192, 0, v153
	v_add_u32_e32 v160, 0xc000, v192
	v_add_u32_e32 v161, 0xe000, v192
	s_add_u32 m0, s4, 0xc000
	v_lshl_add_u64 v[242:243], s[0:1], 0, v[134:135]
	s_add_u32 vcc_lo, s0, s82
	s_addc_u32 vcc_hi, s1, s83
	global_load_lds_dwordx4 v132, vcc
	s_add_u32 m0, s4, 0xe000
	s_nop 0
	global_load_lds_dwordx4 v134, vcc
	s_waitcnt lgkmcnt(8)
	s_barrier
	s_waitcnt lgkmcnt(0)
	v_mfma_f32_16x16x32_bf16 v[124:127], v[178:181], v[162:165], v[124:127]
	v_mfma_f32_16x16x32_bf16 v[120:123], v[178:181], v[170:173], v[120:123]
	v_mfma_f32_16x16x32_bf16 v[116:119], v[186:189], v[162:165], v[116:119]
	v_mfma_f32_16x16x32_bf16 v[112:115], v[186:189], v[170:173], v[112:115]
	v_mfma_f32_16x16x32_bf16 v[108:111], v[198:201], v[162:165], v[108:111]
	v_mfma_f32_16x16x32_bf16 v[104:107], v[198:201], v[170:173], v[104:107]
	v_mfma_f32_16x16x32_bf16 v[100:103], v[206:209], v[162:165], v[100:103]
	v_mfma_f32_16x16x32_bf16 v[96:99], v[206:209], v[170:173], v[96:99]
	v_mfma_f32_16x16x32_bf16 v[124:127], v[182:185], v[166:169], v[124:127]
	v_mfma_f32_16x16x32_bf16 v[120:123], v[182:185], v[174:177], v[120:123]
	v_mfma_f32_16x16x32_bf16 v[116:119], v[194:197], v[166:169], v[116:119]
	v_mfma_f32_16x16x32_bf16 v[112:115], v[194:197], v[174:177], v[112:115]
	v_mfma_f32_16x16x32_bf16 v[108:111], v[202:205], v[166:169], v[108:111]
	v_mfma_f32_16x16x32_bf16 v[104:107], v[202:205], v[174:177], v[104:107]
	v_mfma_f32_16x16x32_bf16 v[100:103], v[222:225], v[166:169], v[100:103]
	v_mfma_f32_16x16x32_bf16 v[96:99], v[222:225], v[174:177], v[96:99]
	s_barrier
	ds_read_b128 v[226:229], v152 offset:16384
	ds_read_b128 v[230:233], v152 offset:17408
	ds_read_b128 v[234:237], v152 offset:18432
	ds_read_b128 v[238:241], v152 offset:19456
	v_lshl_add_u64 v[244:245], s[0:1], 0, v[128:129]
	s_add_u32 m0, s4, s28
	s_nop 0
	s_add_u32 vcc_lo, s0, s74
	s_addc_u32 vcc_hi, s1, s75
	global_load_lds_dwordx4 v128, vcc
	v_lshl_add_u64 v[246:247], s[0:1], 0, v[130:131]
	s_add_u32 m0, s4, s28
	s_add_u32 m0, m0, 0x2000
	s_nop 0
	global_load_lds_dwordx4 v130, vcc
	s_barrier
	s_waitcnt lgkmcnt(0)
	v_mfma_f32_16x16x32_bf16 v[92:95], v[178:181], v[226:229], v[92:95]
	v_mfma_f32_16x16x32_bf16 v[88:91], v[178:181], v[234:237], v[88:91]
	v_mfma_f32_16x16x32_bf16 v[84:87], v[186:189], v[226:229], v[84:87]
	v_mfma_f32_16x16x32_bf16 v[80:83], v[186:189], v[234:237], v[80:83]
	v_mfma_f32_16x16x32_bf16 v[76:79], v[198:201], v[226:229], v[76:79]
	v_mfma_f32_16x16x32_bf16 v[72:75], v[198:201], v[234:237], v[72:75]
	v_mfma_f32_16x16x32_bf16 v[68:71], v[206:209], v[226:229], v[68:71]
	v_mfma_f32_16x16x32_bf16 v[64:67], v[206:209], v[234:237], v[64:67]
	v_mfma_f32_16x16x32_bf16 v[92:95], v[182:185], v[230:233], v[92:95]
	ds_read_b128 v[178:181], v137 offset:16384
	v_mfma_f32_16x16x32_bf16 v[88:91], v[182:185], v[238:241], v[88:91]
	v_mfma_f32_16x16x32_bf16 v[84:87], v[194:197], v[230:233], v[84:87]
	ds_read_b128 v[186:189], v137 offset:18432
	v_mfma_f32_16x16x32_bf16 v[80:83], v[194:197], v[238:241], v[80:83]
	v_mfma_f32_16x16x32_bf16 v[76:79], v[202:205], v[230:233], v[76:79]
	ds_read_b128 v[198:201], v137 offset:20480
	v_mfma_f32_16x16x32_bf16 v[72:75], v[202:205], v[238:241], v[72:75]
	v_mfma_f32_16x16x32_bf16 v[68:71], v[222:225], v[230:233], v[68:71]
	ds_read_b128 v[206:209], v137 offset:22528
	v_mfma_f32_16x16x32_bf16 v[64:67], v[222:225], v[238:241], v[64:67]
	s_barrier
	ds_read_b128 v[182:185], v137 offset:17408
	ds_read_b128 v[194:197], v137 offset:19456
	ds_read_b128 v[202:205], v137 offset:21504
	ds_read_b128 v[222:225], v137 offset:23552
	s_add_u32 m0, s4, 0x0
	s_nop 0
	s_add_u32 vcc_lo, s0, s76
	s_addc_u32 vcc_hi, s1, s77
	global_load_lds_dwordx4 v132, vcc
	s_add_u32 m0, s4, 0x2000
	s_nop 0
	global_load_lds_dwordx4 v134, vcc
	s_waitcnt vmcnt(8)
	s_barrier
	s_waitcnt lgkmcnt(0)
	v_mfma_f32_16x16x32_bf16 v[60:63], v[178:181], v[162:165], v[60:63]
	v_mfma_f32_16x16x32_bf16 v[56:59], v[178:181], v[170:173], v[56:59]
	v_mfma_f32_16x16x32_bf16 v[52:55], v[186:189], v[162:165], v[52:55]
	v_mfma_f32_16x16x32_bf16 v[48:51], v[186:189], v[170:173], v[48:51]
	v_mfma_f32_16x16x32_bf16 v[44:47], v[198:201], v[162:165], v[44:47]
	v_mfma_f32_16x16x32_bf16 v[40:43], v[198:201], v[170:173], v[40:43]
	v_mfma_f32_16x16x32_bf16 v[36:39], v[206:209], v[162:165], v[36:39]
	v_mfma_f32_16x16x32_bf16 v[32:35], v[206:209], v[170:173], v[32:35]
	v_mfma_f32_16x16x32_bf16 v[60:63], v[182:185], v[166:169], v[60:63]
	v_mfma_f32_16x16x32_bf16 v[56:59], v[182:185], v[174:177], v[56:59]
	v_mfma_f32_16x16x32_bf16 v[52:55], v[194:197], v[166:169], v[52:55]
	v_mfma_f32_16x16x32_bf16 v[48:51], v[194:197], v[174:177], v[48:51]
	v_mfma_f32_16x16x32_bf16 v[44:47], v[202:205], v[166:169], v[44:47]
	v_mfma_f32_16x16x32_bf16 v[40:43], v[202:205], v[174:177], v[40:43]
	v_mfma_f32_16x16x32_bf16 v[36:39], v[222:225], v[166:169], v[36:39]
	v_mfma_f32_16x16x32_bf16 v[32:35], v[222:225], v[174:177], v[32:35]
	s_barrier
	ds_read_b128 v[162:165], v152 offset:32768
	ds_read_b128 v[166:169], v152 offset:33792
	ds_read_b128 v[170:173], v152 offset:34816
	ds_read_b128 v[174:177], v152 offset:35840
	s_add_u32 m0, s4, s29
	s_nop 0
	s_add_u32 vcc_lo, s0, s70
	s_addc_u32 vcc_hi, s1, s71
	global_load_lds_dwordx4 v128, vcc
	s_add_u32 m0, s4, s29
	s_add_u32 m0, m0, 0x2000
	s_nop 0
	global_load_lds_dwordx4 v130, vcc
	s_waitcnt vmcnt(6)
	s_barrier
; #define WAIT_V(n) asm volatile("s_waitcnt vmcnt(" #n ")" ::: "memory")
; #define WAIT_L(n) asm volatile("s_waitcnt lgkmcnt(" #n ")" ::: "memory")
; #define BAR __builtin_amdgcn_s_barrier()
; #define SCHED __builtin_amdgcn_sched_barrier(0)
; #define STAGE(P, BASE, br, kt) do { const char* _g = (const char*)((BASE) + (size_t)(br) * GK + (kt) * BK); \
;     __builtin_amdgcn_global_load_lds((const unsigned*)(_g + voff0), (unsigned*)((char*)(P) + tx * 16), 16, 0, 0); \
;     __builtin_amdgcn_global_load_lds((const unsigned*)(_g + voff1), (unsigned*)((char*)(P) + tx * 16 + 8192), 16, 0, 0); } while (0)
; #define LDA(dst, b, h) _Pragma("unroll") for (int m = 0; m < 4; ++m) _Pragma("unroll") for (int k = 0; k < 2; ++k) \
;     dst[m][k] = *reinterpret_cast<const bf16x8*>((char*)shm + abase + (((b) * 2 + (h)) * 16384 + (m * 2 + k) * 1024))
; #define LDB(dst, b, h) _Pragma("unroll") for (int n = 0; n < 2; ++n) _Pragma("unroll") for (int k = 0; k < 2; ++k) \
;     dst[n][k] = *reinterpret_cast<const bf16x8*>((char*)shm + bbase + (((b) * 2 + (h)) * 16384 + (n * 2 + k) * 1024))
; template <bool SWAP>
; __device__ __forceinline__ void gemm_main(const u16* __restrict__ A, const u16* __restrict__ Bt, int brow, int bcol,
;                                           u16* shm, f32x4 (&acc)[2][2][4][2]) {
;     ...
;     WAIT_V(6); BAR; MMA(1, 1, At, B1); BAR;
;     LDB(B0, 1, 0); SCHED; LDA(At, 1, 0); STAGE(SA(0, 1), A, brow + HALF, t + 2);
;     WAIT_L(8); BAR; WAIT_L(0); MMA(0, 0, At, B0); BAR; SCHED;
;     LDB(B1, 1, 1); STAGE(SB(1, 0), Bt, bcol, t + 3);
;     BAR; WAIT_L(0); MMA(0, 1, At, B1); BAR;
;     LDA(At, 1, 1); STAGE(SA(1, 0), A, brow, t + 3);
;     BAR; WAIT_L(0); MMA(1, 0, At, B0); BAR; SCHED;
	v_mfma_f32_16x16x32_bf16 v[28:31], v[178:181], v[226:229], v[28:31]
	v_mfma_f32_16x16x32_bf16 v[24:27], v[178:181], v[234:237], v[24:27]
	v_mfma_f32_16x16x32_bf16 v[20:23], v[186:189], v[226:229], v[20:23]
	v_mfma_f32_16x16x32_bf16 v[16:19], v[186:189], v[234:237], v[16:19]
	v_mfma_f32_16x16x32_bf16 v[12:15], v[198:201], v[226:229], v[12:15]
	v_mfma_f32_16x16x32_bf16 v[8:11], v[198:201], v[234:237], v[8:11]
	v_mfma_f32_16x16x32_bf16 v[4:7], v[206:209], v[226:229], v[4:7]
	v_mfma_f32_16x16x32_bf16 v[0:3], v[206:209], v[234:237], v[0:3]
	v_mfma_f32_16x16x32_bf16 v[28:31], v[182:185], v[230:233], v[28:31]
	ds_read_b128 v[178:181], v137 offset:32768
	v_mfma_f32_16x16x32_bf16 v[24:27], v[182:185], v[238:241], v[24:27]
	v_mfma_f32_16x16x32_bf16 v[20:23], v[194:197], v[230:233], v[20:23]
	ds_read_b128 v[186:189], v137 offset:34816
	v_mfma_f32_16x16x32_bf16 v[16:19], v[194:197], v[238:241], v[16:19]
	v_mfma_f32_16x16x32_bf16 v[12:15], v[202:205], v[230:233], v[12:15]
	ds_read_b128 v[198:201], v137 offset:36864
	v_mfma_f32_16x16x32_bf16 v[8:11], v[202:205], v[238:241], v[8:11]
	v_mfma_f32_16x16x32_bf16 v[4:7], v[222:225], v[230:233], v[4:7]
	ds_read_b128 v[206:209], v137 offset:38912
	v_mfma_f32_16x16x32_bf16 v[0:3], v[222:225], v[238:241], v[0:3]
	s_barrier
	ds_read_b128 v[182:185], v137 offset:33792
	ds_read_b128 v[194:197], v137 offset:35840
	ds_read_b128 v[202:205], v137 offset:37888
	ds_read_b128 v[222:225], v137 offset:39936
	s_add_u32 m0, s4, 0x4000
	s_nop 0
	s_add_u32 vcc_lo, s0, s96
	s_addc_u32 vcc_hi, s1, s97
	global_load_lds_dwordx4 v132, vcc
	s_add_u32 m0, s4, 0x6000
	s_nop 0
	global_load_lds_dwordx4 v134, vcc
	s_waitcnt lgkmcnt(8)
	s_barrier
	s_waitcnt lgkmcnt(0)
	v_mfma_f32_16x16x32_bf16 v[124:127], v[178:181], v[162:165], v[124:127]
	v_mfma_f32_16x16x32_bf16 v[120:123], v[178:181], v[170:173], v[120:123]
	v_mfma_f32_16x16x32_bf16 v[116:119], v[186:189], v[162:165], v[116:119]
	v_mfma_f32_16x16x32_bf16 v[112:115], v[186:189], v[170:173], v[112:115]
	v_mfma_f32_16x16x32_bf16 v[108:111], v[198:201], v[162:165], v[108:111]
	v_mfma_f32_16x16x32_bf16 v[104:107], v[198:201], v[170:173], v[104:107]
	v_mfma_f32_16x16x32_bf16 v[100:103], v[206:209], v[162:165], v[100:103]
	v_mfma_f32_16x16x32_bf16 v[96:99], v[206:209], v[170:173], v[96:99]
	v_mfma_f32_16x16x32_bf16 v[124:127], v[182:185], v[166:169], v[124:127]
	v_mfma_f32_16x16x32_bf16 v[120:123], v[182:185], v[174:177], v[120:123]
	v_mfma_f32_16x16x32_bf16 v[116:119], v[194:197], v[166:169], v[116:119]
	v_mfma_f32_16x16x32_bf16 v[112:115], v[194:197], v[174:177], v[112:115]
	v_mfma_f32_16x16x32_bf16 v[108:111], v[202:205], v[166:169], v[108:111]
	v_mfma_f32_16x16x32_bf16 v[104:107], v[202:205], v[174:177], v[104:107]
	v_mfma_f32_16x16x32_bf16 v[100:103], v[222:225], v[166:169], v[100:103]
	v_mfma_f32_16x16x32_bf16 v[96:99], v[222:225], v[174:177], v[96:99]
	s_barrier
	ds_read_b128 v[226:229], v152 offset:49152
	ds_read_b128 v[230:233], v152 offset:50176
	ds_read_b128 v[234:237], v152 offset:51200
	ds_read_b128 v[238:241], v152 offset:52224
	v_add_u32_e32 v250, s30, v153
	v_add_u32_e32 v250, 0x2000, v250
	s_add_u32 m0, s4, s30
	s_nop 0
	s_add_u32 vcc_lo, s0, s34
	s_addc_u32 vcc_hi, s1, s35
	global_load_lds_dwordx4 v128, vcc
	v_lshl_add_u64 v[248:249], v[246:247], 0, s[34:35]
	s_add_u32 m0, s4, s30
	s_add_u32 m0, m0, 0x2000
	s_nop 0
	global_load_lds_dwordx4 v130, vcc
	s_barrier
	s_waitcnt lgkmcnt(0)
	v_mfma_f32_16x16x32_bf16 v[92:95], v[178:181], v[226:229], v[92:95]
	v_mfma_f32_16x16x32_bf16 v[88:91], v[178:181], v[234:237], v[88:91]
	v_mfma_f32_16x16x32_bf16 v[84:87], v[186:189], v[226:229], v[84:87]
	v_mfma_f32_16x16x32_bf16 v[80:83], v[186:189], v[234:237], v[80:83]
	v_mfma_f32_16x16x32_bf16 v[76:79], v[198:201], v[226:229], v[76:79]
	v_mfma_f32_16x16x32_bf16 v[72:75], v[198:201], v[234:237], v[72:75]
	v_mfma_f32_16x16x32_bf16 v[68:71], v[206:209], v[226:229], v[68:71]
	v_mfma_f32_16x16x32_bf16 v[64:67], v[206:209], v[234:237], v[64:67]
	v_mfma_f32_16x16x32_bf16 v[92:95], v[182:185], v[230:233], v[92:95]
	ds_read_b128 v[178:181], v137 offset:49152
	v_mfma_f32_16x16x32_bf16 v[88:91], v[182:185], v[238:241], v[88:91]
	v_mfma_f32_16x16x32_bf16 v[84:87], v[194:197], v[230:233], v[84:87]
	ds_read_b128 v[186:189], v137 offset:51200
	v_mfma_f32_16x16x32_bf16 v[80:83], v[194:197], v[238:241], v[80:83]
	v_mfma_f32_16x16x32_bf16 v[76:79], v[202:205], v[230:233], v[76:79]
	ds_read_b128 v[198:201], v137 offset:53248
	v_mfma_f32_16x16x32_bf16 v[72:75], v[202:205], v[238:241], v[72:75]
	v_mfma_f32_16x16x32_bf16 v[68:71], v[222:225], v[230:233], v[68:71]
	ds_read_b128 v[206:209], v137 offset:55296
	v_mfma_f32_16x16x32_bf16 v[64:67], v[222:225], v[238:241], v[64:67]
	s_barrier
	ds_read_b128 v[182:185], v137 offset:50176
	ds_read_b128 v[194:197], v137 offset:52224
	ds_read_b128 v[202:205], v137 offset:54272
	ds_read_b128 v[222:225], v137 offset:56320
	v_add_u32_e32 v248, 0x8000, v192
	s_add_u32 m0, s4, 0x8000
	s_nop 0
	s_add_u32 vcc_lo, s0, s36
	s_addc_u32 vcc_hi, s1, s37
	global_load_lds_dwordx4 v132, vcc
	s_add_u32 m0, s4, 0xa000
	s_nop 0
	global_load_lds_dwordx4 v134, vcc
	s_waitcnt vmcnt(8)
	s_barrier
; #define WAIT_V(n) asm volatile("s_waitcnt vmcnt(" #n ")" ::: "memory")
; #define WAIT_L(n) asm volatile("s_waitcnt lgkmcnt(" #n ")" ::: "memory")
; #define BAR __builtin_amdgcn_s_barrier()
; #define SCHED __builtin_amdgcn_sched_barrier(0)
; #define STAGE(P, BASE, br, kt) do { const char* _g = (const char*)((BASE) + (size_t)(br) * GK + (kt) * BK); \
;     __builtin_amdgcn_global_load_lds((const unsigned*)(_g + voff0), (unsigned*)((char*)(P) + tx * 16), 16, 0, 0); \
;     __builtin_amdgcn_global_load_lds((const unsigned*)(_g + voff1), (unsigned*)((char*)(P) + tx * 16 + 8192), 16, 0, 0); } while (0)
; #define LDA(dst, b, h) _Pragma("unroll") for (int m = 0; m < 4; ++m) _Pragma("unroll") for (int k = 0; k < 2; ++k) \
;     dst[m][k] = *reinterpret_cast<const bf16x8*>((char*)shm + abase + (((b) * 2 + (h)) * 16384 + (m * 2 + k) * 1024))
; #define LDB(dst, b, h) _Pragma("unroll") for (int n = 0; n < 2; ++n) _Pragma("unroll") for (int k = 0; k < 2; ++k) \
;     dst[n][k] = *reinterpret_cast<const bf16x8*>((char*)shm + bbase + (((b) * 2 + (h)) * 16384 + (n * 2 + k) * 1024))
; template <bool SWAP>
; __device__ __forceinline__ void gemm_main(const u16* __restrict__ A, const u16* __restrict__ Bt, int brow, int bcol,
;                                           u16* shm, f32x4 (&acc)[2][2][4][2]) {
;     ...
;     BAR; WAIT_L(0); MMA(1, 0, At, B0); BAR; SCHED;
;     STAGE(SB(1, 1), Bt, bcol + HALF, t + 3);
;     WAIT_V(6); BAR; MMA(1, 1, At, B1); BAR;
;   }
;   { LDB(B0, 0, 0); LDA(At, 0, 0); STAGE(SA(1, 1), A, brow + HALF, nt - 1);
;     BAR; WAIT_L(0); MMA(0, 0, At, B0); BAR;
	s_waitcnt lgkmcnt(0)
	v_mfma_f32_16x16x32_bf16 v[60:63], v[178:181], v[162:165], v[60:63]
	v_mfma_f32_16x16x32_bf16 v[56:59], v[178:181], v[170:173], v[56:59]
	v_mfma_f32_16x16x32_bf16 v[52:55], v[186:189], v[162:165], v[52:55]
	v_mfma_f32_16x16x32_bf16 v[48:51], v[186:189], v[170:173], v[48:51]
	v_mfma_f32_16x16x32_bf16 v[44:47], v[198:201], v[162:165], v[44:47]
	v_mfma_f32_16x16x32_bf16 v[40:43], v[198:201], v[170:173], v[40:43]
	v_mfma_f32_16x16x32_bf16 v[36:39], v[206:209], v[162:165], v[36:39]
	v_mfma_f32_16x16x32_bf16 v[32:35], v[206:209], v[170:173], v[32:35]
	v_mfma_f32_16x16x32_bf16 v[60:63], v[182:185], v[166:169], v[60:63]
	v_mfma_f32_16x16x32_bf16 v[56:59], v[182:185], v[174:177], v[56:59]
	v_mfma_f32_16x16x32_bf16 v[52:55], v[194:197], v[166:169], v[52:55]
	v_mfma_f32_16x16x32_bf16 v[48:51], v[194:197], v[174:177], v[48:51]
	v_mfma_f32_16x16x32_bf16 v[44:47], v[202:205], v[166:169], v[44:47]
	v_mfma_f32_16x16x32_bf16 v[40:43], v[202:205], v[174:177], v[40:43]
	v_mfma_f32_16x16x32_bf16 v[36:39], v[222:225], v[166:169], v[36:39]
	v_mfma_f32_16x16x32_bf16 v[32:35], v[222:225], v[174:177], v[32:35]
	s_barrier
	ds_read_b128 v[162:165], v152
	ds_read_b128 v[166:169], v152 offset:1024
	ds_read_b128 v[170:173], v152 offset:2048
	ds_read_b128 v[174:177], v152 offset:3072
	s_add_u32 m0, s4, s31
	s_nop 0
	s_add_u32 vcc_lo, s0, s64
	s_addc_u32 vcc_hi, s1, s65
	global_load_lds_dwordx4 v128, vcc
	v_lshl_add_u64 v[254:255], v[246:247], 0, s[64:65]
	s_add_u32 m0, s4, s31
	s_add_u32 m0, m0, 0x2000
	s_nop 0
	global_load_lds_dwordx4 v130, vcc
	s_waitcnt vmcnt(6)
	s_barrier
	v_mfma_f32_16x16x32_bf16 v[28:31], v[178:181], v[226:229], v[28:31]
	v_mfma_f32_16x16x32_bf16 v[24:27], v[178:181], v[234:237], v[24:27]
	v_mfma_f32_16x16x32_bf16 v[20:23], v[186:189], v[226:229], v[20:23]
	v_mfma_f32_16x16x32_bf16 v[16:19], v[186:189], v[234:237], v[16:19]
	v_mfma_f32_16x16x32_bf16 v[12:15], v[198:201], v[226:229], v[12:15]
	v_mfma_f32_16x16x32_bf16 v[8:11], v[198:201], v[234:237], v[8:11]
	v_mfma_f32_16x16x32_bf16 v[4:7], v[206:209], v[226:229], v[4:7]
	v_mfma_f32_16x16x32_bf16 v[0:3], v[206:209], v[234:237], v[0:3]
	v_mfma_f32_16x16x32_bf16 v[28:31], v[182:185], v[230:233], v[28:31]
	ds_read_b128 v[178:181], v137
	v_mfma_f32_16x16x32_bf16 v[24:27], v[182:185], v[238:241], v[24:27]
	v_mfma_f32_16x16x32_bf16 v[20:23], v[194:197], v[230:233], v[20:23]
	ds_read_b128 v[186:189], v137 offset:2048
	v_mfma_f32_16x16x32_bf16 v[16:19], v[194:197], v[238:241], v[16:19]
	s_add_i32 s3, s3, 2
	s_add_u32 s0, s0, 0x100
	s_addc_u32 s1, s1, 0
	s_cmp_lt_u32 s3, 28
	v_mfma_f32_16x16x32_bf16 v[12:15], v[202:205], v[230:233], v[12:15]
	ds_read_b128 v[198:201], v137 offset:4096
	v_mfma_f32_16x16x32_bf16 v[8:11], v[202:205], v[238:241], v[8:11]
	v_mfma_f32_16x16x32_bf16 v[4:7], v[222:225], v[230:233], v[4:7]
	ds_read_b128 v[206:209], v137 offset:6144
	v_mfma_f32_16x16x32_bf16 v[0:3], v[222:225], v[238:241], v[0:3]
	s_barrier
	s_cbranch_scc1 .LBB0_114
	v_lshlrev_b32_e32 v128, 3, v154
	v_lshlrev_b32_e32 v129, 5, v154
	v_and_b32_e32 v128, 0xffff0, v128
	v_and_b32_e32 v129, 32, v129
	s_or_b32 s0, s24, 0x80
	v_add_u32_e32 v129, v129, v156
	v_add_lshl_u32 v128, v155, v128, 12
	s_ashr_i32 s1, s0, 31
	v_lshl_add_u32 v192, v129, 1, v128
	v_lshlrev_b32_e32 v128, 3, v157
	v_lshlrev_b32_e32 v129, 5, v157
	s_mov_b32 s22, s0
	s_lshl_b64 s[0:1], s[0:1], 12
	v_readlane_b32 s4, v253, 35
	v_and_b32_e32 v128, 0xffff0, v128
	v_and_b32_e32 v129, 32, v129
	v_readlane_b32 s5, v253, 36
	s_add_u32 s0, s4, s0
	v_add_u32_e32 v129, v129, v159
	v_add_lshl_u32 v128, v158, v128, 12
	s_addc_u32 s1, s5, s1
	v_lshl_add_u32 v158, v129, 1, v128
	v_mov_b32_e32 v159, v193
	v_lshl_add_u64 v[190:191], s[0:1], 0, v[192:193]
	s_mov_b64 s[4:5], 0xf80
	v_readfirstlane_b32 s3, v160
	v_lshl_add_u64 v[190:191], v[190:191], 0, s[4:5]
	s_mov_b32 m0, s3
	v_lshl_add_u64 v[158:159], s[0:1], 0, v[158:159]
	v_readfirstlane_b32 s0, v161
	ds_read_b128 v[128:131], v152
	ds_read_b128 v[132:135], v152 offset:1024
	ds_read_b128 v[154:157], v152 offset:2048
	ds_read_b128 v[162:165], v152 offset:3072
	ds_read_b128 v[166:169], v137
	ds_read_b128 v[170:173], v137 offset:1024
	ds_read_b128 v[174:177], v137 offset:2048
	ds_read_b128 v[178:181], v137 offset:3072
	ds_read_b128 v[182:185], v137 offset:4096
	ds_read_b128 v[186:189], v137 offset:5120
	ds_read_b128 v[194:197], v137 offset:6144
	ds_read_b128 v[198:201], v137 offset:7168
	global_load_lds_dwordx4 v[190:191], off
	v_lshl_add_u64 v[158:159], v[158:159], 0, s[4:5]
	s_mov_b32 m0, s0
	s_nop 0
	global_load_lds_dwordx4 v[158:159], off
	s_barrier
	s_waitcnt lgkmcnt(0)
	s_setprio 1
	s_waitcnt lgkmcnt(0)
	v_mfma_f32_16x16x32_bf16 v[124:127], v[166:169], v[128:131], v[124:127]
	v_mfma_f32_16x16x32_bf16 v[120:123], v[166:169], v[154:157], v[120:123]
	v_mfma_f32_16x16x32_bf16 v[116:119], v[174:177], v[128:131], v[116:119]
	v_mfma_f32_16x16x32_bf16 v[112:115], v[174:177], v[154:157], v[112:115]
	v_mfma_f32_16x16x32_bf16 v[108:111], v[182:185], v[128:131], v[108:111]
	v_mfma_f32_16x16x32_bf16 v[104:107], v[182:185], v[154:157], v[104:107]
	v_mfma_f32_16x16x32_bf16 v[100:103], v[194:197], v[128:131], v[100:103]
	v_mfma_f32_16x16x32_bf16 v[96:99], v[194:197], v[154:157], v[96:99]
	v_mfma_f32_16x16x32_bf16 v[124:127], v[170:173], v[132:135], v[124:127]
	v_mfma_f32_16x16x32_bf16 v[120:123], v[170:173], v[162:165], v[120:123]
	v_mfma_f32_16x16x32_bf16 v[116:119], v[178:181], v[132:135], v[116:119]
	v_mfma_f32_16x16x32_bf16 v[112:115], v[178:181], v[162:165], v[112:115]
	v_mfma_f32_16x16x32_bf16 v[108:111], v[186:189], v[132:135], v[108:111]
	v_mfma_f32_16x16x32_bf16 v[104:107], v[186:189], v[162:165], v[104:107]
	v_mfma_f32_16x16x32_bf16 v[100:103], v[198:201], v[132:135], v[100:103]
	v_mfma_f32_16x16x32_bf16 v[96:99], v[198:201], v[162:165], v[96:99]
	s_setprio 0
	s_barrier
; #define WAIT_V(n) asm volatile("s_waitcnt vmcnt(" #n ")" ::: "memory")
; #define WAIT_L(n) asm volatile("s_waitcnt lgkmcnt(" #n ")" ::: "memory")
; #define BAR __builtin_amdgcn_s_barrier()
; #define LDA(dst, b, h) _Pragma("unroll") for (int m = 0; m < 4; ++m) _Pragma("unroll") for (int k = 0; k < 2; ++k) \
;     dst[m][k] = *reinterpret_cast<const bf16x8*>((char*)shm + abase + (((b) * 2 + (h)) * 16384 + (m * 2 + k) * 1024))
; #define LDB(dst, b, h) _Pragma("unroll") for (int n = 0; n < 2; ++n) _Pragma("unroll") for (int k = 0; k < 2; ++k) \
;     dst[n][k] = *reinterpret_cast<const bf16x8*>((char*)shm + bbase + (((b) * 2 + (h)) * 16384 + (n * 2 + k) * 1024))
; template <bool SWAP>
; __device__ __forceinline__ void gemm_main(const u16* __restrict__ A, const u16* __restrict__ Bt, int brow, int bcol,
;                                           u16* shm, f32x4 (&acc)[2][2][4][2]) {
;     ...
;     LDB(B1, 0, 1); BAR; WAIT_L(0); MMA(0, 1, At, B1); BAR;
;     LDA(At, 0, 1); WAIT_V(4); BAR; WAIT_L(0); MMA(1, 0, At, B0); MMA(1, 1, At, B1); BAR; }
;   { LDB(B0, 1, 0); LDA(At, 1, 0); WAIT_V(2); BAR; WAIT_L(0); MMA(0, 0, At, B0); BAR;
	ds_read_b128 v[158:161], v152 offset:16384
	ds_read_b128 v[202:205], v152 offset:17408
	ds_read_b128 v[206:209], v152 offset:18432
	ds_read_b128 v[222:225], v152 offset:19456
	s_barrier
	s_waitcnt lgkmcnt(0)
	s_setprio 1
	s_waitcnt lgkmcnt(0)
	v_mfma_f32_16x16x32_bf16 v[92:95], v[166:169], v[158:161], v[92:95]
	v_mfma_f32_16x16x32_bf16 v[88:91], v[166:169], v[206:209], v[88:91]
	v_mfma_f32_16x16x32_bf16 v[84:87], v[174:177], v[158:161], v[84:87]
	v_mfma_f32_16x16x32_bf16 v[80:83], v[174:177], v[206:209], v[80:83]
	v_mfma_f32_16x16x32_bf16 v[76:79], v[182:185], v[158:161], v[76:79]
	v_mfma_f32_16x16x32_bf16 v[72:75], v[182:185], v[206:209], v[72:75]
	v_mfma_f32_16x16x32_bf16 v[68:71], v[194:197], v[158:161], v[68:71]
	v_mfma_f32_16x16x32_bf16 v[64:67], v[194:197], v[206:209], v[64:67]
	v_mfma_f32_16x16x32_bf16 v[92:95], v[170:173], v[202:205], v[92:95]
	v_mfma_f32_16x16x32_bf16 v[88:91], v[170:173], v[222:225], v[88:91]
	v_mfma_f32_16x16x32_bf16 v[84:87], v[178:181], v[202:205], v[84:87]
	v_mfma_f32_16x16x32_bf16 v[80:83], v[178:181], v[222:225], v[80:83]
	v_mfma_f32_16x16x32_bf16 v[76:79], v[186:189], v[202:205], v[76:79]
	v_mfma_f32_16x16x32_bf16 v[72:75], v[186:189], v[222:225], v[72:75]
	v_mfma_f32_16x16x32_bf16 v[68:71], v[198:201], v[202:205], v[68:71]
	v_mfma_f32_16x16x32_bf16 v[64:67], v[198:201], v[222:225], v[64:67]
	s_setprio 0
	s_barrier
	ds_read_b128 v[166:169], v137 offset:16384
	ds_read_b128 v[170:173], v137 offset:17408
	ds_read_b128 v[174:177], v137 offset:18432
	ds_read_b128 v[178:181], v137 offset:19456
	ds_read_b128 v[182:185], v137 offset:20480
	ds_read_b128 v[186:189], v137 offset:21504
	ds_read_b128 v[194:197], v137 offset:22528
	ds_read_b128 v[198:201], v137 offset:23552
	s_waitcnt vmcnt(4)
	s_barrier
	s_waitcnt lgkmcnt(0)
	s_setprio 1
	s_waitcnt lgkmcnt(0)
	v_mfma_f32_16x16x32_bf16 v[60:63], v[166:169], v[128:131], v[60:63]
	v_mfma_f32_16x16x32_bf16 v[56:59], v[166:169], v[154:157], v[56:59]
	v_mfma_f32_16x16x32_bf16 v[52:55], v[174:177], v[128:131], v[52:55]
	v_mfma_f32_16x16x32_bf16 v[48:51], v[174:177], v[154:157], v[48:51]
	v_mfma_f32_16x16x32_bf16 v[44:47], v[182:185], v[128:131], v[44:47]
	v_mfma_f32_16x16x32_bf16 v[40:43], v[182:185], v[154:157], v[40:43]
	v_mfma_f32_16x16x32_bf16 v[36:39], v[194:197], v[128:131], v[36:39]
	v_mfma_f32_16x16x32_bf16 v[32:35], v[194:197], v[154:157], v[32:35]
	v_mfma_f32_16x16x32_bf16 v[60:63], v[170:173], v[132:135], v[60:63]
	v_mfma_f32_16x16x32_bf16 v[56:59], v[170:173], v[162:165], v[56:59]
	v_mfma_f32_16x16x32_bf16 v[52:55], v[178:181], v[132:135], v[52:55]
	v_mfma_f32_16x16x32_bf16 v[48:51], v[178:181], v[162:165], v[48:51]
	v_mfma_f32_16x16x32_bf16 v[44:47], v[186:189], v[132:135], v[44:47]
	v_mfma_f32_16x16x32_bf16 v[40:43], v[186:189], v[162:165], v[40:43]
	v_mfma_f32_16x16x32_bf16 v[36:39], v[198:201], v[132:135], v[36:39]
	v_mfma_f32_16x16x32_bf16 v[32:35], v[198:201], v[162:165], v[32:35]
	s_setprio 0
	s_setprio 1
	v_mfma_f32_16x16x32_bf16 v[28:31], v[166:169], v[158:161], v[28:31]
	v_mfma_f32_16x16x32_bf16 v[24:27], v[166:169], v[206:209], v[24:27]
	v_mfma_f32_16x16x32_bf16 v[20:23], v[174:177], v[158:161], v[20:23]
	v_mfma_f32_16x16x32_bf16 v[16:19], v[174:177], v[206:209], v[16:19]
	v_mfma_f32_16x16x32_bf16 v[12:15], v[182:185], v[158:161], v[12:15]
	v_mfma_f32_16x16x32_bf16 v[8:11], v[182:185], v[206:209], v[8:11]
	v_mfma_f32_16x16x32_bf16 v[4:7], v[194:197], v[158:161], v[4:7]
	v_mfma_f32_16x16x32_bf16 v[0:3], v[194:197], v[206:209], v[0:3]
	v_mfma_f32_16x16x32_bf16 v[28:31], v[170:173], v[202:205], v[28:31]
	v_mfma_f32_16x16x32_bf16 v[24:27], v[170:173], v[222:225], v[24:27]
	v_mfma_f32_16x16x32_bf16 v[20:23], v[178:181], v[202:205], v[20:23]
	v_mfma_f32_16x16x32_bf16 v[16:19], v[178:181], v[222:225], v[16:19]
	v_mfma_f32_16x16x32_bf16 v[12:15], v[186:189], v[202:205], v[12:15]
	v_mfma_f32_16x16x32_bf16 v[8:11], v[186:189], v[222:225], v[8:11]
	v_mfma_f32_16x16x32_bf16 v[4:7], v[198:201], v[202:205], v[4:7]
	v_mfma_f32_16x16x32_bf16 v[0:3], v[198:201], v[222:225], v[0:3]
	s_setprio 0
	s_barrier
	ds_read_b128 v[128:131], v152 offset:32768
	ds_read_b128 v[132:135], v152 offset:33792
	ds_read_b128 v[154:157], v152 offset:34816
	ds_read_b128 v[158:161], v152 offset:35840
	ds_read_b128 v[162:165], v137 offset:32768
	ds_read_b128 v[166:169], v137 offset:33792
	ds_read_b128 v[170:173], v137 offset:34816
	ds_read_b128 v[174:177], v137 offset:35840
	ds_read_b128 v[178:181], v137 offset:36864
	ds_read_b128 v[182:185], v137 offset:37888
	ds_read_b128 v[186:189], v137 offset:38912
	ds_read_b128 v[194:197], v137 offset:39936
	s_waitcnt vmcnt(2)
	s_barrier
; #define WAIT_V(n) asm volatile("s_waitcnt vmcnt(" #n ")" ::: "memory")
; #define WAIT_L(n) asm volatile("s_waitcnt lgkmcnt(" #n ")" ::: "memory")
; #define BAR __builtin_amdgcn_s_barrier()
; #define LDA(dst, b, h) _Pragma("unroll") for (int m = 0; m < 4; ++m) _Pragma("unroll") for (int k = 0; k < 2; ++k) \
;     dst[m][k] = *reinterpret_cast<const bf16x8*>((char*)shm + abase + (((b) * 2 + (h)) * 16384 + (m * 2 + k) * 1024))
; #define LDB(dst, b, h) _Pragma("unroll") for (int n = 0; n < 2; ++n) _Pragma("unroll") for (int k = 0; k < 2; ++k) \
;     dst[n][k] = *reinterpret_cast<const bf16x8*>((char*)shm + bbase + (((b) * 2 + (h)) * 16384 + (n * 2 + k) * 1024))
; template <bool SWAP>
; __device__ __forceinline__ void gemm_main(const u16* __restrict__ A, const u16* __restrict__ Bt, int brow, int bcol,
;                                           u16* shm, f32x4 (&acc)[2][2][4][2]) {
;     ...
;   { LDB(B0, 1, 0); LDA(At, 1, 0); WAIT_V(2); BAR; WAIT_L(0); MMA(0, 0, At, B0); BAR;
;     LDB(B1, 1, 1); WAIT_V(0); BAR; WAIT_L(0); MMA(0, 1, At, B1); BAR;
;     LDA(At, 1, 1); BAR; WAIT_L(0); MMA(1, 0, At, B0); MMA(1, 1, At, B1); BAR; }
;   if (wr == 0) BAR;
; __device__ __forceinline__ void phase_inproj1(const Params& p, char* smem) {
;     ...
;       gemm_main<false>(A, Bt, brow, nt * 256, (u16*)smem, acc);
;       if (nt < 16) {
	s_waitcnt lgkmcnt(0)
	s_setprio 1
	s_waitcnt lgkmcnt(0)
	v_mfma_f32_16x16x32_bf16 v[124:127], v[162:165], v[128:131], v[124:127]
	v_mfma_f32_16x16x32_bf16 v[120:123], v[162:165], v[154:157], v[120:123]
	v_mfma_f32_16x16x32_bf16 v[116:119], v[170:173], v[128:131], v[116:119]
	v_mfma_f32_16x16x32_bf16 v[112:115], v[170:173], v[154:157], v[112:115]
	v_mfma_f32_16x16x32_bf16 v[108:111], v[178:181], v[128:131], v[108:111]
	v_mfma_f32_16x16x32_bf16 v[104:107], v[178:181], v[154:157], v[104:107]
	v_mfma_f32_16x16x32_bf16 v[100:103], v[186:189], v[128:131], v[100:103]
	v_mfma_f32_16x16x32_bf16 v[96:99], v[186:189], v[154:157], v[96:99]
	v_mfma_f32_16x16x32_bf16 v[124:127], v[166:169], v[132:135], v[124:127]
	v_mfma_f32_16x16x32_bf16 v[120:123], v[166:169], v[158:161], v[120:123]
	v_mfma_f32_16x16x32_bf16 v[116:119], v[174:177], v[132:135], v[116:119]
	v_mfma_f32_16x16x32_bf16 v[112:115], v[174:177], v[158:161], v[112:115]
	v_mfma_f32_16x16x32_bf16 v[108:111], v[182:185], v[132:135], v[108:111]
	v_mfma_f32_16x16x32_bf16 v[104:107], v[182:185], v[158:161], v[104:107]
	v_mfma_f32_16x16x32_bf16 v[100:103], v[194:197], v[132:135], v[100:103]
	v_mfma_f32_16x16x32_bf16 v[96:99], v[194:197], v[158:161], v[96:99]
	s_setprio 0
	s_barrier
	ds_read_b128 v[198:201], v152 offset:49152
	ds_read_b128 v[202:205], v152 offset:50176
	ds_read_b128 v[206:209], v152 offset:51200
	ds_read_b128 v[222:225], v152 offset:52224
	s_waitcnt vmcnt(0)
	s_barrier
	s_waitcnt lgkmcnt(0)
	s_setprio 1
	s_waitcnt lgkmcnt(0)
	v_mfma_f32_16x16x32_bf16 v[92:95], v[162:165], v[198:201], v[92:95]
	v_mfma_f32_16x16x32_bf16 v[88:91], v[162:165], v[206:209], v[88:91]
	v_mfma_f32_16x16x32_bf16 v[84:87], v[170:173], v[198:201], v[84:87]
	v_mfma_f32_16x16x32_bf16 v[80:83], v[170:173], v[206:209], v[80:83]
	v_mfma_f32_16x16x32_bf16 v[76:79], v[178:181], v[198:201], v[76:79]
	v_mfma_f32_16x16x32_bf16 v[72:75], v[178:181], v[206:209], v[72:75]
	v_mfma_f32_16x16x32_bf16 v[68:71], v[186:189], v[198:201], v[68:71]
	v_mfma_f32_16x16x32_bf16 v[64:67], v[186:189], v[206:209], v[64:67]
	v_mfma_f32_16x16x32_bf16 v[92:95], v[166:169], v[202:205], v[92:95]
	v_mfma_f32_16x16x32_bf16 v[88:91], v[166:169], v[222:225], v[88:91]
	v_mfma_f32_16x16x32_bf16 v[84:87], v[174:177], v[202:205], v[84:87]
	v_mfma_f32_16x16x32_bf16 v[80:83], v[174:177], v[222:225], v[80:83]
	v_mfma_f32_16x16x32_bf16 v[76:79], v[182:185], v[202:205], v[76:79]
	v_mfma_f32_16x16x32_bf16 v[72:75], v[182:185], v[222:225], v[72:75]
	v_mfma_f32_16x16x32_bf16 v[68:71], v[194:197], v[202:205], v[68:71]
	v_mfma_f32_16x16x32_bf16 v[64:67], v[194:197], v[222:225], v[64:67]
	s_setprio 0
	s_barrier
	ds_read_b128 v[162:165], v137 offset:49152
	ds_read_b128 v[166:169], v137 offset:50176
	ds_read_b128 v[170:173], v137 offset:51200
	ds_read_b128 v[174:177], v137 offset:52224
	ds_read_b128 v[178:181], v137 offset:53248
	ds_read_b128 v[182:185], v137 offset:54272
	ds_read_b128 v[186:189], v137 offset:55296
	ds_read_b128 v[194:197], v137 offset:56320
	s_barrier
	s_waitcnt lgkmcnt(0)
	s_setprio 1
	s_waitcnt lgkmcnt(0)
	v_mfma_f32_16x16x32_bf16 v[60:63], v[162:165], v[128:131], v[60:63]
	v_mfma_f32_16x16x32_bf16 v[56:59], v[162:165], v[154:157], v[56:59]
	v_mfma_f32_16x16x32_bf16 v[52:55], v[170:173], v[128:131], v[52:55]
	v_mfma_f32_16x16x32_bf16 v[48:51], v[170:173], v[154:157], v[48:51]
	v_mfma_f32_16x16x32_bf16 v[44:47], v[178:181], v[128:131], v[44:47]
	v_mfma_f32_16x16x32_bf16 v[40:43], v[178:181], v[154:157], v[40:43]
	v_mfma_f32_16x16x32_bf16 v[36:39], v[186:189], v[128:131], v[36:39]
	v_mfma_f32_16x16x32_bf16 v[32:35], v[186:189], v[154:157], v[32:35]
	v_mfma_f32_16x16x32_bf16 v[60:63], v[166:169], v[132:135], v[60:63]
	v_mfma_f32_16x16x32_bf16 v[56:59], v[166:169], v[158:161], v[56:59]
	v_mfma_f32_16x16x32_bf16 v[52:55], v[174:177], v[132:135], v[52:55]
	v_mfma_f32_16x16x32_bf16 v[48:51], v[174:177], v[158:161], v[48:51]
	v_mfma_f32_16x16x32_bf16 v[44:47], v[182:185], v[132:135], v[44:47]
	v_mfma_f32_16x16x32_bf16 v[40:43], v[182:185], v[158:161], v[40:43]
	v_mfma_f32_16x16x32_bf16 v[36:39], v[194:197], v[132:135], v[36:39]
	v_mfma_f32_16x16x32_bf16 v[32:35], v[194:197], v[158:161], v[32:35]
	s_setprio 0
	s_setprio 1
	v_mfma_f32_16x16x32_bf16 v[28:31], v[162:165], v[198:201], v[28:31]
	v_mfma_f32_16x16x32_bf16 v[24:27], v[162:165], v[206:209], v[24:27]
	v_mfma_f32_16x16x32_bf16 v[20:23], v[170:173], v[198:201], v[20:23]
	v_mfma_f32_16x16x32_bf16 v[16:19], v[170:173], v[206:209], v[16:19]
	v_mfma_f32_16x16x32_bf16 v[12:15], v[178:181], v[198:201], v[12:15]
	v_mfma_f32_16x16x32_bf16 v[8:11], v[178:181], v[206:209], v[8:11]
	v_mfma_f32_16x16x32_bf16 v[4:7], v[186:189], v[198:201], v[4:7]
	v_mfma_f32_16x16x32_bf16 v[0:3], v[186:189], v[206:209], v[0:3]
	v_mfma_f32_16x16x32_bf16 v[28:31], v[166:169], v[202:205], v[28:31]
	v_mfma_f32_16x16x32_bf16 v[24:27], v[166:169], v[222:225], v[24:27]
	v_mfma_f32_16x16x32_bf16 v[20:23], v[174:177], v[202:205], v[20:23]
	v_mfma_f32_16x16x32_bf16 v[16:19], v[174:177], v[222:225], v[16:19]
	v_mfma_f32_16x16x32_bf16 v[12:15], v[182:185], v[202:205], v[12:15]
	v_mfma_f32_16x16x32_bf16 v[8:11], v[182:185], v[222:225], v[8:11]
	v_mfma_f32_16x16x32_bf16 v[4:7], v[194:197], v[202:205], v[4:7]
	v_mfma_f32_16x16x32_bf16 v[0:3], v[194:197], v[222:225], v[0:3]
	s_setprio 0
	s_movk_i32 s0, 0x100
	v_cmp_gt_u32_e32 vcc, s0, v136
	s_barrier
	s_and_saveexec_b64 s[0:1], vcc
	s_cbranch_execz .LBB0_118
	s_barrier
	s_or_b64 exec, exec, s[0:1]
	s_cmp_gt_u32 s2, 15
	s_mov_b64 s[0:1], -1
	s_cbranch_scc1 .LBB0_119

; #define WAIT_V(n) asm volatile("s_waitcnt vmcnt(" #n ")" ::: "memory")
; #define WAIT_L(n) asm volatile("s_waitcnt lgkmcnt(" #n ")" ::: "memory")
; #define BAR __builtin_amdgcn_s_barrier()
; #define SCHED __builtin_amdgcn_sched_barrier(0)
; #define STAGE(P, BASE, br, kt) do { const char* _g = (const char*)((BASE) + (size_t)(br) * GK + (kt) * BK); \
;     __builtin_amdgcn_global_load_lds((const unsigned*)(_g + voff0), (unsigned*)((char*)(P) + tx * 16), 16, 0, 0); \
;     __builtin_amdgcn_global_load_lds((const unsigned*)(_g + voff1), (unsigned*)((char*)(P) + tx * 16 + 8192), 16, 0, 0); } while (0)
; #define LDA(dst, b, h) _Pragma("unroll") for (int m = 0; m < 4; ++m) _Pragma("unroll") for (int k = 0; k < 2; ++k) \
;     dst[m][k] = *reinterpret_cast<const bf16x8*>((char*)shm + abase + (((b) * 2 + (h)) * 16384 + (m * 2 + k) * 1024))
; #define LDB(dst, b, h) _Pragma("unroll") for (int n = 0; n < 2; ++n) _Pragma("unroll") for (int k = 0; k < 2; ++k) \
;     dst[n][k] = *reinterpret_cast<const bf16x8*>((char*)shm + bbase + (((b) * 2 + (h)) * 16384 + (n * 2 + k) * 1024))
; template <bool SWAP>
; __device__ __forceinline__ void gemm_main(const u16* __restrict__ A, const u16* __restrict__ Bt, int brow, int bcol,
;                                           u16* shm, f32x4 (&acc)[2][2][4][2]) {
;     ...
;   for (int t = 0; t < nt - 2; t += 2) {
;     LDB(B0, 0, 0); SCHED; LDA(At, 0, 0); STAGE(SA(1, 1), A, brow + HALF, t + 1);
;     WAIT_L(8); BAR; WAIT_L(0); MMA(0, 0, At, B0); BAR; SCHED;
;     LDB(B1, 0, 1); STAGE(SB(0, 0), Bt, bcol, t + 2);
;     BAR; WAIT_L(0); MMA(0, 1, At, B1); BAR;
;     LDA(At, 0, 1); STAGE(SA(0, 0), A, brow, t + 2);
;     BAR; WAIT_L(0); MMA(1, 0, At, B0); BAR; SCHED;
;     STAGE(SB(0, 1), Bt, bcol + HALF, t + 2);
;     WAIT_V(6); BAR; MMA(1, 1, At, B1); BAR;
.LBB0_200:
	ds_read_b128 v[182:185], v137 offset:1024
	ds_read_b128 v[194:197], v137 offset:3072
	ds_read_b128 v[202:205], v137 offset:5120
	ds_read_b128 v[222:225], v137 offset:7168
	v_add_u32_e32 v192, 0, v153
	v_add_u32_e32 v160, 0xc000, v192
	v_add_u32_e32 v161, 0xe000, v192
	s_add_u32 m0, s3, 0xc000
	v_lshl_add_u64 v[242:243], s[0:1], 0, v[134:135]
	s_add_u32 vcc_lo, s0, s82
	s_addc_u32 vcc_hi, s1, s83
	global_load_lds_dwordx4 v132, vcc
	s_add_u32 m0, s3, 0xe000
	s_nop 0
	global_load_lds_dwordx4 v134, vcc
	s_waitcnt lgkmcnt(8)
	s_barrier
	s_waitcnt lgkmcnt(0)
	v_mfma_f32_16x16x32_bf16 v[124:127], v[162:165], v[178:181], v[124:127]
	v_mfma_f32_16x16x32_bf16 v[120:123], v[170:173], v[178:181], v[120:123]
	v_mfma_f32_16x16x32_bf16 v[116:119], v[162:165], v[186:189], v[116:119]
	v_mfma_f32_16x16x32_bf16 v[112:115], v[170:173], v[186:189], v[112:115]
	v_mfma_f32_16x16x32_bf16 v[108:111], v[162:165], v[198:201], v[108:111]
	v_mfma_f32_16x16x32_bf16 v[104:107], v[170:173], v[198:201], v[104:107]
	v_mfma_f32_16x16x32_bf16 v[100:103], v[162:165], v[206:209], v[100:103]
	v_mfma_f32_16x16x32_bf16 v[96:99], v[170:173], v[206:209], v[96:99]
	v_mfma_f32_16x16x32_bf16 v[124:127], v[166:169], v[182:185], v[124:127]
	v_mfma_f32_16x16x32_bf16 v[120:123], v[174:177], v[182:185], v[120:123]
	v_mfma_f32_16x16x32_bf16 v[116:119], v[166:169], v[194:197], v[116:119]
	v_mfma_f32_16x16x32_bf16 v[112:115], v[174:177], v[194:197], v[112:115]
	v_mfma_f32_16x16x32_bf16 v[108:111], v[166:169], v[202:205], v[108:111]
	v_mfma_f32_16x16x32_bf16 v[104:107], v[174:177], v[202:205], v[104:107]
	v_mfma_f32_16x16x32_bf16 v[100:103], v[166:169], v[222:225], v[100:103]
	v_mfma_f32_16x16x32_bf16 v[96:99], v[174:177], v[222:225], v[96:99]
	s_barrier
	ds_read_b128 v[226:229], v152 offset:16384
	ds_read_b128 v[230:233], v152 offset:17408
	ds_read_b128 v[234:237], v152 offset:18432
	ds_read_b128 v[238:241], v152 offset:19456
	v_lshl_add_u64 v[244:245], s[0:1], 0, v[128:129]
	s_add_u32 m0, s3, s28
	s_nop 0
	s_add_u32 vcc_lo, s0, s74
	s_addc_u32 vcc_hi, s1, s75
	global_load_lds_dwordx4 v128, vcc
	v_lshl_add_u64 v[246:247], s[0:1], 0, v[130:131]
	s_add_u32 m0, s3, s28
	s_add_u32 m0, m0, 0x2000
	s_nop 0
	global_load_lds_dwordx4 v130, vcc
	s_barrier
	s_waitcnt lgkmcnt(0)
	v_mfma_f32_16x16x32_bf16 v[92:95], v[226:229], v[178:181], v[92:95]
	v_mfma_f32_16x16x32_bf16 v[88:91], v[234:237], v[178:181], v[88:91]
	v_mfma_f32_16x16x32_bf16 v[84:87], v[226:229], v[186:189], v[84:87]
	v_mfma_f32_16x16x32_bf16 v[80:83], v[234:237], v[186:189], v[80:83]
	v_mfma_f32_16x16x32_bf16 v[76:79], v[226:229], v[198:201], v[76:79]
	v_mfma_f32_16x16x32_bf16 v[72:75], v[234:237], v[198:201], v[72:75]
	v_mfma_f32_16x16x32_bf16 v[68:71], v[226:229], v[206:209], v[68:71]
	v_mfma_f32_16x16x32_bf16 v[64:67], v[234:237], v[206:209], v[64:67]
	v_mfma_f32_16x16x32_bf16 v[92:95], v[230:233], v[182:185], v[92:95]
	ds_read_b128 v[178:181], v137 offset:16384
	v_mfma_f32_16x16x32_bf16 v[88:91], v[238:241], v[182:185], v[88:91]
	v_mfma_f32_16x16x32_bf16 v[84:87], v[230:233], v[194:197], v[84:87]
	ds_read_b128 v[186:189], v137 offset:18432
	v_mfma_f32_16x16x32_bf16 v[80:83], v[238:241], v[194:197], v[80:83]
	v_mfma_f32_16x16x32_bf16 v[76:79], v[230:233], v[202:205], v[76:79]
	ds_read_b128 v[198:201], v137 offset:20480
	v_mfma_f32_16x16x32_bf16 v[72:75], v[238:241], v[202:205], v[72:75]
	v_mfma_f32_16x16x32_bf16 v[68:71], v[230:233], v[222:225], v[68:71]
	ds_read_b128 v[206:209], v137 offset:22528
	v_mfma_f32_16x16x32_bf16 v[64:67], v[238:241], v[222:225], v[64:67]
	s_barrier
	ds_read_b128 v[182:185], v137 offset:17408
	ds_read_b128 v[194:197], v137 offset:19456
	ds_read_b128 v[202:205], v137 offset:21504
	ds_read_b128 v[222:225], v137 offset:23552
	s_add_u32 m0, s3, 0x0
	s_nop 0
	s_add_u32 vcc_lo, s0, s76
	s_addc_u32 vcc_hi, s1, s77
	global_load_lds_dwordx4 v132, vcc
	s_add_u32 m0, s3, 0x2000
	s_nop 0
	global_load_lds_dwordx4 v134, vcc
	s_waitcnt vmcnt(8)
	s_barrier
	s_waitcnt lgkmcnt(0)
	v_mfma_f32_16x16x32_bf16 v[60:63], v[162:165], v[178:181], v[60:63]
	v_mfma_f32_16x16x32_bf16 v[56:59], v[170:173], v[178:181], v[56:59]
	v_mfma_f32_16x16x32_bf16 v[52:55], v[162:165], v[186:189], v[52:55]
	v_mfma_f32_16x16x32_bf16 v[48:51], v[170:173], v[186:189], v[48:51]
	v_mfma_f32_16x16x32_bf16 v[44:47], v[162:165], v[198:201], v[44:47]
	v_mfma_f32_16x16x32_bf16 v[40:43], v[170:173], v[198:201], v[40:43]
	v_mfma_f32_16x16x32_bf16 v[36:39], v[162:165], v[206:209], v[36:39]
	v_mfma_f32_16x16x32_bf16 v[32:35], v[170:173], v[206:209], v[32:35]
	v_mfma_f32_16x16x32_bf16 v[60:63], v[166:169], v[182:185], v[60:63]
	v_mfma_f32_16x16x32_bf16 v[56:59], v[174:177], v[182:185], v[56:59]
	v_mfma_f32_16x16x32_bf16 v[52:55], v[166:169], v[194:197], v[52:55]
	v_mfma_f32_16x16x32_bf16 v[48:51], v[174:177], v[194:197], v[48:51]
	v_mfma_f32_16x16x32_bf16 v[44:47], v[166:169], v[202:205], v[44:47]
	v_mfma_f32_16x16x32_bf16 v[40:43], v[174:177], v[202:205], v[40:43]
	v_mfma_f32_16x16x32_bf16 v[36:39], v[166:169], v[222:225], v[36:39]
	v_mfma_f32_16x16x32_bf16 v[32:35], v[174:177], v[222:225], v[32:35]
	s_barrier
	ds_read_b128 v[162:165], v152 offset:32768
	ds_read_b128 v[166:169], v152 offset:33792
	ds_read_b128 v[170:173], v152 offset:34816
	ds_read_b128 v[174:177], v152 offset:35840
	s_add_u32 m0, s3, s29
	s_nop 0
	s_add_u32 vcc_lo, s0, s70
	s_addc_u32 vcc_hi, s1, s71
	global_load_lds_dwordx4 v128, vcc
	s_add_u32 m0, s3, s29
	s_add_u32 m0, m0, 0x2000
	s_nop 0
	global_load_lds_dwordx4 v130, vcc
	s_waitcnt vmcnt(6)
	s_barrier
; #define WAIT_V(n) asm volatile("s_waitcnt vmcnt(" #n ")" ::: "memory")
; #define WAIT_L(n) asm volatile("s_waitcnt lgkmcnt(" #n ")" ::: "memory")
; #define BAR __builtin_amdgcn_s_barrier()
; #define SCHED __builtin_amdgcn_sched_barrier(0)
; #define STAGE(P, BASE, br, kt) do { const char* _g = (const char*)((BASE) + (size_t)(br) * GK + (kt) * BK); \
;     __builtin_amdgcn_global_load_lds((const unsigned*)(_g + voff0), (unsigned*)((char*)(P) + tx * 16), 16, 0, 0); \
;     __builtin_amdgcn_global_load_lds((const unsigned*)(_g + voff1), (unsigned*)((char*)(P) + tx * 16 + 8192), 16, 0, 0); } while (0)
; #define LDA(dst, b, h) _Pragma("unroll") for (int m = 0; m < 4; ++m) _Pragma("unroll") for (int k = 0; k < 2; ++k) \
;     dst[m][k] = *reinterpret_cast<const bf16x8*>((char*)shm + abase + (((b) * 2 + (h)) * 16384 + (m * 2 + k) * 1024))
; #define LDB(dst, b, h) _Pragma("unroll") for (int n = 0; n < 2; ++n) _Pragma("unroll") for (int k = 0; k < 2; ++k) \
;     dst[n][k] = *reinterpret_cast<const bf16x8*>((char*)shm + bbase + (((b) * 2 + (h)) * 16384 + (n * 2 + k) * 1024))
; template <bool SWAP>
; __device__ __forceinline__ void gemm_main(const u16* __restrict__ A, const u16* __restrict__ Bt, int brow, int bcol,
;                                           u16* shm, f32x4 (&acc)[2][2][4][2]) {
;     ...
;     WAIT_V(6); BAR; MMA(1, 1, At, B1); BAR;
;     LDB(B0, 1, 0); SCHED; LDA(At, 1, 0); STAGE(SA(0, 1), A, brow + HALF, t + 2);
;     WAIT_L(8); BAR; WAIT_L(0); MMA(0, 0, At, B0); BAR; SCHED;
;     LDB(B1, 1, 1); STAGE(SB(1, 0), Bt, bcol, t + 3);
;     BAR; WAIT_L(0); MMA(0, 1, At, B1); BAR;
;     LDA(At, 1, 1); STAGE(SA(1, 0), A, brow, t + 3);
;     BAR; WAIT_L(0); MMA(1, 0, At, B0); BAR; SCHED;
	v_mfma_f32_16x16x32_bf16 v[28:31], v[226:229], v[178:181], v[28:31]
	v_mfma_f32_16x16x32_bf16 v[24:27], v[234:237], v[178:181], v[24:27]
	v_mfma_f32_16x16x32_bf16 v[20:23], v[226:229], v[186:189], v[20:23]
	v_mfma_f32_16x16x32_bf16 v[16:19], v[234:237], v[186:189], v[16:19]
	v_mfma_f32_16x16x32_bf16 v[12:15], v[226:229], v[198:201], v[12:15]
	v_mfma_f32_16x16x32_bf16 v[8:11], v[234:237], v[198:201], v[8:11]
	v_mfma_f32_16x16x32_bf16 v[4:7], v[226:229], v[206:209], v[4:7]
	v_mfma_f32_16x16x32_bf16 v[0:3], v[234:237], v[206:209], v[0:3]
	v_mfma_f32_16x16x32_bf16 v[28:31], v[230:233], v[182:185], v[28:31]
	ds_read_b128 v[178:181], v137 offset:32768
	v_mfma_f32_16x16x32_bf16 v[24:27], v[238:241], v[182:185], v[24:27]
	v_mfma_f32_16x16x32_bf16 v[20:23], v[230:233], v[194:197], v[20:23]
	ds_read_b128 v[186:189], v137 offset:34816
	v_mfma_f32_16x16x32_bf16 v[16:19], v[238:241], v[194:197], v[16:19]
	v_mfma_f32_16x16x32_bf16 v[12:15], v[230:233], v[202:205], v[12:15]
	ds_read_b128 v[198:201], v137 offset:36864
	v_mfma_f32_16x16x32_bf16 v[8:11], v[238:241], v[202:205], v[8:11]
	v_mfma_f32_16x16x32_bf16 v[4:7], v[230:233], v[222:225], v[4:7]
	ds_read_b128 v[206:209], v137 offset:38912
	v_mfma_f32_16x16x32_bf16 v[0:3], v[238:241], v[222:225], v[0:3]
	s_barrier
	ds_read_b128 v[182:185], v137 offset:33792
	ds_read_b128 v[194:197], v137 offset:35840
	ds_read_b128 v[202:205], v137 offset:37888
	ds_read_b128 v[222:225], v137 offset:39936
	s_add_u32 m0, s3, 0x4000
	s_nop 0
	s_add_u32 vcc_lo, s0, s96
	s_addc_u32 vcc_hi, s1, s97
	global_load_lds_dwordx4 v132, vcc
	s_add_u32 m0, s3, 0x6000
	s_nop 0
	global_load_lds_dwordx4 v134, vcc
	s_waitcnt lgkmcnt(8)
	s_barrier
	s_waitcnt lgkmcnt(0)
	v_mfma_f32_16x16x32_bf16 v[124:127], v[162:165], v[178:181], v[124:127]
	v_mfma_f32_16x16x32_bf16 v[120:123], v[170:173], v[178:181], v[120:123]
	v_mfma_f32_16x16x32_bf16 v[116:119], v[162:165], v[186:189], v[116:119]
	v_mfma_f32_16x16x32_bf16 v[112:115], v[170:173], v[186:189], v[112:115]
	v_mfma_f32_16x16x32_bf16 v[108:111], v[162:165], v[198:201], v[108:111]
	v_mfma_f32_16x16x32_bf16 v[104:107], v[170:173], v[198:201], v[104:107]
	v_mfma_f32_16x16x32_bf16 v[100:103], v[162:165], v[206:209], v[100:103]
	v_mfma_f32_16x16x32_bf16 v[96:99], v[170:173], v[206:209], v[96:99]
	v_mfma_f32_16x16x32_bf16 v[124:127], v[166:169], v[182:185], v[124:127]
	v_mfma_f32_16x16x32_bf16 v[120:123], v[174:177], v[182:185], v[120:123]
	v_mfma_f32_16x16x32_bf16 v[116:119], v[166:169], v[194:197], v[116:119]
	v_mfma_f32_16x16x32_bf16 v[112:115], v[174:177], v[194:197], v[112:115]
	v_mfma_f32_16x16x32_bf16 v[108:111], v[166:169], v[202:205], v[108:111]
	v_mfma_f32_16x16x32_bf16 v[104:107], v[174:177], v[202:205], v[104:107]
	v_mfma_f32_16x16x32_bf16 v[100:103], v[166:169], v[222:225], v[100:103]
	v_mfma_f32_16x16x32_bf16 v[96:99], v[174:177], v[222:225], v[96:99]
	s_barrier
	ds_read_b128 v[226:229], v152 offset:49152
	ds_read_b128 v[230:233], v152 offset:50176
	ds_read_b128 v[234:237], v152 offset:51200
	ds_read_b128 v[238:241], v152 offset:52224
	v_add_u32_e32 v250, s30, v153
	v_add_u32_e32 v250, 0x2000, v250
	s_add_u32 m0, s3, s30
	s_nop 0
	s_add_u32 vcc_lo, s0, s34
	s_addc_u32 vcc_hi, s1, s35
	global_load_lds_dwordx4 v128, vcc
	v_lshl_add_u64 v[248:249], v[246:247], 0, s[34:35]
	s_add_u32 m0, s3, s30
	s_add_u32 m0, m0, 0x2000
	s_nop 0
	global_load_lds_dwordx4 v130, vcc
	s_barrier
	s_waitcnt lgkmcnt(0)
	v_mfma_f32_16x16x32_bf16 v[92:95], v[226:229], v[178:181], v[92:95]
	v_mfma_f32_16x16x32_bf16 v[88:91], v[234:237], v[178:181], v[88:91]
	v_mfma_f32_16x16x32_bf16 v[84:87], v[226:229], v[186:189], v[84:87]
	v_mfma_f32_16x16x32_bf16 v[80:83], v[234:237], v[186:189], v[80:83]
	v_mfma_f32_16x16x32_bf16 v[76:79], v[226:229], v[198:201], v[76:79]
	v_mfma_f32_16x16x32_bf16 v[72:75], v[234:237], v[198:201], v[72:75]
	v_mfma_f32_16x16x32_bf16 v[68:71], v[226:229], v[206:209], v[68:71]
	v_mfma_f32_16x16x32_bf16 v[64:67], v[234:237], v[206:209], v[64:67]
	v_mfma_f32_16x16x32_bf16 v[92:95], v[230:233], v[182:185], v[92:95]
	ds_read_b128 v[178:181], v137 offset:49152
	v_mfma_f32_16x16x32_bf16 v[88:91], v[238:241], v[182:185], v[88:91]
	v_mfma_f32_16x16x32_bf16 v[84:87], v[230:233], v[194:197], v[84:87]
	ds_read_b128 v[186:189], v137 offset:51200
	v_mfma_f32_16x16x32_bf16 v[80:83], v[238:241], v[194:197], v[80:83]
	v_mfma_f32_16x16x32_bf16 v[76:79], v[230:233], v[202:205], v[76:79]
	ds_read_b128 v[198:201], v137 offset:53248
	v_mfma_f32_16x16x32_bf16 v[72:75], v[238:241], v[202:205], v[72:75]
	v_mfma_f32_16x16x32_bf16 v[68:71], v[230:233], v[222:225], v[68:71]
	ds_read_b128 v[206:209], v137 offset:55296
	v_mfma_f32_16x16x32_bf16 v[64:67], v[238:241], v[222:225], v[64:67]
	s_barrier
	ds_read_b128 v[182:185], v137 offset:50176
	ds_read_b128 v[194:197], v137 offset:52224
	ds_read_b128 v[202:205], v137 offset:54272
	ds_read_b128 v[222:225], v137 offset:56320
	v_add_u32_e32 v248, 0x8000, v192
	s_add_u32 m0, s3, 0x8000
	s_nop 0
	s_add_u32 vcc_lo, s0, s36
	s_addc_u32 vcc_hi, s1, s37
	global_load_lds_dwordx4 v132, vcc
	s_add_u32 m0, s3, 0xa000
	s_nop 0
	global_load_lds_dwordx4 v134, vcc
	s_waitcnt vmcnt(8)
	s_barrier
; #define WAIT_V(n) asm volatile("s_waitcnt vmcnt(" #n ")" ::: "memory")
; #define WAIT_L(n) asm volatile("s_waitcnt lgkmcnt(" #n ")" ::: "memory")
; #define BAR __builtin_amdgcn_s_barrier()
; #define SCHED __builtin_amdgcn_sched_barrier(0)
; #define STAGE(P, BASE, br, kt) do { const char* _g = (const char*)((BASE) + (size_t)(br) * GK + (kt) * BK); \
;     __builtin_amdgcn_global_load_lds((const unsigned*)(_g + voff0), (unsigned*)((char*)(P) + tx * 16), 16, 0, 0); \
;     __builtin_amdgcn_global_load_lds((const unsigned*)(_g + voff1), (unsigned*)((char*)(P) + tx * 16 + 8192), 16, 0, 0); } while (0)
; #define LDA(dst, b, h) _Pragma("unroll") for (int m = 0; m < 4; ++m) _Pragma("unroll") for (int k = 0; k < 2; ++k) \
;     dst[m][k] = *reinterpret_cast<const bf16x8*>((char*)shm + abase + (((b) * 2 + (h)) * 16384 + (m * 2 + k) * 1024))
; #define LDB(dst, b, h) _Pragma("unroll") for (int n = 0; n < 2; ++n) _Pragma("unroll") for (int k = 0; k < 2; ++k) \
;     dst[n][k] = *reinterpret_cast<const bf16x8*>((char*)shm + bbase + (((b) * 2 + (h)) * 16384 + (n * 2 + k) * 1024))
; template <bool SWAP>
; __device__ __forceinline__ void gemm_main(const u16* __restrict__ A, const u16* __restrict__ Bt, int brow, int bcol,
;                                           u16* shm, f32x4 (&acc)[2][2][4][2]) {
;     ...
;     BAR; WAIT_L(0); MMA(1, 0, At, B0); BAR; SCHED;
;     STAGE(SB(1, 1), Bt, bcol + HALF, t + 3);
;     WAIT_V(6); BAR; MMA(1, 1, At, B1); BAR;
;   }
;   { LDB(B0, 0, 0); LDA(At, 0, 0); STAGE(SA(1, 1), A, brow + HALF, nt - 1);
;     BAR; WAIT_L(0); MMA(0, 0, At, B0); BAR;
	s_waitcnt lgkmcnt(0)
	v_mfma_f32_16x16x32_bf16 v[60:63], v[162:165], v[178:181], v[60:63]
	v_mfma_f32_16x16x32_bf16 v[56:59], v[170:173], v[178:181], v[56:59]
	v_mfma_f32_16x16x32_bf16 v[52:55], v[162:165], v[186:189], v[52:55]
	v_mfma_f32_16x16x32_bf16 v[48:51], v[170:173], v[186:189], v[48:51]
	v_mfma_f32_16x16x32_bf16 v[44:47], v[162:165], v[198:201], v[44:47]
	v_mfma_f32_16x16x32_bf16 v[40:43], v[170:173], v[198:201], v[40:43]
	v_mfma_f32_16x16x32_bf16 v[36:39], v[162:165], v[206:209], v[36:39]
	v_mfma_f32_16x16x32_bf16 v[32:35], v[170:173], v[206:209], v[32:35]
	v_mfma_f32_16x16x32_bf16 v[60:63], v[166:169], v[182:185], v[60:63]
	v_mfma_f32_16x16x32_bf16 v[56:59], v[174:177], v[182:185], v[56:59]
	v_mfma_f32_16x16x32_bf16 v[52:55], v[166:169], v[194:197], v[52:55]
	v_mfma_f32_16x16x32_bf16 v[48:51], v[174:177], v[194:197], v[48:51]
	v_mfma_f32_16x16x32_bf16 v[44:47], v[166:169], v[202:205], v[44:47]
	v_mfma_f32_16x16x32_bf16 v[40:43], v[174:177], v[202:205], v[40:43]
	v_mfma_f32_16x16x32_bf16 v[36:39], v[166:169], v[222:225], v[36:39]
	v_mfma_f32_16x16x32_bf16 v[32:35], v[174:177], v[222:225], v[32:35]
	s_barrier
	ds_read_b128 v[162:165], v152
	ds_read_b128 v[166:169], v152 offset:1024
	ds_read_b128 v[170:173], v152 offset:2048
	ds_read_b128 v[174:177], v152 offset:3072
	s_add_u32 m0, s3, s31
	s_nop 0
	s_add_u32 vcc_lo, s0, s64
	s_addc_u32 vcc_hi, s1, s65
	global_load_lds_dwordx4 v128, vcc
	v_lshl_add_u64 v[254:255], v[246:247], 0, s[64:65]
	s_add_u32 m0, s3, s31
	s_add_u32 m0, m0, 0x2000
	s_nop 0
	global_load_lds_dwordx4 v130, vcc
	s_waitcnt vmcnt(6)
	s_barrier
	v_mfma_f32_16x16x32_bf16 v[28:31], v[226:229], v[178:181], v[28:31]
	v_mfma_f32_16x16x32_bf16 v[24:27], v[234:237], v[178:181], v[24:27]
	v_mfma_f32_16x16x32_bf16 v[20:23], v[226:229], v[186:189], v[20:23]
	v_mfma_f32_16x16x32_bf16 v[16:19], v[234:237], v[186:189], v[16:19]
	v_mfma_f32_16x16x32_bf16 v[12:15], v[226:229], v[198:201], v[12:15]
	v_mfma_f32_16x16x32_bf16 v[8:11], v[234:237], v[198:201], v[8:11]
	v_mfma_f32_16x16x32_bf16 v[4:7], v[226:229], v[206:209], v[4:7]
	v_mfma_f32_16x16x32_bf16 v[0:3], v[234:237], v[206:209], v[0:3]
	v_mfma_f32_16x16x32_bf16 v[28:31], v[230:233], v[182:185], v[28:31]
	ds_read_b128 v[178:181], v137
	v_mfma_f32_16x16x32_bf16 v[24:27], v[238:241], v[182:185], v[24:27]
	v_mfma_f32_16x16x32_bf16 v[20:23], v[230:233], v[194:197], v[20:23]
	ds_read_b128 v[186:189], v137 offset:2048
	v_mfma_f32_16x16x32_bf16 v[16:19], v[238:241], v[194:197], v[16:19]
	s_add_i32 s2, s2, 2
	s_add_u32 s0, s0, 0x100
	s_addc_u32 s1, s1, 0
	s_cmp_lt_u32 s2, 28
	v_mfma_f32_16x16x32_bf16 v[12:15], v[230:233], v[202:205], v[12:15]
	ds_read_b128 v[198:201], v137 offset:4096
	v_mfma_f32_16x16x32_bf16 v[8:11], v[238:241], v[202:205], v[8:11]
	v_mfma_f32_16x16x32_bf16 v[4:7], v[230:233], v[222:225], v[4:7]
	ds_read_b128 v[206:209], v137 offset:6144
	v_mfma_f32_16x16x32_bf16 v[0:3], v[238:241], v[222:225], v[0:3]
	s_barrier
	s_cbranch_scc1 .LBB0_200
	v_lshlrev_b32_e32 v128, 3, v154
	v_lshlrev_b32_e32 v129, 5, v154
	v_and_b32_e32 v128, 0xffff0, v128
	v_and_b32_e32 v129, 32, v129
	s_or_b32 s0, s24, 0x80
	v_add_u32_e32 v129, v129, v156
	v_add_lshl_u32 v128, v155, v128, 12
	s_ashr_i32 s1, s0, 31
	v_lshl_add_u32 v192, v129, 1, v128
	v_lshlrev_b32_e32 v128, 3, v157
	v_lshlrev_b32_e32 v129, 5, v157
	s_lshl_b64 s[0:1], s[0:1], 12
	v_readlane_b32 s2, v253, 35
	v_and_b32_e32 v128, 0xffff0, v128
	v_and_b32_e32 v129, 32, v129
	v_readlane_b32 s3, v253, 36
	s_add_u32 s0, s2, s0
	v_add_u32_e32 v129, v129, v159
	v_add_lshl_u32 v128, v158, v128, 12
	s_addc_u32 s1, s3, s1
	v_lshl_add_u32 v158, v129, 1, v128
	v_mov_b32_e32 v159, v193
	v_lshl_add_u64 v[190:191], s[0:1], 0, v[192:193]
	s_mov_b64 s[4:5], 0xf80
	v_readfirstlane_b32 s2, v160
	v_lshl_add_u64 v[190:191], v[190:191], 0, s[4:5]
	s_mov_b32 m0, s2
	v_lshl_add_u64 v[158:159], s[0:1], 0, v[158:159]
	v_readfirstlane_b32 s0, v161
	ds_read_b128 v[128:131], v152
	ds_read_b128 v[132:135], v152 offset:1024
	ds_read_b128 v[154:157], v152 offset:2048
	ds_read_b128 v[162:165], v152 offset:3072
	ds_read_b128 v[166:169], v137
	ds_read_b128 v[170:173], v137 offset:1024
	ds_read_b128 v[174:177], v137 offset:2048
	ds_read_b128 v[178:181], v137 offset:3072
	ds_read_b128 v[182:185], v137 offset:4096
	ds_read_b128 v[186:189], v137 offset:5120
	ds_read_b128 v[194:197], v137 offset:6144
	ds_read_b128 v[198:201], v137 offset:7168
	global_load_lds_dwordx4 v[190:191], off
	v_lshl_add_u64 v[158:159], v[158:159], 0, s[4:5]
	s_mov_b32 m0, s0
	s_nop 0
	global_load_lds_dwordx4 v[158:159], off
	s_barrier
	s_waitcnt lgkmcnt(0)
	s_setprio 1
	s_waitcnt lgkmcnt(0)
	v_mfma_f32_16x16x32_bf16 v[124:127], v[128:131], v[166:169], v[124:127]
	v_mfma_f32_16x16x32_bf16 v[116:119], v[128:131], v[174:177], v[116:119]
	v_mfma_f32_16x16x32_bf16 v[108:111], v[128:131], v[182:185], v[108:111]
	v_mfma_f32_16x16x32_bf16 v[100:103], v[128:131], v[194:197], v[100:103]
	v_mfma_f32_16x16x32_bf16 v[124:127], v[132:135], v[170:173], v[124:127]
	v_mfma_f32_16x16x32_bf16 v[120:123], v[154:157], v[166:169], v[120:123]
	v_mfma_f32_16x16x32_bf16 v[116:119], v[132:135], v[178:181], v[116:119]
	v_mfma_f32_16x16x32_bf16 v[112:115], v[154:157], v[174:177], v[112:115]
	v_mfma_f32_16x16x32_bf16 v[108:111], v[132:135], v[186:189], v[108:111]
	v_mfma_f32_16x16x32_bf16 v[104:107], v[154:157], v[182:185], v[104:107]
	v_mfma_f32_16x16x32_bf16 v[100:103], v[132:135], v[198:201], v[100:103]
	v_mfma_f32_16x16x32_bf16 v[96:99], v[154:157], v[194:197], v[96:99]
	v_mfma_f32_16x16x32_bf16 v[158:161], v[162:165], v[170:173], v[120:123]
	v_mfma_f32_16x16x32_bf16 v[202:205], v[162:165], v[178:181], v[112:115]
	v_mfma_f32_16x16x32_bf16 v[206:209], v[162:165], v[186:189], v[104:107]
	v_mfma_f32_16x16x32_bf16 v[222:225], v[162:165], v[198:201], v[96:99]
	s_setprio 0
	s_barrier
; #define WAIT_V(n) asm volatile("s_waitcnt vmcnt(" #n ")" ::: "memory")
; #define WAIT_L(n) asm volatile("s_waitcnt lgkmcnt(" #n ")" ::: "memory")
; #define BAR __builtin_amdgcn_s_barrier()
; #define LDA(dst, b, h) _Pragma("unroll") for (int m = 0; m < 4; ++m) _Pragma("unroll") for (int k = 0; k < 2; ++k) \
;     dst[m][k] = *reinterpret_cast<const bf16x8*>((char*)shm + abase + (((b) * 2 + (h)) * 16384 + (m * 2 + k) * 1024))
; #define LDB(dst, b, h) _Pragma("unroll") for (int n = 0; n < 2; ++n) _Pragma("unroll") for (int k = 0; k < 2; ++k) \
;     dst[n][k] = *reinterpret_cast<const bf16x8*>((char*)shm + bbase + (((b) * 2 + (h)) * 16384 + (n * 2 + k) * 1024))
; template <bool SWAP>
; __device__ __forceinline__ void gemm_main(const u16* __restrict__ A, const u16* __restrict__ Bt, int brow, int bcol,
;                                           u16* shm, f32x4 (&acc)[2][2][4][2]) {
;     ...
;     LDB(B1, 0, 1); BAR; WAIT_L(0); MMA(0, 1, At, B1); BAR;
;     LDA(At, 0, 1); WAIT_V(4); BAR; WAIT_L(0); MMA(1, 0, At, B0); MMA(1, 1, At, B1); BAR; }
;   { LDB(B0, 1, 0); LDA(At, 1, 0); WAIT_V(2); BAR; WAIT_L(0); MMA(0, 0, At, B0); BAR;
	s_nop 1
	ds_read_b128 v[96:99], v152 offset:16384
	ds_read_b128 v[104:107], v152 offset:17408
	ds_read_b128 v[112:115], v152 offset:18432
	ds_read_b128 v[120:123], v152 offset:19456
	s_barrier
	s_waitcnt lgkmcnt(0)
	s_setprio 1
	s_waitcnt lgkmcnt(0)
	v_mfma_f32_16x16x32_bf16 v[92:95], v[96:99], v[166:169], v[92:95]
	v_mfma_f32_16x16x32_bf16 v[84:87], v[96:99], v[174:177], v[84:87]
	v_mfma_f32_16x16x32_bf16 v[76:79], v[96:99], v[182:185], v[76:79]
	v_mfma_f32_16x16x32_bf16 v[68:71], v[96:99], v[194:197], v[68:71]
	v_mfma_f32_16x16x32_bf16 v[92:95], v[104:107], v[170:173], v[92:95]
	v_mfma_f32_16x16x32_bf16 v[88:91], v[112:115], v[166:169], v[88:91]
	v_mfma_f32_16x16x32_bf16 v[84:87], v[104:107], v[178:181], v[84:87]
	v_mfma_f32_16x16x32_bf16 v[80:83], v[112:115], v[174:177], v[80:83]
	v_mfma_f32_16x16x32_bf16 v[76:79], v[104:107], v[186:189], v[76:79]
	v_mfma_f32_16x16x32_bf16 v[72:75], v[112:115], v[182:185], v[72:75]
	v_mfma_f32_16x16x32_bf16 v[68:71], v[104:107], v[198:201], v[68:71]
	v_mfma_f32_16x16x32_bf16 v[64:67], v[112:115], v[194:197], v[64:67]
	v_mfma_f32_16x16x32_bf16 v[166:169], v[120:123], v[170:173], v[88:91]
	v_mfma_f32_16x16x32_bf16 v[170:173], v[120:123], v[178:181], v[80:83]
	v_mfma_f32_16x16x32_bf16 v[174:177], v[120:123], v[186:189], v[72:75]
	v_mfma_f32_16x16x32_bf16 v[178:181], v[120:123], v[198:201], v[64:67]
	s_setprio 0
	s_barrier
	s_nop 1
	ds_read_b128 v[64:67], v137 offset:16384
	ds_read_b128 v[72:75], v137 offset:17408
	ds_read_b128 v[80:83], v137 offset:18432
	ds_read_b128 v[88:91], v137 offset:19456
	ds_read_b128 v[182:185], v137 offset:20480
	ds_read_b128 v[186:189], v137 offset:21504
	ds_read_b128 v[194:197], v137 offset:22528
	ds_read_b128 v[198:201], v137 offset:23552
	s_waitcnt vmcnt(4)
	s_barrier
	s_waitcnt lgkmcnt(0)
	s_setprio 1
	s_waitcnt lgkmcnt(0)
	v_mfma_f32_16x16x32_bf16 v[60:63], v[128:131], v[64:67], v[60:63]
	v_mfma_f32_16x16x32_bf16 v[52:55], v[128:131], v[80:83], v[52:55]
	v_mfma_f32_16x16x32_bf16 v[44:47], v[128:131], v[182:185], v[44:47]
	v_mfma_f32_16x16x32_bf16 v[36:39], v[128:131], v[194:197], v[36:39]
	v_mfma_f32_16x16x32_bf16 v[60:63], v[132:135], v[72:75], v[60:63]
	v_mfma_f32_16x16x32_bf16 v[56:59], v[154:157], v[64:67], v[56:59]
	v_mfma_f32_16x16x32_bf16 v[52:55], v[132:135], v[88:91], v[52:55]
	v_mfma_f32_16x16x32_bf16 v[48:51], v[154:157], v[80:83], v[48:51]
	v_mfma_f32_16x16x32_bf16 v[44:47], v[132:135], v[186:189], v[44:47]
	v_mfma_f32_16x16x32_bf16 v[40:43], v[154:157], v[182:185], v[40:43]
	v_mfma_f32_16x16x32_bf16 v[36:39], v[132:135], v[198:201], v[36:39]
	v_mfma_f32_16x16x32_bf16 v[32:35], v[154:157], v[194:197], v[32:35]
	v_mfma_f32_16x16x32_bf16 v[226:229], v[162:165], v[72:75], v[56:59]
	v_mfma_f32_16x16x32_bf16 v[230:233], v[162:165], v[88:91], v[48:51]
	v_mfma_f32_16x16x32_bf16 v[234:237], v[162:165], v[186:189], v[40:43]
	v_mfma_f32_16x16x32_bf16 v[128:131], v[162:165], v[198:201], v[32:35]
	s_setprio 0
	s_setprio 1
	v_mfma_f32_16x16x32_bf16 v[28:31], v[96:99], v[64:67], v[28:31]
	v_mfma_f32_16x16x32_bf16 v[20:23], v[96:99], v[80:83], v[20:23]
	v_mfma_f32_16x16x32_bf16 v[12:15], v[96:99], v[182:185], v[12:15]
	v_mfma_f32_16x16x32_bf16 v[4:7], v[96:99], v[194:197], v[4:7]
	v_mfma_f32_16x16x32_bf16 v[28:31], v[104:107], v[72:75], v[28:31]
	v_mfma_f32_16x16x32_bf16 v[24:27], v[112:115], v[64:67], v[24:27]
	v_mfma_f32_16x16x32_bf16 v[20:23], v[104:107], v[88:91], v[20:23]
	v_mfma_f32_16x16x32_bf16 v[16:19], v[112:115], v[80:83], v[16:19]
	v_mfma_f32_16x16x32_bf16 v[12:15], v[104:107], v[186:189], v[12:15]
	v_mfma_f32_16x16x32_bf16 v[8:11], v[112:115], v[182:185], v[8:11]
	v_mfma_f32_16x16x32_bf16 v[4:7], v[104:107], v[198:201], v[4:7]
	v_mfma_f32_16x16x32_bf16 v[0:3], v[112:115], v[194:197], v[0:3]
	v_mfma_f32_16x16x32_bf16 v[132:135], v[120:123], v[72:75], v[24:27]
	v_mfma_f32_16x16x32_bf16 v[154:157], v[120:123], v[88:91], v[16:19]
	v_mfma_f32_16x16x32_bf16 v[162:165], v[120:123], v[186:189], v[8:11]
	v_mfma_f32_16x16x32_bf16 v[182:185], v[120:123], v[198:201], v[0:3]
	s_setprio 0
	s_barrier
	s_nop 1
	ds_read_b128 v[0:3], v152 offset:32768
	ds_read_b128 v[8:11], v152 offset:33792
	ds_read_b128 v[16:19], v152 offset:34816
	ds_read_b128 v[24:27], v152 offset:35840
	ds_read_b128 v[32:35], v137 offset:32768
	ds_read_b128 v[40:43], v137 offset:33792
	ds_read_b128 v[48:51], v137 offset:34816
	ds_read_b128 v[56:59], v137 offset:35840
	ds_read_b128 v[64:67], v137 offset:36864
	ds_read_b128 v[186:189], v137 offset:37888
	ds_read_b128 v[194:197], v137 offset:38912
	ds_read_b128 v[198:201], v137 offset:39936
	s_waitcnt vmcnt(2)
	s_barrier
; #define WAIT_V(n) asm volatile("s_waitcnt vmcnt(" #n ")" ::: "memory")
; #define WAIT_L(n) asm volatile("s_waitcnt lgkmcnt(" #n ")" ::: "memory")
; #define BAR __builtin_amdgcn_s_barrier()
; #define LDA(dst, b, h) _Pragma("unroll") for (int m = 0; m < 4; ++m) _Pragma("unroll") for (int k = 0; k < 2; ++k) \
;     dst[m][k] = *reinterpret_cast<const bf16x8*>((char*)shm + abase + (((b) * 2 + (h)) * 16384 + (m * 2 + k) * 1024))
; #define LDB(dst, b, h) _Pragma("unroll") for (int n = 0; n < 2; ++n) _Pragma("unroll") for (int k = 0; k < 2; ++k) \
;     dst[n][k] = *reinterpret_cast<const bf16x8*>((char*)shm + bbase + (((b) * 2 + (h)) * 16384 + (n * 2 + k) * 1024))
; template <bool SWAP>
; __device__ __forceinline__ void gemm_main(const u16* __restrict__ A, const u16* __restrict__ Bt, int brow, int bcol,
;                                           u16* shm, f32x4 (&acc)[2][2][4][2]) {
;     ...
;   { LDB(B0, 1, 0); LDA(At, 1, 0); WAIT_V(2); BAR; WAIT_L(0); MMA(0, 0, At, B0); BAR;
;     LDB(B1, 1, 1); WAIT_V(0); BAR; WAIT_L(0); MMA(0, 1, At, B1); BAR;
;     LDA(At, 1, 1); BAR; WAIT_L(0); MMA(1, 0, At, B0); MMA(1, 1, At, B1); BAR; }
;   if (wr == 0) BAR;
	s_waitcnt lgkmcnt(0)
	s_setprio 1
	s_waitcnt lgkmcnt(0)
	v_mfma_f32_16x16x32_bf16 v[72:75], v[0:3], v[32:35], v[124:127]
	v_mfma_f32_16x16x32_bf16 v[120:123], v[8:11], v[40:43], v[72:75]
	v_mfma_f32_16x16x32_bf16 v[72:75], v[16:19], v[32:35], v[158:161]
	v_mfma_f32_16x16x32_bf16 v[124:127], v[24:27], v[40:43], v[72:75]
	v_mfma_f32_16x16x32_bf16 v[72:75], v[0:3], v[48:51], v[116:119]
	v_mfma_f32_16x16x32_bf16 v[112:115], v[8:11], v[56:59], v[72:75]
	v_mfma_f32_16x16x32_bf16 v[72:75], v[16:19], v[48:51], v[202:205]
	v_mfma_f32_16x16x32_bf16 v[116:119], v[24:27], v[56:59], v[72:75]
	v_mfma_f32_16x16x32_bf16 v[72:75], v[0:3], v[64:67], v[108:111]
	v_mfma_f32_16x16x32_bf16 v[104:107], v[8:11], v[186:189], v[72:75]
	v_mfma_f32_16x16x32_bf16 v[72:75], v[16:19], v[64:67], v[206:209]
	v_mfma_f32_16x16x32_bf16 v[108:111], v[24:27], v[186:189], v[72:75]
	v_mfma_f32_16x16x32_bf16 v[72:75], v[0:3], v[194:197], v[100:103]
	v_mfma_f32_16x16x32_bf16 v[96:99], v[8:11], v[198:201], v[72:75]
	v_mfma_f32_16x16x32_bf16 v[72:75], v[16:19], v[194:197], v[222:225]
	v_mfma_f32_16x16x32_bf16 v[100:103], v[24:27], v[198:201], v[72:75]
	s_setprio 0
	s_barrier
	ds_read_b128 v[158:161], v152 offset:49152
	ds_read_b128 v[202:205], v152 offset:50176
	ds_read_b128 v[206:209], v152 offset:51200
	ds_read_b128 v[222:225], v152 offset:52224
	s_waitcnt vmcnt(0)
	s_barrier
	s_waitcnt lgkmcnt(0)
	s_setprio 1
	s_waitcnt lgkmcnt(0)
	v_mfma_f32_16x16x32_bf16 v[72:75], v[158:161], v[32:35], v[92:95]
	v_mfma_f32_16x16x32_bf16 v[32:35], v[206:209], v[32:35], v[166:169]
	v_mfma_f32_16x16x32_bf16 v[92:95], v[222:225], v[40:43], v[32:35]
	v_mfma_f32_16x16x32_bf16 v[32:35], v[158:161], v[48:51], v[84:87]
	v_mfma_f32_16x16x32_bf16 v[80:83], v[202:205], v[56:59], v[32:35]
	v_mfma_f32_16x16x32_bf16 v[32:35], v[206:209], v[48:51], v[170:173]
	v_mfma_f32_16x16x32_bf16 v[84:87], v[222:225], v[56:59], v[32:35]
	v_mfma_f32_16x16x32_bf16 v[32:35], v[158:161], v[64:67], v[76:79]
	v_mfma_f32_16x16x32_bf16 v[88:91], v[202:205], v[40:43], v[72:75]
	v_mfma_f32_16x16x32_bf16 v[72:75], v[202:205], v[186:189], v[32:35]
	v_mfma_f32_16x16x32_bf16 v[32:35], v[206:209], v[64:67], v[174:177]
	v_mfma_f32_16x16x32_bf16 v[76:79], v[222:225], v[186:189], v[32:35]
	v_mfma_f32_16x16x32_bf16 v[32:35], v[158:161], v[194:197], v[68:71]
	v_mfma_f32_16x16x32_bf16 v[64:67], v[202:205], v[198:201], v[32:35]
	v_mfma_f32_16x16x32_bf16 v[32:35], v[206:209], v[194:197], v[178:181]
	v_mfma_f32_16x16x32_bf16 v[68:71], v[222:225], v[198:201], v[32:35]
	s_setprio 0
	s_barrier
	ds_read_b128 v[166:169], v137 offset:49152
	ds_read_b128 v[170:173], v137 offset:50176
	ds_read_b128 v[174:177], v137 offset:51200
	ds_read_b128 v[178:181], v137 offset:52224
	ds_read_b128 v[186:189], v137 offset:53248
	ds_read_b128 v[194:197], v137 offset:54272
	ds_read_b128 v[198:201], v137 offset:55296
	ds_read_b128 v[238:241], v137 offset:56320
	s_barrier
	s_waitcnt lgkmcnt(0)
	s_setprio 1
	s_waitcnt lgkmcnt(0)
	v_mfma_f32_16x16x32_bf16 v[32:35], v[0:3], v[166:169], v[60:63]
	v_mfma_f32_16x16x32_bf16 v[56:59], v[8:11], v[170:173], v[32:35]
	v_mfma_f32_16x16x32_bf16 v[32:35], v[16:19], v[166:169], v[226:229]
	v_mfma_f32_16x16x32_bf16 v[60:63], v[24:27], v[170:173], v[32:35]
	v_mfma_f32_16x16x32_bf16 v[32:35], v[0:3], v[174:177], v[52:55]
	v_mfma_f32_16x16x32_bf16 v[48:51], v[8:11], v[178:181], v[32:35]
	v_mfma_f32_16x16x32_bf16 v[32:35], v[16:19], v[174:177], v[230:233]
	v_mfma_f32_16x16x32_bf16 v[52:55], v[24:27], v[178:181], v[32:35]
	v_mfma_f32_16x16x32_bf16 v[32:35], v[0:3], v[186:189], v[44:47]
	v_mfma_f32_16x16x32_bf16 v[40:43], v[8:11], v[194:197], v[32:35]
	v_mfma_f32_16x16x32_bf16 v[32:35], v[16:19], v[186:189], v[234:237]
	v_mfma_f32_16x16x32_bf16 v[0:3], v[0:3], v[198:201], v[36:39]
	v_mfma_f32_16x16x32_bf16 v[44:47], v[24:27], v[194:197], v[32:35]
	v_mfma_f32_16x16x32_bf16 v[32:35], v[8:11], v[238:241], v[0:3]
	v_mfma_f32_16x16x32_bf16 v[0:3], v[16:19], v[198:201], v[128:131]
	v_mfma_f32_16x16x32_bf16 v[36:39], v[24:27], v[238:241], v[0:3]
	s_setprio 0
	s_setprio 1
	v_mfma_f32_16x16x32_bf16 v[0:3], v[158:161], v[166:169], v[28:31]
	v_mfma_f32_16x16x32_bf16 v[24:27], v[202:205], v[170:173], v[0:3]
	v_mfma_f32_16x16x32_bf16 v[0:3], v[206:209], v[166:169], v[132:135]
	v_mfma_f32_16x16x32_bf16 v[28:31], v[222:225], v[170:173], v[0:3]
	v_mfma_f32_16x16x32_bf16 v[0:3], v[158:161], v[174:177], v[20:23]
	v_mfma_f32_16x16x32_bf16 v[16:19], v[202:205], v[178:181], v[0:3]
	v_mfma_f32_16x16x32_bf16 v[0:3], v[206:209], v[174:177], v[154:157]
	v_mfma_f32_16x16x32_bf16 v[20:23], v[222:225], v[178:181], v[0:3]
	v_mfma_f32_16x16x32_bf16 v[0:3], v[158:161], v[186:189], v[12:15]
	v_mfma_f32_16x16x32_bf16 v[8:11], v[202:205], v[194:197], v[0:3]
	v_mfma_f32_16x16x32_bf16 v[0:3], v[206:209], v[186:189], v[162:165]
	v_mfma_f32_16x16x32_bf16 v[12:15], v[222:225], v[194:197], v[0:3]
	v_mfma_f32_16x16x32_bf16 v[0:3], v[158:161], v[198:201], v[4:7]
	v_mfma_f32_16x16x32_bf16 v[4:7], v[206:209], v[198:201], v[182:185]
	v_mfma_f32_16x16x32_bf16 v[0:3], v[202:205], v[238:241], v[0:3]
	v_mfma_f32_16x16x32_bf16 v[4:7], v[222:225], v[238:241], v[4:7]
	s_setprio 0
	s_movk_i32 s0, 0x100
	v_cmp_gt_u32_e32 vcc, s0, v136
	s_barrier
	s_and_saveexec_b64 s[0:1], vcc
	s_cbranch_execz .LBB0_203
	s_barrier

; #define WAIT_V(n) asm volatile("s_waitcnt vmcnt(" #n ")" ::: "memory")
; #define WAIT_L(n) asm volatile("s_waitcnt lgkmcnt(" #n ")" ::: "memory")
; #define BAR __builtin_amdgcn_s_barrier()
; #define SCHED __builtin_amdgcn_sched_barrier(0)
; #define STAGE(P, BASE, br, kt) do { const char* _g = (const char*)((BASE) + (size_t)(br) * GK + (kt) * BK); \
;     __builtin_amdgcn_global_load_lds((const unsigned*)(_g + voff0), (unsigned*)((char*)(P) + tx * 16), 16, 0, 0); \
;     __builtin_amdgcn_global_load_lds((const unsigned*)(_g + voff1), (unsigned*)((char*)(P) + tx * 16 + 8192), 16, 0, 0); } while (0)
; #define LDA(dst, b, h) _Pragma("unroll") for (int m = 0; m < 4; ++m) _Pragma("unroll") for (int k = 0; k < 2; ++k) \
;     dst[m][k] = *reinterpret_cast<const bf16x8*>((char*)shm + abase + (((b) * 2 + (h)) * 16384 + (m * 2 + k) * 1024))
; #define LDB(dst, b, h) _Pragma("unroll") for (int n = 0; n < 2; ++n) _Pragma("unroll") for (int k = 0; k < 2; ++k) \
;     dst[n][k] = *reinterpret_cast<const bf16x8*>((char*)shm + bbase + (((b) * 2 + (h)) * 16384 + (n * 2 + k) * 1024))
; template <bool SWAP>
; __device__ __forceinline__ void gemm_main(const u16* __restrict__ A, const u16* __restrict__ Bt, int brow, int bcol,
;                                           u16* shm, f32x4 (&acc)[2][2][4][2]) {
;     ...
;   for (int t = 0; t < nt - 2; t += 2) {
;     LDB(B0, 0, 0); SCHED; LDA(At, 0, 0); STAGE(SA(1, 1), A, brow + HALF, t + 1);
;     WAIT_L(8); BAR; WAIT_L(0); MMA(0, 0, At, B0); BAR; SCHED;
;     LDB(B1, 0, 1); STAGE(SB(0, 0), Bt, bcol, t + 2);
;     BAR; WAIT_L(0); MMA(0, 1, At, B1); BAR;
;     LDA(At, 0, 1); STAGE(SA(0, 0), A, brow, t + 2);
;     BAR; WAIT_L(0); MMA(1, 0, At, B0); BAR; SCHED;
;     STAGE(SB(0, 1), Bt, bcol + HALF, t + 2);
;     WAIT_V(6); BAR; MMA(1, 1, At, B1); BAR;
.LBB0_436:
	ds_read_b128 v[170:173], v137 offset:1024
	ds_read_b128 v[178:181], v137 offset:3072
	ds_read_b128 v[186:189], v137 offset:5120
	ds_read_b128 v[198:201], v137 offset:7168
	v_add_u32_e32 v192, 0, v139
	v_add_u32_e32 v148, 0xc000, v192
	v_add_u32_e32 v149, 0xe000, v192
	s_add_u32 m0, s2, 0xc000
	v_lshl_add_u64 v[232:233], s[50:51], 0, v[134:135]
	s_add_u32 vcc_lo, s50, s82
	s_addc_u32 vcc_hi, s51, s83
	global_load_lds_dwordx4 v132, vcc
	s_add_u32 m0, s2, 0xe000
	s_nop 0
	global_load_lds_dwordx4 v134, vcc
	s_waitcnt lgkmcnt(8)
	s_barrier
	s_waitcnt lgkmcnt(0)
	v_mfma_f32_16x16x32_bf16 v[124:127], v[150:153], v[166:169], v[124:127]
	v_mfma_f32_16x16x32_bf16 v[120:123], v[158:161], v[166:169], v[120:123]
	v_mfma_f32_16x16x32_bf16 v[116:119], v[150:153], v[174:177], v[116:119]
	v_mfma_f32_16x16x32_bf16 v[112:115], v[158:161], v[174:177], v[112:115]
	v_mfma_f32_16x16x32_bf16 v[108:111], v[150:153], v[182:185], v[108:111]
	v_mfma_f32_16x16x32_bf16 v[104:107], v[158:161], v[182:185], v[104:107]
	v_mfma_f32_16x16x32_bf16 v[100:103], v[150:153], v[194:197], v[100:103]
	v_mfma_f32_16x16x32_bf16 v[96:99], v[158:161], v[194:197], v[96:99]
	v_mfma_f32_16x16x32_bf16 v[124:127], v[154:157], v[170:173], v[124:127]
	v_mfma_f32_16x16x32_bf16 v[120:123], v[162:165], v[170:173], v[120:123]
	v_mfma_f32_16x16x32_bf16 v[116:119], v[154:157], v[178:181], v[116:119]
	v_mfma_f32_16x16x32_bf16 v[112:115], v[162:165], v[178:181], v[112:115]
	v_mfma_f32_16x16x32_bf16 v[108:111], v[154:157], v[186:189], v[108:111]
	v_mfma_f32_16x16x32_bf16 v[104:107], v[162:165], v[186:189], v[104:107]
	v_mfma_f32_16x16x32_bf16 v[100:103], v[154:157], v[198:201], v[100:103]
	v_mfma_f32_16x16x32_bf16 v[96:99], v[162:165], v[198:201], v[96:99]
	s_barrier
	ds_read_b128 v[202:205], v138 offset:16384
	ds_read_b128 v[206:209], v138 offset:17408
	ds_read_b128 v[224:227], v138 offset:18432
	ds_read_b128 v[228:231], v138 offset:19456
	s_add_u32 m0, s2, s28
	s_nop 0
	s_add_u32 vcc_lo, s50, s74
	s_addc_u32 vcc_hi, s51, s75
	global_load_lds_dwordx4 v128, vcc
	v_lshl_add_u64 v[236:237], s[50:51], 0, v[130:131]
	s_add_u32 m0, s2, s28
	s_add_u32 m0, m0, 0x2000
	s_nop 0
	global_load_lds_dwordx4 v130, vcc
	s_barrier
	s_waitcnt lgkmcnt(0)
	v_mfma_f32_16x16x32_bf16 v[92:95], v[202:205], v[166:169], v[92:95]
	v_mfma_f32_16x16x32_bf16 v[88:91], v[224:227], v[166:169], v[88:91]
	v_mfma_f32_16x16x32_bf16 v[84:87], v[202:205], v[174:177], v[84:87]
	v_mfma_f32_16x16x32_bf16 v[80:83], v[224:227], v[174:177], v[80:83]
	v_mfma_f32_16x16x32_bf16 v[76:79], v[202:205], v[182:185], v[76:79]
	v_mfma_f32_16x16x32_bf16 v[72:75], v[224:227], v[182:185], v[72:75]
	v_mfma_f32_16x16x32_bf16 v[68:71], v[202:205], v[194:197], v[68:71]
	v_mfma_f32_16x16x32_bf16 v[64:67], v[224:227], v[194:197], v[64:67]
	v_mfma_f32_16x16x32_bf16 v[92:95], v[206:209], v[170:173], v[92:95]
	ds_read_b128 v[166:169], v137 offset:16384
	v_mfma_f32_16x16x32_bf16 v[88:91], v[228:231], v[170:173], v[88:91]
	v_mfma_f32_16x16x32_bf16 v[84:87], v[206:209], v[178:181], v[84:87]
	ds_read_b128 v[174:177], v137 offset:18432
	v_mfma_f32_16x16x32_bf16 v[80:83], v[228:231], v[178:181], v[80:83]
	v_mfma_f32_16x16x32_bf16 v[76:79], v[206:209], v[186:189], v[76:79]
	ds_read_b128 v[182:185], v137 offset:20480
	v_mfma_f32_16x16x32_bf16 v[72:75], v[228:231], v[186:189], v[72:75]
	v_mfma_f32_16x16x32_bf16 v[68:71], v[206:209], v[198:201], v[68:71]
	ds_read_b128 v[194:197], v137 offset:22528
	v_mfma_f32_16x16x32_bf16 v[64:67], v[228:231], v[198:201], v[64:67]
	s_barrier
	ds_read_b128 v[170:173], v137 offset:17408
	ds_read_b128 v[178:181], v137 offset:19456
	ds_read_b128 v[186:189], v137 offset:21504
	ds_read_b128 v[198:201], v137 offset:23552
	s_add_u32 m0, s2, 0x0
	s_nop 0
	s_add_u32 vcc_lo, s50, s76
	s_addc_u32 vcc_hi, s51, s77
	global_load_lds_dwordx4 v132, vcc
	s_add_u32 m0, s2, 0x2000
	s_nop 0
	global_load_lds_dwordx4 v134, vcc
	s_waitcnt vmcnt(8)
	s_barrier
	s_waitcnt lgkmcnt(0)
	v_mfma_f32_16x16x32_bf16 v[60:63], v[150:153], v[166:169], v[60:63]
	v_mfma_f32_16x16x32_bf16 v[56:59], v[158:161], v[166:169], v[56:59]
	v_mfma_f32_16x16x32_bf16 v[52:55], v[150:153], v[174:177], v[52:55]
	v_mfma_f32_16x16x32_bf16 v[48:51], v[158:161], v[174:177], v[48:51]
	v_mfma_f32_16x16x32_bf16 v[44:47], v[150:153], v[182:185], v[44:47]
	v_mfma_f32_16x16x32_bf16 v[40:43], v[158:161], v[182:185], v[40:43]
	v_mfma_f32_16x16x32_bf16 v[36:39], v[150:153], v[194:197], v[36:39]
	v_mfma_f32_16x16x32_bf16 v[32:35], v[158:161], v[194:197], v[32:35]
	v_mfma_f32_16x16x32_bf16 v[60:63], v[154:157], v[170:173], v[60:63]
	v_mfma_f32_16x16x32_bf16 v[56:59], v[162:165], v[170:173], v[56:59]
	v_mfma_f32_16x16x32_bf16 v[52:55], v[154:157], v[178:181], v[52:55]
	v_mfma_f32_16x16x32_bf16 v[48:51], v[162:165], v[178:181], v[48:51]
	v_mfma_f32_16x16x32_bf16 v[44:47], v[154:157], v[186:189], v[44:47]
	v_mfma_f32_16x16x32_bf16 v[40:43], v[162:165], v[186:189], v[40:43]
	v_mfma_f32_16x16x32_bf16 v[36:39], v[154:157], v[198:201], v[36:39]
	v_mfma_f32_16x16x32_bf16 v[32:35], v[162:165], v[198:201], v[32:35]
	s_barrier
	ds_read_b128 v[150:153], v138 offset:32768
	ds_read_b128 v[154:157], v138 offset:33792
	ds_read_b128 v[158:161], v138 offset:34816
	ds_read_b128 v[162:165], v138 offset:35840
	s_add_u32 m0, s2, s29
	s_nop 0
	s_add_u32 vcc_lo, s50, s70
	s_addc_u32 vcc_hi, s51, s71
	global_load_lds_dwordx4 v128, vcc
	s_add_u32 m0, s2, s29
	s_add_u32 m0, m0, 0x2000
	s_nop 0
	global_load_lds_dwordx4 v130, vcc
	s_waitcnt vmcnt(6)
	s_barrier
; #define WAIT_V(n) asm volatile("s_waitcnt vmcnt(" #n ")" ::: "memory")
; #define WAIT_L(n) asm volatile("s_waitcnt lgkmcnt(" #n ")" ::: "memory")
; #define BAR __builtin_amdgcn_s_barrier()
; #define SCHED __builtin_amdgcn_sched_barrier(0)
; #define STAGE(P, BASE, br, kt) do { const char* _g = (const char*)((BASE) + (size_t)(br) * GK + (kt) * BK); \
;     __builtin_amdgcn_global_load_lds((const unsigned*)(_g + voff0), (unsigned*)((char*)(P) + tx * 16), 16, 0, 0); \
;     __builtin_amdgcn_global_load_lds((const unsigned*)(_g + voff1), (unsigned*)((char*)(P) + tx * 16 + 8192), 16, 0, 0); } while (0)
; #define LDA(dst, b, h) _Pragma("unroll") for (int m = 0; m < 4; ++m) _Pragma("unroll") for (int k = 0; k < 2; ++k) \
;     dst[m][k] = *reinterpret_cast<const bf16x8*>((char*)shm + abase + (((b) * 2 + (h)) * 16384 + (m * 2 + k) * 1024))
; #define LDB(dst, b, h) _Pragma("unroll") for (int n = 0; n < 2; ++n) _Pragma("unroll") for (int k = 0; k < 2; ++k) \
;     dst[n][k] = *reinterpret_cast<const bf16x8*>((char*)shm + bbase + (((b) * 2 + (h)) * 16384 + (n * 2 + k) * 1024))
; template <bool SWAP>
; __device__ __forceinline__ void gemm_main(const u16* __restrict__ A, const u16* __restrict__ Bt, int brow, int bcol,
;                                           u16* shm, f32x4 (&acc)[2][2][4][2]) {
;     ...
;     WAIT_V(6); BAR; MMA(1, 1, At, B1); BAR;
;     LDB(B0, 1, 0); SCHED; LDA(At, 1, 0); STAGE(SA(0, 1), A, brow + HALF, t + 2);
;     WAIT_L(8); BAR; WAIT_L(0); MMA(0, 0, At, B0); BAR; SCHED;
;     LDB(B1, 1, 1); STAGE(SB(1, 0), Bt, bcol, t + 3);
;     BAR; WAIT_L(0); MMA(0, 1, At, B1); BAR;
;     LDA(At, 1, 1); STAGE(SA(1, 0), A, brow, t + 3);
;     BAR; WAIT_L(0); MMA(1, 0, At, B0); BAR; SCHED;
	v_mfma_f32_16x16x32_bf16 v[28:31], v[202:205], v[166:169], v[28:31]
	v_mfma_f32_16x16x32_bf16 v[24:27], v[224:227], v[166:169], v[24:27]
	v_mfma_f32_16x16x32_bf16 v[20:23], v[202:205], v[174:177], v[20:23]
	v_mfma_f32_16x16x32_bf16 v[16:19], v[224:227], v[174:177], v[16:19]
	v_mfma_f32_16x16x32_bf16 v[12:15], v[202:205], v[182:185], v[12:15]
	v_mfma_f32_16x16x32_bf16 v[8:11], v[224:227], v[182:185], v[8:11]
	v_mfma_f32_16x16x32_bf16 v[4:7], v[202:205], v[194:197], v[4:7]
	v_mfma_f32_16x16x32_bf16 v[0:3], v[224:227], v[194:197], v[0:3]
	v_mfma_f32_16x16x32_bf16 v[28:31], v[206:209], v[170:173], v[28:31]
	ds_read_b128 v[166:169], v137 offset:32768
	v_mfma_f32_16x16x32_bf16 v[24:27], v[228:231], v[170:173], v[24:27]
	v_mfma_f32_16x16x32_bf16 v[20:23], v[206:209], v[178:181], v[20:23]
	ds_read_b128 v[174:177], v137 offset:34816
	v_mfma_f32_16x16x32_bf16 v[16:19], v[228:231], v[178:181], v[16:19]
	v_mfma_f32_16x16x32_bf16 v[12:15], v[206:209], v[186:189], v[12:15]
	ds_read_b128 v[182:185], v137 offset:36864
	v_mfma_f32_16x16x32_bf16 v[8:11], v[228:231], v[186:189], v[8:11]
	v_mfma_f32_16x16x32_bf16 v[4:7], v[206:209], v[198:201], v[4:7]
	ds_read_b128 v[194:197], v137 offset:38912
	v_mfma_f32_16x16x32_bf16 v[0:3], v[228:231], v[198:201], v[0:3]
	s_barrier
	ds_read_b128 v[170:173], v137 offset:33792
	ds_read_b128 v[178:181], v137 offset:35840
	ds_read_b128 v[186:189], v137 offset:37888
	ds_read_b128 v[198:201], v137 offset:39936
	s_add_u32 m0, s2, 0x4000
	s_nop 0
	s_add_u32 vcc_lo, s50, s96
	s_addc_u32 vcc_hi, s51, s97
	global_load_lds_dwordx4 v132, vcc
	s_add_u32 m0, s2, 0x6000
	s_nop 0
	global_load_lds_dwordx4 v134, vcc
	s_waitcnt lgkmcnt(8)
	s_barrier
	s_waitcnt lgkmcnt(0)
	v_mfma_f32_16x16x32_bf16 v[124:127], v[150:153], v[166:169], v[124:127]
	v_mfma_f32_16x16x32_bf16 v[120:123], v[158:161], v[166:169], v[120:123]
	v_mfma_f32_16x16x32_bf16 v[116:119], v[150:153], v[174:177], v[116:119]
	v_mfma_f32_16x16x32_bf16 v[112:115], v[158:161], v[174:177], v[112:115]
	v_mfma_f32_16x16x32_bf16 v[108:111], v[150:153], v[182:185], v[108:111]
	v_mfma_f32_16x16x32_bf16 v[104:107], v[158:161], v[182:185], v[104:107]
	v_mfma_f32_16x16x32_bf16 v[100:103], v[150:153], v[194:197], v[100:103]
	v_mfma_f32_16x16x32_bf16 v[96:99], v[158:161], v[194:197], v[96:99]
	v_mfma_f32_16x16x32_bf16 v[124:127], v[154:157], v[170:173], v[124:127]
	v_mfma_f32_16x16x32_bf16 v[120:123], v[162:165], v[170:173], v[120:123]
	v_mfma_f32_16x16x32_bf16 v[116:119], v[154:157], v[178:181], v[116:119]
	v_mfma_f32_16x16x32_bf16 v[112:115], v[162:165], v[178:181], v[112:115]
	v_mfma_f32_16x16x32_bf16 v[108:111], v[154:157], v[186:189], v[108:111]
	v_mfma_f32_16x16x32_bf16 v[104:107], v[162:165], v[186:189], v[104:107]
	v_mfma_f32_16x16x32_bf16 v[100:103], v[154:157], v[198:201], v[100:103]
	v_mfma_f32_16x16x32_bf16 v[96:99], v[162:165], v[198:201], v[96:99]
	s_barrier
	ds_read_b128 v[202:205], v138 offset:49152
	ds_read_b128 v[206:209], v138 offset:50176
	ds_read_b128 v[224:227], v138 offset:51200
	ds_read_b128 v[228:231], v138 offset:52224
	s_add_u32 m0, s2, s30
	s_nop 0
	s_add_u32 vcc_lo, s50, s34
	s_addc_u32 vcc_hi, s51, s35
	global_load_lds_dwordx4 v128, vcc
	v_lshl_add_u64 v[238:239], v[236:237], 0, s[34:35]
	s_add_u32 m0, s2, s30
	s_add_u32 m0, m0, 0x2000
	s_nop 0
	global_load_lds_dwordx4 v130, vcc
	s_barrier
	s_waitcnt lgkmcnt(0)
	v_mfma_f32_16x16x32_bf16 v[92:95], v[202:205], v[166:169], v[92:95]
	v_mfma_f32_16x16x32_bf16 v[88:91], v[224:227], v[166:169], v[88:91]
	v_mfma_f32_16x16x32_bf16 v[84:87], v[202:205], v[174:177], v[84:87]
	v_mfma_f32_16x16x32_bf16 v[80:83], v[224:227], v[174:177], v[80:83]
	v_mfma_f32_16x16x32_bf16 v[76:79], v[202:205], v[182:185], v[76:79]
	v_mfma_f32_16x16x32_bf16 v[72:75], v[224:227], v[182:185], v[72:75]
	v_mfma_f32_16x16x32_bf16 v[68:71], v[202:205], v[194:197], v[68:71]
	v_mfma_f32_16x16x32_bf16 v[64:67], v[224:227], v[194:197], v[64:67]
	v_mfma_f32_16x16x32_bf16 v[92:95], v[206:209], v[170:173], v[92:95]
	ds_read_b128 v[166:169], v137 offset:49152
	v_mfma_f32_16x16x32_bf16 v[88:91], v[228:231], v[170:173], v[88:91]
	v_mfma_f32_16x16x32_bf16 v[84:87], v[206:209], v[178:181], v[84:87]
	ds_read_b128 v[174:177], v137 offset:51200
	v_mfma_f32_16x16x32_bf16 v[80:83], v[228:231], v[178:181], v[80:83]
	v_mfma_f32_16x16x32_bf16 v[76:79], v[206:209], v[186:189], v[76:79]
	ds_read_b128 v[182:185], v137 offset:53248
	v_mfma_f32_16x16x32_bf16 v[72:75], v[228:231], v[186:189], v[72:75]
	v_mfma_f32_16x16x32_bf16 v[68:71], v[206:209], v[198:201], v[68:71]
	ds_read_b128 v[194:197], v137 offset:55296
	v_mfma_f32_16x16x32_bf16 v[64:67], v[228:231], v[198:201], v[64:67]
	s_barrier
	ds_read_b128 v[170:173], v137 offset:50176
	ds_read_b128 v[178:181], v137 offset:52224
	ds_read_b128 v[186:189], v137 offset:54272
	ds_read_b128 v[198:201], v137 offset:56320
	v_add_u32_e32 v223, 0x8000, v192
	s_add_u32 m0, s2, 0x8000
	s_nop 0
	s_add_u32 vcc_lo, s50, s36
	s_addc_u32 vcc_hi, s51, s37
	global_load_lds_dwordx4 v132, vcc
	v_lshl_add_u64 v[190:191], v[232:233], 0, s[36:37]
	s_add_u32 m0, s2, 0xa000
	s_nop 0
	global_load_lds_dwordx4 v134, vcc
	s_waitcnt vmcnt(8)
	s_barrier
; #define WAIT_V(n) asm volatile("s_waitcnt vmcnt(" #n ")" ::: "memory")
; #define WAIT_L(n) asm volatile("s_waitcnt lgkmcnt(" #n ")" ::: "memory")
; #define BAR __builtin_amdgcn_s_barrier()
; #define SCHED __builtin_amdgcn_sched_barrier(0)
; #define STAGE(P, BASE, br, kt) do { const char* _g = (const char*)((BASE) + (size_t)(br) * GK + (kt) * BK); \
;     __builtin_amdgcn_global_load_lds((const unsigned*)(_g + voff0), (unsigned*)((char*)(P) + tx * 16), 16, 0, 0); \
;     __builtin_amdgcn_global_load_lds((const unsigned*)(_g + voff1), (unsigned*)((char*)(P) + tx * 16 + 8192), 16, 0, 0); } while (0)
; #define LDA(dst, b, h) _Pragma("unroll") for (int m = 0; m < 4; ++m) _Pragma("unroll") for (int k = 0; k < 2; ++k) \
;     dst[m][k] = *reinterpret_cast<const bf16x8*>((char*)shm + abase + (((b) * 2 + (h)) * 16384 + (m * 2 + k) * 1024))
; #define LDB(dst, b, h) _Pragma("unroll") for (int n = 0; n < 2; ++n) _Pragma("unroll") for (int k = 0; k < 2; ++k) \
;     dst[n][k] = *reinterpret_cast<const bf16x8*>((char*)shm + bbase + (((b) * 2 + (h)) * 16384 + (n * 2 + k) * 1024))
; template <bool SWAP>
; __device__ __forceinline__ void gemm_main(const u16* __restrict__ A, const u16* __restrict__ Bt, int brow, int bcol,
;                                           u16* shm, f32x4 (&acc)[2][2][4][2]) {
;     ...
;     BAR; WAIT_L(0); MMA(1, 0, At, B0); BAR; SCHED;
;     STAGE(SB(1, 1), Bt, bcol + HALF, t + 3);
;     WAIT_V(6); BAR; MMA(1, 1, At, B1); BAR;
;   }
;   { LDB(B0, 0, 0); LDA(At, 0, 0); STAGE(SA(1, 1), A, brow + HALF, nt - 1);
;     BAR; WAIT_L(0); MMA(0, 0, At, B0); BAR;
	s_waitcnt lgkmcnt(0)
	v_mfma_f32_16x16x32_bf16 v[60:63], v[150:153], v[166:169], v[60:63]
	v_mfma_f32_16x16x32_bf16 v[56:59], v[158:161], v[166:169], v[56:59]
	v_mfma_f32_16x16x32_bf16 v[52:55], v[150:153], v[174:177], v[52:55]
	v_mfma_f32_16x16x32_bf16 v[48:51], v[158:161], v[174:177], v[48:51]
	v_mfma_f32_16x16x32_bf16 v[44:47], v[150:153], v[182:185], v[44:47]
	v_mfma_f32_16x16x32_bf16 v[40:43], v[158:161], v[182:185], v[40:43]
	v_mfma_f32_16x16x32_bf16 v[36:39], v[150:153], v[194:197], v[36:39]
	v_mfma_f32_16x16x32_bf16 v[32:35], v[158:161], v[194:197], v[32:35]
	v_mfma_f32_16x16x32_bf16 v[60:63], v[154:157], v[170:173], v[60:63]
	v_mfma_f32_16x16x32_bf16 v[56:59], v[162:165], v[170:173], v[56:59]
	v_mfma_f32_16x16x32_bf16 v[52:55], v[154:157], v[178:181], v[52:55]
	v_mfma_f32_16x16x32_bf16 v[48:51], v[162:165], v[178:181], v[48:51]
	v_mfma_f32_16x16x32_bf16 v[44:47], v[154:157], v[186:189], v[44:47]
	v_mfma_f32_16x16x32_bf16 v[40:43], v[162:165], v[186:189], v[40:43]
	v_mfma_f32_16x16x32_bf16 v[36:39], v[154:157], v[198:201], v[36:39]
	v_mfma_f32_16x16x32_bf16 v[32:35], v[162:165], v[198:201], v[32:35]
	s_barrier
	ds_read_b128 v[150:153], v138
	ds_read_b128 v[154:157], v138 offset:1024
	ds_read_b128 v[158:161], v138 offset:2048
	ds_read_b128 v[162:165], v138 offset:3072
	s_add_u32 m0, s2, s31
	s_nop 0
	s_add_u32 vcc_lo, s50, s64
	s_addc_u32 vcc_hi, s51, s65
	global_load_lds_dwordx4 v128, vcc
	v_lshl_add_u64 v[254:255], v[236:237], 0, s[64:65]
	s_add_u32 m0, s2, s31
	s_add_u32 m0, m0, 0x2000
	s_nop 0
	global_load_lds_dwordx4 v130, vcc
	s_waitcnt vmcnt(6)
	s_barrier
	v_mfma_f32_16x16x32_bf16 v[28:31], v[202:205], v[166:169], v[28:31]
	v_mfma_f32_16x16x32_bf16 v[24:27], v[224:227], v[166:169], v[24:27]
	v_mfma_f32_16x16x32_bf16 v[20:23], v[202:205], v[174:177], v[20:23]
	v_mfma_f32_16x16x32_bf16 v[16:19], v[224:227], v[174:177], v[16:19]
	v_mfma_f32_16x16x32_bf16 v[12:15], v[202:205], v[182:185], v[12:15]
	v_mfma_f32_16x16x32_bf16 v[8:11], v[224:227], v[182:185], v[8:11]
	v_mfma_f32_16x16x32_bf16 v[4:7], v[202:205], v[194:197], v[4:7]
	v_mfma_f32_16x16x32_bf16 v[0:3], v[224:227], v[194:197], v[0:3]
	v_mfma_f32_16x16x32_bf16 v[28:31], v[206:209], v[170:173], v[28:31]
	ds_read_b128 v[166:169], v137
	v_mfma_f32_16x16x32_bf16 v[24:27], v[228:231], v[170:173], v[24:27]
	v_mfma_f32_16x16x32_bf16 v[20:23], v[206:209], v[178:181], v[20:23]
	ds_read_b128 v[174:177], v137 offset:2048
	v_mfma_f32_16x16x32_bf16 v[16:19], v[228:231], v[178:181], v[16:19]
	s_add_i32 s1, s1, 2
	v_lshl_add_u64 v[128:129], v[128:129], 0, s[74:75]
	v_lshl_add_u64 v[130:131], v[130:131], 0, s[74:75]
	v_lshl_add_u64 v[132:133], v[132:133], 0, s[74:75]
	v_lshl_add_u64 v[134:135], v[134:135], 0, s[74:75]
	s_cmp_lt_u32 s1, 28
	v_mfma_f32_16x16x32_bf16 v[12:15], v[206:209], v[186:189], v[12:15]
	ds_read_b128 v[182:185], v137 offset:4096
	v_mfma_f32_16x16x32_bf16 v[8:11], v[228:231], v[186:189], v[8:11]
	v_mfma_f32_16x16x32_bf16 v[4:7], v[206:209], v[198:201], v[4:7]
	ds_read_b128 v[194:197], v137 offset:6144
	v_mfma_f32_16x16x32_bf16 v[0:3], v[228:231], v[198:201], v[0:3]
	s_barrier
	s_cbranch_scc1 .LBB0_436
	v_lshlrev_b32_e32 v128, 3, v142
	v_lshlrev_b32_e32 v129, 5, v142
	v_and_b32_e32 v128, 0xffff0, v128
	v_and_b32_e32 v129, 32, v129
	s_or_b32 s2, s0, 0x80
	v_add_u32_e32 v129, v129, v144
	v_add_lshl_u32 v128, v143, v128, 12
	s_ashr_i32 s3, s2, 31
	v_lshl_add_u32 v192, v129, 1, v128
	v_lshlrev_b32_e32 v128, 3, v145
	v_lshlrev_b32_e32 v129, 5, v145
	s_lshl_b64 s[2:3], s[2:3], 12
	v_and_b32_e32 v128, 0xffff0, v128
	v_and_b32_e32 v129, 32, v129
	s_add_u32 s2, s16, s2
	v_add_u32_e32 v129, v129, v147
	v_add_lshl_u32 v128, v146, v128, 12
	s_addc_u32 s3, s17, s3
	v_lshl_add_u32 v146, v129, 1, v128
	v_mov_b32_e32 v147, v193
	v_lshl_add_u64 v[186:187], s[2:3], 0, v[192:193]
	s_mov_b64 s[8:9], 0xf80
	v_readfirstlane_b32 s1, v148
	v_lshl_add_u64 v[186:187], v[186:187], 0, s[8:9]
	s_mov_b32 m0, s1
	v_lshl_add_u64 v[146:147], s[2:3], 0, v[146:147]
	v_readfirstlane_b32 s1, v149
	ds_read_b128 v[128:131], v138
	ds_read_b128 v[132:135], v138 offset:1024
	ds_read_b128 v[142:145], v138 offset:2048
	ds_read_b128 v[150:153], v138 offset:3072
	ds_read_b128 v[154:157], v137
	ds_read_b128 v[158:161], v137 offset:1024
	ds_read_b128 v[162:165], v137 offset:2048
	ds_read_b128 v[166:169], v137 offset:3072
	ds_read_b128 v[170:173], v137 offset:4096
	ds_read_b128 v[174:177], v137 offset:5120
	ds_read_b128 v[178:181], v137 offset:6144
	ds_read_b128 v[182:185], v137 offset:7168
	global_load_lds_dwordx4 v[186:187], off
	v_lshl_add_u64 v[146:147], v[146:147], 0, s[8:9]
	s_mov_b32 m0, s1
	s_nop 0
	global_load_lds_dwordx4 v[146:147], off
	s_barrier
	s_waitcnt lgkmcnt(0)
	s_setprio 1
	s_waitcnt lgkmcnt(0)
	v_mfma_f32_16x16x32_bf16 v[124:127], v[128:131], v[154:157], v[124:127]
	v_mfma_f32_16x16x32_bf16 v[112:115], v[142:145], v[162:165], v[112:115]
	v_mfma_f32_16x16x32_bf16 v[104:107], v[142:145], v[170:173], v[104:107]
	v_mfma_f32_16x16x32_bf16 v[96:99], v[142:145], v[178:181], v[96:99]
	v_mfma_f32_16x16x32_bf16 v[124:127], v[132:135], v[158:161], v[124:127]
	v_mfma_f32_16x16x32_bf16 v[120:123], v[142:145], v[154:157], v[120:123]
	v_mfma_f32_16x16x32_bf16 v[116:119], v[128:131], v[162:165], v[116:119]
	v_mfma_f32_16x16x32_bf16 v[112:115], v[150:153], v[166:169], v[112:115]
	v_mfma_f32_16x16x32_bf16 v[108:111], v[128:131], v[170:173], v[108:111]
	v_mfma_f32_16x16x32_bf16 v[104:107], v[150:153], v[174:177], v[104:107]
	v_mfma_f32_16x16x32_bf16 v[100:103], v[128:131], v[178:181], v[100:103]
	v_mfma_f32_16x16x32_bf16 v[96:99], v[150:153], v[182:185], v[96:99]
	v_mfma_f32_16x16x32_bf16 v[146:149], v[150:153], v[158:161], v[120:123]
	v_mfma_f32_16x16x32_bf16 v[186:189], v[132:135], v[166:169], v[116:119]
	v_mfma_f32_16x16x32_bf16 v[194:197], v[132:135], v[174:177], v[108:111]
	v_mfma_f32_16x16x32_bf16 v[198:201], v[132:135], v[182:185], v[100:103]
	s_setprio 0
	s_barrier
; #define WAIT_V(n) asm volatile("s_waitcnt vmcnt(" #n ")" ::: "memory")
; #define WAIT_L(n) asm volatile("s_waitcnt lgkmcnt(" #n ")" ::: "memory")
; #define BAR __builtin_amdgcn_s_barrier()
; #define LDA(dst, b, h) _Pragma("unroll") for (int m = 0; m < 4; ++m) _Pragma("unroll") for (int k = 0; k < 2; ++k) \
;     dst[m][k] = *reinterpret_cast<const bf16x8*>((char*)shm + abase + (((b) * 2 + (h)) * 16384 + (m * 2 + k) * 1024))
; #define LDB(dst, b, h) _Pragma("unroll") for (int n = 0; n < 2; ++n) _Pragma("unroll") for (int k = 0; k < 2; ++k) \
;     dst[n][k] = *reinterpret_cast<const bf16x8*>((char*)shm + bbase + (((b) * 2 + (h)) * 16384 + (n * 2 + k) * 1024))
; template <bool SWAP>
; __device__ __forceinline__ void gemm_main(const u16* __restrict__ A, const u16* __restrict__ Bt, int brow, int bcol,
;                                           u16* shm, f32x4 (&acc)[2][2][4][2]) {
;     ...
;     LDB(B1, 0, 1); BAR; WAIT_L(0); MMA(0, 1, At, B1); BAR;
;     LDA(At, 0, 1); WAIT_V(4); BAR; WAIT_L(0); MMA(1, 0, At, B0); MMA(1, 1, At, B1); BAR; }
;   { LDB(B0, 1, 0); LDA(At, 1, 0); WAIT_V(2); BAR; WAIT_L(0); MMA(0, 0, At, B0); BAR;
	s_nop 0
	ds_read_b128 v[100:103], v138 offset:16384
	ds_read_b128 v[108:111], v138 offset:17408
	ds_read_b128 v[116:119], v138 offset:18432
	ds_read_b128 v[120:123], v138 offset:19456
	s_barrier
	s_waitcnt lgkmcnt(0)
	s_setprio 1
	s_waitcnt lgkmcnt(0)
	v_mfma_f32_16x16x32_bf16 v[88:91], v[116:119], v[154:157], v[88:91]
	v_mfma_f32_16x16x32_bf16 v[80:83], v[116:119], v[162:165], v[80:83]
	v_mfma_f32_16x16x32_bf16 v[72:75], v[116:119], v[170:173], v[72:75]
	v_mfma_f32_16x16x32_bf16 v[64:67], v[116:119], v[178:181], v[64:67]
	v_mfma_f32_16x16x32_bf16 v[92:95], v[100:103], v[154:157], v[92:95]
	v_mfma_f32_16x16x32_bf16 v[88:91], v[120:123], v[158:161], v[88:91]
	v_mfma_f32_16x16x32_bf16 v[84:87], v[100:103], v[162:165], v[84:87]
	v_mfma_f32_16x16x32_bf16 v[80:83], v[120:123], v[166:169], v[80:83]
	v_mfma_f32_16x16x32_bf16 v[76:79], v[100:103], v[170:173], v[76:79]
	v_mfma_f32_16x16x32_bf16 v[72:75], v[120:123], v[174:177], v[72:75]
	v_mfma_f32_16x16x32_bf16 v[68:71], v[100:103], v[178:181], v[68:71]
	v_mfma_f32_16x16x32_bf16 v[64:67], v[120:123], v[182:185], v[64:67]
	v_mfma_f32_16x16x32_bf16 v[202:205], v[108:111], v[158:161], v[92:95]
	v_mfma_f32_16x16x32_bf16 v[154:157], v[108:111], v[166:169], v[84:87]
	v_mfma_f32_16x16x32_bf16 v[158:161], v[108:111], v[174:177], v[76:79]
	v_mfma_f32_16x16x32_bf16 v[162:165], v[108:111], v[182:185], v[68:71]
	s_setprio 0
	s_barrier
	s_nop 0
	ds_read_b128 v[68:71], v137 offset:16384
	ds_read_b128 v[76:79], v137 offset:17408
	ds_read_b128 v[84:87], v137 offset:18432
	ds_read_b128 v[92:95], v137 offset:19456
	ds_read_b128 v[166:169], v137 offset:20480
	ds_read_b128 v[170:173], v137 offset:21504
	ds_read_b128 v[174:177], v137 offset:22528
	ds_read_b128 v[178:181], v137 offset:23552
	s_waitcnt vmcnt(4)
	s_barrier
	s_waitcnt lgkmcnt(0)
	s_setprio 1
	s_waitcnt lgkmcnt(0)
	v_mfma_f32_16x16x32_bf16 v[60:63], v[128:131], v[68:71], v[60:63]
	v_mfma_f32_16x16x32_bf16 v[56:59], v[142:145], v[68:71], v[56:59]
	v_mfma_f32_16x16x32_bf16 v[48:51], v[142:145], v[84:87], v[48:51]
	v_mfma_f32_16x16x32_bf16 v[40:43], v[142:145], v[166:169], v[40:43]
	v_mfma_f32_16x16x32_bf16 v[32:35], v[142:145], v[174:177], v[32:35]
	v_mfma_f32_16x16x32_bf16 v[60:63], v[132:135], v[76:79], v[60:63]
	v_mfma_f32_16x16x32_bf16 v[56:59], v[150:153], v[76:79], v[56:59]
	v_mfma_f32_16x16x32_bf16 v[52:55], v[128:131], v[84:87], v[52:55]
	v_mfma_f32_16x16x32_bf16 v[48:51], v[150:153], v[92:95], v[48:51]
	v_mfma_f32_16x16x32_bf16 v[44:47], v[128:131], v[166:169], v[44:47]
	v_mfma_f32_16x16x32_bf16 v[40:43], v[150:153], v[170:173], v[40:43]
	v_mfma_f32_16x16x32_bf16 v[36:39], v[128:131], v[174:177], v[36:39]
	v_mfma_f32_16x16x32_bf16 v[32:35], v[150:153], v[178:181], v[32:35]
	v_mfma_f32_16x16x32_bf16 v[182:185], v[132:135], v[92:95], v[52:55]
	v_mfma_f32_16x16x32_bf16 v[206:209], v[132:135], v[170:173], v[44:47]
	v_mfma_f32_16x16x32_bf16 v[128:131], v[132:135], v[178:181], v[36:39]
	s_setprio 0
	s_setprio 1
	v_mfma_f32_16x16x32_bf16 v[24:27], v[116:119], v[68:71], v[24:27]
	v_mfma_f32_16x16x32_bf16 v[16:19], v[116:119], v[84:87], v[16:19]
	v_mfma_f32_16x16x32_bf16 v[8:11], v[116:119], v[166:169], v[8:11]
	v_mfma_f32_16x16x32_bf16 v[0:3], v[116:119], v[174:177], v[0:3]
	v_mfma_f32_16x16x32_bf16 v[28:31], v[100:103], v[68:71], v[28:31]
	v_mfma_f32_16x16x32_bf16 v[24:27], v[120:123], v[76:79], v[24:27]
	v_mfma_f32_16x16x32_bf16 v[20:23], v[100:103], v[84:87], v[20:23]
	v_mfma_f32_16x16x32_bf16 v[16:19], v[120:123], v[92:95], v[16:19]
	v_mfma_f32_16x16x32_bf16 v[12:15], v[100:103], v[166:169], v[12:15]
	v_mfma_f32_16x16x32_bf16 v[8:11], v[120:123], v[170:173], v[8:11]
	v_mfma_f32_16x16x32_bf16 v[4:7], v[100:103], v[174:177], v[4:7]
	v_mfma_f32_16x16x32_bf16 v[0:3], v[120:123], v[178:181], v[0:3]
	v_mfma_f32_16x16x32_bf16 v[132:135], v[108:111], v[76:79], v[28:31]
	v_mfma_f32_16x16x32_bf16 v[142:145], v[108:111], v[92:95], v[20:23]
	v_mfma_f32_16x16x32_bf16 v[150:153], v[108:111], v[170:173], v[12:15]
	v_mfma_f32_16x16x32_bf16 v[166:169], v[108:111], v[178:181], v[4:7]
	s_setprio 0
	s_barrier
	s_nop 0
	ds_read_b128 v[4:7], v138 offset:32768
	ds_read_b128 v[12:15], v138 offset:33792
	ds_read_b128 v[170:173], v138 offset:34816
	ds_read_b128 v[174:177], v138 offset:35840
	ds_read_b128 v[20:23], v137 offset:32768
	ds_read_b128 v[28:31], v137 offset:33792
	ds_read_b128 v[36:39], v137 offset:34816
	ds_read_b128 v[44:47], v137 offset:35840
	ds_read_b128 v[52:55], v137 offset:36864
	ds_read_b128 v[178:181], v137 offset:37888
	ds_read_b128 v[224:227], v137 offset:38912
	ds_read_b128 v[228:231], v137 offset:39936
	s_waitcnt vmcnt(2)
	s_barrier
; #define WAIT_V(n) asm volatile("s_waitcnt vmcnt(" #n ")" ::: "memory")
; #define WAIT_L(n) asm volatile("s_waitcnt lgkmcnt(" #n ")" ::: "memory")
; #define BAR __builtin_amdgcn_s_barrier()
; #define LDA(dst, b, h) _Pragma("unroll") for (int m = 0; m < 4; ++m) _Pragma("unroll") for (int k = 0; k < 2; ++k) \
;     dst[m][k] = *reinterpret_cast<const bf16x8*>((char*)shm + abase + (((b) * 2 + (h)) * 16384 + (m * 2 + k) * 1024))
; #define LDB(dst, b, h) _Pragma("unroll") for (int n = 0; n < 2; ++n) _Pragma("unroll") for (int k = 0; k < 2; ++k) \
;     dst[n][k] = *reinterpret_cast<const bf16x8*>((char*)shm + bbase + (((b) * 2 + (h)) * 16384 + (n * 2 + k) * 1024))
; template <bool SWAP>
; __device__ __forceinline__ void gemm_main(const u16* __restrict__ A, const u16* __restrict__ Bt, int brow, int bcol,
;                                           u16* shm, f32x4 (&acc)[2][2][4][2]) {
;     ...
;   { LDB(B0, 1, 0); LDA(At, 1, 0); WAIT_V(2); BAR; WAIT_L(0); MMA(0, 0, At, B0); BAR;
;     LDB(B1, 1, 1); WAIT_V(0); BAR; WAIT_L(0); MMA(0, 1, At, B1); BAR;
;     LDA(At, 1, 1); BAR; WAIT_L(0); MMA(1, 0, At, B0); MMA(1, 1, At, B1); BAR; }
;   if (wr == 0) BAR;
	s_waitcnt lgkmcnt(0)
	s_setprio 1
	s_waitcnt lgkmcnt(0)
	v_mfma_f32_16x16x32_bf16 v[68:71], v[4:7], v[20:23], v[124:127]
	v_mfma_f32_16x16x32_bf16 v[120:123], v[12:15], v[28:31], v[68:71]
	v_mfma_f32_16x16x32_bf16 v[68:71], v[170:173], v[20:23], v[146:149]
	v_mfma_f32_16x16x32_bf16 v[116:119], v[174:177], v[28:31], v[68:71]
	v_mfma_f32_16x16x32_bf16 v[68:71], v[4:7], v[36:39], v[186:189]
	v_mfma_f32_16x16x32_bf16 v[108:111], v[12:15], v[44:47], v[68:71]
	v_mfma_f32_16x16x32_bf16 v[68:71], v[170:173], v[36:39], v[112:115]
	v_mfma_f32_16x16x32_bf16 v[100:103], v[174:177], v[44:47], v[68:71]
	v_mfma_f32_16x16x32_bf16 v[68:71], v[4:7], v[52:55], v[194:197]
	v_mfma_f32_16x16x32_bf16 v[92:95], v[12:15], v[178:181], v[68:71]
	v_mfma_f32_16x16x32_bf16 v[68:71], v[170:173], v[52:55], v[104:107]
	v_mfma_f32_16x16x32_bf16 v[84:87], v[174:177], v[178:181], v[68:71]
	v_mfma_f32_16x16x32_bf16 v[68:71], v[4:7], v[224:227], v[198:201]
	v_mfma_f32_16x16x32_bf16 v[76:79], v[12:15], v[228:231], v[68:71]
	v_mfma_f32_16x16x32_bf16 v[68:71], v[170:173], v[224:227], v[96:99]
	v_mfma_f32_16x16x32_bf16 v[68:71], v[174:177], v[228:231], v[68:71]
	s_setprio 0
	s_barrier
	ds_read_b128 v[146:149], v138 offset:49152
	ds_read_b128 v[186:189], v138 offset:50176
	ds_read_b128 v[194:197], v138 offset:51200
	ds_read_b128 v[198:201], v138 offset:52224
	s_waitcnt vmcnt(0)
	s_barrier
	s_waitcnt lgkmcnt(0)
	s_setprio 1
	s_waitcnt lgkmcnt(0)
	v_mfma_f32_16x16x32_bf16 v[96:99], v[146:149], v[20:23], v[202:205]
	v_mfma_f32_16x16x32_bf16 v[20:23], v[194:197], v[20:23], v[88:91]
	v_mfma_f32_16x16x32_bf16 v[112:115], v[198:201], v[28:31], v[20:23]
	v_mfma_f32_16x16x32_bf16 v[20:23], v[146:149], v[36:39], v[154:157]
	v_mfma_f32_16x16x32_bf16 v[104:107], v[186:189], v[44:47], v[20:23]
	v_mfma_f32_16x16x32_bf16 v[20:23], v[194:197], v[36:39], v[80:83]
	v_mfma_f32_16x16x32_bf16 v[124:127], v[186:189], v[28:31], v[96:99]
	v_mfma_f32_16x16x32_bf16 v[96:99], v[198:201], v[44:47], v[20:23]
	v_mfma_f32_16x16x32_bf16 v[20:23], v[146:149], v[52:55], v[158:161]
	v_mfma_f32_16x16x32_bf16 v[88:91], v[186:189], v[178:181], v[20:23]
	v_mfma_f32_16x16x32_bf16 v[20:23], v[194:197], v[52:55], v[72:75]
	v_mfma_f32_16x16x32_bf16 v[80:83], v[198:201], v[178:181], v[20:23]
	v_mfma_f32_16x16x32_bf16 v[20:23], v[146:149], v[224:227], v[162:165]
	v_mfma_f32_16x16x32_bf16 v[72:75], v[186:189], v[228:231], v[20:23]
	v_mfma_f32_16x16x32_bf16 v[20:23], v[194:197], v[224:227], v[64:67]
	v_mfma_f32_16x16x32_bf16 v[64:67], v[198:201], v[228:231], v[20:23]
	s_setprio 0
	s_barrier
	ds_read_b128 v[154:157], v137 offset:49152
	ds_read_b128 v[158:161], v137 offset:50176
	ds_read_b128 v[162:165], v137 offset:51200
	ds_read_b128 v[178:181], v137 offset:52224
	ds_read_b128 v[202:205], v137 offset:53248
	ds_read_b128 v[224:227], v137 offset:54272
	ds_read_b128 v[228:231], v137 offset:55296
	ds_read_b128 v[232:235], v137 offset:56320
	s_barrier
	s_waitcnt lgkmcnt(0)
	s_setprio 1
	s_waitcnt lgkmcnt(0)
	v_mfma_f32_16x16x32_bf16 v[20:23], v[4:7], v[154:157], v[60:63]
	v_mfma_f32_16x16x32_bf16 v[60:63], v[12:15], v[158:161], v[20:23]
	v_mfma_f32_16x16x32_bf16 v[20:23], v[170:173], v[154:157], v[56:59]
	v_mfma_f32_16x16x32_bf16 v[52:55], v[174:177], v[158:161], v[20:23]
	v_mfma_f32_16x16x32_bf16 v[20:23], v[4:7], v[162:165], v[182:185]
	v_mfma_f32_16x16x32_bf16 v[44:47], v[12:15], v[178:181], v[20:23]
	v_mfma_f32_16x16x32_bf16 v[20:23], v[170:173], v[162:165], v[48:51]
	v_mfma_f32_16x16x32_bf16 v[36:39], v[174:177], v[178:181], v[20:23]
	v_mfma_f32_16x16x32_bf16 v[20:23], v[4:7], v[202:205], v[206:209]
	v_mfma_f32_16x16x32_bf16 v[4:7], v[4:7], v[228:231], v[128:131]
	v_mfma_f32_16x16x32_bf16 v[28:31], v[12:15], v[224:227], v[20:23]
	v_mfma_f32_16x16x32_bf16 v[20:23], v[170:173], v[202:205], v[40:43]
	v_mfma_f32_16x16x32_bf16 v[12:15], v[12:15], v[232:235], v[4:7]
	v_mfma_f32_16x16x32_bf16 v[4:7], v[170:173], v[228:231], v[32:35]
	v_mfma_f32_16x16x32_bf16 v[20:23], v[174:177], v[224:227], v[20:23]
	v_mfma_f32_16x16x32_bf16 v[4:7], v[174:177], v[232:235], v[4:7]
	s_setprio 0
	s_setprio 1
	v_mfma_f32_16x16x32_bf16 v[32:35], v[146:149], v[154:157], v[132:135]
	v_mfma_f32_16x16x32_bf16 v[24:27], v[194:197], v[154:157], v[24:27]
	v_mfma_f32_16x16x32_bf16 v[16:19], v[194:197], v[162:165], v[16:19]
	v_mfma_f32_16x16x32_bf16 v[56:59], v[186:189], v[158:161], v[32:35]
	v_mfma_f32_16x16x32_bf16 v[48:51], v[198:201], v[158:161], v[24:27]
	v_mfma_f32_16x16x32_bf16 v[24:27], v[146:149], v[162:165], v[142:145]
	v_mfma_f32_16x16x32_bf16 v[32:35], v[198:201], v[178:181], v[16:19]
	v_mfma_f32_16x16x32_bf16 v[16:19], v[146:149], v[202:205], v[150:153]
	v_mfma_f32_16x16x32_bf16 v[8:11], v[194:197], v[202:205], v[8:11]
	v_mfma_f32_16x16x32_bf16 v[40:43], v[186:189], v[178:181], v[24:27]
	v_mfma_f32_16x16x32_bf16 v[24:27], v[186:189], v[224:227], v[16:19]
	v_mfma_f32_16x16x32_bf16 v[16:19], v[198:201], v[224:227], v[8:11]
	v_mfma_f32_16x16x32_bf16 v[8:11], v[146:149], v[228:231], v[166:169]
	v_mfma_f32_16x16x32_bf16 v[0:3], v[194:197], v[228:231], v[0:3]
	v_mfma_f32_16x16x32_bf16 v[8:11], v[186:189], v[232:235], v[8:11]
	v_mfma_f32_16x16x32_bf16 v[0:3], v[198:201], v[232:235], v[0:3]
	s_setprio 0
	s_movk_i32 s1, 0x100
	v_cmp_gt_u32_e32 vcc, s1, v136
	s_barrier
	s_and_saveexec_b64 s[8:9], vcc
	s_cbranch_execz .LBB0_439
	s_barrier

; #define WAIT_V(n) asm volatile("s_waitcnt vmcnt(" #n ")" ::: "memory")
; #define WAIT_L(n) asm volatile("s_waitcnt lgkmcnt(" #n ")" ::: "memory")
; #define BAR __builtin_amdgcn_s_barrier()
; #define SCHED __builtin_amdgcn_sched_barrier(0)
; #define STAGE(P, BASE, br, kt) do { const char* _g = (const char*)((BASE) + (size_t)(br) * GK + (kt) * BK); \
;     __builtin_amdgcn_global_load_lds((const unsigned*)(_g + voff0), (unsigned*)((char*)(P) + tx * 16), 16, 0, 0); \
;     __builtin_amdgcn_global_load_lds((const unsigned*)(_g + voff1), (unsigned*)((char*)(P) + tx * 16 + 8192), 16, 0, 0); } while (0)
; #define LDA(dst, b, h) _Pragma("unroll") for (int m = 0; m < 4; ++m) _Pragma("unroll") for (int k = 0; k < 2; ++k) \
;     dst[m][k] = *reinterpret_cast<const bf16x8*>((char*)shm + abase + (((b) * 2 + (h)) * 16384 + (m * 2 + k) * 1024))
; #define LDB(dst, b, h) _Pragma("unroll") for (int n = 0; n < 2; ++n) _Pragma("unroll") for (int k = 0; k < 2; ++k) \
;     dst[n][k] = *reinterpret_cast<const bf16x8*>((char*)shm + bbase + (((b) * 2 + (h)) * 16384 + (n * 2 + k) * 1024))
; template <bool SWAP>
; __device__ __forceinline__ void gemm_main(const u16* __restrict__ A, const u16* __restrict__ Bt, int brow, int bcol,
;                                           u16* shm, f32x4 (&acc)[2][2][4][2]) {
;     ...
;     LDB(B0, 0, 0); SCHED; LDA(At, 0, 0); STAGE(SA(1, 1), A, brow + HALF, t + 1);
;     WAIT_L(8); BAR; WAIT_L(0); MMA(0, 0, At, B0); BAR; SCHED;
;     LDB(B1, 0, 1); STAGE(SB(0, 0), Bt, bcol, t + 2);
;     BAR; WAIT_L(0); MMA(0, 1, At, B1); BAR;
;     LDA(At, 0, 1); STAGE(SA(0, 0), A, brow, t + 2);
;     BAR; WAIT_L(0); MMA(1, 0, At, B0); BAR; SCHED;
;     STAGE(SB(0, 1), Bt, bcol + HALF, t + 2);
;     WAIT_V(6); BAR; MMA(1, 1, At, B1); BAR;
;     LDB(B0, 1, 0); SCHED; LDA(At, 1, 0); STAGE(SA(0, 1), A, brow + HALF, t + 2);
.LBB0_564:
	ds_read_b128 v[168:171], v137 offset:1024
	ds_read_b128 v[176:179], v137 offset:3072
	ds_read_b128 v[184:187], v137 offset:5120
	ds_read_b128 v[194:197], v137 offset:7168
	v_add_u32_e32 v192, 0, v141
	v_add_u32_e32 v146, 0xc000, v192
	v_lshl_add_u64 v[230:231], s[0:1], 0, v[132:133]
	v_add_u32_e32 v147, 0xe000, v192
	v_lshl_add_u64 v[198:199], v[230:231], 0, s[8:9]
	s_add_u32 m0, s4, 0xc000
	v_lshl_add_u64 v[232:233], s[0:1], 0, v[134:135]
	global_load_lds_dwordx4 v[198:199], off
	v_lshl_add_u64 v[198:199], v[232:233], 0, s[8:9]
	s_add_u32 m0, s4, 0xe000
	s_nop 0
	global_load_lds_dwordx4 v[198:199], off
	s_waitcnt lgkmcnt(8)
	s_barrier
	s_waitcnt lgkmcnt(0)
	v_mfma_f32_16x16x32_bf16 v[124:127], v[148:151], v[164:167], v[124:127]
	v_mfma_f32_16x16x32_bf16 v[120:123], v[156:159], v[164:167], v[120:123]
	v_mfma_f32_16x16x32_bf16 v[116:119], v[148:151], v[172:175], v[116:119]
	v_mfma_f32_16x16x32_bf16 v[112:115], v[156:159], v[172:175], v[112:115]
	v_mfma_f32_16x16x32_bf16 v[108:111], v[148:151], v[180:183], v[108:111]
	v_mfma_f32_16x16x32_bf16 v[104:107], v[156:159], v[180:183], v[104:107]
	v_mfma_f32_16x16x32_bf16 v[100:103], v[148:151], v[188:191], v[100:103]
	v_mfma_f32_16x16x32_bf16 v[96:99], v[156:159], v[188:191], v[96:99]
	v_mfma_f32_16x16x32_bf16 v[124:127], v[152:155], v[168:171], v[124:127]
	v_mfma_f32_16x16x32_bf16 v[120:123], v[160:163], v[168:171], v[120:123]
	v_mfma_f32_16x16x32_bf16 v[116:119], v[152:155], v[176:179], v[116:119]
	v_mfma_f32_16x16x32_bf16 v[112:115], v[160:163], v[176:179], v[112:115]
	v_mfma_f32_16x16x32_bf16 v[108:111], v[152:155], v[184:187], v[108:111]
	v_mfma_f32_16x16x32_bf16 v[104:107], v[160:163], v[184:187], v[104:107]
	v_mfma_f32_16x16x32_bf16 v[100:103], v[152:155], v[194:197], v[100:103]
	v_mfma_f32_16x16x32_bf16 v[96:99], v[160:163], v[194:197], v[96:99]
	s_barrier
	ds_read_b128 v[198:201], v138 offset:16384
	ds_read_b128 v[202:205], v138 offset:17408
	ds_read_b128 v[206:209], v138 offset:18432
	ds_read_b128 v[226:229], v138 offset:19456
	v_lshl_add_u64 v[234:235], s[0:1], 0, v[128:129]
	v_lshl_add_u64 v[236:237], v[234:235], 0, s[12:13]
	s_add_u32 m0, s4, s28
	s_nop 0
	global_load_lds_dwordx4 v[236:237], off
	v_lshl_add_u64 v[236:237], s[0:1], 0, v[130:131]
	v_lshl_add_u64 v[238:239], v[236:237], 0, s[12:13]
	s_add_u32 m0, s4, s28
	s_add_u32 m0, m0, 0x2000
	s_nop 0
	global_load_lds_dwordx4 v[238:239], off
	s_barrier
	s_waitcnt lgkmcnt(0)
	v_mfma_f32_16x16x32_bf16 v[92:95], v[198:201], v[164:167], v[92:95]
	v_mfma_f32_16x16x32_bf16 v[88:91], v[206:209], v[164:167], v[88:91]
	v_mfma_f32_16x16x32_bf16 v[84:87], v[198:201], v[172:175], v[84:87]
	v_mfma_f32_16x16x32_bf16 v[80:83], v[206:209], v[172:175], v[80:83]
	v_mfma_f32_16x16x32_bf16 v[76:79], v[198:201], v[180:183], v[76:79]
	v_mfma_f32_16x16x32_bf16 v[72:75], v[206:209], v[180:183], v[72:75]
	v_mfma_f32_16x16x32_bf16 v[68:71], v[198:201], v[188:191], v[68:71]
	v_mfma_f32_16x16x32_bf16 v[64:67], v[206:209], v[188:191], v[64:67]
	v_mfma_f32_16x16x32_bf16 v[92:95], v[202:205], v[168:171], v[92:95]
	ds_read_b128 v[164:167], v137 offset:16384
	v_mfma_f32_16x16x32_bf16 v[88:91], v[226:229], v[168:171], v[88:91]
	v_mfma_f32_16x16x32_bf16 v[84:87], v[202:205], v[176:179], v[84:87]
	ds_read_b128 v[172:175], v137 offset:18432
	v_mfma_f32_16x16x32_bf16 v[80:83], v[226:229], v[176:179], v[80:83]
	v_mfma_f32_16x16x32_bf16 v[76:79], v[202:205], v[184:187], v[76:79]
	ds_read_b128 v[180:183], v137 offset:20480
	v_mfma_f32_16x16x32_bf16 v[72:75], v[226:229], v[184:187], v[72:75]
	v_mfma_f32_16x16x32_bf16 v[68:71], v[202:205], v[194:197], v[68:71]
	ds_read_b128 v[188:191], v137 offset:22528
	v_mfma_f32_16x16x32_bf16 v[64:67], v[226:229], v[194:197], v[64:67]
	s_barrier
	ds_read_b128 v[168:171], v137 offset:17408
	ds_read_b128 v[176:179], v137 offset:19456
	ds_read_b128 v[184:187], v137 offset:21504
	ds_read_b128 v[194:197], v137 offset:23552
	v_lshl_add_u64 v[238:239], v[230:231], 0, s[14:15]
	s_add_u32 m0, s4, 0x0
	s_nop 0
	global_load_lds_dwordx4 v[238:239], off
	v_lshl_add_u64 v[238:239], v[232:233], 0, s[14:15]
	s_add_u32 m0, s4, 0x2000
	s_nop 0
	global_load_lds_dwordx4 v[238:239], off
	s_waitcnt vmcnt(8)
	s_barrier
	s_waitcnt lgkmcnt(0)
	v_mfma_f32_16x16x32_bf16 v[60:63], v[148:151], v[164:167], v[60:63]
	v_mfma_f32_16x16x32_bf16 v[56:59], v[156:159], v[164:167], v[56:59]
	v_mfma_f32_16x16x32_bf16 v[52:55], v[148:151], v[172:175], v[52:55]
	v_mfma_f32_16x16x32_bf16 v[48:51], v[156:159], v[172:175], v[48:51]
	v_mfma_f32_16x16x32_bf16 v[44:47], v[148:151], v[180:183], v[44:47]
	v_mfma_f32_16x16x32_bf16 v[40:43], v[156:159], v[180:183], v[40:43]
	v_mfma_f32_16x16x32_bf16 v[36:39], v[148:151], v[188:191], v[36:39]
	v_mfma_f32_16x16x32_bf16 v[32:35], v[156:159], v[188:191], v[32:35]
	v_mfma_f32_16x16x32_bf16 v[60:63], v[152:155], v[168:171], v[60:63]
	v_mfma_f32_16x16x32_bf16 v[56:59], v[160:163], v[168:171], v[56:59]
	v_mfma_f32_16x16x32_bf16 v[52:55], v[152:155], v[176:179], v[52:55]
	v_mfma_f32_16x16x32_bf16 v[48:51], v[160:163], v[176:179], v[48:51]
	v_mfma_f32_16x16x32_bf16 v[44:47], v[152:155], v[184:187], v[44:47]
	v_mfma_f32_16x16x32_bf16 v[40:43], v[160:163], v[184:187], v[40:43]
	v_mfma_f32_16x16x32_bf16 v[36:39], v[152:155], v[194:197], v[36:39]
	v_mfma_f32_16x16x32_bf16 v[32:35], v[160:163], v[194:197], v[32:35]
	s_barrier
	ds_read_b128 v[148:151], v138 offset:32768
	ds_read_b128 v[152:155], v138 offset:33792
	ds_read_b128 v[156:159], v138 offset:34816
	ds_read_b128 v[160:163], v138 offset:35840
	v_lshl_add_u64 v[254:255], v[234:235], 0, s[16:17]
	s_add_u32 m0, s4, s29
	s_nop 0
	global_load_lds_dwordx4 v[254:255], off
	v_lshl_add_u64 v[254:255], v[236:237], 0, s[16:17]
	s_add_u32 m0, s4, s29
	s_add_u32 m0, m0, 0x2000
	s_nop 0
	global_load_lds_dwordx4 v[254:255], off
	s_waitcnt vmcnt(6)
	s_barrier
; #define WAIT_V(n) asm volatile("s_waitcnt vmcnt(" #n ")" ::: "memory")
; #define WAIT_L(n) asm volatile("s_waitcnt lgkmcnt(" #n ")" ::: "memory")
; #define BAR __builtin_amdgcn_s_barrier()
; #define SCHED __builtin_amdgcn_sched_barrier(0)
; #define STAGE(P, BASE, br, kt) do { const char* _g = (const char*)((BASE) + (size_t)(br) * GK + (kt) * BK); \
;     __builtin_amdgcn_global_load_lds((const unsigned*)(_g + voff0), (unsigned*)((char*)(P) + tx * 16), 16, 0, 0); \
;     __builtin_amdgcn_global_load_lds((const unsigned*)(_g + voff1), (unsigned*)((char*)(P) + tx * 16 + 8192), 16, 0, 0); } while (0)
; #define LDA(dst, b, h) _Pragma("unroll") for (int m = 0; m < 4; ++m) _Pragma("unroll") for (int k = 0; k < 2; ++k) \
;     dst[m][k] = *reinterpret_cast<const bf16x8*>((char*)shm + abase + (((b) * 2 + (h)) * 16384 + (m * 2 + k) * 1024))
; #define LDB(dst, b, h) _Pragma("unroll") for (int n = 0; n < 2; ++n) _Pragma("unroll") for (int k = 0; k < 2; ++k) \
;     dst[n][k] = *reinterpret_cast<const bf16x8*>((char*)shm + bbase + (((b) * 2 + (h)) * 16384 + (n * 2 + k) * 1024))
; template <bool SWAP>
; __device__ __forceinline__ void gemm_main(const u16* __restrict__ A, const u16* __restrict__ Bt, int brow, int bcol,
;                                           u16* shm, f32x4 (&acc)[2][2][4][2]) {
;     ...
;     WAIT_V(6); BAR; MMA(1, 1, At, B1); BAR;
;     LDB(B0, 1, 0); SCHED; LDA(At, 1, 0); STAGE(SA(0, 1), A, brow + HALF, t + 2);
;     WAIT_L(8); BAR; WAIT_L(0); MMA(0, 0, At, B0); BAR; SCHED;
;     LDB(B1, 1, 1); STAGE(SB(1, 0), Bt, bcol, t + 3);
;     BAR; WAIT_L(0); MMA(0, 1, At, B1); BAR;
;     LDA(At, 1, 1); STAGE(SA(1, 0), A, brow, t + 3);
	v_mfma_f32_16x16x32_bf16 v[28:31], v[198:201], v[164:167], v[28:31]
	v_mfma_f32_16x16x32_bf16 v[24:27], v[206:209], v[164:167], v[24:27]
	v_mfma_f32_16x16x32_bf16 v[20:23], v[198:201], v[172:175], v[20:23]
	v_mfma_f32_16x16x32_bf16 v[16:19], v[206:209], v[172:175], v[16:19]
	v_mfma_f32_16x16x32_bf16 v[12:15], v[198:201], v[180:183], v[12:15]
	v_mfma_f32_16x16x32_bf16 v[8:11], v[206:209], v[180:183], v[8:11]
	v_mfma_f32_16x16x32_bf16 v[4:7], v[198:201], v[188:191], v[4:7]
	v_mfma_f32_16x16x32_bf16 v[0:3], v[206:209], v[188:191], v[0:3]
	v_mfma_f32_16x16x32_bf16 v[28:31], v[202:205], v[168:171], v[28:31]
	ds_read_b128 v[164:167], v137 offset:32768
	v_mfma_f32_16x16x32_bf16 v[24:27], v[226:229], v[168:171], v[24:27]
	v_mfma_f32_16x16x32_bf16 v[20:23], v[202:205], v[176:179], v[20:23]
	ds_read_b128 v[172:175], v137 offset:34816
	v_mfma_f32_16x16x32_bf16 v[16:19], v[226:229], v[176:179], v[16:19]
	v_mfma_f32_16x16x32_bf16 v[12:15], v[202:205], v[184:187], v[12:15]
	ds_read_b128 v[180:183], v137 offset:36864
	v_mfma_f32_16x16x32_bf16 v[8:11], v[226:229], v[184:187], v[8:11]
	v_mfma_f32_16x16x32_bf16 v[4:7], v[202:205], v[194:197], v[4:7]
	ds_read_b128 v[188:191], v137 offset:38912
	v_mfma_f32_16x16x32_bf16 v[0:3], v[226:229], v[194:197], v[0:3]
	s_barrier
	ds_read_b128 v[168:171], v137 offset:33792
	ds_read_b128 v[176:179], v137 offset:35840
	ds_read_b128 v[184:187], v137 offset:37888
	ds_read_b128 v[194:197], v137 offset:39936
	v_lshl_add_u64 v[198:199], v[230:231], 0, s[18:19]
	s_add_u32 m0, s4, 0x4000
	s_nop 0
	global_load_lds_dwordx4 v[198:199], off
	v_lshl_add_u64 v[198:199], v[232:233], 0, s[18:19]
	s_add_u32 m0, s4, 0x6000
	s_nop 0
	global_load_lds_dwordx4 v[198:199], off
	s_waitcnt lgkmcnt(8)
	s_barrier
	s_waitcnt lgkmcnt(0)
	v_mfma_f32_16x16x32_bf16 v[124:127], v[148:151], v[164:167], v[124:127]
	v_mfma_f32_16x16x32_bf16 v[120:123], v[156:159], v[164:167], v[120:123]
	v_mfma_f32_16x16x32_bf16 v[116:119], v[148:151], v[172:175], v[116:119]
	v_mfma_f32_16x16x32_bf16 v[112:115], v[156:159], v[172:175], v[112:115]
	v_mfma_f32_16x16x32_bf16 v[108:111], v[148:151], v[180:183], v[108:111]
	v_mfma_f32_16x16x32_bf16 v[104:107], v[156:159], v[180:183], v[104:107]
	v_mfma_f32_16x16x32_bf16 v[100:103], v[148:151], v[188:191], v[100:103]
	v_mfma_f32_16x16x32_bf16 v[96:99], v[156:159], v[188:191], v[96:99]
	v_mfma_f32_16x16x32_bf16 v[124:127], v[152:155], v[168:171], v[124:127]
	v_mfma_f32_16x16x32_bf16 v[120:123], v[160:163], v[168:171], v[120:123]
	v_mfma_f32_16x16x32_bf16 v[116:119], v[152:155], v[176:179], v[116:119]
	v_mfma_f32_16x16x32_bf16 v[112:115], v[160:163], v[176:179], v[112:115]
	v_mfma_f32_16x16x32_bf16 v[108:111], v[152:155], v[184:187], v[108:111]
	v_mfma_f32_16x16x32_bf16 v[104:107], v[160:163], v[184:187], v[104:107]
	v_mfma_f32_16x16x32_bf16 v[100:103], v[152:155], v[194:197], v[100:103]
	v_mfma_f32_16x16x32_bf16 v[96:99], v[160:163], v[194:197], v[96:99]
	s_barrier
	ds_read_b128 v[198:201], v138 offset:49152
	ds_read_b128 v[202:205], v138 offset:50176
	ds_read_b128 v[206:209], v138 offset:51200
	ds_read_b128 v[226:229], v138 offset:52224
	v_lshl_add_u64 v[238:239], v[234:235], 0, s[24:25]
	s_add_u32 m0, s4, s30
	s_nop 0
	global_load_lds_dwordx4 v[238:239], off
	v_lshl_add_u64 v[238:239], v[236:237], 0, s[24:25]
	s_add_u32 m0, s4, s30
	s_add_u32 m0, m0, 0x2000
	s_nop 0
	global_load_lds_dwordx4 v[238:239], off
	s_barrier
	s_waitcnt lgkmcnt(0)
	v_mfma_f32_16x16x32_bf16 v[92:95], v[198:201], v[164:167], v[92:95]
	v_mfma_f32_16x16x32_bf16 v[88:91], v[206:209], v[164:167], v[88:91]
	v_mfma_f32_16x16x32_bf16 v[84:87], v[198:201], v[172:175], v[84:87]
	v_mfma_f32_16x16x32_bf16 v[80:83], v[206:209], v[172:175], v[80:83]
	v_mfma_f32_16x16x32_bf16 v[76:79], v[198:201], v[180:183], v[76:79]
	v_mfma_f32_16x16x32_bf16 v[72:75], v[206:209], v[180:183], v[72:75]
	v_mfma_f32_16x16x32_bf16 v[68:71], v[198:201], v[188:191], v[68:71]
	v_mfma_f32_16x16x32_bf16 v[64:67], v[206:209], v[188:191], v[64:67]
	v_mfma_f32_16x16x32_bf16 v[92:95], v[202:205], v[168:171], v[92:95]
	ds_read_b128 v[164:167], v137 offset:49152
	v_mfma_f32_16x16x32_bf16 v[88:91], v[226:229], v[168:171], v[88:91]
	v_mfma_f32_16x16x32_bf16 v[84:87], v[202:205], v[176:179], v[84:87]
	ds_read_b128 v[172:175], v137 offset:51200
	v_mfma_f32_16x16x32_bf16 v[80:83], v[226:229], v[176:179], v[80:83]
	v_mfma_f32_16x16x32_bf16 v[76:79], v[202:205], v[184:187], v[76:79]
	ds_read_b128 v[180:183], v137 offset:53248
	v_mfma_f32_16x16x32_bf16 v[72:75], v[226:229], v[184:187], v[72:75]
	v_mfma_f32_16x16x32_bf16 v[68:71], v[202:205], v[194:197], v[68:71]
	ds_read_b128 v[188:191], v137 offset:55296
	v_mfma_f32_16x16x32_bf16 v[64:67], v[226:229], v[194:197], v[64:67]
	s_barrier
	ds_read_b128 v[168:171], v137 offset:50176
	ds_read_b128 v[176:179], v137 offset:52224
	ds_read_b128 v[184:187], v137 offset:54272
	ds_read_b128 v[194:197], v137 offset:56320
	v_add_u32_e32 v225, 0x8000, v192
	v_lshl_add_u64 v[230:231], v[230:231], 0, vcc
	s_add_u32 m0, s4, 0x8000
	s_nop 0
	global_load_lds_dwordx4 v[230:231], off
	v_lshl_add_u64 v[230:231], v[232:233], 0, vcc
	s_add_u32 m0, s4, 0xa000
	s_nop 0
	global_load_lds_dwordx4 v[230:231], off
	s_waitcnt vmcnt(8)
	s_barrier
; #define WAIT_V(n) asm volatile("s_waitcnt vmcnt(" #n ")" ::: "memory")
; #define WAIT_L(n) asm volatile("s_waitcnt lgkmcnt(" #n ")" ::: "memory")
; #define BAR __builtin_amdgcn_s_barrier()
; #define SCHED __builtin_amdgcn_sched_barrier(0)
; #define STAGE(P, BASE, br, kt) do { const char* _g = (const char*)((BASE) + (size_t)(br) * GK + (kt) * BK); \
;     __builtin_amdgcn_global_load_lds((const unsigned*)(_g + voff0), (unsigned*)((char*)(P) + tx * 16), 16, 0, 0); \
;     __builtin_amdgcn_global_load_lds((const unsigned*)(_g + voff1), (unsigned*)((char*)(P) + tx * 16 + 8192), 16, 0, 0); } while (0)
; #define LDA(dst, b, h) _Pragma("unroll") for (int m = 0; m < 4; ++m) _Pragma("unroll") for (int k = 0; k < 2; ++k) \
;     dst[m][k] = *reinterpret_cast<const bf16x8*>((char*)shm + abase + (((b) * 2 + (h)) * 16384 + (m * 2 + k) * 1024))
; #define LDB(dst, b, h) _Pragma("unroll") for (int n = 0; n < 2; ++n) _Pragma("unroll") for (int k = 0; k < 2; ++k) \
;     dst[n][k] = *reinterpret_cast<const bf16x8*>((char*)shm + bbase + (((b) * 2 + (h)) * 16384 + (n * 2 + k) * 1024))
; template <bool SWAP>
; __device__ __forceinline__ void gemm_main(const u16* __restrict__ A, const u16* __restrict__ Bt, int brow, int bcol,
;                                           u16* shm, f32x4 (&acc)[2][2][4][2]) {
;     ...
;     LDA(At, 1, 1); STAGE(SA(1, 0), A, brow, t + 3);
;     BAR; WAIT_L(0); MMA(1, 0, At, B0); BAR; SCHED;
;     STAGE(SB(1, 1), Bt, bcol + HALF, t + 3);
;     WAIT_V(6); BAR; MMA(1, 1, At, B1); BAR;
;   }
;   { LDB(B0, 0, 0); LDA(At, 0, 0); STAGE(SA(1, 1), A, brow + HALF, nt - 1);
;     BAR; WAIT_L(0); MMA(0, 0, At, B0); BAR;
	s_waitcnt lgkmcnt(0)
	v_mfma_f32_16x16x32_bf16 v[60:63], v[148:151], v[164:167], v[60:63]
	v_mfma_f32_16x16x32_bf16 v[56:59], v[156:159], v[164:167], v[56:59]
	v_mfma_f32_16x16x32_bf16 v[52:55], v[148:151], v[172:175], v[52:55]
	v_mfma_f32_16x16x32_bf16 v[48:51], v[156:159], v[172:175], v[48:51]
	v_mfma_f32_16x16x32_bf16 v[44:47], v[148:151], v[180:183], v[44:47]
	v_mfma_f32_16x16x32_bf16 v[40:43], v[156:159], v[180:183], v[40:43]
	v_mfma_f32_16x16x32_bf16 v[36:39], v[148:151], v[188:191], v[36:39]
	v_mfma_f32_16x16x32_bf16 v[32:35], v[156:159], v[188:191], v[32:35]
	v_mfma_f32_16x16x32_bf16 v[60:63], v[152:155], v[168:171], v[60:63]
	v_mfma_f32_16x16x32_bf16 v[56:59], v[160:163], v[168:171], v[56:59]
	v_mfma_f32_16x16x32_bf16 v[52:55], v[152:155], v[176:179], v[52:55]
	v_mfma_f32_16x16x32_bf16 v[48:51], v[160:163], v[176:179], v[48:51]
	v_mfma_f32_16x16x32_bf16 v[44:47], v[152:155], v[184:187], v[44:47]
	v_mfma_f32_16x16x32_bf16 v[40:43], v[160:163], v[184:187], v[40:43]
	v_mfma_f32_16x16x32_bf16 v[36:39], v[152:155], v[194:197], v[36:39]
	v_mfma_f32_16x16x32_bf16 v[32:35], v[160:163], v[194:197], v[32:35]
	s_barrier
	ds_read_b128 v[148:151], v138
	ds_read_b128 v[152:155], v138 offset:1024
	ds_read_b128 v[156:159], v138 offset:2048
	ds_read_b128 v[160:163], v138 offset:3072
	v_lshl_add_u64 v[254:255], v[234:235], 0, s[42:43]
	s_add_u32 m0, s4, s31
	s_nop 0
	global_load_lds_dwordx4 v[254:255], off
	v_lshl_add_u64 v[254:255], v[236:237], 0, s[42:43]
	s_add_u32 m0, s4, s31
	s_add_u32 m0, m0, 0x2000
	s_nop 0
	global_load_lds_dwordx4 v[254:255], off
	s_waitcnt vmcnt(6)
	s_barrier
	v_mfma_f32_16x16x32_bf16 v[28:31], v[198:201], v[164:167], v[28:31]
	v_mfma_f32_16x16x32_bf16 v[24:27], v[206:209], v[164:167], v[24:27]
	v_mfma_f32_16x16x32_bf16 v[20:23], v[198:201], v[172:175], v[20:23]
	v_mfma_f32_16x16x32_bf16 v[16:19], v[206:209], v[172:175], v[16:19]
	v_mfma_f32_16x16x32_bf16 v[12:15], v[198:201], v[180:183], v[12:15]
	v_mfma_f32_16x16x32_bf16 v[8:11], v[206:209], v[180:183], v[8:11]
	v_mfma_f32_16x16x32_bf16 v[4:7], v[198:201], v[188:191], v[4:7]
	v_mfma_f32_16x16x32_bf16 v[0:3], v[206:209], v[188:191], v[0:3]
	v_mfma_f32_16x16x32_bf16 v[28:31], v[202:205], v[168:171], v[28:31]
	ds_read_b128 v[164:167], v137
	v_mfma_f32_16x16x32_bf16 v[24:27], v[226:229], v[168:171], v[24:27]
	v_mfma_f32_16x16x32_bf16 v[20:23], v[202:205], v[176:179], v[20:23]
	ds_read_b128 v[172:175], v137 offset:2048
	v_mfma_f32_16x16x32_bf16 v[16:19], v[226:229], v[176:179], v[16:19]
	s_add_i32 s3, s3, 2
	s_add_u32 s0, s0, 0x100
	s_addc_u32 s1, s1, 0
	s_cmp_lt_u32 s3, 28
	v_mfma_f32_16x16x32_bf16 v[12:15], v[202:205], v[184:187], v[12:15]
	ds_read_b128 v[180:183], v137 offset:4096
	v_mfma_f32_16x16x32_bf16 v[8:11], v[226:229], v[184:187], v[8:11]
	v_mfma_f32_16x16x32_bf16 v[4:7], v[202:205], v[194:197], v[4:7]
	ds_read_b128 v[188:191], v137 offset:6144
	v_mfma_f32_16x16x32_bf16 v[0:3], v[226:229], v[194:197], v[0:3]
	s_barrier
	s_cbranch_scc1 .LBB0_564
	s_and_b32 s0, s2, 0xffffe0
	s_and_b32 s1, s54, 31
	s_or_b32 s0, s0, s1
	s_lshl_b32 s8, s0, 8
	v_lshlrev_b32_e32 v128, 3, v139
	v_lshlrev_b32_e32 v129, 5, v139
	v_and_b32_e32 v128, 0xffff0, v128
	v_and_b32_e32 v129, 32, v129
	s_or_b32 s0, s8, 0x80
	v_add_u32_e32 v129, v129, v142
	v_add_lshl_u32 v128, v140, v128, 12
	s_ashr_i32 s1, s0, 31
	v_lshl_add_u32 v192, v129, 1, v128
	v_lshlrev_b32_e32 v128, 3, v143
	v_lshlrev_b32_e32 v129, 5, v143
	s_lshl_b64 s[12:13], s[0:1], 12
	v_readlane_b32 s0, v251, 36
	v_and_b32_e32 v128, 0xffff0, v128
	v_and_b32_e32 v129, 32, v129
	v_readlane_b32 s1, v251, 37
	s_add_u32 s0, s0, s12
	v_add_u32_e32 v129, v129, v145
	v_add_lshl_u32 v128, v144, v128, 12
	s_addc_u32 s1, s1, s13
	v_lshl_add_u32 v144, v129, 1, v128
	v_mov_b32_e32 v145, v193
	v_lshl_add_u64 v[184:185], s[0:1], 0, v[192:193]
	s_mov_b64 s[4:5], 0xf80
	v_readfirstlane_b32 s2, v146
	v_lshl_add_u64 v[184:185], v[184:185], 0, s[4:5]
	s_mov_b32 m0, s2
	v_lshl_add_u64 v[144:145], s[0:1], 0, v[144:145]
	v_readfirstlane_b32 s0, v147
	ds_read_b128 v[128:131], v138
	ds_read_b128 v[132:135], v138 offset:1024
	ds_read_b128 v[140:143], v138 offset:2048
	ds_read_b128 v[148:151], v138 offset:3072
	ds_read_b128 v[152:155], v137
	ds_read_b128 v[156:159], v137 offset:1024
	ds_read_b128 v[160:163], v137 offset:2048
	ds_read_b128 v[164:167], v137 offset:3072
	ds_read_b128 v[168:171], v137 offset:4096
	ds_read_b128 v[172:175], v137 offset:5120
	ds_read_b128 v[176:179], v137 offset:6144
	ds_read_b128 v[180:183], v137 offset:7168
	global_load_lds_dwordx4 v[184:185], off
	v_lshl_add_u64 v[144:145], v[144:145], 0, s[4:5]
	s_mov_b32 m0, s0
	s_nop 0
	global_load_lds_dwordx4 v[144:145], off
	s_barrier
	s_waitcnt lgkmcnt(0)
	s_setprio 1
	s_waitcnt lgkmcnt(0)
	v_mfma_f32_16x16x32_bf16 v[124:127], v[128:131], v[152:155], v[124:127]
	v_mfma_f32_16x16x32_bf16 v[116:119], v[128:131], v[160:163], v[116:119]
	v_mfma_f32_16x16x32_bf16 v[112:115], v[140:143], v[160:163], v[112:115]
	v_mfma_f32_16x16x32_bf16 v[108:111], v[128:131], v[168:171], v[108:111]
	v_mfma_f32_16x16x32_bf16 v[104:107], v[140:143], v[168:171], v[104:107]
	v_mfma_f32_16x16x32_bf16 v[100:103], v[128:131], v[176:179], v[100:103]
	v_mfma_f32_16x16x32_bf16 v[96:99], v[140:143], v[176:179], v[96:99]
	v_mfma_f32_16x16x32_bf16 v[124:127], v[132:135], v[156:159], v[124:127]
	v_mfma_f32_16x16x32_bf16 v[120:123], v[140:143], v[152:155], v[120:123]
	v_mfma_f32_16x16x32_bf16 v[116:119], v[132:135], v[164:167], v[116:119]
	v_mfma_f32_16x16x32_bf16 v[112:115], v[148:151], v[164:167], v[112:115]
	v_mfma_f32_16x16x32_bf16 v[108:111], v[132:135], v[172:175], v[108:111]
	v_mfma_f32_16x16x32_bf16 v[104:107], v[148:151], v[172:175], v[104:107]
	v_mfma_f32_16x16x32_bf16 v[100:103], v[132:135], v[180:183], v[100:103]
	v_mfma_f32_16x16x32_bf16 v[96:99], v[148:151], v[180:183], v[96:99]
	v_mfma_f32_16x16x32_bf16 v[120:123], v[148:151], v[156:159], v[120:123]
	s_setprio 0
	s_barrier
; #define WAIT_V(n) asm volatile("s_waitcnt vmcnt(" #n ")" ::: "memory")
; #define WAIT_L(n) asm volatile("s_waitcnt lgkmcnt(" #n ")" ::: "memory")
; #define BAR __builtin_amdgcn_s_barrier()
; #define LDA(dst, b, h) _Pragma("unroll") for (int m = 0; m < 4; ++m) _Pragma("unroll") for (int k = 0; k < 2; ++k) \
;     dst[m][k] = *reinterpret_cast<const bf16x8*>((char*)shm + abase + (((b) * 2 + (h)) * 16384 + (m * 2 + k) * 1024))
; #define LDB(dst, b, h) _Pragma("unroll") for (int n = 0; n < 2; ++n) _Pragma("unroll") for (int k = 0; k < 2; ++k) \
;     dst[n][k] = *reinterpret_cast<const bf16x8*>((char*)shm + bbase + (((b) * 2 + (h)) * 16384 + (n * 2 + k) * 1024))
; template <bool SWAP>
; __device__ __forceinline__ void gemm_main(const u16* __restrict__ A, const u16* __restrict__ Bt, int brow, int bcol,
;                                           u16* shm, f32x4 (&acc)[2][2][4][2]) {
;     ...
;     BAR; WAIT_L(0); MMA(0, 0, At, B0); BAR;
;     LDB(B1, 0, 1); BAR; WAIT_L(0); MMA(0, 1, At, B1); BAR;
;     LDA(At, 0, 1); WAIT_V(4); BAR; WAIT_L(0); MMA(1, 0, At, B0); MMA(1, 1, At, B1); BAR; }
;   { LDB(B0, 1, 0); LDA(At, 1, 0); WAIT_V(2); BAR; WAIT_L(0); MMA(0, 0, At, B0); BAR;
	ds_read_b128 v[144:147], v138 offset:16384
	ds_read_b128 v[184:187], v138 offset:17408
	ds_read_b128 v[188:191], v138 offset:18432
	ds_read_b128 v[194:197], v138 offset:19456
	s_barrier
	s_waitcnt lgkmcnt(0)
	s_setprio 1
	s_waitcnt lgkmcnt(0)
	v_mfma_f32_16x16x32_bf16 v[92:95], v[144:147], v[152:155], v[92:95]
	v_mfma_f32_16x16x32_bf16 v[88:91], v[188:191], v[152:155], v[88:91]
	v_mfma_f32_16x16x32_bf16 v[84:87], v[144:147], v[160:163], v[84:87]
	v_mfma_f32_16x16x32_bf16 v[80:83], v[188:191], v[160:163], v[80:83]
	v_mfma_f32_16x16x32_bf16 v[76:79], v[144:147], v[168:171], v[76:79]
	v_mfma_f32_16x16x32_bf16 v[72:75], v[188:191], v[168:171], v[72:75]
	v_mfma_f32_16x16x32_bf16 v[68:71], v[144:147], v[176:179], v[68:71]
	v_mfma_f32_16x16x32_bf16 v[64:67], v[188:191], v[176:179], v[64:67]
	v_mfma_f32_16x16x32_bf16 v[92:95], v[184:187], v[156:159], v[92:95]
	v_mfma_f32_16x16x32_bf16 v[88:91], v[194:197], v[156:159], v[88:91]
	v_mfma_f32_16x16x32_bf16 v[84:87], v[184:187], v[164:167], v[84:87]
	v_mfma_f32_16x16x32_bf16 v[80:83], v[194:197], v[164:167], v[80:83]
	v_mfma_f32_16x16x32_bf16 v[76:79], v[184:187], v[172:175], v[76:79]
	v_mfma_f32_16x16x32_bf16 v[72:75], v[194:197], v[172:175], v[72:75]
	v_mfma_f32_16x16x32_bf16 v[68:71], v[184:187], v[180:183], v[68:71]
	v_mfma_f32_16x16x32_bf16 v[64:67], v[194:197], v[180:183], v[64:67]
	s_setprio 0
	s_barrier
	ds_read_b128 v[152:155], v137 offset:16384
	ds_read_b128 v[156:159], v137 offset:17408
	ds_read_b128 v[160:163], v137 offset:18432
	ds_read_b128 v[164:167], v137 offset:19456
	ds_read_b128 v[168:171], v137 offset:20480
	ds_read_b128 v[172:175], v137 offset:21504
	ds_read_b128 v[176:179], v137 offset:22528
	ds_read_b128 v[180:183], v137 offset:23552
	s_waitcnt vmcnt(4)
	s_barrier
	s_waitcnt lgkmcnt(0)
	s_setprio 1
	s_waitcnt lgkmcnt(0)
	v_mfma_f32_16x16x32_bf16 v[60:63], v[128:131], v[152:155], v[60:63]
	v_mfma_f32_16x16x32_bf16 v[56:59], v[140:143], v[152:155], v[56:59]
	v_mfma_f32_16x16x32_bf16 v[52:55], v[128:131], v[160:163], v[52:55]
	v_mfma_f32_16x16x32_bf16 v[48:51], v[140:143], v[160:163], v[48:51]
	v_mfma_f32_16x16x32_bf16 v[44:47], v[128:131], v[168:171], v[44:47]
	v_mfma_f32_16x16x32_bf16 v[40:43], v[140:143], v[168:171], v[40:43]
	v_mfma_f32_16x16x32_bf16 v[36:39], v[128:131], v[176:179], v[36:39]
	v_mfma_f32_16x16x32_bf16 v[32:35], v[140:143], v[176:179], v[32:35]
	v_mfma_f32_16x16x32_bf16 v[60:63], v[132:135], v[156:159], v[60:63]
	v_mfma_f32_16x16x32_bf16 v[56:59], v[148:151], v[156:159], v[56:59]
	v_mfma_f32_16x16x32_bf16 v[52:55], v[132:135], v[164:167], v[52:55]
	v_mfma_f32_16x16x32_bf16 v[48:51], v[148:151], v[164:167], v[48:51]
	v_mfma_f32_16x16x32_bf16 v[44:47], v[132:135], v[172:175], v[44:47]
	v_mfma_f32_16x16x32_bf16 v[40:43], v[148:151], v[172:175], v[40:43]
	v_mfma_f32_16x16x32_bf16 v[36:39], v[132:135], v[180:183], v[36:39]
	v_mfma_f32_16x16x32_bf16 v[32:35], v[148:151], v[180:183], v[32:35]
	s_setprio 0
	s_setprio 1
	v_mfma_f32_16x16x32_bf16 v[28:31], v[144:147], v[152:155], v[28:31]
	v_mfma_f32_16x16x32_bf16 v[24:27], v[188:191], v[152:155], v[24:27]
	v_mfma_f32_16x16x32_bf16 v[20:23], v[144:147], v[160:163], v[20:23]
	v_mfma_f32_16x16x32_bf16 v[16:19], v[188:191], v[160:163], v[16:19]
	v_mfma_f32_16x16x32_bf16 v[12:15], v[144:147], v[168:171], v[12:15]
	v_mfma_f32_16x16x32_bf16 v[8:11], v[188:191], v[168:171], v[8:11]
	v_mfma_f32_16x16x32_bf16 v[4:7], v[144:147], v[176:179], v[4:7]
	v_mfma_f32_16x16x32_bf16 v[0:3], v[188:191], v[176:179], v[0:3]
	v_mfma_f32_16x16x32_bf16 v[28:31], v[184:187], v[156:159], v[28:31]
	v_mfma_f32_16x16x32_bf16 v[24:27], v[194:197], v[156:159], v[24:27]
	v_mfma_f32_16x16x32_bf16 v[20:23], v[184:187], v[164:167], v[20:23]
	v_mfma_f32_16x16x32_bf16 v[16:19], v[194:197], v[164:167], v[16:19]
	v_mfma_f32_16x16x32_bf16 v[12:15], v[184:187], v[172:175], v[12:15]
	v_mfma_f32_16x16x32_bf16 v[8:11], v[194:197], v[172:175], v[8:11]
	v_mfma_f32_16x16x32_bf16 v[4:7], v[184:187], v[180:183], v[4:7]
	v_mfma_f32_16x16x32_bf16 v[0:3], v[194:197], v[180:183], v[0:3]
	s_setprio 0
	s_barrier
	ds_read_b128 v[132:135], v138 offset:32768
	ds_read_b128 v[140:143], v138 offset:33792
	ds_read_b128 v[144:147], v138 offset:34816
	ds_read_b128 v[148:151], v138 offset:35840
	ds_read_b128 v[152:155], v137 offset:32768
	ds_read_b128 v[156:159], v137 offset:33792
	ds_read_b128 v[160:163], v137 offset:34816
	ds_read_b128 v[164:167], v137 offset:35840
	ds_read_b128 v[168:171], v137 offset:36864
	ds_read_b128 v[172:175], v137 offset:37888
	ds_read_b128 v[176:179], v137 offset:38912
	ds_read_b128 v[180:183], v137 offset:39936
	s_waitcnt vmcnt(2)
	s_barrier
; #define WAIT_V(n) asm volatile("s_waitcnt vmcnt(" #n ")" ::: "memory")
; #define WAIT_L(n) asm volatile("s_waitcnt lgkmcnt(" #n ")" ::: "memory")
; #define BAR __builtin_amdgcn_s_barrier()
; #define LDA(dst, b, h) _Pragma("unroll") for (int m = 0; m < 4; ++m) _Pragma("unroll") for (int k = 0; k < 2; ++k) \
;     dst[m][k] = *reinterpret_cast<const bf16x8*>((char*)shm + abase + (((b) * 2 + (h)) * 16384 + (m * 2 + k) * 1024))
; #define LDB(dst, b, h) _Pragma("unroll") for (int n = 0; n < 2; ++n) _Pragma("unroll") for (int k = 0; k < 2; ++k) \
;     dst[n][k] = *reinterpret_cast<const bf16x8*>((char*)shm + bbase + (((b) * 2 + (h)) * 16384 + (n * 2 + k) * 1024))
; template <bool SWAP>
; __device__ __forceinline__ void gemm_main(const u16* __restrict__ A, const u16* __restrict__ Bt, int brow, int bcol,
;                                           u16* shm, f32x4 (&acc)[2][2][4][2]) {
;     ...
;   { LDB(B0, 1, 0); LDA(At, 1, 0); WAIT_V(2); BAR; WAIT_L(0); MMA(0, 0, At, B0); BAR;
;     LDB(B1, 1, 1); WAIT_V(0); BAR; WAIT_L(0); MMA(0, 1, At, B1); BAR;
;     LDA(At, 1, 1); BAR; WAIT_L(0); MMA(1, 0, At, B0); MMA(1, 1, At, B1); BAR; }
;   if (wr == 0) BAR;
	s_waitcnt lgkmcnt(0)
	s_setprio 1
	s_waitcnt lgkmcnt(0)
	v_mfma_f32_16x16x32_bf16 v[124:127], v[132:135], v[152:155], v[124:127]
	v_mfma_f32_16x16x32_bf16 v[120:123], v[144:147], v[152:155], v[120:123]
	v_mfma_f32_16x16x32_bf16 v[116:119], v[132:135], v[160:163], v[116:119]
	v_mfma_f32_16x16x32_bf16 v[112:115], v[144:147], v[160:163], v[112:115]
	v_mfma_f32_16x16x32_bf16 v[108:111], v[132:135], v[168:171], v[108:111]
	v_mfma_f32_16x16x32_bf16 v[104:107], v[144:147], v[168:171], v[104:107]
	v_mfma_f32_16x16x32_bf16 v[100:103], v[132:135], v[176:179], v[100:103]
	v_mfma_f32_16x16x32_bf16 v[96:99], v[144:147], v[176:179], v[96:99]
	v_mfma_f32_16x16x32_bf16 v[128:131], v[140:143], v[156:159], v[124:127]
	v_mfma_f32_16x16x32_bf16 v[124:127], v[148:151], v[156:159], v[120:123]
	v_mfma_f32_16x16x32_bf16 v[116:119], v[140:143], v[164:167], v[116:119]
	v_mfma_f32_16x16x32_bf16 v[112:115], v[148:151], v[164:167], v[112:115]
	v_mfma_f32_16x16x32_bf16 v[108:111], v[140:143], v[172:175], v[108:111]
	v_mfma_f32_16x16x32_bf16 v[104:107], v[148:151], v[172:175], v[104:107]
	v_mfma_f32_16x16x32_bf16 v[100:103], v[140:143], v[180:183], v[100:103]
	v_mfma_f32_16x16x32_bf16 v[96:99], v[148:151], v[180:183], v[96:99]
	s_setprio 0
	s_barrier
	ds_read_b128 v[120:123], v138 offset:49152
	ds_read_b128 v[184:187], v138 offset:50176
	ds_read_b128 v[188:191], v138 offset:51200
	ds_read_b128 v[194:197], v138 offset:52224
	s_waitcnt vmcnt(0)
	s_barrier
	s_waitcnt lgkmcnt(0)
	s_setprio 1
	s_waitcnt lgkmcnt(0)
	v_mfma_f32_16x16x32_bf16 v[92:95], v[120:123], v[152:155], v[92:95]
	v_mfma_f32_16x16x32_bf16 v[88:91], v[188:191], v[152:155], v[88:91]
	v_mfma_f32_16x16x32_bf16 v[84:87], v[120:123], v[160:163], v[84:87]
	v_mfma_f32_16x16x32_bf16 v[80:83], v[188:191], v[160:163], v[80:83]
	v_mfma_f32_16x16x32_bf16 v[76:79], v[120:123], v[168:171], v[76:79]
	v_mfma_f32_16x16x32_bf16 v[72:75], v[188:191], v[168:171], v[72:75]
	v_mfma_f32_16x16x32_bf16 v[68:71], v[120:123], v[176:179], v[68:71]
	v_mfma_f32_16x16x32_bf16 v[64:67], v[188:191], v[176:179], v[64:67]
	v_mfma_f32_16x16x32_bf16 v[92:95], v[184:187], v[156:159], v[92:95]
	v_mfma_f32_16x16x32_bf16 v[88:91], v[194:197], v[156:159], v[88:91]
	v_mfma_f32_16x16x32_bf16 v[84:87], v[184:187], v[164:167], v[84:87]
	v_mfma_f32_16x16x32_bf16 v[80:83], v[194:197], v[164:167], v[80:83]
	v_mfma_f32_16x16x32_bf16 v[76:79], v[184:187], v[172:175], v[76:79]
	v_mfma_f32_16x16x32_bf16 v[72:75], v[194:197], v[172:175], v[72:75]
	v_mfma_f32_16x16x32_bf16 v[68:71], v[184:187], v[180:183], v[68:71]
	v_mfma_f32_16x16x32_bf16 v[64:67], v[194:197], v[180:183], v[64:67]
	s_setprio 0
	s_barrier
	ds_read_b128 v[152:155], v137 offset:49152
	ds_read_b128 v[156:159], v137 offset:50176
	ds_read_b128 v[160:163], v137 offset:51200
	ds_read_b128 v[164:167], v137 offset:52224
	ds_read_b128 v[168:171], v137 offset:53248
	ds_read_b128 v[172:175], v137 offset:54272
	ds_read_b128 v[176:179], v137 offset:55296
	ds_read_b128 v[180:183], v137 offset:56320
	s_barrier
	s_waitcnt lgkmcnt(0)
	s_setprio 1
	s_waitcnt lgkmcnt(0)
	v_mfma_f32_16x16x32_bf16 v[60:63], v[132:135], v[152:155], v[60:63]
	v_mfma_f32_16x16x32_bf16 v[56:59], v[144:147], v[152:155], v[56:59]
	v_mfma_f32_16x16x32_bf16 v[52:55], v[132:135], v[160:163], v[52:55]
	v_mfma_f32_16x16x32_bf16 v[48:51], v[144:147], v[160:163], v[48:51]
	v_mfma_f32_16x16x32_bf16 v[44:47], v[132:135], v[168:171], v[44:47]
	v_mfma_f32_16x16x32_bf16 v[40:43], v[144:147], v[168:171], v[40:43]
	v_mfma_f32_16x16x32_bf16 v[36:39], v[132:135], v[176:179], v[36:39]
	v_mfma_f32_16x16x32_bf16 v[32:35], v[144:147], v[176:179], v[32:35]
	v_mfma_f32_16x16x32_bf16 v[60:63], v[140:143], v[156:159], v[60:63]
	v_mfma_f32_16x16x32_bf16 v[56:59], v[148:151], v[156:159], v[56:59]
	v_mfma_f32_16x16x32_bf16 v[52:55], v[140:143], v[164:167], v[52:55]
	v_mfma_f32_16x16x32_bf16 v[48:51], v[148:151], v[164:167], v[48:51]
	v_mfma_f32_16x16x32_bf16 v[44:47], v[140:143], v[172:175], v[44:47]
	v_mfma_f32_16x16x32_bf16 v[40:43], v[148:151], v[172:175], v[40:43]
	v_mfma_f32_16x16x32_bf16 v[36:39], v[140:143], v[180:183], v[36:39]
	v_mfma_f32_16x16x32_bf16 v[32:35], v[148:151], v[180:183], v[32:35]
	s_setprio 0
	s_setprio 1
	v_mfma_f32_16x16x32_bf16 v[28:31], v[120:123], v[152:155], v[28:31]
	v_mfma_f32_16x16x32_bf16 v[24:27], v[188:191], v[152:155], v[24:27]
	v_mfma_f32_16x16x32_bf16 v[20:23], v[120:123], v[160:163], v[20:23]
	v_mfma_f32_16x16x32_bf16 v[16:19], v[188:191], v[160:163], v[16:19]
	v_mfma_f32_16x16x32_bf16 v[12:15], v[120:123], v[168:171], v[12:15]
	v_mfma_f32_16x16x32_bf16 v[8:11], v[188:191], v[168:171], v[8:11]
	v_mfma_f32_16x16x32_bf16 v[4:7], v[120:123], v[176:179], v[4:7]
	v_mfma_f32_16x16x32_bf16 v[0:3], v[188:191], v[176:179], v[0:3]
	v_mfma_f32_16x16x32_bf16 v[28:31], v[184:187], v[156:159], v[28:31]
	v_mfma_f32_16x16x32_bf16 v[24:27], v[194:197], v[156:159], v[24:27]
	v_mfma_f32_16x16x32_bf16 v[20:23], v[184:187], v[164:167], v[20:23]
	v_mfma_f32_16x16x32_bf16 v[16:19], v[194:197], v[164:167], v[16:19]
	v_mfma_f32_16x16x32_bf16 v[12:15], v[184:187], v[172:175], v[12:15]
	v_mfma_f32_16x16x32_bf16 v[8:11], v[194:197], v[172:175], v[8:11]
	v_mfma_f32_16x16x32_bf16 v[4:7], v[184:187], v[180:183], v[4:7]
	v_mfma_f32_16x16x32_bf16 v[0:3], v[194:197], v[180:183], v[0:3]
	s_setprio 0
	s_movk_i32 s0, 0x100
	v_cmp_gt_u32_e32 vcc, s0, v136
	s_barrier
	s_and_saveexec_b64 s[0:1], vcc
	s_cbranch_execz .LBB0_567
	s_barrier

; #define WAIT_V(n) asm volatile("s_waitcnt vmcnt(" #n ")" ::: "memory")
; #define WAIT_L(n) asm volatile("s_waitcnt lgkmcnt(" #n ")" ::: "memory")
; #define BAR __builtin_amdgcn_s_barrier()
; #define SCHED __builtin_amdgcn_sched_barrier(0)
; #define STAGE(P, BASE, br, kt) do { const char* _g = (const char*)((BASE) + (size_t)(br) * GK + (kt) * BK); \
;     __builtin_amdgcn_global_load_lds((const unsigned*)(_g + voff0), (unsigned*)((char*)(P) + tx * 16), 16, 0, 0); \
;     __builtin_amdgcn_global_load_lds((const unsigned*)(_g + voff1), (unsigned*)((char*)(P) + tx * 16 + 8192), 16, 0, 0); } while (0)
; #define LDA(dst, b, h) _Pragma("unroll") for (int m = 0; m < 4; ++m) _Pragma("unroll") for (int k = 0; k < 2; ++k) \
;     dst[m][k] = *reinterpret_cast<const bf16x8*>((char*)shm + abase + (((b) * 2 + (h)) * 16384 + (m * 2 + k) * 1024))
; #define LDB(dst, b, h) _Pragma("unroll") for (int n = 0; n < 2; ++n) _Pragma("unroll") for (int k = 0; k < 2; ++k) \
;     dst[n][k] = *reinterpret_cast<const bf16x8*>((char*)shm + bbase + (((b) * 2 + (h)) * 16384 + (n * 2 + k) * 1024))
; template <bool SWAP>
; __device__ __forceinline__ void gemm_main(const u16* __restrict__ A, const u16* __restrict__ Bt, int brow, int bcol,
;                                           u16* shm, f32x4 (&acc)[2][2][4][2]) {
;     ...
;     LDB(B0, 0, 0); SCHED; LDA(At, 0, 0); STAGE(SA(1, 1), A, brow + HALF, t + 1);
;     WAIT_L(8); BAR; WAIT_L(0); MMA(0, 0, At, B0); BAR; SCHED;
;     LDB(B1, 0, 1); STAGE(SB(0, 0), Bt, bcol, t + 2);
;     BAR; WAIT_L(0); MMA(0, 1, At, B1); BAR;
;     LDA(At, 0, 1); STAGE(SA(0, 0), A, brow, t + 2);
;     BAR; WAIT_L(0); MMA(1, 0, At, B0); BAR; SCHED;
;     STAGE(SB(0, 1), Bt, bcol + HALF, t + 2);
;     WAIT_V(6); BAR; MMA(1, 1, At, B1); BAR;
;     LDB(B0, 1, 0); SCHED; LDA(At, 1, 0); STAGE(SA(0, 1), A, brow + HALF, t + 2);
.LBB0_570:
	ds_read_b128 v[168:171], v137 offset:1024
	ds_read_b128 v[176:179], v137 offset:3072
	ds_read_b128 v[184:187], v137 offset:5120
	ds_read_b128 v[194:197], v137 offset:7168
	v_add_u32_e32 v192, 0, v140
	v_add_u32_e32 v146, 0xc000, v192
	v_lshl_add_u64 v[230:231], vcc, 0, v[132:133]
	v_add_u32_e32 v147, 0xe000, v192
	v_lshl_add_u64 v[198:199], v[230:231], 0, s[14:15]
	s_add_u32 m0, s24, 0xc000
	v_lshl_add_u64 v[232:233], vcc, 0, v[134:135]
	global_load_lds_dwordx4 v[198:199], off
	v_lshl_add_u64 v[198:199], v[232:233], 0, s[14:15]
	s_add_u32 m0, s24, 0xe000
	s_nop 0
	global_load_lds_dwordx4 v[198:199], off
	s_waitcnt lgkmcnt(8)
	s_barrier
	s_waitcnt lgkmcnt(0)
	v_mfma_f32_16x16x32_bf16 v[124:127], v[148:151], v[164:167], v[124:127]
	v_mfma_f32_16x16x32_bf16 v[120:123], v[156:159], v[164:167], v[120:123]
	v_mfma_f32_16x16x32_bf16 v[116:119], v[148:151], v[172:175], v[116:119]
	v_mfma_f32_16x16x32_bf16 v[112:115], v[156:159], v[172:175], v[112:115]
	v_mfma_f32_16x16x32_bf16 v[108:111], v[148:151], v[180:183], v[108:111]
	v_mfma_f32_16x16x32_bf16 v[104:107], v[156:159], v[180:183], v[104:107]
	v_mfma_f32_16x16x32_bf16 v[100:103], v[148:151], v[188:191], v[100:103]
	v_mfma_f32_16x16x32_bf16 v[96:99], v[156:159], v[188:191], v[96:99]
	v_mfma_f32_16x16x32_bf16 v[124:127], v[152:155], v[168:171], v[124:127]
	v_mfma_f32_16x16x32_bf16 v[120:123], v[160:163], v[168:171], v[120:123]
	v_mfma_f32_16x16x32_bf16 v[116:119], v[152:155], v[176:179], v[116:119]
	v_mfma_f32_16x16x32_bf16 v[112:115], v[160:163], v[176:179], v[112:115]
	v_mfma_f32_16x16x32_bf16 v[108:111], v[152:155], v[184:187], v[108:111]
	v_mfma_f32_16x16x32_bf16 v[104:107], v[160:163], v[184:187], v[104:107]
	v_mfma_f32_16x16x32_bf16 v[100:103], v[152:155], v[194:197], v[100:103]
	v_mfma_f32_16x16x32_bf16 v[96:99], v[160:163], v[194:197], v[96:99]
	s_barrier
	ds_read_b128 v[198:201], v138 offset:16384
	ds_read_b128 v[202:205], v138 offset:17408
	ds_read_b128 v[206:209], v138 offset:18432
	ds_read_b128 v[226:229], v138 offset:19456
	v_lshl_add_u64 v[234:235], vcc, 0, v[128:129]
	v_lshl_add_u64 v[236:237], v[234:235], 0, s[16:17]
	s_add_u32 m0, s24, s28
	s_nop 0
	global_load_lds_dwordx4 v[236:237], off
	v_lshl_add_u64 v[236:237], vcc, 0, v[130:131]
	v_lshl_add_u64 v[238:239], v[236:237], 0, s[16:17]
	s_add_u32 m0, s24, s28
	s_add_u32 m0, m0, 0x2000
	s_nop 0
	global_load_lds_dwordx4 v[238:239], off
	s_barrier
	s_waitcnt lgkmcnt(0)
	v_mfma_f32_16x16x32_bf16 v[92:95], v[198:201], v[164:167], v[92:95]
	v_mfma_f32_16x16x32_bf16 v[88:91], v[206:209], v[164:167], v[88:91]
	v_mfma_f32_16x16x32_bf16 v[84:87], v[198:201], v[172:175], v[84:87]
	v_mfma_f32_16x16x32_bf16 v[80:83], v[206:209], v[172:175], v[80:83]
	v_mfma_f32_16x16x32_bf16 v[76:79], v[198:201], v[180:183], v[76:79]
	v_mfma_f32_16x16x32_bf16 v[72:75], v[206:209], v[180:183], v[72:75]
	v_mfma_f32_16x16x32_bf16 v[68:71], v[198:201], v[188:191], v[68:71]
	v_mfma_f32_16x16x32_bf16 v[64:67], v[206:209], v[188:191], v[64:67]
	v_mfma_f32_16x16x32_bf16 v[92:95], v[202:205], v[168:171], v[92:95]
	ds_read_b128 v[164:167], v137 offset:16384
	v_mfma_f32_16x16x32_bf16 v[88:91], v[226:229], v[168:171], v[88:91]
	v_mfma_f32_16x16x32_bf16 v[84:87], v[202:205], v[176:179], v[84:87]
	ds_read_b128 v[172:175], v137 offset:18432
	v_mfma_f32_16x16x32_bf16 v[80:83], v[226:229], v[176:179], v[80:83]
	v_mfma_f32_16x16x32_bf16 v[76:79], v[202:205], v[184:187], v[76:79]
	ds_read_b128 v[180:183], v137 offset:20480
	v_mfma_f32_16x16x32_bf16 v[72:75], v[226:229], v[184:187], v[72:75]
	v_mfma_f32_16x16x32_bf16 v[68:71], v[202:205], v[194:197], v[68:71]
	ds_read_b128 v[188:191], v137 offset:22528
	v_mfma_f32_16x16x32_bf16 v[64:67], v[226:229], v[194:197], v[64:67]
	s_barrier
	ds_read_b128 v[168:171], v137 offset:17408
	ds_read_b128 v[176:179], v137 offset:19456
	ds_read_b128 v[184:187], v137 offset:21504
	ds_read_b128 v[194:197], v137 offset:23552
	v_lshl_add_u64 v[238:239], v[230:231], 0, s[18:19]
	s_add_u32 m0, s24, 0x0
	s_nop 0
	global_load_lds_dwordx4 v[238:239], off
	v_lshl_add_u64 v[238:239], v[232:233], 0, s[18:19]
	s_add_u32 m0, s24, 0x2000
	s_nop 0
	global_load_lds_dwordx4 v[238:239], off
	s_waitcnt vmcnt(8)
	s_barrier
	s_waitcnt lgkmcnt(0)
	v_mfma_f32_16x16x32_bf16 v[60:63], v[148:151], v[164:167], v[60:63]
	v_mfma_f32_16x16x32_bf16 v[56:59], v[156:159], v[164:167], v[56:59]
	v_mfma_f32_16x16x32_bf16 v[52:55], v[148:151], v[172:175], v[52:55]
	v_mfma_f32_16x16x32_bf16 v[48:51], v[156:159], v[172:175], v[48:51]
	v_mfma_f32_16x16x32_bf16 v[44:47], v[148:151], v[180:183], v[44:47]
	v_mfma_f32_16x16x32_bf16 v[40:43], v[156:159], v[180:183], v[40:43]
	v_mfma_f32_16x16x32_bf16 v[36:39], v[148:151], v[188:191], v[36:39]
	v_mfma_f32_16x16x32_bf16 v[32:35], v[156:159], v[188:191], v[32:35]
	v_mfma_f32_16x16x32_bf16 v[60:63], v[152:155], v[168:171], v[60:63]
	v_mfma_f32_16x16x32_bf16 v[56:59], v[160:163], v[168:171], v[56:59]
	v_mfma_f32_16x16x32_bf16 v[52:55], v[152:155], v[176:179], v[52:55]
	v_mfma_f32_16x16x32_bf16 v[48:51], v[160:163], v[176:179], v[48:51]
	v_mfma_f32_16x16x32_bf16 v[44:47], v[152:155], v[184:187], v[44:47]
	v_mfma_f32_16x16x32_bf16 v[40:43], v[160:163], v[184:187], v[40:43]
	v_mfma_f32_16x16x32_bf16 v[36:39], v[152:155], v[194:197], v[36:39]
	v_mfma_f32_16x16x32_bf16 v[32:35], v[160:163], v[194:197], v[32:35]
	s_barrier
	ds_read_b128 v[148:151], v138 offset:32768
	ds_read_b128 v[152:155], v138 offset:33792
	ds_read_b128 v[156:159], v138 offset:34816
	ds_read_b128 v[160:163], v138 offset:35840
	v_lshl_add_u64 v[254:255], v[234:235], 0, s[42:43]
	s_add_u32 m0, s24, s29
	s_nop 0
	global_load_lds_dwordx4 v[254:255], off
	v_lshl_add_u64 v[254:255], v[236:237], 0, s[42:43]
	s_add_u32 m0, s24, s29
	s_add_u32 m0, m0, 0x2000
	s_nop 0
	global_load_lds_dwordx4 v[254:255], off
	s_waitcnt vmcnt(6)
	s_barrier
; #define WAIT_V(n) asm volatile("s_waitcnt vmcnt(" #n ")" ::: "memory")
; #define WAIT_L(n) asm volatile("s_waitcnt lgkmcnt(" #n ")" ::: "memory")
; #define BAR __builtin_amdgcn_s_barrier()
; #define SCHED __builtin_amdgcn_sched_barrier(0)
; #define STAGE(P, BASE, br, kt) do { const char* _g = (const char*)((BASE) + (size_t)(br) * GK + (kt) * BK); \
;     __builtin_amdgcn_global_load_lds((const unsigned*)(_g + voff0), (unsigned*)((char*)(P) + tx * 16), 16, 0, 0); \
;     __builtin_amdgcn_global_load_lds((const unsigned*)(_g + voff1), (unsigned*)((char*)(P) + tx * 16 + 8192), 16, 0, 0); } while (0)
; #define LDA(dst, b, h) _Pragma("unroll") for (int m = 0; m < 4; ++m) _Pragma("unroll") for (int k = 0; k < 2; ++k) \
;     dst[m][k] = *reinterpret_cast<const bf16x8*>((char*)shm + abase + (((b) * 2 + (h)) * 16384 + (m * 2 + k) * 1024))
; #define LDB(dst, b, h) _Pragma("unroll") for (int n = 0; n < 2; ++n) _Pragma("unroll") for (int k = 0; k < 2; ++k) \
;     dst[n][k] = *reinterpret_cast<const bf16x8*>((char*)shm + bbase + (((b) * 2 + (h)) * 16384 + (n * 2 + k) * 1024))
; template <bool SWAP>
; __device__ __forceinline__ void gemm_main(const u16* __restrict__ A, const u16* __restrict__ Bt, int brow, int bcol,
;                                           u16* shm, f32x4 (&acc)[2][2][4][2]) {
;     ...
;     WAIT_V(6); BAR; MMA(1, 1, At, B1); BAR;
;     LDB(B0, 1, 0); SCHED; LDA(At, 1, 0); STAGE(SA(0, 1), A, brow + HALF, t + 2);
;     WAIT_L(8); BAR; WAIT_L(0); MMA(0, 0, At, B0); BAR; SCHED;
;     LDB(B1, 1, 1); STAGE(SB(1, 0), Bt, bcol, t + 3);
;     BAR; WAIT_L(0); MMA(0, 1, At, B1); BAR;
;     LDA(At, 1, 1); STAGE(SA(1, 0), A, brow, t + 3);
	v_mfma_f32_16x16x32_bf16 v[28:31], v[198:201], v[164:167], v[28:31]
	v_mfma_f32_16x16x32_bf16 v[24:27], v[206:209], v[164:167], v[24:27]
	v_mfma_f32_16x16x32_bf16 v[20:23], v[198:201], v[172:175], v[20:23]
	v_mfma_f32_16x16x32_bf16 v[16:19], v[206:209], v[172:175], v[16:19]
	v_mfma_f32_16x16x32_bf16 v[12:15], v[198:201], v[180:183], v[12:15]
	v_mfma_f32_16x16x32_bf16 v[8:11], v[206:209], v[180:183], v[8:11]
	v_mfma_f32_16x16x32_bf16 v[4:7], v[198:201], v[188:191], v[4:7]
	v_mfma_f32_16x16x32_bf16 v[0:3], v[206:209], v[188:191], v[0:3]
	v_mfma_f32_16x16x32_bf16 v[28:31], v[202:205], v[168:171], v[28:31]
	ds_read_b128 v[164:167], v137 offset:32768
	v_mfma_f32_16x16x32_bf16 v[24:27], v[226:229], v[168:171], v[24:27]
	v_mfma_f32_16x16x32_bf16 v[20:23], v[202:205], v[176:179], v[20:23]
	ds_read_b128 v[172:175], v137 offset:34816
	v_mfma_f32_16x16x32_bf16 v[16:19], v[226:229], v[176:179], v[16:19]
	v_mfma_f32_16x16x32_bf16 v[12:15], v[202:205], v[184:187], v[12:15]
	ds_read_b128 v[180:183], v137 offset:36864
	v_mfma_f32_16x16x32_bf16 v[8:11], v[226:229], v[184:187], v[8:11]
	v_mfma_f32_16x16x32_bf16 v[4:7], v[202:205], v[194:197], v[4:7]
	ds_read_b128 v[188:191], v137 offset:38912
	v_mfma_f32_16x16x32_bf16 v[0:3], v[226:229], v[194:197], v[0:3]
	s_barrier
	ds_read_b128 v[168:171], v137 offset:33792
	ds_read_b128 v[176:179], v137 offset:35840
	ds_read_b128 v[184:187], v137 offset:37888
	ds_read_b128 v[194:197], v137 offset:39936
	v_lshl_add_u64 v[198:199], v[230:231], 0, s[22:23]
	s_add_u32 m0, s24, 0x4000
	s_nop 0
	global_load_lds_dwordx4 v[198:199], off
	v_lshl_add_u64 v[198:199], v[232:233], 0, s[22:23]
	s_add_u32 m0, s24, 0x6000
	s_nop 0
	global_load_lds_dwordx4 v[198:199], off
	s_waitcnt lgkmcnt(8)
	s_barrier
	s_waitcnt lgkmcnt(0)
	v_mfma_f32_16x16x32_bf16 v[124:127], v[148:151], v[164:167], v[124:127]
	v_mfma_f32_16x16x32_bf16 v[120:123], v[156:159], v[164:167], v[120:123]
	v_mfma_f32_16x16x32_bf16 v[116:119], v[148:151], v[172:175], v[116:119]
	v_mfma_f32_16x16x32_bf16 v[112:115], v[156:159], v[172:175], v[112:115]
	v_mfma_f32_16x16x32_bf16 v[108:111], v[148:151], v[180:183], v[108:111]
	v_mfma_f32_16x16x32_bf16 v[104:107], v[156:159], v[180:183], v[104:107]
	v_mfma_f32_16x16x32_bf16 v[100:103], v[148:151], v[188:191], v[100:103]
	v_mfma_f32_16x16x32_bf16 v[96:99], v[156:159], v[188:191], v[96:99]
	v_mfma_f32_16x16x32_bf16 v[124:127], v[152:155], v[168:171], v[124:127]
	v_mfma_f32_16x16x32_bf16 v[120:123], v[160:163], v[168:171], v[120:123]
	v_mfma_f32_16x16x32_bf16 v[116:119], v[152:155], v[176:179], v[116:119]
	v_mfma_f32_16x16x32_bf16 v[112:115], v[160:163], v[176:179], v[112:115]
	v_mfma_f32_16x16x32_bf16 v[108:111], v[152:155], v[184:187], v[108:111]
	v_mfma_f32_16x16x32_bf16 v[104:107], v[160:163], v[184:187], v[104:107]
	v_mfma_f32_16x16x32_bf16 v[100:103], v[152:155], v[194:197], v[100:103]
	v_mfma_f32_16x16x32_bf16 v[96:99], v[160:163], v[194:197], v[96:99]
	s_barrier
	ds_read_b128 v[198:201], v138 offset:49152
	ds_read_b128 v[202:205], v138 offset:50176
	ds_read_b128 v[206:209], v138 offset:51200
	ds_read_b128 v[226:229], v138 offset:52224
	v_lshl_add_u64 v[238:239], v[234:235], 0, s[20:21]
	s_add_u32 m0, s24, s30
	s_nop 0
	global_load_lds_dwordx4 v[238:239], off
	v_lshl_add_u64 v[238:239], v[236:237], 0, s[20:21]
	s_add_u32 m0, s24, s30
	s_add_u32 m0, m0, 0x2000
	s_nop 0
	global_load_lds_dwordx4 v[238:239], off
	s_barrier
	s_waitcnt lgkmcnt(0)
	v_mfma_f32_16x16x32_bf16 v[92:95], v[198:201], v[164:167], v[92:95]
	v_mfma_f32_16x16x32_bf16 v[88:91], v[206:209], v[164:167], v[88:91]
	v_mfma_f32_16x16x32_bf16 v[84:87], v[198:201], v[172:175], v[84:87]
	v_mfma_f32_16x16x32_bf16 v[80:83], v[206:209], v[172:175], v[80:83]
	v_mfma_f32_16x16x32_bf16 v[76:79], v[198:201], v[180:183], v[76:79]
	v_mfma_f32_16x16x32_bf16 v[72:75], v[206:209], v[180:183], v[72:75]
	v_mfma_f32_16x16x32_bf16 v[68:71], v[198:201], v[188:191], v[68:71]
	v_mfma_f32_16x16x32_bf16 v[64:67], v[206:209], v[188:191], v[64:67]
	v_mfma_f32_16x16x32_bf16 v[92:95], v[202:205], v[168:171], v[92:95]
	ds_read_b128 v[164:167], v137 offset:49152
	v_mfma_f32_16x16x32_bf16 v[88:91], v[226:229], v[168:171], v[88:91]
	v_mfma_f32_16x16x32_bf16 v[84:87], v[202:205], v[176:179], v[84:87]
	ds_read_b128 v[172:175], v137 offset:51200
	v_mfma_f32_16x16x32_bf16 v[80:83], v[226:229], v[176:179], v[80:83]
	v_mfma_f32_16x16x32_bf16 v[76:79], v[202:205], v[184:187], v[76:79]
	ds_read_b128 v[180:183], v137 offset:53248
	v_mfma_f32_16x16x32_bf16 v[72:75], v[226:229], v[184:187], v[72:75]
	v_mfma_f32_16x16x32_bf16 v[68:71], v[202:205], v[194:197], v[68:71]
	ds_read_b128 v[188:191], v137 offset:55296
	v_mfma_f32_16x16x32_bf16 v[64:67], v[226:229], v[194:197], v[64:67]
	s_barrier
	ds_read_b128 v[168:171], v137 offset:50176
	ds_read_b128 v[176:179], v137 offset:52224
	ds_read_b128 v[184:187], v137 offset:54272
	ds_read_b128 v[194:197], v137 offset:56320
	v_lshl_add_u64 v[230:231], v[230:231], 0, s[92:93]
	s_add_u32 m0, s24, 0x8000
	s_nop 0
	global_load_lds_dwordx4 v[230:231], off
	v_lshl_add_u64 v[230:231], v[232:233], 0, s[92:93]
	s_add_u32 m0, s24, 0xa000
	s_nop 0
	global_load_lds_dwordx4 v[230:231], off
	s_waitcnt vmcnt(8)
	s_barrier
; #define WAIT_V(n) asm volatile("s_waitcnt vmcnt(" #n ")" ::: "memory")
; #define WAIT_L(n) asm volatile("s_waitcnt lgkmcnt(" #n ")" ::: "memory")
; #define BAR __builtin_amdgcn_s_barrier()
; #define SCHED __builtin_amdgcn_sched_barrier(0)
; #define STAGE(P, BASE, br, kt) do { const char* _g = (const char*)((BASE) + (size_t)(br) * GK + (kt) * BK); \
;     __builtin_amdgcn_global_load_lds((const unsigned*)(_g + voff0), (unsigned*)((char*)(P) + tx * 16), 16, 0, 0); \
;     __builtin_amdgcn_global_load_lds((const unsigned*)(_g + voff1), (unsigned*)((char*)(P) + tx * 16 + 8192), 16, 0, 0); } while (0)
; #define LDA(dst, b, h) _Pragma("unroll") for (int m = 0; m < 4; ++m) _Pragma("unroll") for (int k = 0; k < 2; ++k) \
;     dst[m][k] = *reinterpret_cast<const bf16x8*>((char*)shm + abase + (((b) * 2 + (h)) * 16384 + (m * 2 + k) * 1024))
; #define LDB(dst, b, h) _Pragma("unroll") for (int n = 0; n < 2; ++n) _Pragma("unroll") for (int k = 0; k < 2; ++k) \
;     dst[n][k] = *reinterpret_cast<const bf16x8*>((char*)shm + bbase + (((b) * 2 + (h)) * 16384 + (n * 2 + k) * 1024))
; template <bool SWAP>
; __device__ __forceinline__ void gemm_main(const u16* __restrict__ A, const u16* __restrict__ Bt, int brow, int bcol,
;                                           u16* shm, f32x4 (&acc)[2][2][4][2]) {
;     ...
;     LDA(At, 1, 1); STAGE(SA(1, 0), A, brow, t + 3);
;     BAR; WAIT_L(0); MMA(1, 0, At, B0); BAR; SCHED;
;     STAGE(SB(1, 1), Bt, bcol + HALF, t + 3);
;     WAIT_V(6); BAR; MMA(1, 1, At, B1); BAR;
;   }
;   { LDB(B0, 0, 0); LDA(At, 0, 0); STAGE(SA(1, 1), A, brow + HALF, nt - 1);
;     BAR; WAIT_L(0); MMA(0, 0, At, B0); BAR;
	s_waitcnt lgkmcnt(0)
	v_mfma_f32_16x16x32_bf16 v[60:63], v[148:151], v[164:167], v[60:63]
	v_mfma_f32_16x16x32_bf16 v[56:59], v[156:159], v[164:167], v[56:59]
	v_mfma_f32_16x16x32_bf16 v[52:55], v[148:151], v[172:175], v[52:55]
	v_mfma_f32_16x16x32_bf16 v[48:51], v[156:159], v[172:175], v[48:51]
	v_mfma_f32_16x16x32_bf16 v[44:47], v[148:151], v[180:183], v[44:47]
	v_mfma_f32_16x16x32_bf16 v[40:43], v[156:159], v[180:183], v[40:43]
	v_mfma_f32_16x16x32_bf16 v[36:39], v[148:151], v[188:191], v[36:39]
	v_mfma_f32_16x16x32_bf16 v[32:35], v[156:159], v[188:191], v[32:35]
	v_mfma_f32_16x16x32_bf16 v[60:63], v[152:155], v[168:171], v[60:63]
	v_mfma_f32_16x16x32_bf16 v[56:59], v[160:163], v[168:171], v[56:59]
	v_mfma_f32_16x16x32_bf16 v[52:55], v[152:155], v[176:179], v[52:55]
	v_mfma_f32_16x16x32_bf16 v[48:51], v[160:163], v[176:179], v[48:51]
	v_mfma_f32_16x16x32_bf16 v[44:47], v[152:155], v[184:187], v[44:47]
	v_mfma_f32_16x16x32_bf16 v[40:43], v[160:163], v[184:187], v[40:43]
	v_mfma_f32_16x16x32_bf16 v[36:39], v[152:155], v[194:197], v[36:39]
	v_mfma_f32_16x16x32_bf16 v[32:35], v[160:163], v[194:197], v[32:35]
	s_barrier
	ds_read_b128 v[148:151], v138
	ds_read_b128 v[152:155], v138 offset:1024
	ds_read_b128 v[156:159], v138 offset:2048
	ds_read_b128 v[160:163], v138 offset:3072
	v_lshl_add_u64 v[254:255], v[234:235], 0, s[72:73]
	s_add_u32 m0, s24, s31
	s_nop 0
	global_load_lds_dwordx4 v[254:255], off
	v_lshl_add_u64 v[254:255], v[236:237], 0, s[72:73]
	s_add_u32 m0, s24, s31
	s_add_u32 m0, m0, 0x2000
	s_nop 0
	global_load_lds_dwordx4 v[254:255], off
	s_waitcnt vmcnt(6)
	s_barrier
	v_mfma_f32_16x16x32_bf16 v[28:31], v[198:201], v[164:167], v[28:31]
	v_mfma_f32_16x16x32_bf16 v[24:27], v[206:209], v[164:167], v[24:27]
	v_mfma_f32_16x16x32_bf16 v[20:23], v[198:201], v[172:175], v[20:23]
	v_mfma_f32_16x16x32_bf16 v[16:19], v[206:209], v[172:175], v[16:19]
	v_mfma_f32_16x16x32_bf16 v[12:15], v[198:201], v[180:183], v[12:15]
	v_mfma_f32_16x16x32_bf16 v[8:11], v[206:209], v[180:183], v[8:11]
	v_mfma_f32_16x16x32_bf16 v[4:7], v[198:201], v[188:191], v[4:7]
	v_mfma_f32_16x16x32_bf16 v[0:3], v[206:209], v[188:191], v[0:3]
	v_mfma_f32_16x16x32_bf16 v[28:31], v[202:205], v[168:171], v[28:31]
	ds_read_b128 v[164:167], v137
	v_mfma_f32_16x16x32_bf16 v[24:27], v[226:229], v[168:171], v[24:27]
	v_mfma_f32_16x16x32_bf16 v[20:23], v[202:205], v[176:179], v[20:23]
	ds_read_b128 v[172:175], v137 offset:2048
	v_mfma_f32_16x16x32_bf16 v[16:19], v[226:229], v[176:179], v[16:19]
	s_add_i32 s3, s3, 2
	s_add_u32 vcc_lo, vcc_lo, 0x100
	s_addc_u32 vcc_hi, vcc_hi, 0
	s_cmp_lt_u32 s3, 28
	v_mfma_f32_16x16x32_bf16 v[12:15], v[202:205], v[184:187], v[12:15]
	ds_read_b128 v[180:183], v137 offset:4096
	v_mfma_f32_16x16x32_bf16 v[8:11], v[226:229], v[184:187], v[8:11]
	v_mfma_f32_16x16x32_bf16 v[4:7], v[202:205], v[194:197], v[4:7]
	ds_read_b128 v[188:191], v137 offset:6144
	v_mfma_f32_16x16x32_bf16 v[0:3], v[226:229], v[194:197], v[0:3]
	s_barrier
	s_cbranch_scc1 .LBB0_570
	v_lshlrev_b32_e32 v128, 3, v139
	v_lshlrev_b32_e32 v129, 5, v139
	v_and_b32_e32 v128, 0xffff0, v128
	v_and_b32_e32 v129, 32, v129
	v_add_u32_e32 v129, v129, v142
	v_add_lshl_u32 v128, v141, v128, 12
	v_lshl_add_u32 v192, v129, 1, v128
	v_lshlrev_b32_e32 v128, 3, v143
	v_lshlrev_b32_e32 v129, 5, v143
	v_and_b32_e32 v128, 0xffff0, v128
	v_and_b32_e32 v129, 32, v129
	v_add_u32_e32 v129, v129, v145
	v_add_lshl_u32 v128, v144, v128, 12
	v_lshl_add_u32 v144, v129, 1, v128
	v_mov_b32_e32 v145, v193
	v_lshl_add_u64 v[184:185], s[4:5], 0, v[192:193]
	s_mov_b64 s[14:15], 0xf80
	v_readfirstlane_b32 s3, v146
	v_lshl_add_u64 v[184:185], v[184:185], 0, s[14:15]
	s_mov_b32 m0, s3
	v_lshl_add_u64 v[144:145], s[4:5], 0, v[144:145]
	v_readfirstlane_b32 s3, v147
	ds_read_b128 v[128:131], v138
	ds_read_b128 v[132:135], v138 offset:1024
	ds_read_b128 v[140:143], v138 offset:2048
	ds_read_b128 v[148:151], v138 offset:3072
	ds_read_b128 v[152:155], v137
	ds_read_b128 v[156:159], v137 offset:1024
	ds_read_b128 v[160:163], v137 offset:2048
	ds_read_b128 v[164:167], v137 offset:3072
	ds_read_b128 v[168:171], v137 offset:4096
	ds_read_b128 v[172:175], v137 offset:5120
	ds_read_b128 v[176:179], v137 offset:6144
	ds_read_b128 v[180:183], v137 offset:7168
	global_load_lds_dwordx4 v[184:185], off
	v_lshl_add_u64 v[144:145], v[144:145], 0, s[14:15]
	s_mov_b32 m0, s3
	s_nop 0
	global_load_lds_dwordx4 v[144:145], off
	s_barrier
	s_waitcnt lgkmcnt(0)
	s_setprio 1
	s_waitcnt lgkmcnt(0)
	v_mfma_f32_16x16x32_bf16 v[116:119], v[128:131], v[160:163], v[116:119]
	v_mfma_f32_16x16x32_bf16 v[112:115], v[140:143], v[160:163], v[112:115]
	v_mfma_f32_16x16x32_bf16 v[100:103], v[128:131], v[176:179], v[100:103]
	v_mfma_f32_16x16x32_bf16 v[96:99], v[140:143], v[176:179], v[96:99]
	v_mfma_f32_16x16x32_bf16 v[124:127], v[128:131], v[152:155], v[124:127]
	v_mfma_f32_16x16x32_bf16 v[120:123], v[140:143], v[152:155], v[120:123]
	v_mfma_f32_16x16x32_bf16 v[116:119], v[132:135], v[164:167], v[116:119]
	v_mfma_f32_16x16x32_bf16 v[112:115], v[148:151], v[164:167], v[112:115]
	v_mfma_f32_16x16x32_bf16 v[108:111], v[128:131], v[168:171], v[108:111]
	v_mfma_f32_16x16x32_bf16 v[104:107], v[140:143], v[168:171], v[104:107]
	v_mfma_f32_16x16x32_bf16 v[100:103], v[132:135], v[180:183], v[100:103]
	v_mfma_f32_16x16x32_bf16 v[96:99], v[148:151], v[180:183], v[96:99]
	v_mfma_f32_16x16x32_bf16 v[124:127], v[132:135], v[156:159], v[124:127]
	v_mfma_f32_16x16x32_bf16 v[120:123], v[148:151], v[156:159], v[120:123]
	v_mfma_f32_16x16x32_bf16 v[108:111], v[132:135], v[172:175], v[108:111]
	v_mfma_f32_16x16x32_bf16 v[104:107], v[148:151], v[172:175], v[104:107]
	s_setprio 0
	s_barrier
; #define WAIT_V(n) asm volatile("s_waitcnt vmcnt(" #n ")" ::: "memory")
; #define WAIT_L(n) asm volatile("s_waitcnt lgkmcnt(" #n ")" ::: "memory")
; #define BAR __builtin_amdgcn_s_barrier()
; #define LDA(dst, b, h) _Pragma("unroll") for (int m = 0; m < 4; ++m) _Pragma("unroll") for (int k = 0; k < 2; ++k) \
;     dst[m][k] = *reinterpret_cast<const bf16x8*>((char*)shm + abase + (((b) * 2 + (h)) * 16384 + (m * 2 + k) * 1024))
; #define LDB(dst, b, h) _Pragma("unroll") for (int n = 0; n < 2; ++n) _Pragma("unroll") for (int k = 0; k < 2; ++k) \
;     dst[n][k] = *reinterpret_cast<const bf16x8*>((char*)shm + bbase + (((b) * 2 + (h)) * 16384 + (n * 2 + k) * 1024))
; template <bool SWAP>
; __device__ __forceinline__ void gemm_main(const u16* __restrict__ A, const u16* __restrict__ Bt, int brow, int bcol,
;                                           u16* shm, f32x4 (&acc)[2][2][4][2]) {
;     ...
;     BAR; WAIT_L(0); MMA(0, 0, At, B0); BAR;
;     LDB(B1, 0, 1); BAR; WAIT_L(0); MMA(0, 1, At, B1); BAR;
;     LDA(At, 0, 1); WAIT_V(4); BAR; WAIT_L(0); MMA(1, 0, At, B0); MMA(1, 1, At, B1); BAR; }
;   { LDB(B0, 1, 0); LDA(At, 1, 0); WAIT_V(2); BAR; WAIT_L(0); MMA(0, 0, At, B0); BAR;
	ds_read_b128 v[144:147], v138 offset:16384
	ds_read_b128 v[184:187], v138 offset:17408
	ds_read_b128 v[188:191], v138 offset:18432
	ds_read_b128 v[194:197], v138 offset:19456
	s_barrier
	s_waitcnt lgkmcnt(0)
	s_setprio 1
	s_waitcnt lgkmcnt(0)
	v_mfma_f32_16x16x32_bf16 v[92:95], v[144:147], v[152:155], v[92:95]
	v_mfma_f32_16x16x32_bf16 v[88:91], v[188:191], v[152:155], v[88:91]
	v_mfma_f32_16x16x32_bf16 v[84:87], v[144:147], v[160:163], v[84:87]
	v_mfma_f32_16x16x32_bf16 v[80:83], v[188:191], v[160:163], v[80:83]
	v_mfma_f32_16x16x32_bf16 v[76:79], v[144:147], v[168:171], v[76:79]
	v_mfma_f32_16x16x32_bf16 v[72:75], v[188:191], v[168:171], v[72:75]
	v_mfma_f32_16x16x32_bf16 v[68:71], v[144:147], v[176:179], v[68:71]
	v_mfma_f32_16x16x32_bf16 v[64:67], v[188:191], v[176:179], v[64:67]
	v_mfma_f32_16x16x32_bf16 v[92:95], v[184:187], v[156:159], v[92:95]
	v_mfma_f32_16x16x32_bf16 v[88:91], v[194:197], v[156:159], v[88:91]
	v_mfma_f32_16x16x32_bf16 v[84:87], v[184:187], v[164:167], v[84:87]
	v_mfma_f32_16x16x32_bf16 v[80:83], v[194:197], v[164:167], v[80:83]
	v_mfma_f32_16x16x32_bf16 v[76:79], v[184:187], v[172:175], v[76:79]
	v_mfma_f32_16x16x32_bf16 v[72:75], v[194:197], v[172:175], v[72:75]
	v_mfma_f32_16x16x32_bf16 v[68:71], v[184:187], v[180:183], v[68:71]
	v_mfma_f32_16x16x32_bf16 v[64:67], v[194:197], v[180:183], v[64:67]
	s_setprio 0
	s_barrier
	ds_read_b128 v[152:155], v137 offset:16384
	ds_read_b128 v[156:159], v137 offset:17408
	ds_read_b128 v[160:163], v137 offset:18432
	ds_read_b128 v[164:167], v137 offset:19456
	ds_read_b128 v[168:171], v137 offset:20480
	ds_read_b128 v[172:175], v137 offset:21504
	ds_read_b128 v[176:179], v137 offset:22528
	ds_read_b128 v[180:183], v137 offset:23552
	s_waitcnt vmcnt(4)
	s_barrier
	s_waitcnt lgkmcnt(0)
	s_setprio 1
	s_waitcnt lgkmcnt(0)
	v_mfma_f32_16x16x32_bf16 v[60:63], v[128:131], v[152:155], v[60:63]
	v_mfma_f32_16x16x32_bf16 v[56:59], v[140:143], v[152:155], v[56:59]
	v_mfma_f32_16x16x32_bf16 v[52:55], v[128:131], v[160:163], v[52:55]
	v_mfma_f32_16x16x32_bf16 v[48:51], v[140:143], v[160:163], v[48:51]
	v_mfma_f32_16x16x32_bf16 v[44:47], v[128:131], v[168:171], v[44:47]
	v_mfma_f32_16x16x32_bf16 v[40:43], v[140:143], v[168:171], v[40:43]
	v_mfma_f32_16x16x32_bf16 v[36:39], v[128:131], v[176:179], v[36:39]
	v_mfma_f32_16x16x32_bf16 v[32:35], v[140:143], v[176:179], v[32:35]
	v_mfma_f32_16x16x32_bf16 v[60:63], v[132:135], v[156:159], v[60:63]
	v_mfma_f32_16x16x32_bf16 v[56:59], v[148:151], v[156:159], v[56:59]
	v_mfma_f32_16x16x32_bf16 v[52:55], v[132:135], v[164:167], v[52:55]
	v_mfma_f32_16x16x32_bf16 v[48:51], v[148:151], v[164:167], v[48:51]
	v_mfma_f32_16x16x32_bf16 v[44:47], v[132:135], v[172:175], v[44:47]
	v_mfma_f32_16x16x32_bf16 v[40:43], v[148:151], v[172:175], v[40:43]
	v_mfma_f32_16x16x32_bf16 v[36:39], v[132:135], v[180:183], v[36:39]
	v_mfma_f32_16x16x32_bf16 v[32:35], v[148:151], v[180:183], v[32:35]
	s_setprio 0
	s_setprio 1
	v_mfma_f32_16x16x32_bf16 v[28:31], v[144:147], v[152:155], v[28:31]
	v_mfma_f32_16x16x32_bf16 v[24:27], v[188:191], v[152:155], v[24:27]
	v_mfma_f32_16x16x32_bf16 v[20:23], v[144:147], v[160:163], v[20:23]
	v_mfma_f32_16x16x32_bf16 v[16:19], v[188:191], v[160:163], v[16:19]
	v_mfma_f32_16x16x32_bf16 v[12:15], v[144:147], v[168:171], v[12:15]
	v_mfma_f32_16x16x32_bf16 v[8:11], v[188:191], v[168:171], v[8:11]
	v_mfma_f32_16x16x32_bf16 v[4:7], v[144:147], v[176:179], v[4:7]
	v_mfma_f32_16x16x32_bf16 v[0:3], v[188:191], v[176:179], v[0:3]
	v_mfma_f32_16x16x32_bf16 v[28:31], v[184:187], v[156:159], v[28:31]
	v_mfma_f32_16x16x32_bf16 v[24:27], v[194:197], v[156:159], v[24:27]
	v_mfma_f32_16x16x32_bf16 v[20:23], v[184:187], v[164:167], v[20:23]
	v_mfma_f32_16x16x32_bf16 v[16:19], v[194:197], v[164:167], v[16:19]
	v_mfma_f32_16x16x32_bf16 v[12:15], v[184:187], v[172:175], v[12:15]
	v_mfma_f32_16x16x32_bf16 v[8:11], v[194:197], v[172:175], v[8:11]
	v_mfma_f32_16x16x32_bf16 v[4:7], v[184:187], v[180:183], v[4:7]
	v_mfma_f32_16x16x32_bf16 v[0:3], v[194:197], v[180:183], v[0:3]
	s_setprio 0
	s_barrier
	ds_read_b128 v[140:143], v138 offset:32768
	ds_read_b128 v[152:155], v138 offset:33792
	ds_read_b128 v[156:159], v138 offset:34816
	ds_read_b128 v[160:163], v138 offset:35840
	ds_read_b128 v[164:167], v137 offset:32768
	ds_read_b128 v[168:171], v137 offset:33792
	ds_read_b128 v[172:175], v137 offset:34816
	ds_read_b128 v[176:179], v137 offset:35840
	ds_read_b128 v[180:183], v137 offset:36864
	ds_read_b128 v[184:187], v137 offset:37888
	ds_read_b128 v[188:191], v137 offset:38912
	ds_read_b128 v[194:197], v137 offset:39936
	s_waitcnt vmcnt(2)
	s_barrier
; #define WAIT_V(n) asm volatile("s_waitcnt vmcnt(" #n ")" ::: "memory")
; #define WAIT_L(n) asm volatile("s_waitcnt lgkmcnt(" #n ")" ::: "memory")
; #define BAR __builtin_amdgcn_s_barrier()
; #define LDA(dst, b, h) _Pragma("unroll") for (int m = 0; m < 4; ++m) _Pragma("unroll") for (int k = 0; k < 2; ++k) \
;     dst[m][k] = *reinterpret_cast<const bf16x8*>((char*)shm + abase + (((b) * 2 + (h)) * 16384 + (m * 2 + k) * 1024))
; #define LDB(dst, b, h) _Pragma("unroll") for (int n = 0; n < 2; ++n) _Pragma("unroll") for (int k = 0; k < 2; ++k) \
;     dst[n][k] = *reinterpret_cast<const bf16x8*>((char*)shm + bbase + (((b) * 2 + (h)) * 16384 + (n * 2 + k) * 1024))
; template <bool SWAP>
; __device__ __forceinline__ void gemm_main(const u16* __restrict__ A, const u16* __restrict__ Bt, int brow, int bcol,
;                                           u16* shm, f32x4 (&acc)[2][2][4][2]) {
;     ...
;   { LDB(B0, 1, 0); LDA(At, 1, 0); WAIT_V(2); BAR; WAIT_L(0); MMA(0, 0, At, B0); BAR;
;     LDB(B1, 1, 1); WAIT_V(0); BAR; WAIT_L(0); MMA(0, 1, At, B1); BAR;
;     LDA(At, 1, 1); BAR; WAIT_L(0); MMA(1, 0, At, B0); MMA(1, 1, At, B1); BAR; }
;   if (wr == 0) BAR;
	s_waitcnt lgkmcnt(0)
	s_setprio 1
	s_waitcnt lgkmcnt(0)
	v_mfma_f32_16x16x32_bf16 v[124:127], v[140:143], v[164:167], v[124:127]
	v_mfma_f32_16x16x32_bf16 v[120:123], v[156:159], v[164:167], v[120:123]
	v_mfma_f32_16x16x32_bf16 v[116:119], v[140:143], v[172:175], v[116:119]
	v_mfma_f32_16x16x32_bf16 v[112:115], v[156:159], v[172:175], v[112:115]
	v_mfma_f32_16x16x32_bf16 v[108:111], v[140:143], v[180:183], v[108:111]
	v_mfma_f32_16x16x32_bf16 v[104:107], v[156:159], v[180:183], v[104:107]
	v_mfma_f32_16x16x32_bf16 v[100:103], v[140:143], v[188:191], v[100:103]
	v_mfma_f32_16x16x32_bf16 v[96:99], v[156:159], v[188:191], v[96:99]
	v_mfma_f32_16x16x32_bf16 v[148:151], v[152:155], v[168:171], v[124:127]
	v_mfma_f32_16x16x32_bf16 v[144:147], v[160:163], v[168:171], v[120:123]
	v_mfma_f32_16x16x32_bf16 v[132:135], v[152:155], v[176:179], v[116:119]
	v_mfma_f32_16x16x32_bf16 v[128:131], v[160:163], v[176:179], v[112:115]
	v_mfma_f32_16x16x32_bf16 v[116:119], v[152:155], v[184:187], v[108:111]
	v_mfma_f32_16x16x32_bf16 v[112:115], v[160:163], v[184:187], v[104:107]
	v_mfma_f32_16x16x32_bf16 v[100:103], v[152:155], v[194:197], v[100:103]
	v_mfma_f32_16x16x32_bf16 v[96:99], v[160:163], v[194:197], v[96:99]
	s_setprio 0
	s_barrier
	ds_read_b128 v[104:107], v138 offset:49152
	ds_read_b128 v[108:111], v138 offset:50176
	ds_read_b128 v[120:123], v138 offset:51200
	ds_read_b128 v[124:127], v138 offset:52224
	s_waitcnt vmcnt(0)
	s_barrier
	s_waitcnt lgkmcnt(0)
	s_setprio 1
	s_waitcnt lgkmcnt(0)
	v_mfma_f32_16x16x32_bf16 v[92:95], v[104:107], v[164:167], v[92:95]
	v_mfma_f32_16x16x32_bf16 v[88:91], v[120:123], v[164:167], v[88:91]
	v_mfma_f32_16x16x32_bf16 v[84:87], v[104:107], v[172:175], v[84:87]
	v_mfma_f32_16x16x32_bf16 v[80:83], v[120:123], v[172:175], v[80:83]
	v_mfma_f32_16x16x32_bf16 v[76:79], v[104:107], v[180:183], v[76:79]
	v_mfma_f32_16x16x32_bf16 v[72:75], v[120:123], v[180:183], v[72:75]
	v_mfma_f32_16x16x32_bf16 v[68:71], v[104:107], v[188:191], v[68:71]
	v_mfma_f32_16x16x32_bf16 v[64:67], v[120:123], v[188:191], v[64:67]
	v_mfma_f32_16x16x32_bf16 v[92:95], v[108:111], v[168:171], v[92:95]
	v_mfma_f32_16x16x32_bf16 v[88:91], v[124:127], v[168:171], v[88:91]
	v_mfma_f32_16x16x32_bf16 v[84:87], v[108:111], v[176:179], v[84:87]
	v_mfma_f32_16x16x32_bf16 v[80:83], v[124:127], v[176:179], v[80:83]
	v_mfma_f32_16x16x32_bf16 v[76:79], v[108:111], v[184:187], v[76:79]
	v_mfma_f32_16x16x32_bf16 v[72:75], v[124:127], v[184:187], v[72:75]
	v_mfma_f32_16x16x32_bf16 v[68:71], v[108:111], v[194:197], v[68:71]
	v_mfma_f32_16x16x32_bf16 v[64:67], v[124:127], v[194:197], v[64:67]
	s_setprio 0
	s_barrier
	ds_read_b128 v[164:167], v137 offset:49152
	ds_read_b128 v[168:171], v137 offset:50176
	ds_read_b128 v[172:175], v137 offset:51200
	ds_read_b128 v[176:179], v137 offset:52224
	ds_read_b128 v[180:183], v137 offset:53248
	ds_read_b128 v[184:187], v137 offset:54272
	ds_read_b128 v[188:191], v137 offset:55296
	ds_read_b128 v[194:197], v137 offset:56320
	s_barrier
	s_waitcnt lgkmcnt(0)
	s_setprio 1
	s_waitcnt lgkmcnt(0)
	v_mfma_f32_16x16x32_bf16 v[60:63], v[140:143], v[164:167], v[60:63]
	v_mfma_f32_16x16x32_bf16 v[56:59], v[156:159], v[164:167], v[56:59]
	v_mfma_f32_16x16x32_bf16 v[52:55], v[140:143], v[172:175], v[52:55]
	v_mfma_f32_16x16x32_bf16 v[48:51], v[156:159], v[172:175], v[48:51]
	v_mfma_f32_16x16x32_bf16 v[44:47], v[140:143], v[180:183], v[44:47]
	v_mfma_f32_16x16x32_bf16 v[40:43], v[156:159], v[180:183], v[40:43]
	v_mfma_f32_16x16x32_bf16 v[36:39], v[140:143], v[188:191], v[36:39]
	v_mfma_f32_16x16x32_bf16 v[32:35], v[156:159], v[188:191], v[32:35]
	v_mfma_f32_16x16x32_bf16 v[60:63], v[152:155], v[168:171], v[60:63]
	v_mfma_f32_16x16x32_bf16 v[56:59], v[160:163], v[168:171], v[56:59]
	v_mfma_f32_16x16x32_bf16 v[52:55], v[152:155], v[176:179], v[52:55]
	v_mfma_f32_16x16x32_bf16 v[48:51], v[160:163], v[176:179], v[48:51]
	v_mfma_f32_16x16x32_bf16 v[44:47], v[152:155], v[184:187], v[44:47]
	v_mfma_f32_16x16x32_bf16 v[40:43], v[160:163], v[184:187], v[40:43]
	v_mfma_f32_16x16x32_bf16 v[36:39], v[152:155], v[194:197], v[36:39]
	v_mfma_f32_16x16x32_bf16 v[32:35], v[160:163], v[194:197], v[32:35]
	s_setprio 0
	s_setprio 1
	v_mfma_f32_16x16x32_bf16 v[28:31], v[104:107], v[164:167], v[28:31]
	v_mfma_f32_16x16x32_bf16 v[24:27], v[120:123], v[164:167], v[24:27]
	v_mfma_f32_16x16x32_bf16 v[20:23], v[104:107], v[172:175], v[20:23]
	v_mfma_f32_16x16x32_bf16 v[16:19], v[120:123], v[172:175], v[16:19]
	v_mfma_f32_16x16x32_bf16 v[12:15], v[104:107], v[180:183], v[12:15]
	v_mfma_f32_16x16x32_bf16 v[8:11], v[120:123], v[180:183], v[8:11]
	v_mfma_f32_16x16x32_bf16 v[4:7], v[104:107], v[188:191], v[4:7]
	v_mfma_f32_16x16x32_bf16 v[0:3], v[120:123], v[188:191], v[0:3]
	v_mfma_f32_16x16x32_bf16 v[28:31], v[108:111], v[168:171], v[28:31]
	v_mfma_f32_16x16x32_bf16 v[24:27], v[124:127], v[168:171], v[24:27]
	v_mfma_f32_16x16x32_bf16 v[20:23], v[108:111], v[176:179], v[20:23]
	v_mfma_f32_16x16x32_bf16 v[16:19], v[124:127], v[176:179], v[16:19]
	v_mfma_f32_16x16x32_bf16 v[12:15], v[108:111], v[184:187], v[12:15]
	v_mfma_f32_16x16x32_bf16 v[8:11], v[124:127], v[184:187], v[8:11]
	v_mfma_f32_16x16x32_bf16 v[4:7], v[108:111], v[194:197], v[4:7]
	v_mfma_f32_16x16x32_bf16 v[0:3], v[124:127], v[194:197], v[0:3]
	s_setprio 0
	s_movk_i32 s3, 0x100
	v_cmp_gt_u32_e32 vcc, s3, v136
	s_barrier
	s_and_saveexec_b64 s[4:5], vcc
	s_cbranch_execz .LBB0_573
	s_barrier

; #define WAIT_V(n) asm volatile("s_waitcnt vmcnt(" #n ")" ::: "memory")
; #define WAIT_L(n) asm volatile("s_waitcnt lgkmcnt(" #n ")" ::: "memory")
; #define BAR __builtin_amdgcn_s_barrier()
; #define SCHED __builtin_amdgcn_sched_barrier(0)
; #define STAGE(P, BASE, br, kt) do { const char* _g = (const char*)((BASE) + (size_t)(br) * GK + (kt) * BK); \
;     __builtin_amdgcn_global_load_lds((const unsigned*)(_g + voff0), (unsigned*)((char*)(P) + tx * 16), 16, 0, 0); \
;     __builtin_amdgcn_global_load_lds((const unsigned*)(_g + voff1), (unsigned*)((char*)(P) + tx * 16 + 8192), 16, 0, 0); } while (0)
; #define LDA(dst, b, h) _Pragma("unroll") for (int m = 0; m < 4; ++m) _Pragma("unroll") for (int k = 0; k < 2; ++k) \
;     dst[m][k] = *reinterpret_cast<const bf16x8*>((char*)shm + abase + (((b) * 2 + (h)) * 16384 + (m * 2 + k) * 1024))
; #define LDB(dst, b, h) _Pragma("unroll") for (int n = 0; n < 2; ++n) _Pragma("unroll") for (int k = 0; k < 2; ++k) \
;     dst[n][k] = *reinterpret_cast<const bf16x8*>((char*)shm + bbase + (((b) * 2 + (h)) * 16384 + (n * 2 + k) * 1024))
; template <bool SWAP>
; __device__ __forceinline__ void gemm_main(const u16* __restrict__ A, const u16* __restrict__ Bt, int brow, int bcol,
;                                           u16* shm, f32x4 (&acc)[2][2][4][2]) {
;     ...
;     LDB(B0, 0, 0); SCHED; LDA(At, 0, 0); STAGE(SA(1, 1), A, brow + HALF, t + 1);
;     WAIT_L(8); BAR; WAIT_L(0); MMA(0, 0, At, B0); BAR; SCHED;
;     LDB(B1, 0, 1); STAGE(SB(0, 0), Bt, bcol, t + 2);
;     BAR; WAIT_L(0); MMA(0, 1, At, B1); BAR;
;     LDA(At, 0, 1); STAGE(SA(0, 0), A, brow, t + 2);
;     BAR; WAIT_L(0); MMA(1, 0, At, B0); BAR; SCHED;
;     STAGE(SB(0, 1), Bt, bcol + HALF, t + 2);
;     WAIT_V(6); BAR; MMA(1, 1, At, B1); BAR;
;     LDB(B0, 1, 0); SCHED; LDA(At, 1, 0); STAGE(SA(0, 1), A, brow + HALF, t + 2);
.LBB0_576:
	ds_read_b128 v[168:171], v137 offset:1024
	ds_read_b128 v[176:179], v137 offset:3072
	ds_read_b128 v[184:187], v137 offset:5120
	ds_read_b128 v[194:197], v137 offset:7168
	v_add_u32_e32 v192, 0, v140
	v_add_u32_e32 v146, 0xc000, v192
	v_add_u32_e32 v147, 0xe000, v192
	s_add_u32 m0, s3, 0xc000
	v_lshl_add_u64 v[232:233], s[4:5], 0, v[134:135]
	s_add_u32 vcc_lo, s4, s10
	s_addc_u32 vcc_hi, s5, s11
	global_load_lds_dwordx4 v132, vcc
	s_add_u32 m0, s3, 0xe000
	s_nop 0
	global_load_lds_dwordx4 v134, vcc
	s_waitcnt lgkmcnt(8)
	s_barrier
	s_waitcnt lgkmcnt(0)
	v_mfma_f32_16x16x32_bf16 v[124:127], v[148:151], v[164:167], v[124:127]
	v_mfma_f32_16x16x32_bf16 v[120:123], v[156:159], v[164:167], v[120:123]
	v_mfma_f32_16x16x32_bf16 v[116:119], v[148:151], v[172:175], v[116:119]
	v_mfma_f32_16x16x32_bf16 v[112:115], v[156:159], v[172:175], v[112:115]
	v_mfma_f32_16x16x32_bf16 v[108:111], v[148:151], v[180:183], v[108:111]
	v_mfma_f32_16x16x32_bf16 v[104:107], v[156:159], v[180:183], v[104:107]
	v_mfma_f32_16x16x32_bf16 v[100:103], v[148:151], v[188:191], v[100:103]
	v_mfma_f32_16x16x32_bf16 v[96:99], v[156:159], v[188:191], v[96:99]
	v_mfma_f32_16x16x32_bf16 v[124:127], v[152:155], v[168:171], v[124:127]
	v_mfma_f32_16x16x32_bf16 v[120:123], v[160:163], v[168:171], v[120:123]
	v_mfma_f32_16x16x32_bf16 v[116:119], v[152:155], v[176:179], v[116:119]
	v_mfma_f32_16x16x32_bf16 v[112:115], v[160:163], v[176:179], v[112:115]
	v_mfma_f32_16x16x32_bf16 v[108:111], v[152:155], v[184:187], v[108:111]
	v_mfma_f32_16x16x32_bf16 v[104:107], v[160:163], v[184:187], v[104:107]
	v_mfma_f32_16x16x32_bf16 v[100:103], v[152:155], v[194:197], v[100:103]
	v_mfma_f32_16x16x32_bf16 v[96:99], v[160:163], v[194:197], v[96:99]
	s_barrier
	ds_read_b128 v[198:201], v138 offset:16384
	ds_read_b128 v[202:205], v138 offset:17408
	ds_read_b128 v[206:209], v138 offset:18432
	ds_read_b128 v[226:229], v138 offset:19456
	v_lshl_add_u64 v[234:235], s[4:5], 0, v[128:129]
	s_add_u32 m0, s3, s28
	s_nop 0
	s_add_u32 vcc_lo, s4, s12
	s_addc_u32 vcc_hi, s5, s13
	global_load_lds_dwordx4 v128, vcc
	v_lshl_add_u64 v[236:237], s[4:5], 0, v[130:131]
	s_add_u32 m0, s3, s28
	s_add_u32 m0, m0, 0x2000
	s_nop 0
	global_load_lds_dwordx4 v130, vcc
	s_barrier
	s_waitcnt lgkmcnt(0)
	v_mfma_f32_16x16x32_bf16 v[92:95], v[198:201], v[164:167], v[92:95]
	v_mfma_f32_16x16x32_bf16 v[88:91], v[206:209], v[164:167], v[88:91]
	v_mfma_f32_16x16x32_bf16 v[84:87], v[198:201], v[172:175], v[84:87]
	v_mfma_f32_16x16x32_bf16 v[80:83], v[206:209], v[172:175], v[80:83]
	v_mfma_f32_16x16x32_bf16 v[76:79], v[198:201], v[180:183], v[76:79]
	v_mfma_f32_16x16x32_bf16 v[72:75], v[206:209], v[180:183], v[72:75]
	v_mfma_f32_16x16x32_bf16 v[68:71], v[198:201], v[188:191], v[68:71]
	v_mfma_f32_16x16x32_bf16 v[64:67], v[206:209], v[188:191], v[64:67]
	v_mfma_f32_16x16x32_bf16 v[92:95], v[202:205], v[168:171], v[92:95]
	ds_read_b128 v[164:167], v137 offset:16384
	v_mfma_f32_16x16x32_bf16 v[88:91], v[226:229], v[168:171], v[88:91]
	v_mfma_f32_16x16x32_bf16 v[84:87], v[202:205], v[176:179], v[84:87]
	ds_read_b128 v[172:175], v137 offset:18432
	v_mfma_f32_16x16x32_bf16 v[80:83], v[226:229], v[176:179], v[80:83]
	v_mfma_f32_16x16x32_bf16 v[76:79], v[202:205], v[184:187], v[76:79]
	ds_read_b128 v[180:183], v137 offset:20480
	v_mfma_f32_16x16x32_bf16 v[72:75], v[226:229], v[184:187], v[72:75]
	v_mfma_f32_16x16x32_bf16 v[68:71], v[202:205], v[194:197], v[68:71]
	ds_read_b128 v[188:191], v137 offset:22528
	v_mfma_f32_16x16x32_bf16 v[64:67], v[226:229], v[194:197], v[64:67]
	s_barrier
	ds_read_b128 v[168:171], v137 offset:17408
	ds_read_b128 v[176:179], v137 offset:19456
	ds_read_b128 v[184:187], v137 offset:21504
	ds_read_b128 v[194:197], v137 offset:23552
	s_add_u32 m0, s3, 0x0
	s_nop 0
	s_add_u32 vcc_lo, s4, s14
	s_addc_u32 vcc_hi, s5, s15
	global_load_lds_dwordx4 v132, vcc
	s_add_u32 m0, s3, 0x2000
	s_nop 0
	global_load_lds_dwordx4 v134, vcc
	s_waitcnt vmcnt(8)
	s_barrier
	s_waitcnt lgkmcnt(0)
	v_mfma_f32_16x16x32_bf16 v[60:63], v[148:151], v[164:167], v[60:63]
	v_mfma_f32_16x16x32_bf16 v[56:59], v[156:159], v[164:167], v[56:59]
	v_mfma_f32_16x16x32_bf16 v[52:55], v[148:151], v[172:175], v[52:55]
	v_mfma_f32_16x16x32_bf16 v[48:51], v[156:159], v[172:175], v[48:51]
	v_mfma_f32_16x16x32_bf16 v[44:47], v[148:151], v[180:183], v[44:47]
	v_mfma_f32_16x16x32_bf16 v[40:43], v[156:159], v[180:183], v[40:43]
	v_mfma_f32_16x16x32_bf16 v[36:39], v[148:151], v[188:191], v[36:39]
	v_mfma_f32_16x16x32_bf16 v[32:35], v[156:159], v[188:191], v[32:35]
	v_mfma_f32_16x16x32_bf16 v[60:63], v[152:155], v[168:171], v[60:63]
	v_mfma_f32_16x16x32_bf16 v[56:59], v[160:163], v[168:171], v[56:59]
	v_mfma_f32_16x16x32_bf16 v[52:55], v[152:155], v[176:179], v[52:55]
	v_mfma_f32_16x16x32_bf16 v[48:51], v[160:163], v[176:179], v[48:51]
	v_mfma_f32_16x16x32_bf16 v[44:47], v[152:155], v[184:187], v[44:47]
	v_mfma_f32_16x16x32_bf16 v[40:43], v[160:163], v[184:187], v[40:43]
	v_mfma_f32_16x16x32_bf16 v[36:39], v[152:155], v[194:197], v[36:39]
	v_mfma_f32_16x16x32_bf16 v[32:35], v[160:163], v[194:197], v[32:35]
	s_barrier
	ds_read_b128 v[148:151], v138 offset:32768
	ds_read_b128 v[152:155], v138 offset:33792
	ds_read_b128 v[156:159], v138 offset:34816
	ds_read_b128 v[160:163], v138 offset:35840
	s_add_u32 m0, s3, s29
	s_nop 0
	s_add_u32 vcc_lo, s4, s80
	s_addc_u32 vcc_hi, s5, s81
	global_load_lds_dwordx4 v128, vcc
	s_add_u32 m0, s3, s29
	s_add_u32 m0, m0, 0x2000
	s_nop 0
	global_load_lds_dwordx4 v130, vcc
	s_waitcnt vmcnt(6)
	s_barrier
; #define WAIT_V(n) asm volatile("s_waitcnt vmcnt(" #n ")" ::: "memory")
; #define WAIT_L(n) asm volatile("s_waitcnt lgkmcnt(" #n ")" ::: "memory")
; #define BAR __builtin_amdgcn_s_barrier()
; #define SCHED __builtin_amdgcn_sched_barrier(0)
; #define STAGE(P, BASE, br, kt) do { const char* _g = (const char*)((BASE) + (size_t)(br) * GK + (kt) * BK); \
;     __builtin_amdgcn_global_load_lds((const unsigned*)(_g + voff0), (unsigned*)((char*)(P) + tx * 16), 16, 0, 0); \
;     __builtin_amdgcn_global_load_lds((const unsigned*)(_g + voff1), (unsigned*)((char*)(P) + tx * 16 + 8192), 16, 0, 0); } while (0)
; #define LDA(dst, b, h) _Pragma("unroll") for (int m = 0; m < 4; ++m) _Pragma("unroll") for (int k = 0; k < 2; ++k) \
;     dst[m][k] = *reinterpret_cast<const bf16x8*>((char*)shm + abase + (((b) * 2 + (h)) * 16384 + (m * 2 + k) * 1024))
; #define LDB(dst, b, h) _Pragma("unroll") for (int n = 0; n < 2; ++n) _Pragma("unroll") for (int k = 0; k < 2; ++k) \
;     dst[n][k] = *reinterpret_cast<const bf16x8*>((char*)shm + bbase + (((b) * 2 + (h)) * 16384 + (n * 2 + k) * 1024))
; template <bool SWAP>
; __device__ __forceinline__ void gemm_main(const u16* __restrict__ A, const u16* __restrict__ Bt, int brow, int bcol,
;                                           u16* shm, f32x4 (&acc)[2][2][4][2]) {
;     ...
;     WAIT_V(6); BAR; MMA(1, 1, At, B1); BAR;
;     LDB(B0, 1, 0); SCHED; LDA(At, 1, 0); STAGE(SA(0, 1), A, brow + HALF, t + 2);
;     WAIT_L(8); BAR; WAIT_L(0); MMA(0, 0, At, B0); BAR; SCHED;
;     LDB(B1, 1, 1); STAGE(SB(1, 0), Bt, bcol, t + 3);
;     BAR; WAIT_L(0); MMA(0, 1, At, B1); BAR;
;     LDA(At, 1, 1); STAGE(SA(1, 0), A, brow, t + 3);
	v_mfma_f32_16x16x32_bf16 v[28:31], v[198:201], v[164:167], v[28:31]
	v_mfma_f32_16x16x32_bf16 v[24:27], v[206:209], v[164:167], v[24:27]
	v_mfma_f32_16x16x32_bf16 v[20:23], v[198:201], v[172:175], v[20:23]
	v_mfma_f32_16x16x32_bf16 v[16:19], v[206:209], v[172:175], v[16:19]
	v_mfma_f32_16x16x32_bf16 v[12:15], v[198:201], v[180:183], v[12:15]
	v_mfma_f32_16x16x32_bf16 v[8:11], v[206:209], v[180:183], v[8:11]
	v_mfma_f32_16x16x32_bf16 v[4:7], v[198:201], v[188:191], v[4:7]
	v_mfma_f32_16x16x32_bf16 v[0:3], v[206:209], v[188:191], v[0:3]
	v_mfma_f32_16x16x32_bf16 v[28:31], v[202:205], v[168:171], v[28:31]
	ds_read_b128 v[164:167], v137 offset:32768
	v_mfma_f32_16x16x32_bf16 v[24:27], v[226:229], v[168:171], v[24:27]
	v_mfma_f32_16x16x32_bf16 v[20:23], v[202:205], v[176:179], v[20:23]
	ds_read_b128 v[172:175], v137 offset:34816
	v_mfma_f32_16x16x32_bf16 v[16:19], v[226:229], v[176:179], v[16:19]
	v_mfma_f32_16x16x32_bf16 v[12:15], v[202:205], v[184:187], v[12:15]
	ds_read_b128 v[180:183], v137 offset:36864
	v_mfma_f32_16x16x32_bf16 v[8:11], v[226:229], v[184:187], v[8:11]
	v_mfma_f32_16x16x32_bf16 v[4:7], v[202:205], v[194:197], v[4:7]
	ds_read_b128 v[188:191], v137 offset:38912
	v_mfma_f32_16x16x32_bf16 v[0:3], v[226:229], v[194:197], v[0:3]
	s_barrier
	ds_read_b128 v[168:171], v137 offset:33792
	ds_read_b128 v[176:179], v137 offset:35840
	ds_read_b128 v[184:187], v137 offset:37888
	ds_read_b128 v[194:197], v137 offset:39936
	s_add_u32 m0, s3, 0x4000
	s_nop 0
	s_add_u32 vcc_lo, s4, s66
	s_addc_u32 vcc_hi, s5, s67
	global_load_lds_dwordx4 v132, vcc
	s_add_u32 m0, s3, 0x6000
	s_nop 0
	global_load_lds_dwordx4 v134, vcc
	s_waitcnt lgkmcnt(8)
	s_barrier
	s_waitcnt lgkmcnt(0)
	v_mfma_f32_16x16x32_bf16 v[124:127], v[148:151], v[164:167], v[124:127]
	v_mfma_f32_16x16x32_bf16 v[120:123], v[156:159], v[164:167], v[120:123]
	v_mfma_f32_16x16x32_bf16 v[116:119], v[148:151], v[172:175], v[116:119]
	v_mfma_f32_16x16x32_bf16 v[112:115], v[156:159], v[172:175], v[112:115]
	v_mfma_f32_16x16x32_bf16 v[108:111], v[148:151], v[180:183], v[108:111]
	v_mfma_f32_16x16x32_bf16 v[104:107], v[156:159], v[180:183], v[104:107]
	v_mfma_f32_16x16x32_bf16 v[100:103], v[148:151], v[188:191], v[100:103]
	v_mfma_f32_16x16x32_bf16 v[96:99], v[156:159], v[188:191], v[96:99]
	v_mfma_f32_16x16x32_bf16 v[124:127], v[152:155], v[168:171], v[124:127]
	v_mfma_f32_16x16x32_bf16 v[120:123], v[160:163], v[168:171], v[120:123]
	v_mfma_f32_16x16x32_bf16 v[116:119], v[152:155], v[176:179], v[116:119]
	v_mfma_f32_16x16x32_bf16 v[112:115], v[160:163], v[176:179], v[112:115]
	v_mfma_f32_16x16x32_bf16 v[108:111], v[152:155], v[184:187], v[108:111]
	v_mfma_f32_16x16x32_bf16 v[104:107], v[160:163], v[184:187], v[104:107]
	v_mfma_f32_16x16x32_bf16 v[100:103], v[152:155], v[194:197], v[100:103]
	v_mfma_f32_16x16x32_bf16 v[96:99], v[160:163], v[194:197], v[96:99]
	s_barrier
	ds_read_b128 v[198:201], v138 offset:49152
	ds_read_b128 v[202:205], v138 offset:50176
	ds_read_b128 v[206:209], v138 offset:51200
	ds_read_b128 v[226:229], v138 offset:52224
	s_add_u32 m0, s3, s30
	s_nop 0
	s_add_u32 vcc_lo, s4, s86
	s_addc_u32 vcc_hi, s5, s87
	global_load_lds_dwordx4 v128, vcc
	v_lshl_add_u64 v[238:239], v[236:237], 0, s[86:87]
	s_add_u32 m0, s3, s30
	s_add_u32 m0, m0, 0x2000
	s_nop 0
	global_load_lds_dwordx4 v130, vcc
	s_barrier
	s_waitcnt lgkmcnt(0)
	v_mfma_f32_16x16x32_bf16 v[92:95], v[198:201], v[164:167], v[92:95]
	v_mfma_f32_16x16x32_bf16 v[88:91], v[206:209], v[164:167], v[88:91]
	v_mfma_f32_16x16x32_bf16 v[84:87], v[198:201], v[172:175], v[84:87]
	v_mfma_f32_16x16x32_bf16 v[80:83], v[206:209], v[172:175], v[80:83]
	v_mfma_f32_16x16x32_bf16 v[76:79], v[198:201], v[180:183], v[76:79]
	v_mfma_f32_16x16x32_bf16 v[72:75], v[206:209], v[180:183], v[72:75]
	v_mfma_f32_16x16x32_bf16 v[68:71], v[198:201], v[188:191], v[68:71]
	v_mfma_f32_16x16x32_bf16 v[64:67], v[206:209], v[188:191], v[64:67]
	v_mfma_f32_16x16x32_bf16 v[92:95], v[202:205], v[168:171], v[92:95]
	ds_read_b128 v[164:167], v137 offset:49152
	v_mfma_f32_16x16x32_bf16 v[88:91], v[226:229], v[168:171], v[88:91]
	v_mfma_f32_16x16x32_bf16 v[84:87], v[202:205], v[176:179], v[84:87]
	ds_read_b128 v[172:175], v137 offset:51200
	v_mfma_f32_16x16x32_bf16 v[80:83], v[226:229], v[176:179], v[80:83]
	v_mfma_f32_16x16x32_bf16 v[76:79], v[202:205], v[184:187], v[76:79]
	ds_read_b128 v[180:183], v137 offset:53248
	v_mfma_f32_16x16x32_bf16 v[72:75], v[226:229], v[184:187], v[72:75]
	v_mfma_f32_16x16x32_bf16 v[68:71], v[202:205], v[194:197], v[68:71]
	ds_read_b128 v[188:191], v137 offset:55296
	v_mfma_f32_16x16x32_bf16 v[64:67], v[226:229], v[194:197], v[64:67]
	s_barrier
	ds_read_b128 v[168:171], v137 offset:50176
	ds_read_b128 v[176:179], v137 offset:52224
	ds_read_b128 v[184:187], v137 offset:54272
	ds_read_b128 v[194:197], v137 offset:56320
	v_add_u32_e32 v225, 0x8000, v192
	s_add_u32 m0, s3, 0x8000
	s_nop 0
	s_add_u32 vcc_lo, s4, s26
	s_addc_u32 vcc_hi, s5, s27
	global_load_lds_dwordx4 v132, vcc
	v_lshl_add_u64 v[230:231], v[232:233], 0, s[26:27]
	s_add_u32 m0, s3, 0xa000
	s_nop 0
	global_load_lds_dwordx4 v134, vcc
	s_waitcnt vmcnt(8)
	s_barrier
; #define WAIT_V(n) asm volatile("s_waitcnt vmcnt(" #n ")" ::: "memory")
; #define WAIT_L(n) asm volatile("s_waitcnt lgkmcnt(" #n ")" ::: "memory")
; #define BAR __builtin_amdgcn_s_barrier()
; #define SCHED __builtin_amdgcn_sched_barrier(0)
; #define STAGE(P, BASE, br, kt) do { const char* _g = (const char*)((BASE) + (size_t)(br) * GK + (kt) * BK); \
;     __builtin_amdgcn_global_load_lds((const unsigned*)(_g + voff0), (unsigned*)((char*)(P) + tx * 16), 16, 0, 0); \
;     __builtin_amdgcn_global_load_lds((const unsigned*)(_g + voff1), (unsigned*)((char*)(P) + tx * 16 + 8192), 16, 0, 0); } while (0)
; #define LDA(dst, b, h) _Pragma("unroll") for (int m = 0; m < 4; ++m) _Pragma("unroll") for (int k = 0; k < 2; ++k) \
;     dst[m][k] = *reinterpret_cast<const bf16x8*>((char*)shm + abase + (((b) * 2 + (h)) * 16384 + (m * 2 + k) * 1024))
; #define LDB(dst, b, h) _Pragma("unroll") for (int n = 0; n < 2; ++n) _Pragma("unroll") for (int k = 0; k < 2; ++k) \
;     dst[n][k] = *reinterpret_cast<const bf16x8*>((char*)shm + bbase + (((b) * 2 + (h)) * 16384 + (n * 2 + k) * 1024))
; template <bool SWAP>
; __device__ __forceinline__ void gemm_main(const u16* __restrict__ A, const u16* __restrict__ Bt, int brow, int bcol,
;                                           u16* shm, f32x4 (&acc)[2][2][4][2]) {
;     ...
;     LDA(At, 1, 1); STAGE(SA(1, 0), A, brow, t + 3);
;     BAR; WAIT_L(0); MMA(1, 0, At, B0); BAR; SCHED;
;     STAGE(SB(1, 1), Bt, bcol + HALF, t + 3);
;     WAIT_V(6); BAR; MMA(1, 1, At, B1); BAR;
;   }
;   { LDB(B0, 0, 0); LDA(At, 0, 0); STAGE(SA(1, 1), A, brow + HALF, nt - 1);
;     BAR; WAIT_L(0); MMA(0, 0, At, B0); BAR;
	s_waitcnt lgkmcnt(0)
	v_mfma_f32_16x16x32_bf16 v[60:63], v[148:151], v[164:167], v[60:63]
	v_mfma_f32_16x16x32_bf16 v[56:59], v[156:159], v[164:167], v[56:59]
	v_mfma_f32_16x16x32_bf16 v[52:55], v[148:151], v[172:175], v[52:55]
	v_mfma_f32_16x16x32_bf16 v[48:51], v[156:159], v[172:175], v[48:51]
	v_mfma_f32_16x16x32_bf16 v[44:47], v[148:151], v[180:183], v[44:47]
	v_mfma_f32_16x16x32_bf16 v[40:43], v[156:159], v[180:183], v[40:43]
	v_mfma_f32_16x16x32_bf16 v[36:39], v[148:151], v[188:191], v[36:39]
	v_mfma_f32_16x16x32_bf16 v[32:35], v[156:159], v[188:191], v[32:35]
	v_mfma_f32_16x16x32_bf16 v[60:63], v[152:155], v[168:171], v[60:63]
	v_mfma_f32_16x16x32_bf16 v[56:59], v[160:163], v[168:171], v[56:59]
	v_mfma_f32_16x16x32_bf16 v[52:55], v[152:155], v[176:179], v[52:55]
	v_mfma_f32_16x16x32_bf16 v[48:51], v[160:163], v[176:179], v[48:51]
	v_mfma_f32_16x16x32_bf16 v[44:47], v[152:155], v[184:187], v[44:47]
	v_mfma_f32_16x16x32_bf16 v[40:43], v[160:163], v[184:187], v[40:43]
	v_mfma_f32_16x16x32_bf16 v[36:39], v[152:155], v[194:197], v[36:39]
	v_mfma_f32_16x16x32_bf16 v[32:35], v[160:163], v[194:197], v[32:35]
	s_barrier
	ds_read_b128 v[148:151], v138
	ds_read_b128 v[152:155], v138 offset:1024
	ds_read_b128 v[156:159], v138 offset:2048
	ds_read_b128 v[160:163], v138 offset:3072
	s_add_u32 m0, s3, s31
	s_nop 0
	s_add_u32 vcc_lo, s4, s56
	s_addc_u32 vcc_hi, s5, s57
	global_load_lds_dwordx4 v128, vcc
	v_lshl_add_u64 v[254:255], v[236:237], 0, s[56:57]
	s_add_u32 m0, s3, s31
	s_add_u32 m0, m0, 0x2000
	s_nop 0
	global_load_lds_dwordx4 v130, vcc
	s_waitcnt vmcnt(6)
	s_barrier
	v_mfma_f32_16x16x32_bf16 v[28:31], v[198:201], v[164:167], v[28:31]
	v_mfma_f32_16x16x32_bf16 v[24:27], v[206:209], v[164:167], v[24:27]
	v_mfma_f32_16x16x32_bf16 v[20:23], v[198:201], v[172:175], v[20:23]
	v_mfma_f32_16x16x32_bf16 v[16:19], v[206:209], v[172:175], v[16:19]
	v_mfma_f32_16x16x32_bf16 v[12:15], v[198:201], v[180:183], v[12:15]
	v_mfma_f32_16x16x32_bf16 v[8:11], v[206:209], v[180:183], v[8:11]
	v_mfma_f32_16x16x32_bf16 v[4:7], v[198:201], v[188:191], v[4:7]
	v_mfma_f32_16x16x32_bf16 v[0:3], v[206:209], v[188:191], v[0:3]
	v_mfma_f32_16x16x32_bf16 v[28:31], v[202:205], v[168:171], v[28:31]
	ds_read_b128 v[164:167], v137
	v_mfma_f32_16x16x32_bf16 v[24:27], v[226:229], v[168:171], v[24:27]
	v_mfma_f32_16x16x32_bf16 v[20:23], v[202:205], v[176:179], v[20:23]
	ds_read_b128 v[172:175], v137 offset:2048
	v_mfma_f32_16x16x32_bf16 v[16:19], v[226:229], v[176:179], v[16:19]
	s_add_i32 s2, s2, 2
	s_add_u32 s4, s4, 0x100
	s_addc_u32 s5, s5, 0
	s_cmp_lt_u32 s2, 28
	v_mfma_f32_16x16x32_bf16 v[12:15], v[202:205], v[184:187], v[12:15]
	ds_read_b128 v[180:183], v137 offset:4096
	v_mfma_f32_16x16x32_bf16 v[8:11], v[226:229], v[184:187], v[8:11]
	v_mfma_f32_16x16x32_bf16 v[4:7], v[202:205], v[194:197], v[4:7]
	ds_read_b128 v[188:191], v137 offset:6144
	v_mfma_f32_16x16x32_bf16 v[0:3], v[226:229], v[194:197], v[0:3]
	s_barrier
	s_cbranch_scc1 .LBB0_576
	v_lshlrev_b32_e32 v128, 3, v139
	v_lshlrev_b32_e32 v129, 5, v139
	v_and_b32_e32 v128, 0xffff0, v128
	v_and_b32_e32 v129, 32, v129
	v_add_u32_e32 v129, v129, v142
	v_add_lshl_u32 v128, v141, v128, 12
	v_lshl_add_u32 v192, v129, 1, v128
	v_lshlrev_b32_e32 v128, 3, v143
	v_lshlrev_b32_e32 v129, 5, v143
	v_and_b32_e32 v128, 0xffff0, v128
	v_and_b32_e32 v129, 32, v129
	v_add_u32_e32 v129, v129, v145
	v_add_lshl_u32 v128, v144, v128, 12
	v_lshl_add_u32 v144, v129, 1, v128
	v_mov_b32_e32 v145, v193
	v_lshl_add_u64 v[184:185], s[0:1], 0, v[192:193]
	s_mov_b64 s[4:5], 0xf80
	v_readfirstlane_b32 s2, v146
	v_lshl_add_u64 v[184:185], v[184:185], 0, s[4:5]
	s_mov_b32 m0, s2
	v_lshl_add_u64 v[144:145], s[0:1], 0, v[144:145]
	v_readfirstlane_b32 s0, v147
	ds_read_b128 v[128:131], v138
	ds_read_b128 v[132:135], v138 offset:1024
	ds_read_b128 v[140:143], v138 offset:2048
	ds_read_b128 v[148:151], v138 offset:3072
	ds_read_b128 v[152:155], v137
	ds_read_b128 v[156:159], v137 offset:1024
	ds_read_b128 v[160:163], v137 offset:2048
	ds_read_b128 v[164:167], v137 offset:3072
	ds_read_b128 v[168:171], v137 offset:4096
	ds_read_b128 v[172:175], v137 offset:5120
	ds_read_b128 v[176:179], v137 offset:6144
	ds_read_b128 v[180:183], v137 offset:7168
	global_load_lds_dwordx4 v[184:185], off
	v_lshl_add_u64 v[144:145], v[144:145], 0, s[4:5]
	s_mov_b32 m0, s0
	s_nop 0
	global_load_lds_dwordx4 v[144:145], off
	s_barrier
	s_waitcnt lgkmcnt(0)
	s_setprio 1
	s_waitcnt lgkmcnt(0)
	v_mfma_f32_16x16x32_bf16 v[124:127], v[128:131], v[152:155], v[124:127]
	v_mfma_f32_16x16x32_bf16 v[120:123], v[140:143], v[152:155], v[120:123]
	v_mfma_f32_16x16x32_bf16 v[116:119], v[128:131], v[160:163], v[116:119]
	v_mfma_f32_16x16x32_bf16 v[112:115], v[140:143], v[160:163], v[112:115]
	v_mfma_f32_16x16x32_bf16 v[108:111], v[128:131], v[168:171], v[108:111]
	v_mfma_f32_16x16x32_bf16 v[104:107], v[140:143], v[168:171], v[104:107]
	v_mfma_f32_16x16x32_bf16 v[100:103], v[128:131], v[176:179], v[100:103]
	v_mfma_f32_16x16x32_bf16 v[96:99], v[140:143], v[176:179], v[96:99]
	v_mfma_f32_16x16x32_bf16 v[124:127], v[132:135], v[156:159], v[124:127]
	v_mfma_f32_16x16x32_bf16 v[120:123], v[148:151], v[156:159], v[120:123]
	v_mfma_f32_16x16x32_bf16 v[116:119], v[132:135], v[164:167], v[116:119]
	v_mfma_f32_16x16x32_bf16 v[112:115], v[148:151], v[164:167], v[112:115]
	v_mfma_f32_16x16x32_bf16 v[108:111], v[132:135], v[172:175], v[108:111]
	v_mfma_f32_16x16x32_bf16 v[104:107], v[148:151], v[172:175], v[104:107]
	v_mfma_f32_16x16x32_bf16 v[100:103], v[132:135], v[180:183], v[100:103]
	v_mfma_f32_16x16x32_bf16 v[96:99], v[148:151], v[180:183], v[96:99]
	s_setprio 0
	s_barrier
; #define WAIT_V(n) asm volatile("s_waitcnt vmcnt(" #n ")" ::: "memory")
; #define WAIT_L(n) asm volatile("s_waitcnt lgkmcnt(" #n ")" ::: "memory")
; #define BAR __builtin_amdgcn_s_barrier()
; #define LDA(dst, b, h) _Pragma("unroll") for (int m = 0; m < 4; ++m) _Pragma("unroll") for (int k = 0; k < 2; ++k) \
;     dst[m][k] = *reinterpret_cast<const bf16x8*>((char*)shm + abase + (((b) * 2 + (h)) * 16384 + (m * 2 + k) * 1024))
; #define LDB(dst, b, h) _Pragma("unroll") for (int n = 0; n < 2; ++n) _Pragma("unroll") for (int k = 0; k < 2; ++k) \
;     dst[n][k] = *reinterpret_cast<const bf16x8*>((char*)shm + bbase + (((b) * 2 + (h)) * 16384 + (n * 2 + k) * 1024))
; template <bool SWAP>
; __device__ __forceinline__ void gemm_main(const u16* __restrict__ A, const u16* __restrict__ Bt, int brow, int bcol,
;                                           u16* shm, f32x4 (&acc)[2][2][4][2]) {
;     ...
;     BAR; WAIT_L(0); MMA(0, 0, At, B0); BAR;
;     LDB(B1, 0, 1); BAR; WAIT_L(0); MMA(0, 1, At, B1); BAR;
;     LDA(At, 0, 1); WAIT_V(4); BAR; WAIT_L(0); MMA(1, 0, At, B0); MMA(1, 1, At, B1); BAR; }
;   { LDB(B0, 1, 0); LDA(At, 1, 0); WAIT_V(2); BAR; WAIT_L(0); MMA(0, 0, At, B0); BAR;
	ds_read_b128 v[144:147], v138 offset:16384
	ds_read_b128 v[184:187], v138 offset:17408
	ds_read_b128 v[188:191], v138 offset:18432
	ds_read_b128 v[194:197], v138 offset:19456
	s_barrier
	s_waitcnt lgkmcnt(0)
	s_setprio 1
	s_waitcnt lgkmcnt(0)
	v_mfma_f32_16x16x32_bf16 v[92:95], v[144:147], v[152:155], v[92:95]
	v_mfma_f32_16x16x32_bf16 v[88:91], v[188:191], v[152:155], v[88:91]
	v_mfma_f32_16x16x32_bf16 v[84:87], v[144:147], v[160:163], v[84:87]
	v_mfma_f32_16x16x32_bf16 v[80:83], v[188:191], v[160:163], v[80:83]
	v_mfma_f32_16x16x32_bf16 v[76:79], v[144:147], v[168:171], v[76:79]
	v_mfma_f32_16x16x32_bf16 v[72:75], v[188:191], v[168:171], v[72:75]
	v_mfma_f32_16x16x32_bf16 v[68:71], v[144:147], v[176:179], v[68:71]
	v_mfma_f32_16x16x32_bf16 v[64:67], v[188:191], v[176:179], v[64:67]
	v_mfma_f32_16x16x32_bf16 v[92:95], v[184:187], v[156:159], v[92:95]
	v_mfma_f32_16x16x32_bf16 v[88:91], v[194:197], v[156:159], v[88:91]
	v_mfma_f32_16x16x32_bf16 v[84:87], v[184:187], v[164:167], v[84:87]
	v_mfma_f32_16x16x32_bf16 v[80:83], v[194:197], v[164:167], v[80:83]
	v_mfma_f32_16x16x32_bf16 v[76:79], v[184:187], v[172:175], v[76:79]
	v_mfma_f32_16x16x32_bf16 v[72:75], v[194:197], v[172:175], v[72:75]
	v_mfma_f32_16x16x32_bf16 v[68:71], v[184:187], v[180:183], v[68:71]
	v_mfma_f32_16x16x32_bf16 v[64:67], v[194:197], v[180:183], v[64:67]
	s_setprio 0
	s_barrier
	ds_read_b128 v[152:155], v137 offset:16384
	ds_read_b128 v[156:159], v137 offset:17408
	ds_read_b128 v[160:163], v137 offset:18432
	ds_read_b128 v[164:167], v137 offset:19456
	ds_read_b128 v[168:171], v137 offset:20480
	ds_read_b128 v[172:175], v137 offset:21504
	ds_read_b128 v[176:179], v137 offset:22528
	ds_read_b128 v[180:183], v137 offset:23552
	s_waitcnt vmcnt(4)
	s_barrier
	s_waitcnt lgkmcnt(0)
	s_setprio 1
	s_waitcnt lgkmcnt(0)
	v_mfma_f32_16x16x32_bf16 v[60:63], v[128:131], v[152:155], v[60:63]
	v_mfma_f32_16x16x32_bf16 v[56:59], v[140:143], v[152:155], v[56:59]
	v_mfma_f32_16x16x32_bf16 v[52:55], v[128:131], v[160:163], v[52:55]
	v_mfma_f32_16x16x32_bf16 v[48:51], v[140:143], v[160:163], v[48:51]
	v_mfma_f32_16x16x32_bf16 v[44:47], v[128:131], v[168:171], v[44:47]
	v_mfma_f32_16x16x32_bf16 v[40:43], v[140:143], v[168:171], v[40:43]
	v_mfma_f32_16x16x32_bf16 v[36:39], v[128:131], v[176:179], v[36:39]
	v_mfma_f32_16x16x32_bf16 v[32:35], v[140:143], v[176:179], v[32:35]
	v_mfma_f32_16x16x32_bf16 v[60:63], v[132:135], v[156:159], v[60:63]
	v_mfma_f32_16x16x32_bf16 v[56:59], v[148:151], v[156:159], v[56:59]
	v_mfma_f32_16x16x32_bf16 v[52:55], v[132:135], v[164:167], v[52:55]
	v_mfma_f32_16x16x32_bf16 v[48:51], v[148:151], v[164:167], v[48:51]
	v_mfma_f32_16x16x32_bf16 v[44:47], v[132:135], v[172:175], v[44:47]
	v_mfma_f32_16x16x32_bf16 v[40:43], v[148:151], v[172:175], v[40:43]
	v_mfma_f32_16x16x32_bf16 v[36:39], v[132:135], v[180:183], v[36:39]
	v_mfma_f32_16x16x32_bf16 v[32:35], v[148:151], v[180:183], v[32:35]
	s_setprio 0
	s_setprio 1
	v_mfma_f32_16x16x32_bf16 v[28:31], v[144:147], v[152:155], v[28:31]
	v_mfma_f32_16x16x32_bf16 v[24:27], v[188:191], v[152:155], v[24:27]
	v_mfma_f32_16x16x32_bf16 v[20:23], v[144:147], v[160:163], v[20:23]
	v_mfma_f32_16x16x32_bf16 v[16:19], v[188:191], v[160:163], v[16:19]
	v_mfma_f32_16x16x32_bf16 v[12:15], v[144:147], v[168:171], v[12:15]
	v_mfma_f32_16x16x32_bf16 v[8:11], v[188:191], v[168:171], v[8:11]
	v_mfma_f32_16x16x32_bf16 v[4:7], v[144:147], v[176:179], v[4:7]
	v_mfma_f32_16x16x32_bf16 v[0:3], v[188:191], v[176:179], v[0:3]
	v_mfma_f32_16x16x32_bf16 v[28:31], v[184:187], v[156:159], v[28:31]
	v_mfma_f32_16x16x32_bf16 v[24:27], v[194:197], v[156:159], v[24:27]
	v_mfma_f32_16x16x32_bf16 v[20:23], v[184:187], v[164:167], v[20:23]
	v_mfma_f32_16x16x32_bf16 v[16:19], v[194:197], v[164:167], v[16:19]
	v_mfma_f32_16x16x32_bf16 v[12:15], v[184:187], v[172:175], v[12:15]
	v_mfma_f32_16x16x32_bf16 v[8:11], v[194:197], v[172:175], v[8:11]
	v_mfma_f32_16x16x32_bf16 v[4:7], v[184:187], v[180:183], v[4:7]
	v_mfma_f32_16x16x32_bf16 v[0:3], v[194:197], v[180:183], v[0:3]
	s_setprio 0
	s_barrier
	ds_read_b128 v[128:131], v138 offset:32768
	ds_read_b128 v[132:135], v138 offset:33792
	ds_read_b128 v[140:143], v138 offset:34816
	ds_read_b128 v[144:147], v138 offset:35840
	ds_read_b128 v[148:151], v137 offset:32768
	ds_read_b128 v[152:155], v137 offset:33792
	ds_read_b128 v[156:159], v137 offset:34816
	ds_read_b128 v[160:163], v137 offset:35840
	ds_read_b128 v[164:167], v137 offset:36864
	ds_read_b128 v[168:171], v137 offset:37888
	ds_read_b128 v[172:175], v137 offset:38912
	ds_read_b128 v[176:179], v137 offset:39936
	s_waitcnt vmcnt(2)
	s_barrier
; #define WAIT_V(n) asm volatile("s_waitcnt vmcnt(" #n ")" ::: "memory")
; #define WAIT_L(n) asm volatile("s_waitcnt lgkmcnt(" #n ")" ::: "memory")
; #define BAR __builtin_amdgcn_s_barrier()
; #define LDA(dst, b, h) _Pragma("unroll") for (int m = 0; m < 4; ++m) _Pragma("unroll") for (int k = 0; k < 2; ++k) \
;     dst[m][k] = *reinterpret_cast<const bf16x8*>((char*)shm + abase + (((b) * 2 + (h)) * 16384 + (m * 2 + k) * 1024))
; #define LDB(dst, b, h) _Pragma("unroll") for (int n = 0; n < 2; ++n) _Pragma("unroll") for (int k = 0; k < 2; ++k) \
;     dst[n][k] = *reinterpret_cast<const bf16x8*>((char*)shm + bbase + (((b) * 2 + (h)) * 16384 + (n * 2 + k) * 1024))
; template <bool SWAP>
; __device__ __forceinline__ void gemm_main(const u16* __restrict__ A, const u16* __restrict__ Bt, int brow, int bcol,
;                                           u16* shm, f32x4 (&acc)[2][2][4][2]) {
;     ...
;   { LDB(B0, 1, 0); LDA(At, 1, 0); WAIT_V(2); BAR; WAIT_L(0); MMA(0, 0, At, B0); BAR;
;     LDB(B1, 1, 1); WAIT_V(0); BAR; WAIT_L(0); MMA(0, 1, At, B1); BAR;
;     LDA(At, 1, 1); BAR; WAIT_L(0); MMA(1, 0, At, B0); MMA(1, 1, At, B1); BAR; }
;   if (wr == 0) BAR;
	s_waitcnt lgkmcnt(0)
	s_setprio 1
	s_waitcnt lgkmcnt(0)
	v_mfma_f32_16x16x32_bf16 v[124:127], v[128:131], v[148:151], v[124:127]
	v_mfma_f32_16x16x32_bf16 v[120:123], v[140:143], v[148:151], v[120:123]
	v_mfma_f32_16x16x32_bf16 v[116:119], v[128:131], v[156:159], v[116:119]
	v_mfma_f32_16x16x32_bf16 v[112:115], v[140:143], v[156:159], v[112:115]
	v_mfma_f32_16x16x32_bf16 v[108:111], v[128:131], v[164:167], v[108:111]
	v_mfma_f32_16x16x32_bf16 v[104:107], v[140:143], v[164:167], v[104:107]
	v_mfma_f32_16x16x32_bf16 v[100:103], v[128:131], v[172:175], v[100:103]
	v_mfma_f32_16x16x32_bf16 v[96:99], v[140:143], v[172:175], v[96:99]
	v_mfma_f32_16x16x32_bf16 v[124:127], v[132:135], v[152:155], v[124:127]
	v_mfma_f32_16x16x32_bf16 v[120:123], v[144:147], v[152:155], v[120:123]
	v_mfma_f32_16x16x32_bf16 v[116:119], v[132:135], v[160:163], v[116:119]
	v_mfma_f32_16x16x32_bf16 v[112:115], v[144:147], v[160:163], v[112:115]
	v_mfma_f32_16x16x32_bf16 v[108:111], v[132:135], v[168:171], v[108:111]
	v_mfma_f32_16x16x32_bf16 v[104:107], v[144:147], v[168:171], v[104:107]
	v_mfma_f32_16x16x32_bf16 v[100:103], v[132:135], v[176:179], v[100:103]
	v_mfma_f32_16x16x32_bf16 v[96:99], v[144:147], v[176:179], v[96:99]
	s_setprio 0
	s_barrier
	ds_read_b128 v[180:183], v138 offset:49152
	ds_read_b128 v[184:187], v138 offset:50176
	ds_read_b128 v[188:191], v138 offset:51200
	ds_read_b128 v[194:197], v138 offset:52224
	s_waitcnt vmcnt(0)
	s_barrier
	s_waitcnt lgkmcnt(0)
	s_setprio 1
	s_waitcnt lgkmcnt(0)
	v_mfma_f32_16x16x32_bf16 v[92:95], v[180:183], v[148:151], v[92:95]
	v_mfma_f32_16x16x32_bf16 v[88:91], v[188:191], v[148:151], v[88:91]
	v_mfma_f32_16x16x32_bf16 v[84:87], v[180:183], v[156:159], v[84:87]
	v_mfma_f32_16x16x32_bf16 v[80:83], v[188:191], v[156:159], v[80:83]
	v_mfma_f32_16x16x32_bf16 v[76:79], v[180:183], v[164:167], v[76:79]
	v_mfma_f32_16x16x32_bf16 v[72:75], v[188:191], v[164:167], v[72:75]
	v_mfma_f32_16x16x32_bf16 v[68:71], v[180:183], v[172:175], v[68:71]
	v_mfma_f32_16x16x32_bf16 v[64:67], v[188:191], v[172:175], v[64:67]
	v_mfma_f32_16x16x32_bf16 v[92:95], v[184:187], v[152:155], v[92:95]
	v_mfma_f32_16x16x32_bf16 v[88:91], v[194:197], v[152:155], v[88:91]
	v_mfma_f32_16x16x32_bf16 v[84:87], v[184:187], v[160:163], v[84:87]
	v_mfma_f32_16x16x32_bf16 v[80:83], v[194:197], v[160:163], v[80:83]
	v_mfma_f32_16x16x32_bf16 v[76:79], v[184:187], v[168:171], v[76:79]
	v_mfma_f32_16x16x32_bf16 v[72:75], v[194:197], v[168:171], v[72:75]
	v_mfma_f32_16x16x32_bf16 v[68:71], v[184:187], v[176:179], v[68:71]
	v_mfma_f32_16x16x32_bf16 v[64:67], v[194:197], v[176:179], v[64:67]
	s_setprio 0
	s_barrier
	ds_read_b128 v[148:151], v137 offset:49152
	ds_read_b128 v[152:155], v137 offset:50176
	ds_read_b128 v[156:159], v137 offset:51200
	ds_read_b128 v[160:163], v137 offset:52224
	ds_read_b128 v[164:167], v137 offset:53248
	ds_read_b128 v[168:171], v137 offset:54272
	ds_read_b128 v[172:175], v137 offset:55296
	ds_read_b128 v[176:179], v137 offset:56320
	s_barrier
	s_waitcnt lgkmcnt(0)
	s_setprio 1
	s_waitcnt lgkmcnt(0)
	v_mfma_f32_16x16x32_bf16 v[60:63], v[128:131], v[148:151], v[60:63]
	v_mfma_f32_16x16x32_bf16 v[56:59], v[140:143], v[148:151], v[56:59]
	v_mfma_f32_16x16x32_bf16 v[52:55], v[128:131], v[156:159], v[52:55]
	v_mfma_f32_16x16x32_bf16 v[48:51], v[140:143], v[156:159], v[48:51]
	v_mfma_f32_16x16x32_bf16 v[44:47], v[128:131], v[164:167], v[44:47]
	v_mfma_f32_16x16x32_bf16 v[40:43], v[140:143], v[164:167], v[40:43]
	v_mfma_f32_16x16x32_bf16 v[36:39], v[128:131], v[172:175], v[36:39]
	v_mfma_f32_16x16x32_bf16 v[32:35], v[140:143], v[172:175], v[32:35]
	v_mfma_f32_16x16x32_bf16 v[60:63], v[132:135], v[152:155], v[60:63]
	v_mfma_f32_16x16x32_bf16 v[56:59], v[144:147], v[152:155], v[56:59]
	v_mfma_f32_16x16x32_bf16 v[52:55], v[132:135], v[160:163], v[52:55]
	v_mfma_f32_16x16x32_bf16 v[48:51], v[144:147], v[160:163], v[48:51]
	v_mfma_f32_16x16x32_bf16 v[44:47], v[132:135], v[168:171], v[44:47]
	v_mfma_f32_16x16x32_bf16 v[40:43], v[144:147], v[168:171], v[40:43]
	v_mfma_f32_16x16x32_bf16 v[36:39], v[132:135], v[176:179], v[36:39]
	v_mfma_f32_16x16x32_bf16 v[32:35], v[144:147], v[176:179], v[32:35]
	s_setprio 0
	s_setprio 1
	v_mfma_f32_16x16x32_bf16 v[28:31], v[180:183], v[148:151], v[28:31]
	v_mfma_f32_16x16x32_bf16 v[24:27], v[188:191], v[148:151], v[24:27]
	v_mfma_f32_16x16x32_bf16 v[20:23], v[180:183], v[156:159], v[20:23]
	v_mfma_f32_16x16x32_bf16 v[16:19], v[188:191], v[156:159], v[16:19]
	v_mfma_f32_16x16x32_bf16 v[12:15], v[180:183], v[164:167], v[12:15]
	v_mfma_f32_16x16x32_bf16 v[8:11], v[188:191], v[164:167], v[8:11]
	v_mfma_f32_16x16x32_bf16 v[4:7], v[180:183], v[172:175], v[4:7]
	v_mfma_f32_16x16x32_bf16 v[0:3], v[188:191], v[172:175], v[0:3]
	v_mfma_f32_16x16x32_bf16 v[28:31], v[184:187], v[152:155], v[28:31]
	v_mfma_f32_16x16x32_bf16 v[24:27], v[194:197], v[152:155], v[24:27]
	v_mfma_f32_16x16x32_bf16 v[20:23], v[184:187], v[160:163], v[20:23]
	v_mfma_f32_16x16x32_bf16 v[16:19], v[194:197], v[160:163], v[16:19]
	v_mfma_f32_16x16x32_bf16 v[12:15], v[184:187], v[168:171], v[12:15]
	v_mfma_f32_16x16x32_bf16 v[8:11], v[194:197], v[168:171], v[8:11]
	v_mfma_f32_16x16x32_bf16 v[4:7], v[184:187], v[176:179], v[4:7]
	v_mfma_f32_16x16x32_bf16 v[0:3], v[194:197], v[176:179], v[0:3]
	s_setprio 0
	s_movk_i32 s0, 0x100
	v_cmp_gt_u32_e32 vcc, s0, v136
	s_barrier
	s_and_saveexec_b64 s[0:1], vcc
	s_cbranch_execz .LBB0_579
	s_barrier

; #define WAIT_V(n) asm volatile("s_waitcnt vmcnt(" #n ")" ::: "memory")
; #define WAIT_L(n) asm volatile("s_waitcnt lgkmcnt(" #n ")" ::: "memory")
; #define BAR __builtin_amdgcn_s_barrier()
; #define SCHED __builtin_amdgcn_sched_barrier(0)
; #define STAGE(P, BASE, br, kt) do { const char* _g = (const char*)((BASE) + (size_t)(br) * GK + (kt) * BK); \
;     __builtin_amdgcn_global_load_lds((const unsigned*)(_g + voff0), (unsigned*)((char*)(P) + tx * 16), 16, 0, 0); \
;     __builtin_amdgcn_global_load_lds((const unsigned*)(_g + voff1), (unsigned*)((char*)(P) + tx * 16 + 8192), 16, 0, 0); } while (0)
; #define LDA(dst, b, h) _Pragma("unroll") for (int m = 0; m < 4; ++m) _Pragma("unroll") for (int k = 0; k < 2; ++k) \
;     dst[m][k] = *reinterpret_cast<const bf16x8*>((char*)shm + abase + (((b) * 2 + (h)) * 16384 + (m * 2 + k) * 1024))
; #define LDB(dst, b, h) _Pragma("unroll") for (int n = 0; n < 2; ++n) _Pragma("unroll") for (int k = 0; k < 2; ++k) \
;     dst[n][k] = *reinterpret_cast<const bf16x8*>((char*)shm + bbase + (((b) * 2 + (h)) * 16384 + (n * 2 + k) * 1024))
; template <bool SWAP>
; __device__ __forceinline__ void gemm_main(const u16* __restrict__ A, const u16* __restrict__ Bt, int brow, int bcol,
;                                           u16* shm, f32x4 (&acc)[2][2][4][2]) {
;     ...
;     LDB(B0, 0, 0); SCHED; LDA(At, 0, 0); STAGE(SA(1, 1), A, brow + HALF, t + 1);
;     WAIT_L(8); BAR; WAIT_L(0); MMA(0, 0, At, B0); BAR; SCHED;
;     LDB(B1, 0, 1); STAGE(SB(0, 0), Bt, bcol, t + 2);
;     BAR; WAIT_L(0); MMA(0, 1, At, B1); BAR;
;     LDA(At, 0, 1); STAGE(SA(0, 0), A, brow, t + 2);
;     BAR; WAIT_L(0); MMA(1, 0, At, B0); BAR; SCHED;
;     STAGE(SB(0, 1), Bt, bcol + HALF, t + 2);
;     WAIT_V(6); BAR; MMA(1, 1, At, B1); BAR;
;     LDB(B0, 1, 0); SCHED; LDA(At, 1, 0); STAGE(SA(0, 1), A, brow + HALF, t + 2);
.LBB0_627:
	ds_read_b128 v[170:173], v139 offset:1024
	ds_read_b128 v[178:181], v139 offset:3072
	ds_read_b128 v[186:189], v139 offset:5120
	ds_read_b128 v[198:201], v139 offset:7168
	v_add_u32_e32 v192, 0, v142
	v_add_u32_e32 v148, 0xc000, v192
	v_add_u32_e32 v149, 0xe000, v192
	s_add_u32 m0, s9, 0xc000
	v_lshl_add_u64 v[232:233], s[4:5], 0, v[134:135]
	s_add_u32 vcc_lo, s4, s68
	s_addc_u32 vcc_hi, s5, s69
	global_load_lds_dwordx4 v132, vcc
	s_add_u32 m0, s9, 0xe000
	s_nop 0
	global_load_lds_dwordx4 v134, vcc
	s_waitcnt lgkmcnt(8)
	s_barrier
	s_waitcnt lgkmcnt(0)
	v_mfma_f32_16x16x32_bf16 v[124:127], v[150:153], v[166:169], v[124:127]
	v_mfma_f32_16x16x32_bf16 v[120:123], v[158:161], v[166:169], v[120:123]
	v_mfma_f32_16x16x32_bf16 v[116:119], v[150:153], v[174:177], v[116:119]
	v_mfma_f32_16x16x32_bf16 v[112:115], v[158:161], v[174:177], v[112:115]
	v_mfma_f32_16x16x32_bf16 v[108:111], v[150:153], v[182:185], v[108:111]
	v_mfma_f32_16x16x32_bf16 v[104:107], v[158:161], v[182:185], v[104:107]
	v_mfma_f32_16x16x32_bf16 v[100:103], v[150:153], v[194:197], v[100:103]
	v_mfma_f32_16x16x32_bf16 v[96:99], v[158:161], v[194:197], v[96:99]
	v_mfma_f32_16x16x32_bf16 v[124:127], v[154:157], v[170:173], v[124:127]
	v_mfma_f32_16x16x32_bf16 v[120:123], v[162:165], v[170:173], v[120:123]
	v_mfma_f32_16x16x32_bf16 v[116:119], v[154:157], v[178:181], v[116:119]
	v_mfma_f32_16x16x32_bf16 v[112:115], v[162:165], v[178:181], v[112:115]
	v_mfma_f32_16x16x32_bf16 v[108:111], v[154:157], v[186:189], v[108:111]
	v_mfma_f32_16x16x32_bf16 v[104:107], v[162:165], v[186:189], v[104:107]
	v_mfma_f32_16x16x32_bf16 v[100:103], v[154:157], v[198:201], v[100:103]
	v_mfma_f32_16x16x32_bf16 v[96:99], v[162:165], v[198:201], v[96:99]
	s_barrier
	ds_read_b128 v[202:205], v140 offset:16384
	ds_read_b128 v[206:209], v140 offset:17408
	ds_read_b128 v[224:227], v140 offset:18432
	ds_read_b128 v[228:231], v140 offset:19456
	v_lshl_add_u64 v[234:235], s[4:5], 0, v[128:129]
	s_add_u32 m0, s9, s28
	s_nop 0
	s_add_u32 vcc_lo, s4, s94
	s_addc_u32 vcc_hi, s5, s95
	global_load_lds_dwordx4 v128, vcc
	v_lshl_add_u64 v[236:237], s[4:5], 0, v[130:131]
	s_add_u32 m0, s9, s28
	s_add_u32 m0, m0, 0x2000
	s_nop 0
	global_load_lds_dwordx4 v130, vcc
	s_barrier
	s_waitcnt lgkmcnt(0)
	v_mfma_f32_16x16x32_bf16 v[92:95], v[202:205], v[166:169], v[92:95]
	v_mfma_f32_16x16x32_bf16 v[88:91], v[224:227], v[166:169], v[88:91]
	v_mfma_f32_16x16x32_bf16 v[84:87], v[202:205], v[174:177], v[84:87]
	v_mfma_f32_16x16x32_bf16 v[80:83], v[224:227], v[174:177], v[80:83]
	v_mfma_f32_16x16x32_bf16 v[76:79], v[202:205], v[182:185], v[76:79]
	v_mfma_f32_16x16x32_bf16 v[72:75], v[224:227], v[182:185], v[72:75]
	v_mfma_f32_16x16x32_bf16 v[68:71], v[202:205], v[194:197], v[68:71]
	v_mfma_f32_16x16x32_bf16 v[64:67], v[224:227], v[194:197], v[64:67]
	v_mfma_f32_16x16x32_bf16 v[92:95], v[206:209], v[170:173], v[92:95]
	ds_read_b128 v[166:169], v139 offset:16384
	v_mfma_f32_16x16x32_bf16 v[88:91], v[228:231], v[170:173], v[88:91]
	v_mfma_f32_16x16x32_bf16 v[84:87], v[206:209], v[178:181], v[84:87]
	ds_read_b128 v[174:177], v139 offset:18432
	v_mfma_f32_16x16x32_bf16 v[80:83], v[228:231], v[178:181], v[80:83]
	v_mfma_f32_16x16x32_bf16 v[76:79], v[206:209], v[186:189], v[76:79]
	ds_read_b128 v[182:185], v139 offset:20480
	v_mfma_f32_16x16x32_bf16 v[72:75], v[228:231], v[186:189], v[72:75]
	v_mfma_f32_16x16x32_bf16 v[68:71], v[206:209], v[198:201], v[68:71]
	ds_read_b128 v[194:197], v139 offset:22528
	v_mfma_f32_16x16x32_bf16 v[64:67], v[228:231], v[198:201], v[64:67]
	s_barrier
	ds_read_b128 v[170:173], v139 offset:17408
	ds_read_b128 v[178:181], v139 offset:19456
	ds_read_b128 v[186:189], v139 offset:21504
	ds_read_b128 v[198:201], v139 offset:23552
	s_add_u32 m0, s9, 0x0
	s_nop 0
	s_add_u32 vcc_lo, s4, s62
	s_addc_u32 vcc_hi, s5, s63
	global_load_lds_dwordx4 v132, vcc
	s_add_u32 m0, s9, 0x2000
	s_nop 0
	global_load_lds_dwordx4 v134, vcc
	s_waitcnt vmcnt(8)
	s_barrier
	s_waitcnt lgkmcnt(0)
	v_mfma_f32_16x16x32_bf16 v[60:63], v[150:153], v[166:169], v[60:63]
	v_mfma_f32_16x16x32_bf16 v[56:59], v[158:161], v[166:169], v[56:59]
	v_mfma_f32_16x16x32_bf16 v[52:55], v[150:153], v[174:177], v[52:55]
	v_mfma_f32_16x16x32_bf16 v[48:51], v[158:161], v[174:177], v[48:51]
	v_mfma_f32_16x16x32_bf16 v[44:47], v[150:153], v[182:185], v[44:47]
	v_mfma_f32_16x16x32_bf16 v[40:43], v[158:161], v[182:185], v[40:43]
	v_mfma_f32_16x16x32_bf16 v[36:39], v[150:153], v[194:197], v[36:39]
	v_mfma_f32_16x16x32_bf16 v[32:35], v[158:161], v[194:197], v[32:35]
	v_mfma_f32_16x16x32_bf16 v[60:63], v[154:157], v[170:173], v[60:63]
	v_mfma_f32_16x16x32_bf16 v[56:59], v[162:165], v[170:173], v[56:59]
	v_mfma_f32_16x16x32_bf16 v[52:55], v[154:157], v[178:181], v[52:55]
	v_mfma_f32_16x16x32_bf16 v[48:51], v[162:165], v[178:181], v[48:51]
	v_mfma_f32_16x16x32_bf16 v[44:47], v[154:157], v[186:189], v[44:47]
	v_mfma_f32_16x16x32_bf16 v[40:43], v[162:165], v[186:189], v[40:43]
	v_mfma_f32_16x16x32_bf16 v[36:39], v[154:157], v[198:201], v[36:39]
	v_mfma_f32_16x16x32_bf16 v[32:35], v[162:165], v[198:201], v[32:35]
	s_barrier
	ds_read_b128 v[150:153], v140 offset:32768
	ds_read_b128 v[154:157], v140 offset:33792
	ds_read_b128 v[158:161], v140 offset:34816
	ds_read_b128 v[162:165], v140 offset:35840
	s_add_u32 m0, s9, s29
	s_nop 0
	s_add_u32 vcc_lo, s4, s78
	s_addc_u32 vcc_hi, s5, s79
	global_load_lds_dwordx4 v128, vcc
	s_add_u32 m0, s9, s29
	s_add_u32 m0, m0, 0x2000
	s_nop 0
	global_load_lds_dwordx4 v130, vcc
	s_waitcnt vmcnt(6)
	s_barrier
; #define WAIT_V(n) asm volatile("s_waitcnt vmcnt(" #n ")" ::: "memory")
; #define WAIT_L(n) asm volatile("s_waitcnt lgkmcnt(" #n ")" ::: "memory")
; #define BAR __builtin_amdgcn_s_barrier()
; #define SCHED __builtin_amdgcn_sched_barrier(0)
; #define STAGE(P, BASE, br, kt) do { const char* _g = (const char*)((BASE) + (size_t)(br) * GK + (kt) * BK); \
;     __builtin_amdgcn_global_load_lds((const unsigned*)(_g + voff0), (unsigned*)((char*)(P) + tx * 16), 16, 0, 0); \
;     __builtin_amdgcn_global_load_lds((const unsigned*)(_g + voff1), (unsigned*)((char*)(P) + tx * 16 + 8192), 16, 0, 0); } while (0)
; #define LDA(dst, b, h) _Pragma("unroll") for (int m = 0; m < 4; ++m) _Pragma("unroll") for (int k = 0; k < 2; ++k) \
;     dst[m][k] = *reinterpret_cast<const bf16x8*>((char*)shm + abase + (((b) * 2 + (h)) * 16384 + (m * 2 + k) * 1024))
; #define LDB(dst, b, h) _Pragma("unroll") for (int n = 0; n < 2; ++n) _Pragma("unroll") for (int k = 0; k < 2; ++k) \
;     dst[n][k] = *reinterpret_cast<const bf16x8*>((char*)shm + bbase + (((b) * 2 + (h)) * 16384 + (n * 2 + k) * 1024))
; template <bool SWAP>
; __device__ __forceinline__ void gemm_main(const u16* __restrict__ A, const u16* __restrict__ Bt, int brow, int bcol,
;                                           u16* shm, f32x4 (&acc)[2][2][4][2]) {
;     ...
;     WAIT_V(6); BAR; MMA(1, 1, At, B1); BAR;
;     LDB(B0, 1, 0); SCHED; LDA(At, 1, 0); STAGE(SA(0, 1), A, brow + HALF, t + 2);
;     WAIT_L(8); BAR; WAIT_L(0); MMA(0, 0, At, B0); BAR; SCHED;
;     LDB(B1, 1, 1); STAGE(SB(1, 0), Bt, bcol, t + 3);
;     BAR; WAIT_L(0); MMA(0, 1, At, B1); BAR;
;     LDA(At, 1, 1); STAGE(SA(1, 0), A, brow, t + 3);
	v_mfma_f32_16x16x32_bf16 v[28:31], v[202:205], v[166:169], v[28:31]
	v_mfma_f32_16x16x32_bf16 v[24:27], v[224:227], v[166:169], v[24:27]
	v_mfma_f32_16x16x32_bf16 v[20:23], v[202:205], v[174:177], v[20:23]
	v_mfma_f32_16x16x32_bf16 v[16:19], v[224:227], v[174:177], v[16:19]
	v_mfma_f32_16x16x32_bf16 v[12:15], v[202:205], v[182:185], v[12:15]
	v_mfma_f32_16x16x32_bf16 v[8:11], v[224:227], v[182:185], v[8:11]
	v_mfma_f32_16x16x32_bf16 v[4:7], v[202:205], v[194:197], v[4:7]
	v_mfma_f32_16x16x32_bf16 v[0:3], v[224:227], v[194:197], v[0:3]
	v_mfma_f32_16x16x32_bf16 v[28:31], v[206:209], v[170:173], v[28:31]
	ds_read_b128 v[166:169], v139 offset:32768
	v_mfma_f32_16x16x32_bf16 v[24:27], v[228:231], v[170:173], v[24:27]
	v_mfma_f32_16x16x32_bf16 v[20:23], v[206:209], v[178:181], v[20:23]
	ds_read_b128 v[174:177], v139 offset:34816
	v_mfma_f32_16x16x32_bf16 v[16:19], v[228:231], v[178:181], v[16:19]
	v_mfma_f32_16x16x32_bf16 v[12:15], v[206:209], v[186:189], v[12:15]
	ds_read_b128 v[182:185], v139 offset:36864
	v_mfma_f32_16x16x32_bf16 v[8:11], v[228:231], v[186:189], v[8:11]
	v_mfma_f32_16x16x32_bf16 v[4:7], v[206:209], v[198:201], v[4:7]
	ds_read_b128 v[194:197], v139 offset:38912
	v_mfma_f32_16x16x32_bf16 v[0:3], v[228:231], v[198:201], v[0:3]
	s_barrier
	ds_read_b128 v[170:173], v139 offset:33792
	ds_read_b128 v[178:181], v139 offset:35840
	ds_read_b128 v[186:189], v139 offset:37888
	ds_read_b128 v[198:201], v139 offset:39936
	s_add_u32 m0, s9, 0x4000
	s_nop 0
	s_add_u32 vcc_lo, s4, s88
	s_addc_u32 vcc_hi, s5, s89
	global_load_lds_dwordx4 v132, vcc
	s_add_u32 m0, s9, 0x6000
	s_nop 0
	global_load_lds_dwordx4 v134, vcc
	s_waitcnt lgkmcnt(8)
	s_barrier
	s_waitcnt lgkmcnt(0)
	v_mfma_f32_16x16x32_bf16 v[124:127], v[150:153], v[166:169], v[124:127]
	v_mfma_f32_16x16x32_bf16 v[120:123], v[158:161], v[166:169], v[120:123]
	v_mfma_f32_16x16x32_bf16 v[116:119], v[150:153], v[174:177], v[116:119]
	v_mfma_f32_16x16x32_bf16 v[112:115], v[158:161], v[174:177], v[112:115]
	v_mfma_f32_16x16x32_bf16 v[108:111], v[150:153], v[182:185], v[108:111]
	v_mfma_f32_16x16x32_bf16 v[104:107], v[158:161], v[182:185], v[104:107]
	v_mfma_f32_16x16x32_bf16 v[100:103], v[150:153], v[194:197], v[100:103]
	v_mfma_f32_16x16x32_bf16 v[96:99], v[158:161], v[194:197], v[96:99]
	v_mfma_f32_16x16x32_bf16 v[124:127], v[154:157], v[170:173], v[124:127]
	v_mfma_f32_16x16x32_bf16 v[120:123], v[162:165], v[170:173], v[120:123]
	v_mfma_f32_16x16x32_bf16 v[116:119], v[154:157], v[178:181], v[116:119]
	v_mfma_f32_16x16x32_bf16 v[112:115], v[162:165], v[178:181], v[112:115]
	v_mfma_f32_16x16x32_bf16 v[108:111], v[154:157], v[186:189], v[108:111]
	v_mfma_f32_16x16x32_bf16 v[104:107], v[162:165], v[186:189], v[104:107]
	v_mfma_f32_16x16x32_bf16 v[100:103], v[154:157], v[198:201], v[100:103]
	v_mfma_f32_16x16x32_bf16 v[96:99], v[162:165], v[198:201], v[96:99]
	s_barrier
	ds_read_b128 v[202:205], v140 offset:49152
	ds_read_b128 v[206:209], v140 offset:50176
	ds_read_b128 v[224:227], v140 offset:51200
	ds_read_b128 v[228:231], v140 offset:52224
	s_add_u32 m0, s9, s30
	s_nop 0
	s_add_u32 vcc_lo, s4, s52
	s_addc_u32 vcc_hi, s5, s53
	global_load_lds_dwordx4 v128, vcc
	v_lshl_add_u64 v[238:239], v[236:237], 0, s[52:53]
	s_add_u32 m0, s9, s30
	s_add_u32 m0, m0, 0x2000
	s_nop 0
	global_load_lds_dwordx4 v130, vcc
	s_barrier
	s_waitcnt lgkmcnt(0)
	v_mfma_f32_16x16x32_bf16 v[92:95], v[202:205], v[166:169], v[92:95]
	v_mfma_f32_16x16x32_bf16 v[88:91], v[224:227], v[166:169], v[88:91]
	v_mfma_f32_16x16x32_bf16 v[84:87], v[202:205], v[174:177], v[84:87]
	v_mfma_f32_16x16x32_bf16 v[80:83], v[224:227], v[174:177], v[80:83]
	v_mfma_f32_16x16x32_bf16 v[76:79], v[202:205], v[182:185], v[76:79]
	v_mfma_f32_16x16x32_bf16 v[72:75], v[224:227], v[182:185], v[72:75]
	v_mfma_f32_16x16x32_bf16 v[68:71], v[202:205], v[194:197], v[68:71]
	v_mfma_f32_16x16x32_bf16 v[64:67], v[224:227], v[194:197], v[64:67]
	v_mfma_f32_16x16x32_bf16 v[92:95], v[206:209], v[170:173], v[92:95]
	ds_read_b128 v[166:169], v139 offset:49152
	v_mfma_f32_16x16x32_bf16 v[88:91], v[228:231], v[170:173], v[88:91]
	v_mfma_f32_16x16x32_bf16 v[84:87], v[206:209], v[178:181], v[84:87]
	ds_read_b128 v[174:177], v139 offset:51200
	v_mfma_f32_16x16x32_bf16 v[80:83], v[228:231], v[178:181], v[80:83]
	v_mfma_f32_16x16x32_bf16 v[76:79], v[206:209], v[186:189], v[76:79]
	ds_read_b128 v[182:185], v139 offset:53248
	v_mfma_f32_16x16x32_bf16 v[72:75], v[228:231], v[186:189], v[72:75]
	v_mfma_f32_16x16x32_bf16 v[68:71], v[206:209], v[198:201], v[68:71]
	ds_read_b128 v[194:197], v139 offset:55296
	v_mfma_f32_16x16x32_bf16 v[64:67], v[228:231], v[198:201], v[64:67]
	s_barrier
	ds_read_b128 v[170:173], v139 offset:50176
	ds_read_b128 v[178:181], v139 offset:52224
	ds_read_b128 v[186:189], v139 offset:54272
	ds_read_b128 v[198:201], v139 offset:56320
	v_add_u32_e32 v223, 0x8000, v192
	s_add_u32 m0, s9, 0x8000
	s_nop 0
	s_add_u32 vcc_lo, s4, s44
	s_addc_u32 vcc_hi, s5, s45
	global_load_lds_dwordx4 v132, vcc
	v_lshl_add_u64 v[190:191], v[232:233], 0, s[44:45]
	s_add_u32 m0, s9, 0xa000
	s_nop 0
	global_load_lds_dwordx4 v134, vcc
	s_waitcnt vmcnt(8)
	s_barrier
; #define WAIT_V(n) asm volatile("s_waitcnt vmcnt(" #n ")" ::: "memory")
; #define WAIT_L(n) asm volatile("s_waitcnt lgkmcnt(" #n ")" ::: "memory")
; #define BAR __builtin_amdgcn_s_barrier()
; #define SCHED __builtin_amdgcn_sched_barrier(0)
; #define STAGE(P, BASE, br, kt) do { const char* _g = (const char*)((BASE) + (size_t)(br) * GK + (kt) * BK); \
;     __builtin_amdgcn_global_load_lds((const unsigned*)(_g + voff0), (unsigned*)((char*)(P) + tx * 16), 16, 0, 0); \
;     __builtin_amdgcn_global_load_lds((const unsigned*)(_g + voff1), (unsigned*)((char*)(P) + tx * 16 + 8192), 16, 0, 0); } while (0)
; #define LDA(dst, b, h) _Pragma("unroll") for (int m = 0; m < 4; ++m) _Pragma("unroll") for (int k = 0; k < 2; ++k) \
;     dst[m][k] = *reinterpret_cast<const bf16x8*>((char*)shm + abase + (((b) * 2 + (h)) * 16384 + (m * 2 + k) * 1024))
; #define LDB(dst, b, h) _Pragma("unroll") for (int n = 0; n < 2; ++n) _Pragma("unroll") for (int k = 0; k < 2; ++k) \
;     dst[n][k] = *reinterpret_cast<const bf16x8*>((char*)shm + bbase + (((b) * 2 + (h)) * 16384 + (n * 2 + k) * 1024))
; template <bool SWAP>
; __device__ __forceinline__ void gemm_main(const u16* __restrict__ A, const u16* __restrict__ Bt, int brow, int bcol,
;                                           u16* shm, f32x4 (&acc)[2][2][4][2]) {
;     ...
;     LDA(At, 1, 1); STAGE(SA(1, 0), A, brow, t + 3);
;     BAR; WAIT_L(0); MMA(1, 0, At, B0); BAR; SCHED;
;     STAGE(SB(1, 1), Bt, bcol + HALF, t + 3);
;     WAIT_V(6); BAR; MMA(1, 1, At, B1); BAR;
;   }
;   { LDB(B0, 0, 0); LDA(At, 0, 0); STAGE(SA(1, 1), A, brow + HALF, nt - 1);
;     BAR; WAIT_L(0); MMA(0, 0, At, B0); BAR;
	s_waitcnt lgkmcnt(0)
	v_mfma_f32_16x16x32_bf16 v[60:63], v[150:153], v[166:169], v[60:63]
	v_mfma_f32_16x16x32_bf16 v[56:59], v[158:161], v[166:169], v[56:59]
	v_mfma_f32_16x16x32_bf16 v[52:55], v[150:153], v[174:177], v[52:55]
	v_mfma_f32_16x16x32_bf16 v[48:51], v[158:161], v[174:177], v[48:51]
	v_mfma_f32_16x16x32_bf16 v[44:47], v[150:153], v[182:185], v[44:47]
	v_mfma_f32_16x16x32_bf16 v[40:43], v[158:161], v[182:185], v[40:43]
	v_mfma_f32_16x16x32_bf16 v[36:39], v[150:153], v[194:197], v[36:39]
	v_mfma_f32_16x16x32_bf16 v[32:35], v[158:161], v[194:197], v[32:35]
	v_mfma_f32_16x16x32_bf16 v[60:63], v[154:157], v[170:173], v[60:63]
	v_mfma_f32_16x16x32_bf16 v[56:59], v[162:165], v[170:173], v[56:59]
	v_mfma_f32_16x16x32_bf16 v[52:55], v[154:157], v[178:181], v[52:55]
	v_mfma_f32_16x16x32_bf16 v[48:51], v[162:165], v[178:181], v[48:51]
	v_mfma_f32_16x16x32_bf16 v[44:47], v[154:157], v[186:189], v[44:47]
	v_mfma_f32_16x16x32_bf16 v[40:43], v[162:165], v[186:189], v[40:43]
	v_mfma_f32_16x16x32_bf16 v[36:39], v[154:157], v[198:201], v[36:39]
	v_mfma_f32_16x16x32_bf16 v[32:35], v[162:165], v[198:201], v[32:35]
	s_barrier
	ds_read_b128 v[150:153], v140
	ds_read_b128 v[154:157], v140 offset:1024
	ds_read_b128 v[158:161], v140 offset:2048
	ds_read_b128 v[162:165], v140 offset:3072
	s_add_u32 m0, s9, s31
	s_nop 0
	s_add_u32 vcc_lo, s4, s38
	s_addc_u32 vcc_hi, s5, s39
	global_load_lds_dwordx4 v128, vcc
	v_lshl_add_u64 v[254:255], v[236:237], 0, s[38:39]
	s_add_u32 m0, s9, s31
	s_add_u32 m0, m0, 0x2000
	s_nop 0
	global_load_lds_dwordx4 v130, vcc
	s_waitcnt vmcnt(6)
	s_barrier
	v_mfma_f32_16x16x32_bf16 v[28:31], v[202:205], v[166:169], v[28:31]
	v_mfma_f32_16x16x32_bf16 v[24:27], v[224:227], v[166:169], v[24:27]
	v_mfma_f32_16x16x32_bf16 v[20:23], v[202:205], v[174:177], v[20:23]
	v_mfma_f32_16x16x32_bf16 v[16:19], v[224:227], v[174:177], v[16:19]
	v_mfma_f32_16x16x32_bf16 v[12:15], v[202:205], v[182:185], v[12:15]
	v_mfma_f32_16x16x32_bf16 v[8:11], v[224:227], v[182:185], v[8:11]
	v_mfma_f32_16x16x32_bf16 v[4:7], v[202:205], v[194:197], v[4:7]
	v_mfma_f32_16x16x32_bf16 v[0:3], v[224:227], v[194:197], v[0:3]
	v_mfma_f32_16x16x32_bf16 v[28:31], v[206:209], v[170:173], v[28:31]
	ds_read_b128 v[166:169], v139
	v_mfma_f32_16x16x32_bf16 v[24:27], v[228:231], v[170:173], v[24:27]
	v_mfma_f32_16x16x32_bf16 v[20:23], v[206:209], v[178:181], v[20:23]
	ds_read_b128 v[174:177], v139 offset:2048
	v_mfma_f32_16x16x32_bf16 v[16:19], v[228:231], v[178:181], v[16:19]
	s_add_i32 s8, s8, 2
	s_add_u32 s4, s4, 0x100
	s_addc_u32 s5, s5, 0
	s_cmp_lt_u32 s8, 28
	v_mfma_f32_16x16x32_bf16 v[12:15], v[206:209], v[186:189], v[12:15]
	ds_read_b128 v[182:185], v139 offset:4096
	v_mfma_f32_16x16x32_bf16 v[8:11], v[228:231], v[186:189], v[8:11]
	v_mfma_f32_16x16x32_bf16 v[4:7], v[206:209], v[198:201], v[4:7]
	ds_read_b128 v[194:197], v139 offset:6144
	v_mfma_f32_16x16x32_bf16 v[0:3], v[228:231], v[198:201], v[0:3]
	s_barrier
	s_cbranch_scc1 .LBB0_627
	s_and_b32 s4, s7, 0xffffe0
	s_and_b32 s5, s6, 31
	s_or_b32 s4, s4, s5
	s_lshl_b32 s10, s4, 8
	v_lshlrev_b32_e32 v128, 3, v141
	v_lshlrev_b32_e32 v129, 5, v141
	v_and_b32_e32 v128, 0xffff0, v128
	v_and_b32_e32 v129, 32, v129
	s_or_b32 s4, s10, 0x80
	v_add_u32_e32 v129, v129, v144
	v_add_lshl_u32 v128, v143, v128, 12
	s_ashr_i32 s5, s4, 31
	v_lshl_add_u32 v192, v129, 1, v128
	v_lshlrev_b32_e32 v128, 3, v145
	v_lshlrev_b32_e32 v129, 5, v145
	s_lshl_b64 s[4:5], s[4:5], 12
	v_and_b32_e32 v128, 0xffff0, v128
	v_and_b32_e32 v129, 32, v129
	s_add_u32 s4, s84, s4
	v_add_u32_e32 v129, v129, v147
	v_add_lshl_u32 v128, v146, v128, 12
	s_addc_u32 s5, s85, s5
	v_lshl_add_u32 v146, v129, 1, v128
	v_mov_b32_e32 v147, v193
	v_lshl_add_u64 v[186:187], s[4:5], 0, v[192:193]
	s_mov_b64 s[8:9], 0xf80
	v_readfirstlane_b32 s7, v148
	v_lshl_add_u64 v[186:187], v[186:187], 0, s[8:9]
	s_mov_b32 m0, s7
	v_lshl_add_u64 v[146:147], s[4:5], 0, v[146:147]
	v_readfirstlane_b32 s4, v149
	ds_read_b128 v[128:131], v140
	ds_read_b128 v[132:135], v140 offset:1024
	ds_read_b128 v[142:145], v140 offset:2048
	ds_read_b128 v[150:153], v140 offset:3072
	ds_read_b128 v[154:157], v139
	ds_read_b128 v[158:161], v139 offset:1024
	ds_read_b128 v[162:165], v139 offset:2048
	ds_read_b128 v[166:169], v139 offset:3072
	ds_read_b128 v[170:173], v139 offset:4096
	ds_read_b128 v[174:177], v139 offset:5120
	ds_read_b128 v[178:181], v139 offset:6144
	ds_read_b128 v[182:185], v139 offset:7168
	global_load_lds_dwordx4 v[186:187], off
	v_lshl_add_u64 v[146:147], v[146:147], 0, s[8:9]
	s_mov_b32 m0, s4
	s_nop 0
	global_load_lds_dwordx4 v[146:147], off
	s_barrier
	s_waitcnt lgkmcnt(0)
	s_setprio 1
	s_waitcnt lgkmcnt(0)
	v_mfma_f32_16x16x32_bf16 v[124:127], v[128:131], v[154:157], v[124:127]
	v_mfma_f32_16x16x32_bf16 v[116:119], v[128:131], v[162:165], v[116:119]
	v_mfma_f32_16x16x32_bf16 v[108:111], v[128:131], v[170:173], v[108:111]
	v_mfma_f32_16x16x32_bf16 v[100:103], v[128:131], v[178:181], v[100:103]
	v_mfma_f32_16x16x32_bf16 v[124:127], v[132:135], v[158:161], v[124:127]
	v_mfma_f32_16x16x32_bf16 v[120:123], v[142:145], v[154:157], v[120:123]
	v_mfma_f32_16x16x32_bf16 v[116:119], v[132:135], v[166:169], v[116:119]
	v_mfma_f32_16x16x32_bf16 v[112:115], v[142:145], v[162:165], v[112:115]
	v_mfma_f32_16x16x32_bf16 v[108:111], v[132:135], v[174:177], v[108:111]
	v_mfma_f32_16x16x32_bf16 v[104:107], v[142:145], v[170:173], v[104:107]
	v_mfma_f32_16x16x32_bf16 v[100:103], v[132:135], v[182:185], v[100:103]
	v_mfma_f32_16x16x32_bf16 v[96:99], v[142:145], v[178:181], v[96:99]
	v_mfma_f32_16x16x32_bf16 v[146:149], v[150:153], v[158:161], v[120:123]
	v_mfma_f32_16x16x32_bf16 v[186:189], v[150:153], v[166:169], v[112:115]
	v_mfma_f32_16x16x32_bf16 v[194:197], v[150:153], v[174:177], v[104:107]
	v_mfma_f32_16x16x32_bf16 v[198:201], v[150:153], v[182:185], v[96:99]
	s_setprio 0
	s_barrier
; #define WAIT_V(n) asm volatile("s_waitcnt vmcnt(" #n ")" ::: "memory")
; #define WAIT_L(n) asm volatile("s_waitcnt lgkmcnt(" #n ")" ::: "memory")
; #define BAR __builtin_amdgcn_s_barrier()
; #define LDA(dst, b, h) _Pragma("unroll") for (int m = 0; m < 4; ++m) _Pragma("unroll") for (int k = 0; k < 2; ++k) \
;     dst[m][k] = *reinterpret_cast<const bf16x8*>((char*)shm + abase + (((b) * 2 + (h)) * 16384 + (m * 2 + k) * 1024))
; #define LDB(dst, b, h) _Pragma("unroll") for (int n = 0; n < 2; ++n) _Pragma("unroll") for (int k = 0; k < 2; ++k) \
;     dst[n][k] = *reinterpret_cast<const bf16x8*>((char*)shm + bbase + (((b) * 2 + (h)) * 16384 + (n * 2 + k) * 1024))
; template <bool SWAP>
; __device__ __forceinline__ void gemm_main(const u16* __restrict__ A, const u16* __restrict__ Bt, int brow, int bcol,
;                                           u16* shm, f32x4 (&acc)[2][2][4][2]) {
;     ...
;     BAR; WAIT_L(0); MMA(0, 0, At, B0); BAR;
;     LDB(B1, 0, 1); BAR; WAIT_L(0); MMA(0, 1, At, B1); BAR;
;     LDA(At, 0, 1); WAIT_V(4); BAR; WAIT_L(0); MMA(1, 0, At, B0); MMA(1, 1, At, B1); BAR; }
;   { LDB(B0, 1, 0); LDA(At, 1, 0); WAIT_V(2); BAR; WAIT_L(0); MMA(0, 0, At, B0); BAR;
	s_nop 1
	ds_read_b128 v[96:99], v140 offset:16384
	ds_read_b128 v[104:107], v140 offset:17408
	ds_read_b128 v[112:115], v140 offset:18432
	ds_read_b128 v[120:123], v140 offset:19456
	s_barrier
	s_waitcnt lgkmcnt(0)
	s_setprio 1
	s_waitcnt lgkmcnt(0)
	v_mfma_f32_16x16x32_bf16 v[92:95], v[96:99], v[154:157], v[92:95]
	v_mfma_f32_16x16x32_bf16 v[84:87], v[96:99], v[162:165], v[84:87]
	v_mfma_f32_16x16x32_bf16 v[76:79], v[96:99], v[170:173], v[76:79]
	v_mfma_f32_16x16x32_bf16 v[68:71], v[96:99], v[178:181], v[68:71]
	v_mfma_f32_16x16x32_bf16 v[92:95], v[104:107], v[158:161], v[92:95]
	v_mfma_f32_16x16x32_bf16 v[88:91], v[112:115], v[154:157], v[88:91]
	v_mfma_f32_16x16x32_bf16 v[84:87], v[104:107], v[166:169], v[84:87]
	v_mfma_f32_16x16x32_bf16 v[80:83], v[112:115], v[162:165], v[80:83]
	v_mfma_f32_16x16x32_bf16 v[76:79], v[104:107], v[174:177], v[76:79]
	v_mfma_f32_16x16x32_bf16 v[72:75], v[112:115], v[170:173], v[72:75]
	v_mfma_f32_16x16x32_bf16 v[68:71], v[104:107], v[182:185], v[68:71]
	v_mfma_f32_16x16x32_bf16 v[64:67], v[112:115], v[178:181], v[64:67]
	v_mfma_f32_16x16x32_bf16 v[154:157], v[120:123], v[158:161], v[88:91]
	v_mfma_f32_16x16x32_bf16 v[158:161], v[120:123], v[166:169], v[80:83]
	v_mfma_f32_16x16x32_bf16 v[162:165], v[120:123], v[174:177], v[72:75]
	v_mfma_f32_16x16x32_bf16 v[166:169], v[120:123], v[182:185], v[64:67]
	s_setprio 0
	s_barrier
	s_nop 1
	ds_read_b128 v[64:67], v139 offset:16384
	ds_read_b128 v[72:75], v139 offset:17408
	ds_read_b128 v[80:83], v139 offset:18432
	ds_read_b128 v[88:91], v139 offset:19456
	ds_read_b128 v[170:173], v139 offset:20480
	ds_read_b128 v[174:177], v139 offset:21504
	ds_read_b128 v[178:181], v139 offset:22528
	ds_read_b128 v[182:185], v139 offset:23552
	s_waitcnt vmcnt(4)
	s_barrier
	s_waitcnt lgkmcnt(0)
	s_setprio 1
	s_waitcnt lgkmcnt(0)
	v_mfma_f32_16x16x32_bf16 v[60:63], v[128:131], v[64:67], v[60:63]
	v_mfma_f32_16x16x32_bf16 v[52:55], v[128:131], v[80:83], v[52:55]
	v_mfma_f32_16x16x32_bf16 v[44:47], v[128:131], v[170:173], v[44:47]
	v_mfma_f32_16x16x32_bf16 v[36:39], v[128:131], v[178:181], v[36:39]
	v_mfma_f32_16x16x32_bf16 v[60:63], v[132:135], v[72:75], v[60:63]
	v_mfma_f32_16x16x32_bf16 v[56:59], v[142:145], v[64:67], v[56:59]
	v_mfma_f32_16x16x32_bf16 v[52:55], v[132:135], v[88:91], v[52:55]
	v_mfma_f32_16x16x32_bf16 v[48:51], v[142:145], v[80:83], v[48:51]
	v_mfma_f32_16x16x32_bf16 v[44:47], v[132:135], v[174:177], v[44:47]
	v_mfma_f32_16x16x32_bf16 v[40:43], v[142:145], v[170:173], v[40:43]
	v_mfma_f32_16x16x32_bf16 v[36:39], v[132:135], v[182:185], v[36:39]
	v_mfma_f32_16x16x32_bf16 v[32:35], v[142:145], v[178:181], v[32:35]
	v_mfma_f32_16x16x32_bf16 v[202:205], v[150:153], v[72:75], v[56:59]
	v_mfma_f32_16x16x32_bf16 v[206:209], v[150:153], v[88:91], v[48:51]
	v_mfma_f32_16x16x32_bf16 v[224:227], v[150:153], v[174:177], v[40:43]
	v_mfma_f32_16x16x32_bf16 v[128:131], v[150:153], v[182:185], v[32:35]
	s_setprio 0
	s_setprio 1
	v_mfma_f32_16x16x32_bf16 v[28:31], v[96:99], v[64:67], v[28:31]
	v_mfma_f32_16x16x32_bf16 v[20:23], v[96:99], v[80:83], v[20:23]
	v_mfma_f32_16x16x32_bf16 v[12:15], v[96:99], v[170:173], v[12:15]
	v_mfma_f32_16x16x32_bf16 v[4:7], v[96:99], v[178:181], v[4:7]
	v_mfma_f32_16x16x32_bf16 v[28:31], v[104:107], v[72:75], v[28:31]
	v_mfma_f32_16x16x32_bf16 v[24:27], v[112:115], v[64:67], v[24:27]
	v_mfma_f32_16x16x32_bf16 v[20:23], v[104:107], v[88:91], v[20:23]
	v_mfma_f32_16x16x32_bf16 v[16:19], v[112:115], v[80:83], v[16:19]
	v_mfma_f32_16x16x32_bf16 v[12:15], v[104:107], v[174:177], v[12:15]
	v_mfma_f32_16x16x32_bf16 v[8:11], v[112:115], v[170:173], v[8:11]
	v_mfma_f32_16x16x32_bf16 v[4:7], v[104:107], v[182:185], v[4:7]
	v_mfma_f32_16x16x32_bf16 v[0:3], v[112:115], v[178:181], v[0:3]
	v_mfma_f32_16x16x32_bf16 v[132:135], v[120:123], v[72:75], v[24:27]
	v_mfma_f32_16x16x32_bf16 v[142:145], v[120:123], v[88:91], v[16:19]
	v_mfma_f32_16x16x32_bf16 v[150:153], v[120:123], v[174:177], v[8:11]
	v_mfma_f32_16x16x32_bf16 v[170:173], v[120:123], v[182:185], v[0:3]
	s_setprio 0
	s_barrier
	s_nop 1
	ds_read_b128 v[0:3], v140 offset:32768
	ds_read_b128 v[8:11], v140 offset:33792
	ds_read_b128 v[16:19], v140 offset:34816
	ds_read_b128 v[24:27], v140 offset:35840
	ds_read_b128 v[32:35], v139 offset:32768
	ds_read_b128 v[40:43], v139 offset:33792
	ds_read_b128 v[48:51], v139 offset:34816
	ds_read_b128 v[56:59], v139 offset:35840
	ds_read_b128 v[64:67], v139 offset:36864
	ds_read_b128 v[174:177], v139 offset:37888
	ds_read_b128 v[178:181], v139 offset:38912
	ds_read_b128 v[182:185], v139 offset:39936
	s_waitcnt vmcnt(2)
	s_barrier
; #define WAIT_V(n) asm volatile("s_waitcnt vmcnt(" #n ")" ::: "memory")
; #define WAIT_L(n) asm volatile("s_waitcnt lgkmcnt(" #n ")" ::: "memory")
; #define BAR __builtin_amdgcn_s_barrier()
; #define LDA(dst, b, h) _Pragma("unroll") for (int m = 0; m < 4; ++m) _Pragma("unroll") for (int k = 0; k < 2; ++k) \
;     dst[m][k] = *reinterpret_cast<const bf16x8*>((char*)shm + abase + (((b) * 2 + (h)) * 16384 + (m * 2 + k) * 1024))
; #define LDB(dst, b, h) _Pragma("unroll") for (int n = 0; n < 2; ++n) _Pragma("unroll") for (int k = 0; k < 2; ++k) \
;     dst[n][k] = *reinterpret_cast<const bf16x8*>((char*)shm + bbase + (((b) * 2 + (h)) * 16384 + (n * 2 + k) * 1024))
; template <bool SWAP>
; __device__ __forceinline__ void gemm_main(const u16* __restrict__ A, const u16* __restrict__ Bt, int brow, int bcol,
;                                           u16* shm, f32x4 (&acc)[2][2][4][2]) {
;     ...
;   { LDB(B0, 1, 0); LDA(At, 1, 0); WAIT_V(2); BAR; WAIT_L(0); MMA(0, 0, At, B0); BAR;
;     LDB(B1, 1, 1); WAIT_V(0); BAR; WAIT_L(0); MMA(0, 1, At, B1); BAR;
;     LDA(At, 1, 1); BAR; WAIT_L(0); MMA(1, 0, At, B0); MMA(1, 1, At, B1); BAR; }
;   if (wr == 0) BAR;
	s_waitcnt lgkmcnt(0)
	s_setprio 1
	s_waitcnt lgkmcnt(0)
	v_mfma_f32_16x16x32_bf16 v[72:75], v[0:3], v[32:35], v[124:127]
	v_mfma_f32_16x16x32_bf16 v[120:123], v[8:11], v[40:43], v[72:75]
	v_mfma_f32_16x16x32_bf16 v[72:75], v[16:19], v[32:35], v[146:149]
	v_mfma_f32_16x16x32_bf16 v[124:127], v[24:27], v[40:43], v[72:75]
	v_mfma_f32_16x16x32_bf16 v[72:75], v[0:3], v[48:51], v[116:119]
	v_mfma_f32_16x16x32_bf16 v[112:115], v[8:11], v[56:59], v[72:75]
	v_mfma_f32_16x16x32_bf16 v[72:75], v[16:19], v[48:51], v[186:189]
	v_mfma_f32_16x16x32_bf16 v[116:119], v[24:27], v[56:59], v[72:75]
	v_mfma_f32_16x16x32_bf16 v[72:75], v[0:3], v[64:67], v[108:111]
	v_mfma_f32_16x16x32_bf16 v[104:107], v[8:11], v[174:177], v[72:75]
	v_mfma_f32_16x16x32_bf16 v[72:75], v[16:19], v[64:67], v[194:197]
	v_mfma_f32_16x16x32_bf16 v[108:111], v[24:27], v[174:177], v[72:75]
	v_mfma_f32_16x16x32_bf16 v[72:75], v[0:3], v[178:181], v[100:103]
	v_mfma_f32_16x16x32_bf16 v[96:99], v[8:11], v[182:185], v[72:75]
	v_mfma_f32_16x16x32_bf16 v[72:75], v[16:19], v[178:181], v[198:201]
	v_mfma_f32_16x16x32_bf16 v[100:103], v[24:27], v[182:185], v[72:75]
	s_setprio 0
	s_barrier
	ds_read_b128 v[146:149], v140 offset:49152
	ds_read_b128 v[186:189], v140 offset:50176
	ds_read_b128 v[194:197], v140 offset:51200
	ds_read_b128 v[198:201], v140 offset:52224
	s_waitcnt vmcnt(0)
	s_barrier
	s_waitcnt lgkmcnt(0)
	s_setprio 1
	s_waitcnt lgkmcnt(0)
	v_mfma_f32_16x16x32_bf16 v[72:75], v[146:149], v[32:35], v[92:95]
	v_mfma_f32_16x16x32_bf16 v[32:35], v[194:197], v[32:35], v[154:157]
	v_mfma_f32_16x16x32_bf16 v[92:95], v[198:201], v[40:43], v[32:35]
	v_mfma_f32_16x16x32_bf16 v[32:35], v[146:149], v[48:51], v[84:87]
	v_mfma_f32_16x16x32_bf16 v[80:83], v[186:189], v[56:59], v[32:35]
	v_mfma_f32_16x16x32_bf16 v[32:35], v[194:197], v[48:51], v[158:161]
	v_mfma_f32_16x16x32_bf16 v[84:87], v[198:201], v[56:59], v[32:35]
	v_mfma_f32_16x16x32_bf16 v[32:35], v[146:149], v[64:67], v[76:79]
	v_mfma_f32_16x16x32_bf16 v[88:91], v[186:189], v[40:43], v[72:75]
	v_mfma_f32_16x16x32_bf16 v[72:75], v[186:189], v[174:177], v[32:35]
	v_mfma_f32_16x16x32_bf16 v[32:35], v[194:197], v[64:67], v[162:165]
	v_mfma_f32_16x16x32_bf16 v[76:79], v[198:201], v[174:177], v[32:35]
	v_mfma_f32_16x16x32_bf16 v[32:35], v[146:149], v[178:181], v[68:71]
	v_mfma_f32_16x16x32_bf16 v[64:67], v[186:189], v[182:185], v[32:35]
	v_mfma_f32_16x16x32_bf16 v[32:35], v[194:197], v[178:181], v[166:169]
	v_mfma_f32_16x16x32_bf16 v[68:71], v[198:201], v[182:185], v[32:35]
	s_setprio 0
	s_barrier
	ds_read_b128 v[154:157], v139 offset:49152
	ds_read_b128 v[158:161], v139 offset:50176
	ds_read_b128 v[162:165], v139 offset:51200
	ds_read_b128 v[166:169], v139 offset:52224
	ds_read_b128 v[174:177], v139 offset:53248
	ds_read_b128 v[178:181], v139 offset:54272
	ds_read_b128 v[182:185], v139 offset:55296
	ds_read_b128 v[228:231], v139 offset:56320
	s_barrier
	s_waitcnt lgkmcnt(0)
	s_setprio 1
	s_waitcnt lgkmcnt(0)
	v_mfma_f32_16x16x32_bf16 v[32:35], v[0:3], v[154:157], v[60:63]
	v_mfma_f32_16x16x32_bf16 v[56:59], v[8:11], v[158:161], v[32:35]
	v_mfma_f32_16x16x32_bf16 v[32:35], v[16:19], v[154:157], v[202:205]
	v_mfma_f32_16x16x32_bf16 v[60:63], v[24:27], v[158:161], v[32:35]
	v_mfma_f32_16x16x32_bf16 v[32:35], v[0:3], v[162:165], v[52:55]
	v_mfma_f32_16x16x32_bf16 v[48:51], v[8:11], v[166:169], v[32:35]
	v_mfma_f32_16x16x32_bf16 v[32:35], v[16:19], v[162:165], v[206:209]
	v_mfma_f32_16x16x32_bf16 v[52:55], v[24:27], v[166:169], v[32:35]
	v_mfma_f32_16x16x32_bf16 v[32:35], v[0:3], v[174:177], v[44:47]
	v_mfma_f32_16x16x32_bf16 v[40:43], v[8:11], v[178:181], v[32:35]
	v_mfma_f32_16x16x32_bf16 v[32:35], v[16:19], v[174:177], v[224:227]
	v_mfma_f32_16x16x32_bf16 v[0:3], v[0:3], v[182:185], v[36:39]
	v_mfma_f32_16x16x32_bf16 v[44:47], v[24:27], v[178:181], v[32:35]
	v_mfma_f32_16x16x32_bf16 v[32:35], v[8:11], v[228:231], v[0:3]
	v_mfma_f32_16x16x32_bf16 v[0:3], v[16:19], v[182:185], v[128:131]
	v_mfma_f32_16x16x32_bf16 v[36:39], v[24:27], v[228:231], v[0:3]
	s_setprio 0
	s_setprio 1
	v_mfma_f32_16x16x32_bf16 v[0:3], v[146:149], v[154:157], v[28:31]
	v_mfma_f32_16x16x32_bf16 v[24:27], v[186:189], v[158:161], v[0:3]
	v_mfma_f32_16x16x32_bf16 v[0:3], v[194:197], v[154:157], v[132:135]
	v_mfma_f32_16x16x32_bf16 v[28:31], v[198:201], v[158:161], v[0:3]
	v_mfma_f32_16x16x32_bf16 v[0:3], v[146:149], v[162:165], v[20:23]
	v_mfma_f32_16x16x32_bf16 v[16:19], v[186:189], v[166:169], v[0:3]
	v_mfma_f32_16x16x32_bf16 v[0:3], v[194:197], v[162:165], v[142:145]
	v_mfma_f32_16x16x32_bf16 v[20:23], v[198:201], v[166:169], v[0:3]
	v_mfma_f32_16x16x32_bf16 v[0:3], v[146:149], v[174:177], v[12:15]
	v_mfma_f32_16x16x32_bf16 v[8:11], v[186:189], v[178:181], v[0:3]
	v_mfma_f32_16x16x32_bf16 v[0:3], v[194:197], v[174:177], v[150:153]
	v_mfma_f32_16x16x32_bf16 v[12:15], v[198:201], v[178:181], v[0:3]
	v_mfma_f32_16x16x32_bf16 v[0:3], v[146:149], v[182:185], v[4:7]
	v_mfma_f32_16x16x32_bf16 v[4:7], v[194:197], v[182:185], v[170:173]
	v_mfma_f32_16x16x32_bf16 v[0:3], v[186:189], v[228:231], v[0:3]
	v_mfma_f32_16x16x32_bf16 v[4:7], v[198:201], v[228:231], v[4:7]
	s_setprio 0
	s_movk_i32 s4, 0x100
	v_cmp_gt_u32_e32 vcc, s4, v138
	s_barrier
	s_and_saveexec_b64 s[4:5], vcc
	s_cbranch_execz .LBB0_630
	s_barrier
